# GEMM 8-phase loops: s_setprio 1 moved ahead of the barrier opening each MFMA segment, duplicate lgkmcnt(0) dropped, closing barrier moved directly behind the last MFMA
# speedup vs baseline: 1.0062x; 1.0019x over previous
.LBB0_566:
	s_ashr_i32 s9, s8, 31
	v_cmp_lt_i64_e32 vcc, s[10:11], v[144:145]
	s_lshl_b64 s[10:11], s[8:9], 19
	s_add_u32 s10, s40, s10
	s_addc_u32 s11, s41, s11
	s_and_b64 s[12:13], vcc, exec
	s_cselect_b32 s9, s11, s17
	s_cselect_b32 s75, s10, s16
	s_ashr_i32 s7, s6, 31
	s_lshl_b64 s[12:13], s[6:7], 19
	s_add_u32 s12, s48, s12
	s_addc_u32 s13, s49, s13
	s_and_b64 s[18:19], vcc, exec
	s_cselect_b32 s7, s13, s35
	s_cselect_b32 s76, s12, s34
	s_add_u32 s16, s16, 0x40080
	s_addc_u32 s17, s17, 0
	s_add_u32 s77, s34, 0x100
	s_addc_u32 s78, s35, 0
	s_mov_b32 s79, -2
	ds_read_b128 v[154:157], v151
	ds_read_b128 v[158:161], v151 offset:1024
	ds_read_b128 v[162:165], v151 offset:2048
	ds_read_b128 v[166:169], v151 offset:3072
	s_add_u32 s18, s16, 0xfffc0080
	s_addc_u32 s19, s17, -1
	s_cmp_eq_u32 s79, 12
	s_cselect_b32 s19, s9, s19
	s_cselect_b32 s18, s75, s18
	s_cselect_b32 s35, s7, s78
	s_cselect_b32 s34, s76, s77
	v_lshl_add_u64 v[172:173], s[16:17], 0, v[140:141]
	s_add_i32 m0, s53, 0xc000
	ds_read_b128 v[176:179], v152
	ds_read_b128 v[180:183], v152 offset:1024
	ds_read_b128 v[184:187], v152 offset:2048
	ds_read_b128 v[188:191], v152 offset:3072
	ds_read_b128 v[192:195], v152 offset:4096
	ds_read_b128 v[196:199], v152 offset:5120
	ds_read_b128 v[200:203], v152 offset:6144
	ds_read_b128 v[204:207], v152 offset:7168
	global_load_lds_dwordx4 v[172:173], off
	v_lshl_add_u64 v[172:173], s[16:17], 0, v[142:143]
	s_add_i32 m0, s53, 0xe000
	s_nop 0
	global_load_lds_dwordx4 v[172:173], off
	s_waitcnt lgkmcnt(8)
	s_setprio 1
	s_barrier
	s_waitcnt lgkmcnt(0)
	v_mfma_f32_16x16x32_bf16 v[126:129], v[154:157], v[176:179], 0
	v_mfma_f32_16x16x32_bf16 v[122:125], v[162:165], v[176:179], 0
	v_mfma_f32_16x16x32_bf16 v[110:113], v[154:157], v[184:187], 0
	v_mfma_f32_16x16x32_bf16 v[106:109], v[162:165], v[184:187], 0
	v_mfma_f32_16x16x32_bf16 v[94:97], v[154:157], v[192:195], 0
	v_mfma_f32_16x16x32_bf16 v[90:93], v[162:165], v[192:195], 0
	v_mfma_f32_16x16x32_bf16 v[78:81], v[154:157], v[200:203], 0
	v_mfma_f32_16x16x32_bf16 v[74:77], v[162:165], v[200:203], 0
	v_mfma_f32_16x16x32_bf16 v[126:129], v[158:161], v[180:183], v[126:129]
	v_mfma_f32_16x16x32_bf16 v[122:125], v[166:169], v[180:183], v[122:125]
	v_mfma_f32_16x16x32_bf16 v[110:113], v[158:161], v[188:191], v[110:113]
	v_mfma_f32_16x16x32_bf16 v[106:109], v[166:169], v[188:191], v[106:109]
	v_mfma_f32_16x16x32_bf16 v[94:97], v[158:161], v[196:199], v[94:97]
	v_mfma_f32_16x16x32_bf16 v[90:93], v[166:169], v[196:199], v[90:93]
	v_mfma_f32_16x16x32_bf16 v[78:81], v[158:161], v[204:207], v[78:81]
	v_mfma_f32_16x16x32_bf16 v[74:77], v[166:169], v[204:207], v[74:77]
	s_barrier
	s_setprio 0
	s_add_i32 s20, s72, s52
	v_lshl_add_u64 v[172:173], s[34:35], 0, v[134:135]
	s_mov_b32 m0, s20
	ds_read_b128 v[208:211], v153
	ds_read_b128 v[212:215], v153 offset:1024
	ds_read_b128 v[216:219], v153 offset:2048
	ds_read_b128 v[220:223], v153 offset:3072
	global_load_lds_dwordx4 v[172:173], off
	v_lshl_add_u64 v[224:225], s[34:35], 0, v[130:131]
	s_add_i32 m0, s20, 0x2000
	s_nop 0
	global_load_lds_dwordx4 v[224:225], off
	s_setprio 1
	s_barrier
	s_waitcnt lgkmcnt(0)
	v_mfma_f32_16x16x32_bf16 v[118:121], v[208:211], v[176:179], 0
	v_mfma_f32_16x16x32_bf16 v[114:117], v[216:219], v[176:179], 0
	v_mfma_f32_16x16x32_bf16 v[102:105], v[208:211], v[184:187], 0
	v_mfma_f32_16x16x32_bf16 v[98:101], v[216:219], v[184:187], 0
	v_mfma_f32_16x16x32_bf16 v[86:89], v[208:211], v[192:195], 0
	v_mfma_f32_16x16x32_bf16 v[82:85], v[216:219], v[192:195], 0
	v_mfma_f32_16x16x32_bf16 v[70:73], v[208:211], v[200:203], 0
	v_mfma_f32_16x16x32_bf16 v[66:69], v[216:219], v[200:203], 0
	v_mfma_f32_16x16x32_bf16 v[118:121], v[212:215], v[180:183], v[118:121]
	v_mfma_f32_16x16x32_bf16 v[114:117], v[220:223], v[180:183], v[114:117]
	v_mfma_f32_16x16x32_bf16 v[102:105], v[212:215], v[188:191], v[102:105]
	v_mfma_f32_16x16x32_bf16 v[98:101], v[220:223], v[188:191], v[98:101]
	v_mfma_f32_16x16x32_bf16 v[86:89], v[212:215], v[196:199], v[86:89]
	v_mfma_f32_16x16x32_bf16 v[82:85], v[220:223], v[196:199], v[82:85]
	v_mfma_f32_16x16x32_bf16 v[70:73], v[212:215], v[204:207], v[70:73]
	v_mfma_f32_16x16x32_bf16 v[66:69], v[220:223], v[204:207], v[66:69]
	s_barrier
	s_setprio 0
	s_mov_b32 m0, s53
	v_lshl_add_u64 v[226:227], s[18:19], 0, v[136:137]
	ds_read_b128 v[176:179], v152 offset:16384
	ds_read_b128 v[180:183], v152 offset:17408
	ds_read_b128 v[184:187], v152 offset:18432
	ds_read_b128 v[188:191], v152 offset:19456
	ds_read_b128 v[192:195], v152 offset:20480
	ds_read_b128 v[196:199], v152 offset:21504
	ds_read_b128 v[200:203], v152 offset:22528
	ds_read_b128 v[204:207], v152 offset:23552
	global_load_lds_dwordx4 v[226:227], off
	v_lshl_add_u64 v[228:229], s[18:19], 0, v[132:133]
	s_mov_b32 m0, s54
	s_nop 0
	global_load_lds_dwordx4 v[228:229], off
	s_setprio 1
	s_barrier
	s_waitcnt lgkmcnt(0)
	v_mfma_f32_16x16x32_bf16 v[62:65], v[154:157], v[176:179], 0
	v_mfma_f32_16x16x32_bf16 v[58:61], v[162:165], v[176:179], 0
	v_mfma_f32_16x16x32_bf16 v[46:49], v[154:157], v[184:187], 0
	v_mfma_f32_16x16x32_bf16 v[42:45], v[162:165], v[184:187], 0
	v_mfma_f32_16x16x32_bf16 v[30:33], v[154:157], v[192:195], 0
	v_mfma_f32_16x16x32_bf16 v[26:29], v[162:165], v[192:195], 0
	v_mfma_f32_16x16x32_bf16 v[14:17], v[154:157], v[200:203], 0
	v_mfma_f32_16x16x32_bf16 v[10:13], v[162:165], v[200:203], 0
	v_mfma_f32_16x16x32_bf16 v[62:65], v[158:161], v[180:183], v[62:65]
	v_mfma_f32_16x16x32_bf16 v[58:61], v[166:169], v[180:183], v[58:61]
	v_mfma_f32_16x16x32_bf16 v[46:49], v[158:161], v[188:191], v[46:49]
	v_mfma_f32_16x16x32_bf16 v[42:45], v[166:169], v[188:191], v[42:45]
	v_mfma_f32_16x16x32_bf16 v[30:33], v[158:161], v[196:199], v[30:33]
	v_mfma_f32_16x16x32_bf16 v[26:29], v[166:169], v[196:199], v[26:29]
	v_mfma_f32_16x16x32_bf16 v[14:17], v[158:161], v[204:207], v[14:17]
	v_mfma_f32_16x16x32_bf16 v[10:13], v[166:169], v[204:207], v[10:13]
	s_barrier
	s_setprio 0
	s_add_u32 s20, s34, 0x40000
	s_addc_u32 s21, s35, 0
	s_add_i32 s60, s73, s52
	v_lshl_add_u64 v[154:155], s[20:21], 0, v[134:135]
	s_mov_b32 m0, s60
	s_nop 0
	global_load_lds_dwordx4 v[154:155], off
	v_lshl_add_u64 v[154:155], s[20:21], 0, v[130:131]
	s_add_i32 m0, s60, 0x2000
	s_nop 0
	global_load_lds_dwordx4 v[154:155], off
	s_waitcnt vmcnt(6)
	s_setprio 1
	s_barrier
	v_mfma_f32_16x16x32_bf16 v[54:57], v[208:211], v[176:179], 0
	v_mfma_f32_16x16x32_bf16 v[50:53], v[216:219], v[176:179], 0
	v_mfma_f32_16x16x32_bf16 v[38:41], v[208:211], v[184:187], 0
	v_mfma_f32_16x16x32_bf16 v[34:37], v[216:219], v[184:187], 0
	v_mfma_f32_16x16x32_bf16 v[22:25], v[208:211], v[192:195], 0
	v_mfma_f32_16x16x32_bf16 v[18:21], v[216:219], v[192:195], 0
	v_mfma_f32_16x16x32_bf16 v[6:9], v[208:211], v[200:203], 0
	v_mfma_f32_16x16x32_bf16 v[2:5], v[216:219], v[200:203], 0
	v_mfma_f32_16x16x32_bf16 v[54:57], v[212:215], v[180:183], v[54:57]
	v_mfma_f32_16x16x32_bf16 v[50:53], v[220:223], v[180:183], v[50:53]
	v_mfma_f32_16x16x32_bf16 v[38:41], v[212:215], v[188:191], v[38:41]
	v_mfma_f32_16x16x32_bf16 v[34:37], v[220:223], v[188:191], v[34:37]
	v_mfma_f32_16x16x32_bf16 v[22:25], v[212:215], v[196:199], v[22:25]
	v_mfma_f32_16x16x32_bf16 v[18:21], v[220:223], v[196:199], v[18:21]
	v_mfma_f32_16x16x32_bf16 v[6:9], v[212:215], v[204:207], v[6:9]
	v_mfma_f32_16x16x32_bf16 v[2:5], v[220:223], v[204:207], v[2:5]
	s_barrier
	s_setprio 0
	s_add_i32 s20, 0, 0x18000
	v_add_u32_e32 v166, s20, v150
	ds_read_b128 v[154:157], v166
	ds_read_b128 v[158:161], v166 offset:1024
	ds_read_b128 v[162:165], v166 offset:2048
	ds_read_b128 v[166:169], v166 offset:3072
	s_add_u32 s18, s18, 0x40000
	s_addc_u32 s19, s19, 0
	s_mov_b32 m0, s55
	v_lshl_add_u64 v[208:209], s[18:19], 0, v[136:137]
	ds_read_b128 v[176:179], v152 offset:32768
	ds_read_b128 v[180:183], v152 offset:33792
	ds_read_b128 v[184:187], v152 offset:34816
	ds_read_b128 v[188:191], v152 offset:35840
	ds_read_b128 v[192:195], v152 offset:36864
	ds_read_b128 v[196:199], v152 offset:37888
	ds_read_b128 v[200:203], v152 offset:38912
	ds_read_b128 v[204:207], v152 offset:39936
	global_load_lds_dwordx4 v[208:209], off
	v_lshl_add_u64 v[208:209], s[18:19], 0, v[132:133]
	s_mov_b32 m0, s56
	s_nop 0
	global_load_lds_dwordx4 v[208:209], off
	s_waitcnt lgkmcnt(8)
	s_setprio 1
	s_barrier
	s_waitcnt lgkmcnt(0)
	v_mfma_f32_16x16x32_bf16 v[126:129], v[154:157], v[176:179], v[126:129]
	v_mfma_f32_16x16x32_bf16 v[122:125], v[162:165], v[176:179], v[122:125]
	v_mfma_f32_16x16x32_bf16 v[110:113], v[154:157], v[184:187], v[110:113]
	v_mfma_f32_16x16x32_bf16 v[106:109], v[162:165], v[184:187], v[106:109]
	v_mfma_f32_16x16x32_bf16 v[94:97], v[154:157], v[192:195], v[94:97]
	v_mfma_f32_16x16x32_bf16 v[90:93], v[162:165], v[192:195], v[90:93]
	v_mfma_f32_16x16x32_bf16 v[78:81], v[154:157], v[200:203], v[78:81]
	v_mfma_f32_16x16x32_bf16 v[74:77], v[162:165], v[200:203], v[74:77]
	v_mfma_f32_16x16x32_bf16 v[126:129], v[158:161], v[180:183], v[126:129]
	v_mfma_f32_16x16x32_bf16 v[122:125], v[166:169], v[180:183], v[122:125]
	v_mfma_f32_16x16x32_bf16 v[110:113], v[158:161], v[188:191], v[110:113]
	v_mfma_f32_16x16x32_bf16 v[106:109], v[166:169], v[188:191], v[106:109]
	v_mfma_f32_16x16x32_bf16 v[94:97], v[158:161], v[196:199], v[94:97]
	v_mfma_f32_16x16x32_bf16 v[90:93], v[166:169], v[196:199], v[90:93]
	v_mfma_f32_16x16x32_bf16 v[78:81], v[158:161], v[204:207], v[78:81]
	v_mfma_f32_16x16x32_bf16 v[74:77], v[166:169], v[204:207], v[74:77]
	s_barrier
	s_setprio 0
	s_add_i32 s21, 0, 0x1c000
	s_add_i32 s18, s20, s52
	v_add_u32_e32 v171, s21, v150
	v_lshl_add_u64 v[172:173], v[172:173], 0, s[4:5]
	s_mov_b32 m0, s18
	ds_read_b128 v[208:211], v171
	ds_read_b128 v[212:215], v171 offset:1024
	ds_read_b128 v[216:219], v171 offset:2048
	ds_read_b128 v[220:223], v171 offset:3072
	global_load_lds_dwordx4 v[172:173], off
	v_lshl_add_u64 v[172:173], v[224:225], 0, s[4:5]
	s_add_i32 m0, s18, 0x2000
	s_nop 0
	global_load_lds_dwordx4 v[172:173], off
	s_setprio 1
	s_barrier
	s_waitcnt lgkmcnt(0)
	v_mfma_f32_16x16x32_bf16 v[118:121], v[208:211], v[176:179], v[118:121]
	v_mfma_f32_16x16x32_bf16 v[114:117], v[216:219], v[176:179], v[114:117]
	v_mfma_f32_16x16x32_bf16 v[102:105], v[208:211], v[184:187], v[102:105]
	v_mfma_f32_16x16x32_bf16 v[98:101], v[216:219], v[184:187], v[98:101]
	v_mfma_f32_16x16x32_bf16 v[86:89], v[208:211], v[192:195], v[86:89]
	v_mfma_f32_16x16x32_bf16 v[82:85], v[216:219], v[192:195], v[82:85]
	v_mfma_f32_16x16x32_bf16 v[70:73], v[208:211], v[200:203], v[70:73]
	v_mfma_f32_16x16x32_bf16 v[66:69], v[216:219], v[200:203], v[66:69]
	v_mfma_f32_16x16x32_bf16 v[118:121], v[212:215], v[180:183], v[118:121]
	v_mfma_f32_16x16x32_bf16 v[114:117], v[220:223], v[180:183], v[114:117]
	v_mfma_f32_16x16x32_bf16 v[102:105], v[212:215], v[188:191], v[102:105]
	v_mfma_f32_16x16x32_bf16 v[98:101], v[220:223], v[188:191], v[98:101]
	v_mfma_f32_16x16x32_bf16 v[86:89], v[212:215], v[196:199], v[86:89]
	v_mfma_f32_16x16x32_bf16 v[82:85], v[220:223], v[196:199], v[82:85]
	v_mfma_f32_16x16x32_bf16 v[70:73], v[212:215], v[204:207], v[70:73]
	v_mfma_f32_16x16x32_bf16 v[66:69], v[220:223], v[204:207], v[66:69]
	s_barrier
	s_setprio 0
	s_mov_b32 m0, s68
	v_lshl_add_u64 v[172:173], v[226:227], 0, s[4:5]
	ds_read_b128 v[176:179], v152 offset:49152
	ds_read_b128 v[180:183], v152 offset:50176
	ds_read_b128 v[184:187], v152 offset:51200
	ds_read_b128 v[188:191], v152 offset:52224
	ds_read_b128 v[192:195], v152 offset:53248
	ds_read_b128 v[196:199], v152 offset:54272
	ds_read_b128 v[200:203], v152 offset:55296
	ds_read_b128 v[204:207], v152 offset:56320
	global_load_lds_dwordx4 v[172:173], off
	v_lshl_add_u64 v[172:173], v[228:229], 0, s[4:5]
	s_mov_b32 m0, s69
	s_nop 0
	global_load_lds_dwordx4 v[172:173], off
	s_setprio 1
	s_barrier
	s_waitcnt lgkmcnt(0)
	v_mfma_f32_16x16x32_bf16 v[62:65], v[154:157], v[176:179], v[62:65]
	v_mfma_f32_16x16x32_bf16 v[58:61], v[162:165], v[176:179], v[58:61]
	v_mfma_f32_16x16x32_bf16 v[46:49], v[154:157], v[184:187], v[46:49]
	v_mfma_f32_16x16x32_bf16 v[42:45], v[162:165], v[184:187], v[42:45]
	v_mfma_f32_16x16x32_bf16 v[30:33], v[154:157], v[192:195], v[30:33]
	v_mfma_f32_16x16x32_bf16 v[26:29], v[162:165], v[192:195], v[26:29]
	v_mfma_f32_16x16x32_bf16 v[14:17], v[154:157], v[200:203], v[14:17]
	v_mfma_f32_16x16x32_bf16 v[10:13], v[162:165], v[200:203], v[10:13]
	v_mfma_f32_16x16x32_bf16 v[62:65], v[158:161], v[180:183], v[62:65]
	v_mfma_f32_16x16x32_bf16 v[58:61], v[166:169], v[180:183], v[58:61]
	v_mfma_f32_16x16x32_bf16 v[46:49], v[158:161], v[188:191], v[46:49]
	v_mfma_f32_16x16x32_bf16 v[42:45], v[166:169], v[188:191], v[42:45]
	v_mfma_f32_16x16x32_bf16 v[30:33], v[158:161], v[196:199], v[30:33]
	v_mfma_f32_16x16x32_bf16 v[26:29], v[166:169], v[196:199], v[26:29]
	v_mfma_f32_16x16x32_bf16 v[14:17], v[158:161], v[204:207], v[14:17]
	v_mfma_f32_16x16x32_bf16 v[10:13], v[166:169], v[204:207], v[10:13]
	s_barrier
	s_setprio 0
	s_add_u32 s18, s34, 0x40080
	s_addc_u32 s19, s35, 0
	s_add_i32 s20, s21, s52
	v_lshl_add_u64 v[154:155], s[18:19], 0, v[134:135]
	s_mov_b32 m0, s20
	s_nop 0
	global_load_lds_dwordx4 v[154:155], off
	v_lshl_add_u64 v[154:155], s[18:19], 0, v[130:131]
	s_add_i32 m0, s20, 0x2000
	s_nop 0
	global_load_lds_dwordx4 v[154:155], off
	s_waitcnt vmcnt(6)
	s_setprio 1
	s_barrier
	v_mfma_f32_16x16x32_bf16 v[54:57], v[208:211], v[176:179], v[54:57]
	v_mfma_f32_16x16x32_bf16 v[50:53], v[216:219], v[176:179], v[50:53]
	v_mfma_f32_16x16x32_bf16 v[38:41], v[208:211], v[184:187], v[38:41]
	v_mfma_f32_16x16x32_bf16 v[34:37], v[216:219], v[184:187], v[34:37]
	v_mfma_f32_16x16x32_bf16 v[22:25], v[208:211], v[192:195], v[22:25]
	v_mfma_f32_16x16x32_bf16 v[18:21], v[216:219], v[192:195], v[18:21]
	v_mfma_f32_16x16x32_bf16 v[6:9], v[208:211], v[200:203], v[6:9]
	v_mfma_f32_16x16x32_bf16 v[2:5], v[216:219], v[200:203], v[2:5]
	v_mfma_f32_16x16x32_bf16 v[54:57], v[212:215], v[180:183], v[54:57]
	v_mfma_f32_16x16x32_bf16 v[50:53], v[220:223], v[180:183], v[50:53]
	v_mfma_f32_16x16x32_bf16 v[38:41], v[212:215], v[188:191], v[38:41]
	v_mfma_f32_16x16x32_bf16 v[34:37], v[220:223], v[188:191], v[34:37]
	v_mfma_f32_16x16x32_bf16 v[22:25], v[212:215], v[196:199], v[22:25]
	v_mfma_f32_16x16x32_bf16 v[18:21], v[220:223], v[196:199], v[18:21]
	v_mfma_f32_16x16x32_bf16 v[6:9], v[212:215], v[204:207], v[6:9]
	v_mfma_f32_16x16x32_bf16 v[2:5], v[220:223], v[204:207], v[2:5]
	s_barrier
	s_setprio 0
	s_add_i32 s79, s79, 2
	s_add_u32 s16, s16, 0x100
	s_addc_u32 s17, s17, 0
	s_add_u32 s77, s77, 0x100
	s_addc_u32 s78, s78, 0
	s_cmp_gt_u32 s79, 13
.LBB0_567:
	ds_read_b128 v[154:157], v151
	ds_read_b128 v[158:161], v151 offset:1024
	ds_read_b128 v[162:165], v151 offset:2048
	ds_read_b128 v[166:169], v151 offset:3072
	s_add_u32 s18, s16, 0xfffc0080
	s_addc_u32 s19, s17, -1
	s_cmp_eq_u32 s79, 12
	s_cselect_b32 s19, s9, s19
	s_cselect_b32 s18, s75, s18
	s_cselect_b32 s35, s7, s78
	s_cselect_b32 s34, s76, s77
	v_lshl_add_u64 v[172:173], s[16:17], 0, v[140:141]
	s_add_i32 m0, s53, 0xc000
	ds_read_b128 v[176:179], v152
	ds_read_b128 v[180:183], v152 offset:1024
	ds_read_b128 v[184:187], v152 offset:2048
	ds_read_b128 v[188:191], v152 offset:3072
	ds_read_b128 v[192:195], v152 offset:4096
	ds_read_b128 v[196:199], v152 offset:5120
	ds_read_b128 v[200:203], v152 offset:6144
	ds_read_b128 v[204:207], v152 offset:7168
	global_load_lds_dwordx4 v[172:173], off
	v_lshl_add_u64 v[172:173], s[16:17], 0, v[142:143]
	s_add_i32 m0, s53, 0xe000
	s_nop 0
	global_load_lds_dwordx4 v[172:173], off
	s_waitcnt lgkmcnt(8)
	s_setprio 1
	s_barrier
	s_waitcnt lgkmcnt(0)
	v_mfma_f32_16x16x32_bf16 v[126:129], v[154:157], v[176:179], v[126:129]
	v_mfma_f32_16x16x32_bf16 v[122:125], v[162:165], v[176:179], v[122:125]
	v_mfma_f32_16x16x32_bf16 v[110:113], v[154:157], v[184:187], v[110:113]
	v_mfma_f32_16x16x32_bf16 v[106:109], v[162:165], v[184:187], v[106:109]
	v_mfma_f32_16x16x32_bf16 v[94:97], v[154:157], v[192:195], v[94:97]
	v_mfma_f32_16x16x32_bf16 v[90:93], v[162:165], v[192:195], v[90:93]
	v_mfma_f32_16x16x32_bf16 v[78:81], v[154:157], v[200:203], v[78:81]
	v_mfma_f32_16x16x32_bf16 v[74:77], v[162:165], v[200:203], v[74:77]
	v_mfma_f32_16x16x32_bf16 v[126:129], v[158:161], v[180:183], v[126:129]
	v_mfma_f32_16x16x32_bf16 v[122:125], v[166:169], v[180:183], v[122:125]
	v_mfma_f32_16x16x32_bf16 v[110:113], v[158:161], v[188:191], v[110:113]
	v_mfma_f32_16x16x32_bf16 v[106:109], v[166:169], v[188:191], v[106:109]
	v_mfma_f32_16x16x32_bf16 v[94:97], v[158:161], v[196:199], v[94:97]
	v_mfma_f32_16x16x32_bf16 v[90:93], v[166:169], v[196:199], v[90:93]
	v_mfma_f32_16x16x32_bf16 v[78:81], v[158:161], v[204:207], v[78:81]
	v_mfma_f32_16x16x32_bf16 v[74:77], v[166:169], v[204:207], v[74:77]
	s_barrier
	s_setprio 0
	s_add_i32 s20, s72, s52
	v_lshl_add_u64 v[172:173], s[34:35], 0, v[134:135]
	s_mov_b32 m0, s20
	ds_read_b128 v[208:211], v153
	ds_read_b128 v[212:215], v153 offset:1024
	ds_read_b128 v[216:219], v153 offset:2048
	ds_read_b128 v[220:223], v153 offset:3072
	global_load_lds_dwordx4 v[172:173], off
	v_lshl_add_u64 v[224:225], s[34:35], 0, v[130:131]
	s_add_i32 m0, s20, 0x2000
	s_nop 0
	global_load_lds_dwordx4 v[224:225], off
	s_setprio 1
	s_barrier
	s_waitcnt lgkmcnt(0)
	v_mfma_f32_16x16x32_bf16 v[118:121], v[208:211], v[176:179], v[118:121]
	v_mfma_f32_16x16x32_bf16 v[114:117], v[216:219], v[176:179], v[114:117]
	v_mfma_f32_16x16x32_bf16 v[102:105], v[208:211], v[184:187], v[102:105]
	v_mfma_f32_16x16x32_bf16 v[98:101], v[216:219], v[184:187], v[98:101]
	v_mfma_f32_16x16x32_bf16 v[86:89], v[208:211], v[192:195], v[86:89]
	v_mfma_f32_16x16x32_bf16 v[82:85], v[216:219], v[192:195], v[82:85]
	v_mfma_f32_16x16x32_bf16 v[70:73], v[208:211], v[200:203], v[70:73]
	v_mfma_f32_16x16x32_bf16 v[66:69], v[216:219], v[200:203], v[66:69]
	v_mfma_f32_16x16x32_bf16 v[118:121], v[212:215], v[180:183], v[118:121]
	v_mfma_f32_16x16x32_bf16 v[114:117], v[220:223], v[180:183], v[114:117]
	v_mfma_f32_16x16x32_bf16 v[102:105], v[212:215], v[188:191], v[102:105]
	v_mfma_f32_16x16x32_bf16 v[98:101], v[220:223], v[188:191], v[98:101]
	v_mfma_f32_16x16x32_bf16 v[86:89], v[212:215], v[196:199], v[86:89]
	v_mfma_f32_16x16x32_bf16 v[82:85], v[220:223], v[196:199], v[82:85]
	v_mfma_f32_16x16x32_bf16 v[70:73], v[212:215], v[204:207], v[70:73]
	v_mfma_f32_16x16x32_bf16 v[66:69], v[220:223], v[204:207], v[66:69]
	s_barrier
	s_setprio 0
	s_mov_b32 m0, s53
	v_lshl_add_u64 v[226:227], s[18:19], 0, v[136:137]
	ds_read_b128 v[176:179], v152 offset:16384
	ds_read_b128 v[180:183], v152 offset:17408
	ds_read_b128 v[184:187], v152 offset:18432
	ds_read_b128 v[188:191], v152 offset:19456
	ds_read_b128 v[192:195], v152 offset:20480
	ds_read_b128 v[196:199], v152 offset:21504
	ds_read_b128 v[200:203], v152 offset:22528
	ds_read_b128 v[204:207], v152 offset:23552
	global_load_lds_dwordx4 v[226:227], off
	v_lshl_add_u64 v[228:229], s[18:19], 0, v[132:133]
	s_mov_b32 m0, s54
	s_nop 0
	global_load_lds_dwordx4 v[228:229], off
	s_setprio 1
	s_barrier
	s_waitcnt lgkmcnt(0)
	v_mfma_f32_16x16x32_bf16 v[62:65], v[154:157], v[176:179], v[62:65]
	v_mfma_f32_16x16x32_bf16 v[58:61], v[162:165], v[176:179], v[58:61]
	v_mfma_f32_16x16x32_bf16 v[46:49], v[154:157], v[184:187], v[46:49]
	v_mfma_f32_16x16x32_bf16 v[42:45], v[162:165], v[184:187], v[42:45]
	v_mfma_f32_16x16x32_bf16 v[30:33], v[154:157], v[192:195], v[30:33]
	v_mfma_f32_16x16x32_bf16 v[26:29], v[162:165], v[192:195], v[26:29]
	v_mfma_f32_16x16x32_bf16 v[14:17], v[154:157], v[200:203], v[14:17]
	v_mfma_f32_16x16x32_bf16 v[10:13], v[162:165], v[200:203], v[10:13]
	v_mfma_f32_16x16x32_bf16 v[62:65], v[158:161], v[180:183], v[62:65]
	v_mfma_f32_16x16x32_bf16 v[58:61], v[166:169], v[180:183], v[58:61]
	v_mfma_f32_16x16x32_bf16 v[46:49], v[158:161], v[188:191], v[46:49]
	v_mfma_f32_16x16x32_bf16 v[42:45], v[166:169], v[188:191], v[42:45]
	v_mfma_f32_16x16x32_bf16 v[30:33], v[158:161], v[196:199], v[30:33]
	v_mfma_f32_16x16x32_bf16 v[26:29], v[166:169], v[196:199], v[26:29]
	v_mfma_f32_16x16x32_bf16 v[14:17], v[158:161], v[204:207], v[14:17]
	v_mfma_f32_16x16x32_bf16 v[10:13], v[166:169], v[204:207], v[10:13]
	s_barrier
	s_setprio 0
	s_add_u32 s20, s34, 0x40000
	s_addc_u32 s21, s35, 0
	s_add_i32 s60, s73, s52
	v_lshl_add_u64 v[154:155], s[20:21], 0, v[134:135]
	s_mov_b32 m0, s60
	s_nop 0
	global_load_lds_dwordx4 v[154:155], off
	v_lshl_add_u64 v[154:155], s[20:21], 0, v[130:131]
	s_add_i32 m0, s60, 0x2000
	s_nop 0
	global_load_lds_dwordx4 v[154:155], off
	s_waitcnt vmcnt(6)
	s_setprio 1
	s_barrier
	v_mfma_f32_16x16x32_bf16 v[54:57], v[208:211], v[176:179], v[54:57]
	v_mfma_f32_16x16x32_bf16 v[50:53], v[216:219], v[176:179], v[50:53]
	v_mfma_f32_16x16x32_bf16 v[38:41], v[208:211], v[184:187], v[38:41]
	v_mfma_f32_16x16x32_bf16 v[34:37], v[216:219], v[184:187], v[34:37]
	v_mfma_f32_16x16x32_bf16 v[22:25], v[208:211], v[192:195], v[22:25]
	v_mfma_f32_16x16x32_bf16 v[18:21], v[216:219], v[192:195], v[18:21]
	v_mfma_f32_16x16x32_bf16 v[6:9], v[208:211], v[200:203], v[6:9]
	v_mfma_f32_16x16x32_bf16 v[2:5], v[216:219], v[200:203], v[2:5]
	v_mfma_f32_16x16x32_bf16 v[54:57], v[212:215], v[180:183], v[54:57]
	v_mfma_f32_16x16x32_bf16 v[50:53], v[220:223], v[180:183], v[50:53]
	v_mfma_f32_16x16x32_bf16 v[38:41], v[212:215], v[188:191], v[38:41]
	v_mfma_f32_16x16x32_bf16 v[34:37], v[220:223], v[188:191], v[34:37]
	v_mfma_f32_16x16x32_bf16 v[22:25], v[212:215], v[196:199], v[22:25]
	v_mfma_f32_16x16x32_bf16 v[18:21], v[220:223], v[196:199], v[18:21]
	v_mfma_f32_16x16x32_bf16 v[6:9], v[212:215], v[204:207], v[6:9]
	v_mfma_f32_16x16x32_bf16 v[2:5], v[220:223], v[204:207], v[2:5]
	s_barrier
	s_setprio 0
	s_add_i32 s20, 0, 0x18000
	v_add_u32_e32 v166, s20, v150
	ds_read_b128 v[154:157], v166
	ds_read_b128 v[158:161], v166 offset:1024
	ds_read_b128 v[162:165], v166 offset:2048
	ds_read_b128 v[166:169], v166 offset:3072
	s_add_u32 s18, s18, 0x40000
	s_addc_u32 s19, s19, 0
	s_mov_b32 m0, s55
	v_lshl_add_u64 v[208:209], s[18:19], 0, v[136:137]
	ds_read_b128 v[176:179], v152 offset:32768
	ds_read_b128 v[180:183], v152 offset:33792
	ds_read_b128 v[184:187], v152 offset:34816
	ds_read_b128 v[188:191], v152 offset:35840
	ds_read_b128 v[192:195], v152 offset:36864
	ds_read_b128 v[196:199], v152 offset:37888
	ds_read_b128 v[200:203], v152 offset:38912
	ds_read_b128 v[204:207], v152 offset:39936
	global_load_lds_dwordx4 v[208:209], off
	v_lshl_add_u64 v[208:209], s[18:19], 0, v[132:133]
	s_mov_b32 m0, s56
	s_nop 0
	global_load_lds_dwordx4 v[208:209], off
	s_waitcnt lgkmcnt(8)
	s_setprio 1
	s_barrier
	s_waitcnt lgkmcnt(0)
	v_mfma_f32_16x16x32_bf16 v[126:129], v[154:157], v[176:179], v[126:129]
	v_mfma_f32_16x16x32_bf16 v[122:125], v[162:165], v[176:179], v[122:125]
	v_mfma_f32_16x16x32_bf16 v[110:113], v[154:157], v[184:187], v[110:113]
	v_mfma_f32_16x16x32_bf16 v[106:109], v[162:165], v[184:187], v[106:109]
	v_mfma_f32_16x16x32_bf16 v[94:97], v[154:157], v[192:195], v[94:97]
	v_mfma_f32_16x16x32_bf16 v[90:93], v[162:165], v[192:195], v[90:93]
	v_mfma_f32_16x16x32_bf16 v[78:81], v[154:157], v[200:203], v[78:81]
	v_mfma_f32_16x16x32_bf16 v[74:77], v[162:165], v[200:203], v[74:77]
	v_mfma_f32_16x16x32_bf16 v[126:129], v[158:161], v[180:183], v[126:129]
	v_mfma_f32_16x16x32_bf16 v[122:125], v[166:169], v[180:183], v[122:125]
	v_mfma_f32_16x16x32_bf16 v[110:113], v[158:161], v[188:191], v[110:113]
	v_mfma_f32_16x16x32_bf16 v[106:109], v[166:169], v[188:191], v[106:109]
	v_mfma_f32_16x16x32_bf16 v[94:97], v[158:161], v[196:199], v[94:97]
	v_mfma_f32_16x16x32_bf16 v[90:93], v[166:169], v[196:199], v[90:93]
	v_mfma_f32_16x16x32_bf16 v[78:81], v[158:161], v[204:207], v[78:81]
	v_mfma_f32_16x16x32_bf16 v[74:77], v[166:169], v[204:207], v[74:77]
	s_barrier
	s_setprio 0
	s_add_i32 s21, 0, 0x1c000
	s_add_i32 s18, s20, s52
	v_add_u32_e32 v171, s21, v150
	v_lshl_add_u64 v[172:173], v[172:173], 0, s[4:5]
	s_mov_b32 m0, s18
	ds_read_b128 v[208:211], v171
	ds_read_b128 v[212:215], v171 offset:1024
	ds_read_b128 v[216:219], v171 offset:2048
	ds_read_b128 v[220:223], v171 offset:3072
	global_load_lds_dwordx4 v[172:173], off
	v_lshl_add_u64 v[172:173], v[224:225], 0, s[4:5]
	s_add_i32 m0, s18, 0x2000
	s_nop 0
	global_load_lds_dwordx4 v[172:173], off
	s_setprio 1
	s_barrier
	s_waitcnt lgkmcnt(0)
	v_mfma_f32_16x16x32_bf16 v[118:121], v[208:211], v[176:179], v[118:121]
	v_mfma_f32_16x16x32_bf16 v[114:117], v[216:219], v[176:179], v[114:117]
	v_mfma_f32_16x16x32_bf16 v[102:105], v[208:211], v[184:187], v[102:105]
	v_mfma_f32_16x16x32_bf16 v[98:101], v[216:219], v[184:187], v[98:101]
	v_mfma_f32_16x16x32_bf16 v[86:89], v[208:211], v[192:195], v[86:89]
	v_mfma_f32_16x16x32_bf16 v[82:85], v[216:219], v[192:195], v[82:85]
	v_mfma_f32_16x16x32_bf16 v[70:73], v[208:211], v[200:203], v[70:73]
	v_mfma_f32_16x16x32_bf16 v[66:69], v[216:219], v[200:203], v[66:69]
	v_mfma_f32_16x16x32_bf16 v[118:121], v[212:215], v[180:183], v[118:121]
	v_mfma_f32_16x16x32_bf16 v[114:117], v[220:223], v[180:183], v[114:117]
	v_mfma_f32_16x16x32_bf16 v[102:105], v[212:215], v[188:191], v[102:105]
	v_mfma_f32_16x16x32_bf16 v[98:101], v[220:223], v[188:191], v[98:101]
	v_mfma_f32_16x16x32_bf16 v[86:89], v[212:215], v[196:199], v[86:89]
	v_mfma_f32_16x16x32_bf16 v[82:85], v[220:223], v[196:199], v[82:85]
	v_mfma_f32_16x16x32_bf16 v[70:73], v[212:215], v[204:207], v[70:73]
	v_mfma_f32_16x16x32_bf16 v[66:69], v[220:223], v[204:207], v[66:69]
	s_barrier
	s_setprio 0
	s_mov_b32 m0, s68
	v_lshl_add_u64 v[172:173], v[226:227], 0, s[4:5]
	ds_read_b128 v[176:179], v152 offset:49152
	ds_read_b128 v[180:183], v152 offset:50176
	ds_read_b128 v[184:187], v152 offset:51200
	ds_read_b128 v[188:191], v152 offset:52224
	ds_read_b128 v[192:195], v152 offset:53248
	ds_read_b128 v[196:199], v152 offset:54272
	ds_read_b128 v[200:203], v152 offset:55296
	ds_read_b128 v[204:207], v152 offset:56320
	global_load_lds_dwordx4 v[172:173], off
	v_lshl_add_u64 v[172:173], v[228:229], 0, s[4:5]
	s_mov_b32 m0, s69
	s_nop 0
	global_load_lds_dwordx4 v[172:173], off
	s_setprio 1
	s_barrier
	s_waitcnt lgkmcnt(0)
	v_mfma_f32_16x16x32_bf16 v[62:65], v[154:157], v[176:179], v[62:65]
	v_mfma_f32_16x16x32_bf16 v[58:61], v[162:165], v[176:179], v[58:61]
	v_mfma_f32_16x16x32_bf16 v[46:49], v[154:157], v[184:187], v[46:49]
	v_mfma_f32_16x16x32_bf16 v[42:45], v[162:165], v[184:187], v[42:45]
	v_mfma_f32_16x16x32_bf16 v[30:33], v[154:157], v[192:195], v[30:33]
	v_mfma_f32_16x16x32_bf16 v[26:29], v[162:165], v[192:195], v[26:29]
	v_mfma_f32_16x16x32_bf16 v[14:17], v[154:157], v[200:203], v[14:17]
	v_mfma_f32_16x16x32_bf16 v[10:13], v[162:165], v[200:203], v[10:13]
	v_mfma_f32_16x16x32_bf16 v[62:65], v[158:161], v[180:183], v[62:65]
	v_mfma_f32_16x16x32_bf16 v[58:61], v[166:169], v[180:183], v[58:61]
	v_mfma_f32_16x16x32_bf16 v[46:49], v[158:161], v[188:191], v[46:49]
	v_mfma_f32_16x16x32_bf16 v[42:45], v[166:169], v[188:191], v[42:45]
	v_mfma_f32_16x16x32_bf16 v[30:33], v[158:161], v[196:199], v[30:33]
	v_mfma_f32_16x16x32_bf16 v[26:29], v[166:169], v[196:199], v[26:29]
	v_mfma_f32_16x16x32_bf16 v[14:17], v[158:161], v[204:207], v[14:17]
	v_mfma_f32_16x16x32_bf16 v[10:13], v[166:169], v[204:207], v[10:13]
	s_barrier
	s_setprio 0
	s_add_u32 s18, s34, 0x40080
	s_addc_u32 s19, s35, 0
	s_add_i32 s20, s21, s52
	v_lshl_add_u64 v[154:155], s[18:19], 0, v[134:135]
	s_mov_b32 m0, s20
	s_nop 0
	global_load_lds_dwordx4 v[154:155], off
	v_lshl_add_u64 v[154:155], s[18:19], 0, v[130:131]
	s_add_i32 m0, s20, 0x2000
	s_nop 0
	global_load_lds_dwordx4 v[154:155], off
	s_waitcnt vmcnt(6)
	s_setprio 1
	s_barrier
	v_mfma_f32_16x16x32_bf16 v[54:57], v[208:211], v[176:179], v[54:57]
	v_mfma_f32_16x16x32_bf16 v[50:53], v[216:219], v[176:179], v[50:53]
	v_mfma_f32_16x16x32_bf16 v[38:41], v[208:211], v[184:187], v[38:41]
	v_mfma_f32_16x16x32_bf16 v[34:37], v[216:219], v[184:187], v[34:37]
	v_mfma_f32_16x16x32_bf16 v[22:25], v[208:211], v[192:195], v[22:25]
	v_mfma_f32_16x16x32_bf16 v[18:21], v[216:219], v[192:195], v[18:21]
	v_mfma_f32_16x16x32_bf16 v[6:9], v[208:211], v[200:203], v[6:9]
	v_mfma_f32_16x16x32_bf16 v[2:5], v[216:219], v[200:203], v[2:5]
	v_mfma_f32_16x16x32_bf16 v[54:57], v[212:215], v[180:183], v[54:57]
	v_mfma_f32_16x16x32_bf16 v[50:53], v[220:223], v[180:183], v[50:53]
	v_mfma_f32_16x16x32_bf16 v[38:41], v[212:215], v[188:191], v[38:41]
	v_mfma_f32_16x16x32_bf16 v[34:37], v[220:223], v[188:191], v[34:37]
	v_mfma_f32_16x16x32_bf16 v[22:25], v[212:215], v[196:199], v[22:25]
	v_mfma_f32_16x16x32_bf16 v[18:21], v[220:223], v[196:199], v[18:21]
	v_mfma_f32_16x16x32_bf16 v[6:9], v[212:215], v[204:207], v[6:9]
	v_mfma_f32_16x16x32_bf16 v[2:5], v[220:223], v[204:207], v[2:5]
	s_barrier
	s_setprio 0
	s_add_i32 s79, s79, 2
	s_add_u32 s16, s16, 0x100
	s_addc_u32 s17, s17, 0
	s_add_u32 s77, s77, 0x100
	s_addc_u32 s78, s78, 0
	s_cmp_gt_u32 s79, 13
	s_cbranch_scc0 .LBB0_567
	v_mul_f32_e32 v154, 0xbfb8aa3b, v126
	v_mul_f32_e32 v155, 0xbfb8aa3b, v127
	v_exp_f32_e32 v154, v154
	v_exp_f32_e32 v155, v155
	s_and_b64 vcc, exec, s[2:3]
	s_mov_b64 s[34:35], s[12:13]
	v_add_f32_e32 v154, 1.0, v154
	v_add_f32_e32 v155, 1.0, v155
	v_rcp_f32_e32 v156, v154
	v_rcp_f32_e32 v157, v155
	v_mul_f32_e32 v155, 0xbfb8aa3b, v128
	v_exp_f32_e32 v155, v155
	v_lshl_add_u32 v154, s14, 8, v149
	v_pk_mul_f32 v[126:127], v[126:127], v[156:157]
	v_mul_f32_e32 v156, 0xbfb8aa3b, v129
	v_exp_f32_e32 v156, v156
	v_pk_mul_f32 v[118:119], v[126:127], v[118:119]
	v_add_f32_e32 v126, 1.0, v155
	v_mul_f32_e32 v155, 0xbfb8aa3b, v122
	v_add_f32_e32 v127, 1.0, v156
	v_rcp_f32_e32 v126, v126
	v_rcp_f32_e32 v127, v127
	v_exp_f32_e32 v155, v155
	v_mul_f32_e32 v156, 0xbfb8aa3b, v123
	v_exp_f32_e32 v156, v156
	v_pk_mul_f32 v[126:127], v[128:129], v[126:127]
	v_add_f32_e32 v128, 1.0, v155
	v_mul_f32_e32 v155, 0xbfb8aa3b, v124
	v_add_f32_e32 v129, 1.0, v156
	v_exp_f32_e32 v155, v155
	v_mul_f32_e32 v156, 0xbfb8aa3b, v125
	v_exp_f32_e32 v157, v156
	v_rcp_f32_e32 v128, v128
	v_add_f32_e32 v155, 1.0, v155
	v_rcp_f32_e32 v129, v129
	v_rcp_f32_e32 v156, v155
	v_add_f32_e32 v155, 1.0, v157
	v_rcp_f32_e32 v157, v155
	v_pk_mul_f32 v[122:123], v[122:123], v[128:129]
	s_lshl_b32 s14, s15, 7
	v_pk_mul_f32 v[122:123], v[122:123], v[114:115]
	v_pk_mul_f32 v[114:115], v[124:125], v[156:157]
	s_ashr_i32 s15, s14, 31
	v_pk_mul_f32 v[124:125], v[114:115], v[116:117]
	v_mov_b64_e32 v[114:115], s[0:1]
	v_mad_i64_i32 v[116:117], s[16:17], v154, s74, v[114:115]
	s_lshl_b64 s[14:15], s[14:15], 1
	v_lshl_add_u64 v[116:117], v[116:117], 0, s[14:15]
	v_pk_mul_f32 v[120:121], v[126:127], v[120:121]
	v_lshl_add_u64 v[126:127], v[116:117], 0, v[138:139]
	v_cvt_pk_bf16_f32 v116, v118, v119
	v_mul_f32_e32 v118, 0xbfb8aa3b, v110
	v_exp_f32_e32 v119, v118
	v_mul_f32_e32 v118, 0xbfb8aa3b, v111
	v_cvt_pk_bf16_f32 v117, v120, v121
	v_exp_f32_e32 v121, v118
	v_add_f32_e32 v119, 1.0, v119
	v_rcp_f32_e32 v120, v119
	v_cvt_pk_bf16_f32 v118, v122, v123
	v_add_f32_e32 v119, 1.0, v121
	v_rcp_f32_e32 v121, v119
	v_cvt_pk_bf16_f32 v119, v124, v125
	global_store_dwordx4 v[126:127], v[116:119], off nt
	v_pk_mul_f32 v[110:111], v[110:111], v[120:121]
	s_nop 0
	v_mul_f32_e32 v116, 0xbfb8aa3b, v112
	v_mul_f32_e32 v117, 0xbfb8aa3b, v113
	v_exp_f32_e32 v116, v116
	v_exp_f32_e32 v117, v117
	v_pk_mul_f32 v[102:103], v[110:111], v[102:103]
	v_or_b32_e32 v118, 16, v154
	v_add_f32_e32 v110, 1.0, v116
	v_add_f32_e32 v111, 1.0, v117
	v_mul_f32_e32 v116, 0xbfb8aa3b, v106
	v_mul_f32_e32 v117, 0xbfb8aa3b, v107
	v_rcp_f32_e32 v110, v110
	v_rcp_f32_e32 v111, v111
	v_exp_f32_e32 v116, v116
	v_exp_f32_e32 v117, v117
	v_pk_mul_f32 v[110:111], v[112:113], v[110:111]
	v_add_f32_e32 v112, 1.0, v116
	v_add_f32_e32 v113, 1.0, v117
	v_mul_f32_e32 v116, 0xbfb8aa3b, v108
	v_mul_f32_e32 v117, 0xbfb8aa3b, v109
	v_exp_f32_e32 v116, v116
	v_exp_f32_e32 v117, v117
	v_rcp_f32_e32 v112, v112
	v_rcp_f32_e32 v113, v113
	v_add_f32_e32 v116, 1.0, v116
	v_add_f32_e32 v117, 1.0, v117
	v_rcp_f32_e32 v116, v116
	v_rcp_f32_e32 v117, v117
	v_pk_mul_f32 v[106:107], v[106:107], v[112:113]
	v_pk_mul_f32 v[104:105], v[110:111], v[104:105]
	v_pk_mul_f32 v[106:107], v[106:107], v[98:99]
	v_pk_mul_f32 v[98:99], v[108:109], v[116:117]
	s_nop 0
	v_pk_mul_f32 v[108:109], v[98:99], v[100:101]
	v_mad_i64_i32 v[98:99], s[16:17], v118, s74, v[114:115]
	v_mul_f32_e32 v100, 0xbfb8aa3b, v94
	v_lshl_add_u64 v[98:99], v[98:99], 0, s[14:15]
	v_exp_f32_e32 v101, v100
	v_mul_f32_e32 v100, 0xbfb8aa3b, v95
	v_lshl_add_u64 v[110:111], v[98:99], 0, v[138:139]
	v_cvt_pk_bf16_f32 v98, v102, v103
	v_exp_f32_e32 v103, v100
	v_add_f32_e32 v101, 1.0, v101
	v_rcp_f32_e32 v102, v101
	v_cvt_pk_bf16_f32 v99, v104, v105
	v_add_f32_e32 v101, 1.0, v103
	v_cvt_pk_bf16_f32 v100, v106, v107
	v_rcp_f32_e32 v103, v101
	v_cvt_pk_bf16_f32 v101, v108, v109
	global_store_dwordx4 v[110:111], v[98:101], off nt
	v_pk_mul_f32 v[94:95], v[94:95], v[102:103]
	s_nop 0
	v_mul_f32_e32 v98, 0xbfb8aa3b, v96
	v_mul_f32_e32 v99, 0xbfb8aa3b, v97
	v_exp_f32_e32 v98, v98
	v_exp_f32_e32 v99, v99
	v_pk_mul_f32 v[86:87], v[94:95], v[86:87]
	v_or_b32_e32 v100, 32, v154
	v_add_f32_e32 v94, 1.0, v98
	v_add_f32_e32 v95, 1.0, v99
	v_mul_f32_e32 v98, 0xbfb8aa3b, v90
	v_mul_f32_e32 v99, 0xbfb8aa3b, v91
	v_rcp_f32_e32 v94, v94
	v_rcp_f32_e32 v95, v95
	v_exp_f32_e32 v98, v98
	v_exp_f32_e32 v99, v99
	v_pk_mul_f32 v[94:95], v[96:97], v[94:95]
	v_add_f32_e32 v96, 1.0, v98
	v_add_f32_e32 v97, 1.0, v99
	v_mul_f32_e32 v98, 0xbfb8aa3b, v92
	v_mul_f32_e32 v99, 0xbfb8aa3b, v93
	v_exp_f32_e32 v98, v98
	v_exp_f32_e32 v99, v99
	v_rcp_f32_e32 v96, v96
	v_rcp_f32_e32 v97, v97
	v_add_f32_e32 v98, 1.0, v98
	v_add_f32_e32 v99, 1.0, v99
	v_rcp_f32_e32 v98, v98
	v_rcp_f32_e32 v99, v99
	v_pk_mul_f32 v[90:91], v[90:91], v[96:97]
	v_pk_mul_f32 v[88:89], v[94:95], v[88:89]
	v_pk_mul_f32 v[90:91], v[90:91], v[82:83]
	v_pk_mul_f32 v[82:83], v[92:93], v[98:99]
	s_nop 0
	v_pk_mul_f32 v[92:93], v[82:83], v[84:85]
	v_mad_i64_i32 v[82:83], s[16:17], v100, s74, v[114:115]
	v_mul_f32_e32 v84, 0xbfb8aa3b, v78
	v_lshl_add_u64 v[82:83], v[82:83], 0, s[14:15]
	v_exp_f32_e32 v85, v84
	v_mul_f32_e32 v84, 0xbfb8aa3b, v79
	v_lshl_add_u64 v[94:95], v[82:83], 0, v[138:139]
	v_cvt_pk_bf16_f32 v82, v86, v87
	v_exp_f32_e32 v87, v84
	v_add_f32_e32 v85, 1.0, v85
	v_rcp_f32_e32 v86, v85
	v_cvt_pk_bf16_f32 v83, v88, v89
	v_add_f32_e32 v85, 1.0, v87
	v_cvt_pk_bf16_f32 v84, v90, v91
	v_rcp_f32_e32 v87, v85
	v_cvt_pk_bf16_f32 v85, v92, v93
	global_store_dwordx4 v[94:95], v[82:85], off nt
	v_pk_mul_f32 v[78:79], v[78:79], v[86:87]
	s_nop 0
	v_mul_f32_e32 v82, 0xbfb8aa3b, v80
	v_mul_f32_e32 v83, 0xbfb8aa3b, v81
	v_exp_f32_e32 v82, v82
	v_exp_f32_e32 v83, v83
	v_pk_mul_f32 v[70:71], v[78:79], v[70:71]
	v_or_b32_e32 v84, 48, v154
	v_add_f32_e32 v78, 1.0, v82
	v_add_f32_e32 v79, 1.0, v83
	v_mul_f32_e32 v82, 0xbfb8aa3b, v74
	v_mul_f32_e32 v83, 0xbfb8aa3b, v75
	v_rcp_f32_e32 v78, v78
	v_rcp_f32_e32 v79, v79
	v_exp_f32_e32 v82, v82
	v_exp_f32_e32 v83, v83
	v_pk_mul_f32 v[78:79], v[80:81], v[78:79]
	v_add_f32_e32 v80, 1.0, v82
	v_add_f32_e32 v81, 1.0, v83
	v_mul_f32_e32 v82, 0xbfb8aa3b, v76
	v_mul_f32_e32 v83, 0xbfb8aa3b, v77
	v_exp_f32_e32 v82, v82
	v_exp_f32_e32 v83, v83
	v_rcp_f32_e32 v80, v80
	v_rcp_f32_e32 v81, v81
	v_add_f32_e32 v82, 1.0, v82
	v_add_f32_e32 v83, 1.0, v83
	v_rcp_f32_e32 v82, v82
	v_rcp_f32_e32 v83, v83
	v_pk_mul_f32 v[74:75], v[74:75], v[80:81]
	v_pk_mul_f32 v[72:73], v[78:79], v[72:73]
	v_pk_mul_f32 v[74:75], v[74:75], v[66:67]
	v_pk_mul_f32 v[66:67], v[76:77], v[82:83]
	s_nop 0
	v_pk_mul_f32 v[76:77], v[66:67], v[68:69]
	v_mad_i64_i32 v[66:67], s[16:17], v84, s74, v[114:115]
	v_mul_f32_e32 v68, 0xbfb8aa3b, v62
	v_lshl_add_u64 v[66:67], v[66:67], 0, s[14:15]
	v_exp_f32_e32 v69, v68
	v_mul_f32_e32 v68, 0xbfb8aa3b, v63
	v_lshl_add_u64 v[78:79], v[66:67], 0, v[138:139]
	v_cvt_pk_bf16_f32 v66, v70, v71
	v_exp_f32_e32 v71, v68
	v_add_f32_e32 v69, 1.0, v69
	v_rcp_f32_e32 v70, v69
	v_cvt_pk_bf16_f32 v67, v72, v73
	v_add_f32_e32 v69, 1.0, v71
	v_cvt_pk_bf16_f32 v68, v74, v75
	v_rcp_f32_e32 v71, v69
	v_cvt_pk_bf16_f32 v69, v76, v77
	global_store_dwordx4 v[78:79], v[66:69], off nt
	v_pk_mul_f32 v[62:63], v[62:63], v[70:71]
	s_nop 0
	v_mul_f32_e32 v66, 0xbfb8aa3b, v64
	v_mul_f32_e32 v67, 0xbfb8aa3b, v65
	v_exp_f32_e32 v66, v66
	v_exp_f32_e32 v67, v67
	v_pk_mul_f32 v[54:55], v[62:63], v[54:55]
	v_add_u32_e32 v68, 0x80, v154
	v_add_f32_e32 v62, 1.0, v66
	v_add_f32_e32 v63, 1.0, v67
	v_mul_f32_e32 v66, 0xbfb8aa3b, v58
	v_mul_f32_e32 v67, 0xbfb8aa3b, v59
	v_rcp_f32_e32 v62, v62
	v_rcp_f32_e32 v63, v63
	v_exp_f32_e32 v66, v66
	v_exp_f32_e32 v67, v67
	v_pk_mul_f32 v[62:63], v[64:65], v[62:63]
	v_add_f32_e32 v64, 1.0, v66
	v_add_f32_e32 v65, 1.0, v67
	v_mul_f32_e32 v66, 0xbfb8aa3b, v60
	v_mul_f32_e32 v67, 0xbfb8aa3b, v61
	v_exp_f32_e32 v66, v66
	v_exp_f32_e32 v67, v67
	v_rcp_f32_e32 v64, v64
	v_rcp_f32_e32 v65, v65
	v_add_f32_e32 v66, 1.0, v66
	v_add_f32_e32 v67, 1.0, v67
	v_rcp_f32_e32 v66, v66
	v_rcp_f32_e32 v67, v67
	v_pk_mul_f32 v[58:59], v[58:59], v[64:65]
	v_pk_mul_f32 v[56:57], v[62:63], v[56:57]
	v_pk_mul_f32 v[58:59], v[58:59], v[50:51]
	v_pk_mul_f32 v[50:51], v[60:61], v[66:67]
	s_nop 0
	v_pk_mul_f32 v[60:61], v[50:51], v[52:53]
	v_mad_i64_i32 v[50:51], s[16:17], v68, s74, v[114:115]
	v_mul_f32_e32 v52, 0xbfb8aa3b, v46
	v_lshl_add_u64 v[50:51], v[50:51], 0, s[14:15]
	v_exp_f32_e32 v53, v52
	v_mul_f32_e32 v52, 0xbfb8aa3b, v47
	v_lshl_add_u64 v[62:63], v[50:51], 0, v[138:139]
	v_cvt_pk_bf16_f32 v50, v54, v55
	v_exp_f32_e32 v55, v52
	v_add_f32_e32 v53, 1.0, v53
	v_rcp_f32_e32 v54, v53
	v_cvt_pk_bf16_f32 v51, v56, v57
	v_add_f32_e32 v53, 1.0, v55
	v_cvt_pk_bf16_f32 v52, v58, v59
	v_rcp_f32_e32 v55, v53
	v_cvt_pk_bf16_f32 v53, v60, v61
	global_store_dwordx4 v[62:63], v[50:53], off nt
	v_pk_mul_f32 v[46:47], v[46:47], v[54:55]
	s_nop 0
	v_mul_f32_e32 v50, 0xbfb8aa3b, v48
	v_mul_f32_e32 v51, 0xbfb8aa3b, v49
	v_exp_f32_e32 v50, v50
	v_exp_f32_e32 v51, v51
	v_pk_mul_f32 v[38:39], v[46:47], v[38:39]
	v_add_u32_e32 v52, 0x90, v154
	v_add_f32_e32 v46, 1.0, v50
	v_add_f32_e32 v47, 1.0, v51
	v_mul_f32_e32 v50, 0xbfb8aa3b, v42
	v_mul_f32_e32 v51, 0xbfb8aa3b, v43
	v_rcp_f32_e32 v46, v46
	v_rcp_f32_e32 v47, v47
	v_exp_f32_e32 v50, v50
	v_exp_f32_e32 v51, v51
	v_pk_mul_f32 v[46:47], v[48:49], v[46:47]
	v_add_f32_e32 v48, 1.0, v50
	v_add_f32_e32 v49, 1.0, v51
	v_mul_f32_e32 v50, 0xbfb8aa3b, v44
	v_mul_f32_e32 v51, 0xbfb8aa3b, v45
	v_exp_f32_e32 v50, v50
	v_exp_f32_e32 v51, v51
	v_rcp_f32_e32 v48, v48
	v_rcp_f32_e32 v49, v49
	v_add_f32_e32 v50, 1.0, v50
	v_add_f32_e32 v51, 1.0, v51
	v_rcp_f32_e32 v50, v50
	v_rcp_f32_e32 v51, v51
	v_pk_mul_f32 v[42:43], v[42:43], v[48:49]
	v_pk_mul_f32 v[40:41], v[46:47], v[40:41]
	v_pk_mul_f32 v[42:43], v[42:43], v[34:35]
	v_pk_mul_f32 v[34:35], v[44:45], v[50:51]
	s_nop 0
	v_pk_mul_f32 v[44:45], v[34:35], v[36:37]
	v_mad_i64_i32 v[34:35], s[16:17], v52, s74, v[114:115]
	v_mul_f32_e32 v36, 0xbfb8aa3b, v30
	v_lshl_add_u64 v[34:35], v[34:35], 0, s[14:15]
	v_exp_f32_e32 v37, v36
	v_mul_f32_e32 v36, 0xbfb8aa3b, v31
	v_lshl_add_u64 v[46:47], v[34:35], 0, v[138:139]
	v_cvt_pk_bf16_f32 v34, v38, v39
	v_exp_f32_e32 v39, v36
	v_add_f32_e32 v37, 1.0, v37
	v_rcp_f32_e32 v38, v37
	v_cvt_pk_bf16_f32 v35, v40, v41
	v_add_f32_e32 v37, 1.0, v39
	v_cvt_pk_bf16_f32 v36, v42, v43
	v_rcp_f32_e32 v39, v37
	v_cvt_pk_bf16_f32 v37, v44, v45
	global_store_dwordx4 v[46:47], v[34:37], off nt
	v_pk_mul_f32 v[30:31], v[30:31], v[38:39]
	s_nop 0
	v_mul_f32_e32 v34, 0xbfb8aa3b, v32
	v_mul_f32_e32 v35, 0xbfb8aa3b, v33
	v_exp_f32_e32 v34, v34
	v_exp_f32_e32 v35, v35
	v_pk_mul_f32 v[22:23], v[30:31], v[22:23]
	v_add_u32_e32 v36, 0xa0, v154
	v_add_f32_e32 v30, 1.0, v34
	v_add_f32_e32 v31, 1.0, v35
	v_mul_f32_e32 v34, 0xbfb8aa3b, v26
	v_mul_f32_e32 v35, 0xbfb8aa3b, v27
	v_rcp_f32_e32 v30, v30
	v_rcp_f32_e32 v31, v31
	v_exp_f32_e32 v34, v34
	v_exp_f32_e32 v35, v35
	v_pk_mul_f32 v[30:31], v[32:33], v[30:31]
	v_add_f32_e32 v32, 1.0, v34
	v_add_f32_e32 v33, 1.0, v35
	v_mul_f32_e32 v34, 0xbfb8aa3b, v28
	v_mul_f32_e32 v35, 0xbfb8aa3b, v29
	v_exp_f32_e32 v34, v34
	v_exp_f32_e32 v35, v35
	v_rcp_f32_e32 v32, v32
	v_rcp_f32_e32 v33, v33
	v_add_f32_e32 v34, 1.0, v34
	v_add_f32_e32 v35, 1.0, v35
	v_rcp_f32_e32 v34, v34
	v_rcp_f32_e32 v35, v35
	v_pk_mul_f32 v[26:27], v[26:27], v[32:33]
	v_pk_mul_f32 v[24:25], v[30:31], v[24:25]
	v_pk_mul_f32 v[26:27], v[26:27], v[18:19]
	v_pk_mul_f32 v[18:19], v[28:29], v[34:35]
	s_nop 0
	v_pk_mul_f32 v[28:29], v[18:19], v[20:21]
	v_mad_i64_i32 v[18:19], s[16:17], v36, s74, v[114:115]
	v_mul_f32_e32 v20, 0xbfb8aa3b, v14
	v_lshl_add_u64 v[18:19], v[18:19], 0, s[14:15]
	v_exp_f32_e32 v21, v20
	v_mul_f32_e32 v20, 0xbfb8aa3b, v15
	v_lshl_add_u64 v[30:31], v[18:19], 0, v[138:139]
	v_cvt_pk_bf16_f32 v18, v22, v23
	v_exp_f32_e32 v23, v20
	v_add_f32_e32 v21, 1.0, v21
	v_rcp_f32_e32 v22, v21
	v_cvt_pk_bf16_f32 v19, v24, v25
	v_add_f32_e32 v21, 1.0, v23
	v_cvt_pk_bf16_f32 v20, v26, v27
	v_rcp_f32_e32 v23, v21
	v_cvt_pk_bf16_f32 v21, v28, v29
	global_store_dwordx4 v[30:31], v[18:21], off nt
	v_pk_mul_f32 v[14:15], v[14:15], v[22:23]
	s_nop 0
	v_mul_f32_e32 v18, 0xbfb8aa3b, v16
	v_mul_f32_e32 v19, 0xbfb8aa3b, v17
	v_exp_f32_e32 v18, v18
	v_exp_f32_e32 v19, v19
	v_pk_mul_f32 v[6:7], v[14:15], v[6:7]
	v_add_u32_e32 v20, 0xb0, v154
	v_add_f32_e32 v14, 1.0, v18
	v_add_f32_e32 v15, 1.0, v19
	v_mul_f32_e32 v18, 0xbfb8aa3b, v10
	v_mul_f32_e32 v19, 0xbfb8aa3b, v11
	v_rcp_f32_e32 v14, v14
	v_rcp_f32_e32 v15, v15
	v_exp_f32_e32 v18, v18
	v_exp_f32_e32 v19, v19
	v_pk_mul_f32 v[14:15], v[16:17], v[14:15]
	v_add_f32_e32 v16, 1.0, v18
	v_add_f32_e32 v17, 1.0, v19
	v_mul_f32_e32 v18, 0xbfb8aa3b, v12
	v_mul_f32_e32 v19, 0xbfb8aa3b, v13
	v_exp_f32_e32 v18, v18
	v_exp_f32_e32 v19, v19
	v_rcp_f32_e32 v16, v16
	v_rcp_f32_e32 v17, v17
	v_add_f32_e32 v18, 1.0, v18
	v_add_f32_e32 v19, 1.0, v19
	v_rcp_f32_e32 v18, v18
	v_rcp_f32_e32 v19, v19
	v_pk_mul_f32 v[10:11], v[10:11], v[16:17]
	v_pk_mul_f32 v[8:9], v[14:15], v[8:9]
	v_pk_mul_f32 v[10:11], v[10:11], v[2:3]
	v_pk_mul_f32 v[2:3], v[12:13], v[18:19]
	s_nop 0
	v_pk_mul_f32 v[12:13], v[2:3], v[4:5]
	v_mad_i64_i32 v[2:3], s[16:17], v20, s74, v[114:115]
	v_lshl_add_u64 v[2:3], v[2:3], 0, s[14:15]
	v_lshl_add_u64 v[14:15], v[2:3], 0, v[138:139]
	v_cvt_pk_bf16_f32 v2, v6, v7
	v_cvt_pk_bf16_f32 v3, v8, v9
	v_cvt_pk_bf16_f32 v4, v10, v11
	v_cvt_pk_bf16_f32 v5, v12, v13
	s_mov_b32 s15, s6
	s_mov_b32 s14, s8
	s_mov_b64 s[16:17], s[10:11]
	global_store_dwordx4 v[14:15], v[2:5], off nt
	s_cbranch_vccz .LBB0_564
	s_waitcnt vmcnt(0)
	s_cmpk_gt_u32 s33, 0xff
	s_cbranch_scc1 .LBB0_571
	s_barrier

.LBB0_821:
	s_add_u32 s0, s10, 0xb0080
	s_addc_u32 s1, s11, 0
	s_add_u32 s10, s8, 0x100
	s_addc_u32 s11, s9, 0
	s_mov_b32 s49, -2
	s_waitcnt lgkmcnt(0)
	ds_read_b128 v[130:133], v241
	ds_read_b128 v[134:137], v241 offset:1024
	ds_read_b128 v[138:141], v241 offset:2048
	ds_read_b128 v[142:145], v241 offset:3072
	s_add_u32 s6, s0, 0xfff50080
	s_addc_u32 s7, s1, -1
	s_cmp_eq_u32 s49, 40
	s_cselect_b32 s9, s39, s7
	s_cselect_b32 s8, s38, s6
	s_cselect_b32 s7, s41, s11
	s_cselect_b32 s6, s40, s10
	v_lshl_add_u64 v[202:203], s[0:1], 0, v[186:187]
	s_add_i32 m0, s57, 0xc000
	ds_read_b128 v[146:149], v242
	ds_read_b128 v[150:153], v242 offset:1024
	ds_read_b128 v[154:157], v242 offset:2048
	ds_read_b128 v[158:161], v242 offset:3072
	ds_read_b128 v[162:165], v242 offset:4096
	ds_read_b128 v[166:169], v242 offset:5120
	ds_read_b128 v[194:197], v242 offset:6144
	ds_read_b128 v[198:201], v242 offset:7168
	global_load_lds_dwordx4 v[202:203], off
	v_lshl_add_u64 v[202:203], s[0:1], 0, v[188:189]
	s_add_i32 m0, s57, 0xe000
	s_nop 0
	global_load_lds_dwordx4 v[202:203], off
	s_waitcnt lgkmcnt(8)
	s_setprio 1
	s_barrier
	s_waitcnt lgkmcnt(0)
	v_mfma_f32_16x16x32_bf16 v[126:129], v[130:133], v[146:149], 0
	v_mfma_f32_16x16x32_bf16 v[122:125], v[138:141], v[146:149], 0
	v_mfma_f32_16x16x32_bf16 v[110:113], v[130:133], v[154:157], 0
	v_mfma_f32_16x16x32_bf16 v[106:109], v[138:141], v[154:157], 0
	v_mfma_f32_16x16x32_bf16 v[94:97], v[130:133], v[162:165], 0
	v_mfma_f32_16x16x32_bf16 v[90:93], v[138:141], v[162:165], 0
	v_mfma_f32_16x16x32_bf16 v[78:81], v[130:133], v[194:197], 0
	v_mfma_f32_16x16x32_bf16 v[74:77], v[138:141], v[194:197], 0
	v_mfma_f32_16x16x32_bf16 v[126:129], v[134:137], v[150:153], v[126:129]
	v_mfma_f32_16x16x32_bf16 v[122:125], v[142:145], v[150:153], v[122:125]
	v_mfma_f32_16x16x32_bf16 v[110:113], v[134:137], v[158:161], v[110:113]
	v_mfma_f32_16x16x32_bf16 v[106:109], v[142:145], v[158:161], v[106:109]
	v_mfma_f32_16x16x32_bf16 v[94:97], v[134:137], v[166:169], v[94:97]
	v_mfma_f32_16x16x32_bf16 v[90:93], v[142:145], v[166:169], v[90:93]
	v_mfma_f32_16x16x32_bf16 v[78:81], v[134:137], v[198:201], v[78:81]
	v_mfma_f32_16x16x32_bf16 v[74:77], v[142:145], v[198:201], v[74:77]
	s_barrier
	s_setprio 0
	s_add_i32 s20, s77, s56
	v_lshl_add_u64 v[218:219], s[6:7], 0, v[176:177]
	s_mov_b32 m0, s20
	ds_read_b128 v[202:205], v243
	ds_read_b128 v[206:209], v243 offset:1024
	ds_read_b128 v[210:213], v243 offset:2048
	ds_read_b128 v[214:217], v243 offset:3072
	global_load_lds_dwordx4 v[218:219], off
	v_lshl_add_u64 v[220:221], s[6:7], 0, v[180:181]
	s_add_i32 m0, s20, 0x2000
	s_nop 0
	global_load_lds_dwordx4 v[220:221], off
	s_setprio 1
	s_barrier
	s_waitcnt lgkmcnt(0)
	v_mfma_f32_16x16x32_bf16 v[118:121], v[202:205], v[146:149], 0
	v_mfma_f32_16x16x32_bf16 v[114:117], v[210:213], v[146:149], 0
	v_mfma_f32_16x16x32_bf16 v[102:105], v[202:205], v[154:157], 0
	v_mfma_f32_16x16x32_bf16 v[98:101], v[210:213], v[154:157], 0
	v_mfma_f32_16x16x32_bf16 v[86:89], v[202:205], v[162:165], 0
	v_mfma_f32_16x16x32_bf16 v[82:85], v[210:213], v[162:165], 0
	v_mfma_f32_16x16x32_bf16 v[70:73], v[202:205], v[194:197], 0
	v_mfma_f32_16x16x32_bf16 v[66:69], v[210:213], v[194:197], 0
	v_mfma_f32_16x16x32_bf16 v[118:121], v[206:209], v[150:153], v[118:121]
	v_mfma_f32_16x16x32_bf16 v[114:117], v[214:217], v[150:153], v[114:117]
	v_mfma_f32_16x16x32_bf16 v[102:105], v[206:209], v[158:161], v[102:105]
	v_mfma_f32_16x16x32_bf16 v[98:101], v[214:217], v[158:161], v[98:101]
	v_mfma_f32_16x16x32_bf16 v[86:89], v[206:209], v[166:169], v[86:89]
	v_mfma_f32_16x16x32_bf16 v[82:85], v[214:217], v[166:169], v[82:85]
	v_mfma_f32_16x16x32_bf16 v[70:73], v[206:209], v[198:201], v[70:73]
	v_mfma_f32_16x16x32_bf16 v[66:69], v[214:217], v[198:201], v[66:69]
	s_barrier
	s_setprio 0
	s_mov_b32 m0, s57
	v_lshl_add_u64 v[222:223], s[8:9], 0, v[172:173]
	ds_read_b128 v[146:149], v242 offset:16384
	ds_read_b128 v[150:153], v242 offset:17408
	ds_read_b128 v[154:157], v242 offset:18432
	ds_read_b128 v[158:161], v242 offset:19456
	ds_read_b128 v[162:165], v242 offset:20480
	ds_read_b128 v[166:169], v242 offset:21504
	ds_read_b128 v[194:197], v242 offset:22528
	ds_read_b128 v[198:201], v242 offset:23552
	global_load_lds_dwordx4 v[222:223], off
	v_lshl_add_u64 v[224:225], s[8:9], 0, v[178:179]
	s_mov_b32 m0, s68
	s_nop 0
	global_load_lds_dwordx4 v[224:225], off
	s_setprio 1
	s_barrier
	s_waitcnt lgkmcnt(0)
	v_mfma_f32_16x16x32_bf16 v[62:65], v[130:133], v[146:149], 0
	v_mfma_f32_16x16x32_bf16 v[58:61], v[138:141], v[146:149], 0
	v_mfma_f32_16x16x32_bf16 v[46:49], v[130:133], v[154:157], 0
	v_mfma_f32_16x16x32_bf16 v[42:45], v[138:141], v[154:157], 0
	v_mfma_f32_16x16x32_bf16 v[30:33], v[130:133], v[162:165], 0
	v_mfma_f32_16x16x32_bf16 v[26:29], v[138:141], v[162:165], 0
	v_mfma_f32_16x16x32_bf16 v[14:17], v[130:133], v[194:197], 0
	v_mfma_f32_16x16x32_bf16 v[10:13], v[138:141], v[194:197], 0
	v_mfma_f32_16x16x32_bf16 v[62:65], v[134:137], v[150:153], v[62:65]
	v_mfma_f32_16x16x32_bf16 v[58:61], v[142:145], v[150:153], v[58:61]
	v_mfma_f32_16x16x32_bf16 v[46:49], v[134:137], v[158:161], v[46:49]
	v_mfma_f32_16x16x32_bf16 v[42:45], v[142:145], v[158:161], v[42:45]
	v_mfma_f32_16x16x32_bf16 v[30:33], v[134:137], v[166:169], v[30:33]
	v_mfma_f32_16x16x32_bf16 v[26:29], v[142:145], v[166:169], v[26:29]
	v_mfma_f32_16x16x32_bf16 v[14:17], v[134:137], v[198:201], v[14:17]
	v_mfma_f32_16x16x32_bf16 v[10:13], v[142:145], v[198:201], v[10:13]
	s_barrier
	s_setprio 0
	s_add_u32 s20, s6, 0xb0000
	s_addc_u32 s21, s7, 0
	s_add_i32 s50, s78, s56
	v_lshl_add_u64 v[130:131], s[20:21], 0, v[176:177]
	s_mov_b32 m0, s50
	s_nop 0
	global_load_lds_dwordx4 v[130:131], off
	v_lshl_add_u64 v[130:131], s[20:21], 0, v[180:181]
	s_add_i32 m0, s50, 0x2000
	s_nop 0
	global_load_lds_dwordx4 v[130:131], off
	s_waitcnt vmcnt(6)
	s_setprio 1
	s_barrier
	v_mfma_f32_16x16x32_bf16 v[54:57], v[202:205], v[146:149], 0
	v_mfma_f32_16x16x32_bf16 v[50:53], v[210:213], v[146:149], 0
	v_mfma_f32_16x16x32_bf16 v[38:41], v[202:205], v[154:157], 0
	v_mfma_f32_16x16x32_bf16 v[34:37], v[210:213], v[154:157], 0
	v_mfma_f32_16x16x32_bf16 v[22:25], v[202:205], v[162:165], 0
	v_mfma_f32_16x16x32_bf16 v[18:21], v[210:213], v[162:165], 0
	v_mfma_f32_16x16x32_bf16 v[6:9], v[202:205], v[194:197], 0
	v_mfma_f32_16x16x32_bf16 v[2:5], v[210:213], v[194:197], 0
	v_mfma_f32_16x16x32_bf16 v[54:57], v[206:209], v[150:153], v[54:57]
	v_mfma_f32_16x16x32_bf16 v[50:53], v[214:217], v[150:153], v[50:53]
	v_mfma_f32_16x16x32_bf16 v[38:41], v[206:209], v[158:161], v[38:41]
	v_mfma_f32_16x16x32_bf16 v[34:37], v[214:217], v[158:161], v[34:37]
	v_mfma_f32_16x16x32_bf16 v[22:25], v[206:209], v[166:169], v[22:25]
	v_mfma_f32_16x16x32_bf16 v[18:21], v[214:217], v[166:169], v[18:21]
	v_mfma_f32_16x16x32_bf16 v[6:9], v[206:209], v[198:201], v[6:9]
	v_mfma_f32_16x16x32_bf16 v[2:5], v[214:217], v[198:201], v[2:5]
	s_barrier
	s_setprio 0
	s_add_i32 s20, 0, 0x18000
	v_add_u32_e32 v142, s20, v240
	ds_read_b128 v[130:133], v142
	ds_read_b128 v[134:137], v142 offset:1024
	ds_read_b128 v[138:141], v142 offset:2048
	ds_read_b128 v[142:145], v142 offset:3072
	s_add_u32 s8, s8, 0xb0000
	s_addc_u32 s9, s9, 0
	s_mov_b32 m0, s69
	v_lshl_add_u64 v[202:203], s[8:9], 0, v[172:173]
	ds_read_b128 v[146:149], v242 offset:32768
	ds_read_b128 v[150:153], v242 offset:33792
	ds_read_b128 v[154:157], v242 offset:34816
	ds_read_b128 v[158:161], v242 offset:35840
	ds_read_b128 v[162:165], v242 offset:36864
	ds_read_b128 v[166:169], v242 offset:37888
	ds_read_b128 v[194:197], v242 offset:38912
	ds_read_b128 v[198:201], v242 offset:39936
	global_load_lds_dwordx4 v[202:203], off
	v_lshl_add_u64 v[202:203], s[8:9], 0, v[178:179]
	s_mov_b32 m0, s70
	s_nop 0
	global_load_lds_dwordx4 v[202:203], off
	s_waitcnt lgkmcnt(8)
	s_setprio 1
	s_barrier
	s_waitcnt lgkmcnt(0)
	v_mfma_f32_16x16x32_bf16 v[126:129], v[130:133], v[146:149], v[126:129]
	v_mfma_f32_16x16x32_bf16 v[122:125], v[138:141], v[146:149], v[122:125]
	v_mfma_f32_16x16x32_bf16 v[110:113], v[130:133], v[154:157], v[110:113]
	v_mfma_f32_16x16x32_bf16 v[106:109], v[138:141], v[154:157], v[106:109]
	v_mfma_f32_16x16x32_bf16 v[94:97], v[130:133], v[162:165], v[94:97]
	v_mfma_f32_16x16x32_bf16 v[90:93], v[138:141], v[162:165], v[90:93]
	v_mfma_f32_16x16x32_bf16 v[78:81], v[130:133], v[194:197], v[78:81]
	v_mfma_f32_16x16x32_bf16 v[74:77], v[138:141], v[194:197], v[74:77]
	v_mfma_f32_16x16x32_bf16 v[126:129], v[134:137], v[150:153], v[126:129]
	v_mfma_f32_16x16x32_bf16 v[122:125], v[142:145], v[150:153], v[122:125]
	v_mfma_f32_16x16x32_bf16 v[110:113], v[134:137], v[158:161], v[110:113]
	v_mfma_f32_16x16x32_bf16 v[106:109], v[142:145], v[158:161], v[106:109]
	v_mfma_f32_16x16x32_bf16 v[94:97], v[134:137], v[166:169], v[94:97]
	v_mfma_f32_16x16x32_bf16 v[90:93], v[142:145], v[166:169], v[90:93]
	v_mfma_f32_16x16x32_bf16 v[78:81], v[134:137], v[198:201], v[78:81]
	v_mfma_f32_16x16x32_bf16 v[74:77], v[142:145], v[198:201], v[74:77]
	s_barrier
	s_setprio 0
	s_add_i32 s8, 0, 0x1c000
	s_add_i32 s9, s20, s56
	v_add_u32_e32 v184, s8, v240
	v_lshl_add_u64 v[218:219], v[218:219], 0, s[16:17]
	s_mov_b32 m0, s9
	ds_read_b128 v[202:205], v184
	ds_read_b128 v[206:209], v184 offset:1024
	ds_read_b128 v[210:213], v184 offset:2048
	ds_read_b128 v[214:217], v184 offset:3072
	global_load_lds_dwordx4 v[218:219], off
	v_lshl_add_u64 v[218:219], v[220:221], 0, s[16:17]
	s_add_i32 m0, s9, 0x2000
	s_nop 0
	global_load_lds_dwordx4 v[218:219], off
	s_setprio 1
	s_barrier
	s_waitcnt lgkmcnt(0)
	v_mfma_f32_16x16x32_bf16 v[118:121], v[202:205], v[146:149], v[118:121]
	v_mfma_f32_16x16x32_bf16 v[114:117], v[210:213], v[146:149], v[114:117]
	v_mfma_f32_16x16x32_bf16 v[102:105], v[202:205], v[154:157], v[102:105]
	v_mfma_f32_16x16x32_bf16 v[98:101], v[210:213], v[154:157], v[98:101]
	v_mfma_f32_16x16x32_bf16 v[86:89], v[202:205], v[162:165], v[86:89]
	v_mfma_f32_16x16x32_bf16 v[82:85], v[210:213], v[162:165], v[82:85]
	v_mfma_f32_16x16x32_bf16 v[70:73], v[202:205], v[194:197], v[70:73]
	v_mfma_f32_16x16x32_bf16 v[66:69], v[210:213], v[194:197], v[66:69]
	v_mfma_f32_16x16x32_bf16 v[118:121], v[206:209], v[150:153], v[118:121]
	v_mfma_f32_16x16x32_bf16 v[114:117], v[214:217], v[150:153], v[114:117]
	v_mfma_f32_16x16x32_bf16 v[102:105], v[206:209], v[158:161], v[102:105]
	v_mfma_f32_16x16x32_bf16 v[98:101], v[214:217], v[158:161], v[98:101]
	v_mfma_f32_16x16x32_bf16 v[86:89], v[206:209], v[166:169], v[86:89]
	v_mfma_f32_16x16x32_bf16 v[82:85], v[214:217], v[166:169], v[82:85]
	v_mfma_f32_16x16x32_bf16 v[70:73], v[206:209], v[198:201], v[70:73]
	v_mfma_f32_16x16x32_bf16 v[66:69], v[214:217], v[198:201], v[66:69]
	s_barrier
	s_setprio 0
	s_mov_b32 m0, s74
	v_lshl_add_u64 v[218:219], v[222:223], 0, s[16:17]
	ds_read_b128 v[146:149], v242 offset:49152
	ds_read_b128 v[150:153], v242 offset:50176
	ds_read_b128 v[154:157], v242 offset:51200
	ds_read_b128 v[158:161], v242 offset:52224
	ds_read_b128 v[162:165], v242 offset:53248
	ds_read_b128 v[166:169], v242 offset:54272
	ds_read_b128 v[194:197], v242 offset:55296
	ds_read_b128 v[198:201], v242 offset:56320
	global_load_lds_dwordx4 v[218:219], off
	v_lshl_add_u64 v[218:219], v[224:225], 0, s[16:17]
	s_mov_b32 m0, s75
	s_nop 0
	global_load_lds_dwordx4 v[218:219], off
	s_setprio 1
	s_barrier
	s_waitcnt lgkmcnt(0)
	v_mfma_f32_16x16x32_bf16 v[62:65], v[130:133], v[146:149], v[62:65]
	v_mfma_f32_16x16x32_bf16 v[58:61], v[138:141], v[146:149], v[58:61]
	v_mfma_f32_16x16x32_bf16 v[46:49], v[130:133], v[154:157], v[46:49]
	v_mfma_f32_16x16x32_bf16 v[42:45], v[138:141], v[154:157], v[42:45]
	v_mfma_f32_16x16x32_bf16 v[30:33], v[130:133], v[162:165], v[30:33]
	v_mfma_f32_16x16x32_bf16 v[26:29], v[138:141], v[162:165], v[26:29]
	v_mfma_f32_16x16x32_bf16 v[14:17], v[130:133], v[194:197], v[14:17]
	v_mfma_f32_16x16x32_bf16 v[10:13], v[138:141], v[194:197], v[10:13]
	v_mfma_f32_16x16x32_bf16 v[62:65], v[134:137], v[150:153], v[62:65]
	v_mfma_f32_16x16x32_bf16 v[58:61], v[142:145], v[150:153], v[58:61]
	v_mfma_f32_16x16x32_bf16 v[46:49], v[134:137], v[158:161], v[46:49]
	v_mfma_f32_16x16x32_bf16 v[42:45], v[142:145], v[158:161], v[42:45]
	v_mfma_f32_16x16x32_bf16 v[30:33], v[134:137], v[166:169], v[30:33]
	v_mfma_f32_16x16x32_bf16 v[26:29], v[142:145], v[166:169], v[26:29]
	v_mfma_f32_16x16x32_bf16 v[14:17], v[134:137], v[198:201], v[14:17]
	v_mfma_f32_16x16x32_bf16 v[10:13], v[142:145], v[198:201], v[10:13]
	s_barrier
	s_setprio 0
	s_add_u32 s6, s6, 0xb0080
	s_addc_u32 s7, s7, 0
	s_add_i32 s8, s8, s56
	v_lshl_add_u64 v[130:131], s[6:7], 0, v[176:177]
	s_mov_b32 m0, s8
	s_nop 0
	global_load_lds_dwordx4 v[130:131], off
	v_lshl_add_u64 v[130:131], s[6:7], 0, v[180:181]
	s_add_i32 m0, s8, 0x2000
	s_nop 0
	global_load_lds_dwordx4 v[130:131], off
	s_waitcnt vmcnt(6)
	s_setprio 1
	s_barrier
	v_mfma_f32_16x16x32_bf16 v[54:57], v[202:205], v[146:149], v[54:57]
	v_mfma_f32_16x16x32_bf16 v[50:53], v[210:213], v[146:149], v[50:53]
	v_mfma_f32_16x16x32_bf16 v[38:41], v[202:205], v[154:157], v[38:41]
	v_mfma_f32_16x16x32_bf16 v[34:37], v[210:213], v[154:157], v[34:37]
	v_mfma_f32_16x16x32_bf16 v[22:25], v[202:205], v[162:165], v[22:25]
	v_mfma_f32_16x16x32_bf16 v[18:21], v[210:213], v[162:165], v[18:21]
	v_mfma_f32_16x16x32_bf16 v[6:9], v[202:205], v[194:197], v[6:9]
	v_mfma_f32_16x16x32_bf16 v[2:5], v[210:213], v[194:197], v[2:5]
	v_mfma_f32_16x16x32_bf16 v[54:57], v[206:209], v[150:153], v[54:57]
	v_mfma_f32_16x16x32_bf16 v[50:53], v[214:217], v[150:153], v[50:53]
	v_mfma_f32_16x16x32_bf16 v[38:41], v[206:209], v[158:161], v[38:41]
	v_mfma_f32_16x16x32_bf16 v[34:37], v[214:217], v[158:161], v[34:37]
	v_mfma_f32_16x16x32_bf16 v[22:25], v[206:209], v[166:169], v[22:25]
	v_mfma_f32_16x16x32_bf16 v[18:21], v[214:217], v[166:169], v[18:21]
	v_mfma_f32_16x16x32_bf16 v[6:9], v[206:209], v[198:201], v[6:9]
	v_mfma_f32_16x16x32_bf16 v[2:5], v[214:217], v[198:201], v[2:5]
	s_barrier
	s_setprio 0
	s_add_i32 s49, s49, 2
	s_add_u32 s0, s0, 0x100
	s_addc_u32 s1, s1, 0
	s_add_u32 s10, s10, 0x100
	s_addc_u32 s11, s11, 0
	s_cmp_gt_u32 s49, 41
.LBB0_822:
	ds_read_b128 v[130:133], v241
	ds_read_b128 v[134:137], v241 offset:1024
	ds_read_b128 v[138:141], v241 offset:2048
	ds_read_b128 v[142:145], v241 offset:3072
	s_add_u32 s6, s0, 0xfff50080
	s_addc_u32 s7, s1, -1
	s_cmp_eq_u32 s49, 40
	s_cselect_b32 s9, s39, s7
	s_cselect_b32 s8, s38, s6
	s_cselect_b32 s7, s41, s11
	s_cselect_b32 s6, s40, s10
	v_lshl_add_u64 v[202:203], s[0:1], 0, v[186:187]
	s_add_i32 m0, s57, 0xc000
	ds_read_b128 v[146:149], v242
	ds_read_b128 v[150:153], v242 offset:1024
	ds_read_b128 v[154:157], v242 offset:2048
	ds_read_b128 v[158:161], v242 offset:3072
	ds_read_b128 v[162:165], v242 offset:4096
	ds_read_b128 v[166:169], v242 offset:5120
	ds_read_b128 v[194:197], v242 offset:6144
	ds_read_b128 v[198:201], v242 offset:7168
	global_load_lds_dwordx4 v[202:203], off
	v_lshl_add_u64 v[202:203], s[0:1], 0, v[188:189]
	s_add_i32 m0, s57, 0xe000
	s_nop 0
	global_load_lds_dwordx4 v[202:203], off
	s_waitcnt lgkmcnt(8)
	s_setprio 1
	s_barrier
	s_waitcnt lgkmcnt(0)
	v_mfma_f32_16x16x32_bf16 v[126:129], v[130:133], v[146:149], v[126:129]
	v_mfma_f32_16x16x32_bf16 v[122:125], v[138:141], v[146:149], v[122:125]
	v_mfma_f32_16x16x32_bf16 v[110:113], v[130:133], v[154:157], v[110:113]
	v_mfma_f32_16x16x32_bf16 v[106:109], v[138:141], v[154:157], v[106:109]
	v_mfma_f32_16x16x32_bf16 v[94:97], v[130:133], v[162:165], v[94:97]
	v_mfma_f32_16x16x32_bf16 v[90:93], v[138:141], v[162:165], v[90:93]
	v_mfma_f32_16x16x32_bf16 v[78:81], v[130:133], v[194:197], v[78:81]
	v_mfma_f32_16x16x32_bf16 v[74:77], v[138:141], v[194:197], v[74:77]
	v_mfma_f32_16x16x32_bf16 v[126:129], v[134:137], v[150:153], v[126:129]
	v_mfma_f32_16x16x32_bf16 v[122:125], v[142:145], v[150:153], v[122:125]
	v_mfma_f32_16x16x32_bf16 v[110:113], v[134:137], v[158:161], v[110:113]
	v_mfma_f32_16x16x32_bf16 v[106:109], v[142:145], v[158:161], v[106:109]
	v_mfma_f32_16x16x32_bf16 v[94:97], v[134:137], v[166:169], v[94:97]
	v_mfma_f32_16x16x32_bf16 v[90:93], v[142:145], v[166:169], v[90:93]
	v_mfma_f32_16x16x32_bf16 v[78:81], v[134:137], v[198:201], v[78:81]
	v_mfma_f32_16x16x32_bf16 v[74:77], v[142:145], v[198:201], v[74:77]
	s_barrier
	s_setprio 0
	s_add_i32 s20, s77, s56
	v_lshl_add_u64 v[218:219], s[6:7], 0, v[176:177]
	s_mov_b32 m0, s20
	ds_read_b128 v[202:205], v243
	ds_read_b128 v[206:209], v243 offset:1024
	ds_read_b128 v[210:213], v243 offset:2048
	ds_read_b128 v[214:217], v243 offset:3072
	global_load_lds_dwordx4 v[218:219], off
	v_lshl_add_u64 v[220:221], s[6:7], 0, v[180:181]
	s_add_i32 m0, s20, 0x2000
	s_nop 0
	global_load_lds_dwordx4 v[220:221], off
	s_setprio 1
	s_barrier
	s_waitcnt lgkmcnt(0)
	v_mfma_f32_16x16x32_bf16 v[118:121], v[202:205], v[146:149], v[118:121]
	v_mfma_f32_16x16x32_bf16 v[114:117], v[210:213], v[146:149], v[114:117]
	v_mfma_f32_16x16x32_bf16 v[102:105], v[202:205], v[154:157], v[102:105]
	v_mfma_f32_16x16x32_bf16 v[98:101], v[210:213], v[154:157], v[98:101]
	v_mfma_f32_16x16x32_bf16 v[86:89], v[202:205], v[162:165], v[86:89]
	v_mfma_f32_16x16x32_bf16 v[82:85], v[210:213], v[162:165], v[82:85]
	v_mfma_f32_16x16x32_bf16 v[70:73], v[202:205], v[194:197], v[70:73]
	v_mfma_f32_16x16x32_bf16 v[66:69], v[210:213], v[194:197], v[66:69]
	v_mfma_f32_16x16x32_bf16 v[118:121], v[206:209], v[150:153], v[118:121]
	v_mfma_f32_16x16x32_bf16 v[114:117], v[214:217], v[150:153], v[114:117]
	v_mfma_f32_16x16x32_bf16 v[102:105], v[206:209], v[158:161], v[102:105]
	v_mfma_f32_16x16x32_bf16 v[98:101], v[214:217], v[158:161], v[98:101]
	v_mfma_f32_16x16x32_bf16 v[86:89], v[206:209], v[166:169], v[86:89]
	v_mfma_f32_16x16x32_bf16 v[82:85], v[214:217], v[166:169], v[82:85]
	v_mfma_f32_16x16x32_bf16 v[70:73], v[206:209], v[198:201], v[70:73]
	v_mfma_f32_16x16x32_bf16 v[66:69], v[214:217], v[198:201], v[66:69]
	s_barrier
	s_setprio 0
	s_mov_b32 m0, s57
	v_lshl_add_u64 v[222:223], s[8:9], 0, v[172:173]
	ds_read_b128 v[146:149], v242 offset:16384
	ds_read_b128 v[150:153], v242 offset:17408
	ds_read_b128 v[154:157], v242 offset:18432
	ds_read_b128 v[158:161], v242 offset:19456
	ds_read_b128 v[162:165], v242 offset:20480
	ds_read_b128 v[166:169], v242 offset:21504
	ds_read_b128 v[194:197], v242 offset:22528
	ds_read_b128 v[198:201], v242 offset:23552
	global_load_lds_dwordx4 v[222:223], off
	v_lshl_add_u64 v[224:225], s[8:9], 0, v[178:179]
	s_mov_b32 m0, s68
	s_nop 0
	global_load_lds_dwordx4 v[224:225], off
	s_setprio 1
	s_barrier
	s_waitcnt lgkmcnt(0)
	v_mfma_f32_16x16x32_bf16 v[62:65], v[130:133], v[146:149], v[62:65]
	v_mfma_f32_16x16x32_bf16 v[58:61], v[138:141], v[146:149], v[58:61]
	v_mfma_f32_16x16x32_bf16 v[46:49], v[130:133], v[154:157], v[46:49]
	v_mfma_f32_16x16x32_bf16 v[42:45], v[138:141], v[154:157], v[42:45]
	v_mfma_f32_16x16x32_bf16 v[30:33], v[130:133], v[162:165], v[30:33]
	v_mfma_f32_16x16x32_bf16 v[26:29], v[138:141], v[162:165], v[26:29]
	v_mfma_f32_16x16x32_bf16 v[14:17], v[130:133], v[194:197], v[14:17]
	v_mfma_f32_16x16x32_bf16 v[10:13], v[138:141], v[194:197], v[10:13]
	v_mfma_f32_16x16x32_bf16 v[62:65], v[134:137], v[150:153], v[62:65]
	v_mfma_f32_16x16x32_bf16 v[58:61], v[142:145], v[150:153], v[58:61]
	v_mfma_f32_16x16x32_bf16 v[46:49], v[134:137], v[158:161], v[46:49]
	v_mfma_f32_16x16x32_bf16 v[42:45], v[142:145], v[158:161], v[42:45]
	v_mfma_f32_16x16x32_bf16 v[30:33], v[134:137], v[166:169], v[30:33]
	v_mfma_f32_16x16x32_bf16 v[26:29], v[142:145], v[166:169], v[26:29]
	v_mfma_f32_16x16x32_bf16 v[14:17], v[134:137], v[198:201], v[14:17]
	v_mfma_f32_16x16x32_bf16 v[10:13], v[142:145], v[198:201], v[10:13]
	s_barrier
	s_setprio 0
	s_add_u32 s20, s6, 0xb0000
	s_addc_u32 s21, s7, 0
	s_add_i32 s50, s78, s56
	v_lshl_add_u64 v[130:131], s[20:21], 0, v[176:177]
	s_mov_b32 m0, s50
	s_nop 0
	global_load_lds_dwordx4 v[130:131], off
	v_lshl_add_u64 v[130:131], s[20:21], 0, v[180:181]
	s_add_i32 m0, s50, 0x2000
	s_nop 0
	global_load_lds_dwordx4 v[130:131], off
	s_waitcnt vmcnt(6)
	s_setprio 1
	s_barrier
	v_mfma_f32_16x16x32_bf16 v[54:57], v[202:205], v[146:149], v[54:57]
	v_mfma_f32_16x16x32_bf16 v[50:53], v[210:213], v[146:149], v[50:53]
	v_mfma_f32_16x16x32_bf16 v[38:41], v[202:205], v[154:157], v[38:41]
	v_mfma_f32_16x16x32_bf16 v[34:37], v[210:213], v[154:157], v[34:37]
	v_mfma_f32_16x16x32_bf16 v[22:25], v[202:205], v[162:165], v[22:25]
	v_mfma_f32_16x16x32_bf16 v[18:21], v[210:213], v[162:165], v[18:21]
	v_mfma_f32_16x16x32_bf16 v[6:9], v[202:205], v[194:197], v[6:9]
	v_mfma_f32_16x16x32_bf16 v[2:5], v[210:213], v[194:197], v[2:5]
	v_mfma_f32_16x16x32_bf16 v[54:57], v[206:209], v[150:153], v[54:57]
	v_mfma_f32_16x16x32_bf16 v[50:53], v[214:217], v[150:153], v[50:53]
	v_mfma_f32_16x16x32_bf16 v[38:41], v[206:209], v[158:161], v[38:41]
	v_mfma_f32_16x16x32_bf16 v[34:37], v[214:217], v[158:161], v[34:37]
	v_mfma_f32_16x16x32_bf16 v[22:25], v[206:209], v[166:169], v[22:25]
	v_mfma_f32_16x16x32_bf16 v[18:21], v[214:217], v[166:169], v[18:21]
	v_mfma_f32_16x16x32_bf16 v[6:9], v[206:209], v[198:201], v[6:9]
	v_mfma_f32_16x16x32_bf16 v[2:5], v[214:217], v[198:201], v[2:5]
	s_barrier
	s_setprio 0
	s_add_i32 s20, 0, 0x18000
	v_add_u32_e32 v142, s20, v240
	ds_read_b128 v[130:133], v142
	ds_read_b128 v[134:137], v142 offset:1024
	ds_read_b128 v[138:141], v142 offset:2048
	ds_read_b128 v[142:145], v142 offset:3072
	s_add_u32 s8, s8, 0xb0000
	s_addc_u32 s9, s9, 0
	s_mov_b32 m0, s69
	v_lshl_add_u64 v[202:203], s[8:9], 0, v[172:173]
	ds_read_b128 v[146:149], v242 offset:32768
	ds_read_b128 v[150:153], v242 offset:33792
	ds_read_b128 v[154:157], v242 offset:34816
	ds_read_b128 v[158:161], v242 offset:35840
	ds_read_b128 v[162:165], v242 offset:36864
	ds_read_b128 v[166:169], v242 offset:37888
	ds_read_b128 v[194:197], v242 offset:38912
	ds_read_b128 v[198:201], v242 offset:39936
	global_load_lds_dwordx4 v[202:203], off
	v_lshl_add_u64 v[202:203], s[8:9], 0, v[178:179]
	s_mov_b32 m0, s70
	s_nop 0
	global_load_lds_dwordx4 v[202:203], off
	s_waitcnt lgkmcnt(8)
	s_setprio 1
	s_barrier
	s_waitcnt lgkmcnt(0)
	v_mfma_f32_16x16x32_bf16 v[126:129], v[130:133], v[146:149], v[126:129]
	v_mfma_f32_16x16x32_bf16 v[122:125], v[138:141], v[146:149], v[122:125]
	v_mfma_f32_16x16x32_bf16 v[110:113], v[130:133], v[154:157], v[110:113]
	v_mfma_f32_16x16x32_bf16 v[106:109], v[138:141], v[154:157], v[106:109]
	v_mfma_f32_16x16x32_bf16 v[94:97], v[130:133], v[162:165], v[94:97]
	v_mfma_f32_16x16x32_bf16 v[90:93], v[138:141], v[162:165], v[90:93]
	v_mfma_f32_16x16x32_bf16 v[78:81], v[130:133], v[194:197], v[78:81]
	v_mfma_f32_16x16x32_bf16 v[74:77], v[138:141], v[194:197], v[74:77]
	v_mfma_f32_16x16x32_bf16 v[126:129], v[134:137], v[150:153], v[126:129]
	v_mfma_f32_16x16x32_bf16 v[122:125], v[142:145], v[150:153], v[122:125]
	v_mfma_f32_16x16x32_bf16 v[110:113], v[134:137], v[158:161], v[110:113]
	v_mfma_f32_16x16x32_bf16 v[106:109], v[142:145], v[158:161], v[106:109]
	v_mfma_f32_16x16x32_bf16 v[94:97], v[134:137], v[166:169], v[94:97]
	v_mfma_f32_16x16x32_bf16 v[90:93], v[142:145], v[166:169], v[90:93]
	v_mfma_f32_16x16x32_bf16 v[78:81], v[134:137], v[198:201], v[78:81]
	v_mfma_f32_16x16x32_bf16 v[74:77], v[142:145], v[198:201], v[74:77]
	s_barrier
	s_setprio 0
	s_add_i32 s8, 0, 0x1c000
	s_add_i32 s9, s20, s56
	v_add_u32_e32 v184, s8, v240
	v_lshl_add_u64 v[218:219], v[218:219], 0, s[16:17]
	s_mov_b32 m0, s9
	ds_read_b128 v[202:205], v184
	ds_read_b128 v[206:209], v184 offset:1024
	ds_read_b128 v[210:213], v184 offset:2048
	ds_read_b128 v[214:217], v184 offset:3072
	global_load_lds_dwordx4 v[218:219], off
	v_lshl_add_u64 v[218:219], v[220:221], 0, s[16:17]
	s_add_i32 m0, s9, 0x2000
	s_nop 0
	global_load_lds_dwordx4 v[218:219], off
	s_setprio 1
	s_barrier
	s_waitcnt lgkmcnt(0)
	v_mfma_f32_16x16x32_bf16 v[118:121], v[202:205], v[146:149], v[118:121]
	v_mfma_f32_16x16x32_bf16 v[114:117], v[210:213], v[146:149], v[114:117]
	v_mfma_f32_16x16x32_bf16 v[102:105], v[202:205], v[154:157], v[102:105]
	v_mfma_f32_16x16x32_bf16 v[98:101], v[210:213], v[154:157], v[98:101]
	v_mfma_f32_16x16x32_bf16 v[86:89], v[202:205], v[162:165], v[86:89]
	v_mfma_f32_16x16x32_bf16 v[82:85], v[210:213], v[162:165], v[82:85]
	v_mfma_f32_16x16x32_bf16 v[70:73], v[202:205], v[194:197], v[70:73]
	v_mfma_f32_16x16x32_bf16 v[66:69], v[210:213], v[194:197], v[66:69]
	v_mfma_f32_16x16x32_bf16 v[118:121], v[206:209], v[150:153], v[118:121]
	v_mfma_f32_16x16x32_bf16 v[114:117], v[214:217], v[150:153], v[114:117]
	v_mfma_f32_16x16x32_bf16 v[102:105], v[206:209], v[158:161], v[102:105]
	v_mfma_f32_16x16x32_bf16 v[98:101], v[214:217], v[158:161], v[98:101]
	v_mfma_f32_16x16x32_bf16 v[86:89], v[206:209], v[166:169], v[86:89]
	v_mfma_f32_16x16x32_bf16 v[82:85], v[214:217], v[166:169], v[82:85]
	v_mfma_f32_16x16x32_bf16 v[70:73], v[206:209], v[198:201], v[70:73]
	v_mfma_f32_16x16x32_bf16 v[66:69], v[214:217], v[198:201], v[66:69]
	s_barrier
	s_setprio 0
	s_mov_b32 m0, s74
	v_lshl_add_u64 v[218:219], v[222:223], 0, s[16:17]
	ds_read_b128 v[146:149], v242 offset:49152
	ds_read_b128 v[150:153], v242 offset:50176
	ds_read_b128 v[154:157], v242 offset:51200
	ds_read_b128 v[158:161], v242 offset:52224
	ds_read_b128 v[162:165], v242 offset:53248
	ds_read_b128 v[166:169], v242 offset:54272
	ds_read_b128 v[194:197], v242 offset:55296
	ds_read_b128 v[198:201], v242 offset:56320
	global_load_lds_dwordx4 v[218:219], off
	v_lshl_add_u64 v[218:219], v[224:225], 0, s[16:17]
	s_mov_b32 m0, s75
	s_nop 0
	global_load_lds_dwordx4 v[218:219], off
	s_setprio 1
	s_barrier
	s_waitcnt lgkmcnt(0)
	v_mfma_f32_16x16x32_bf16 v[62:65], v[130:133], v[146:149], v[62:65]
	v_mfma_f32_16x16x32_bf16 v[58:61], v[138:141], v[146:149], v[58:61]
	v_mfma_f32_16x16x32_bf16 v[46:49], v[130:133], v[154:157], v[46:49]
	v_mfma_f32_16x16x32_bf16 v[42:45], v[138:141], v[154:157], v[42:45]
	v_mfma_f32_16x16x32_bf16 v[30:33], v[130:133], v[162:165], v[30:33]
	v_mfma_f32_16x16x32_bf16 v[26:29], v[138:141], v[162:165], v[26:29]
	v_mfma_f32_16x16x32_bf16 v[14:17], v[130:133], v[194:197], v[14:17]
	v_mfma_f32_16x16x32_bf16 v[10:13], v[138:141], v[194:197], v[10:13]
	v_mfma_f32_16x16x32_bf16 v[62:65], v[134:137], v[150:153], v[62:65]
	v_mfma_f32_16x16x32_bf16 v[58:61], v[142:145], v[150:153], v[58:61]
	v_mfma_f32_16x16x32_bf16 v[46:49], v[134:137], v[158:161], v[46:49]
	v_mfma_f32_16x16x32_bf16 v[42:45], v[142:145], v[158:161], v[42:45]
	v_mfma_f32_16x16x32_bf16 v[30:33], v[134:137], v[166:169], v[30:33]
	v_mfma_f32_16x16x32_bf16 v[26:29], v[142:145], v[166:169], v[26:29]
	v_mfma_f32_16x16x32_bf16 v[14:17], v[134:137], v[198:201], v[14:17]
	v_mfma_f32_16x16x32_bf16 v[10:13], v[142:145], v[198:201], v[10:13]
	s_barrier
	s_setprio 0
	s_add_u32 s6, s6, 0xb0080
	s_addc_u32 s7, s7, 0
	s_add_i32 s8, s8, s56
	v_lshl_add_u64 v[130:131], s[6:7], 0, v[176:177]
	s_mov_b32 m0, s8
	s_nop 0
	global_load_lds_dwordx4 v[130:131], off
	v_lshl_add_u64 v[130:131], s[6:7], 0, v[180:181]
	s_add_i32 m0, s8, 0x2000
	s_nop 0
	global_load_lds_dwordx4 v[130:131], off
	s_waitcnt vmcnt(6)
	s_setprio 1
	s_barrier
	v_mfma_f32_16x16x32_bf16 v[54:57], v[202:205], v[146:149], v[54:57]
	v_mfma_f32_16x16x32_bf16 v[50:53], v[210:213], v[146:149], v[50:53]
	v_mfma_f32_16x16x32_bf16 v[38:41], v[202:205], v[154:157], v[38:41]
	v_mfma_f32_16x16x32_bf16 v[34:37], v[210:213], v[154:157], v[34:37]
	v_mfma_f32_16x16x32_bf16 v[22:25], v[202:205], v[162:165], v[22:25]
	v_mfma_f32_16x16x32_bf16 v[18:21], v[210:213], v[162:165], v[18:21]
	v_mfma_f32_16x16x32_bf16 v[6:9], v[202:205], v[194:197], v[6:9]
	v_mfma_f32_16x16x32_bf16 v[2:5], v[210:213], v[194:197], v[2:5]
	v_mfma_f32_16x16x32_bf16 v[54:57], v[206:209], v[150:153], v[54:57]
	v_mfma_f32_16x16x32_bf16 v[50:53], v[214:217], v[150:153], v[50:53]
	v_mfma_f32_16x16x32_bf16 v[38:41], v[206:209], v[158:161], v[38:41]
	v_mfma_f32_16x16x32_bf16 v[34:37], v[214:217], v[158:161], v[34:37]
	v_mfma_f32_16x16x32_bf16 v[22:25], v[206:209], v[166:169], v[22:25]
	v_mfma_f32_16x16x32_bf16 v[18:21], v[214:217], v[166:169], v[18:21]
	v_mfma_f32_16x16x32_bf16 v[6:9], v[206:209], v[198:201], v[6:9]
	v_mfma_f32_16x16x32_bf16 v[2:5], v[214:217], v[198:201], v[2:5]
	s_barrier
	s_setprio 0
	s_add_i32 s49, s49, 2
	s_add_u32 s0, s0, 0x100
	s_addc_u32 s1, s1, 0
	s_add_u32 s10, s10, 0x100
	s_addc_u32 s11, s11, 0
	s_cmp_gt_u32 s49, 41
	s_cbranch_scc0 .LBB0_822
	s_min_i32 s0, s48, 0x80
	s_ashr_i32 s0, s0, 3
	s_mul_hi_i32 s1, s0, 0x9000
	s_mul_i32 s0, s0, 0x9000
	s_add_u32 s6, s58, s0
	s_addc_u32 s7, s59, s1
	s_lshl_b32 s50, s34, 8
	s_ashr_i32 s51, s50, 31
	s_lshl_b64 s[0:1], s[50:51], 2
	s_add_u32 s0, s6, s0
	s_addc_u32 s1, s7, s1
	v_lshlrev_b32_e32 v184, 2, v182
	v_lshl_add_u64 v[130:131], s[0:1], 0, v[184:185]
	s_mov_b64 s[0:1], 0x2000
	v_lshl_add_u64 v[132:133], v[130:131], 0, s[0:1]
	s_movk_i32 s0, 0x2000
	v_add_co_u32_e32 v134, vcc, s0, v130
	s_mov_b64 s[0:1], 0x2200
	s_nop 0
	v_addc_co_u32_e32 v135, vcc, 0, v131, vcc
	global_load_dwordx4 v[194:197], v[134:135], off
	global_load_dwordx4 v[220:223], v[132:133], off offset:16
	v_lshl_add_u64 v[132:133], v[130:131], 0, s[0:1]
	s_mov_b64 s[0:1], 0x4000
	global_load_dwordx4 v[198:201], v[134:135], off offset:512
	global_load_dwordx4 v[224:227], v[132:133], off offset:16
	v_lshl_add_u64 v[132:133], v[130:131], 0, s[0:1]
	s_movk_i32 s0, 0x4000
	v_add_co_u32_e32 v134, vcc, s0, v130
	s_mov_b64 s[0:1], 0x4200
	v_lshl_add_u32 v212, s48, 8, v239
	v_addc_co_u32_e32 v135, vcc, 0, v131, vcc
	v_lshl_add_u64 v[130:131], v[130:131], 0, s[0:1]
	global_load_dwordx4 v[154:157], v[134:135], off
	global_load_dwordx4 v[162:165], v[132:133], off offset:16
	global_load_dwordx4 v[158:161], v[134:135], off offset:512
	global_load_dwordx4 v[166:169], v[130:131], off offset:16
	v_add_u32_e32 v130, 0xffff8000, v212
	v_ashrrev_i32_e32 v213, 31, v212
	v_cmp_gt_i32_e64 s[6:7], s76, v212
	v_mov_b32_e32 v134, s72
	v_mov_b32_e32 v135, s29
	v_cndmask_b32_e64 v131, 0, v213, s[6:7]
	v_cndmask_b32_e64 v130, v130, v212, s[6:7]
	v_mov_b32_e32 v136, s71
	v_mov_b32_e32 v137, s28
	v_cndmask_b32_e64 v133, v134, v135, s[6:7]
	v_cndmask_b32_e64 v132, v136, v137, s[6:7]
	v_lshlrev_b64 v[130:131], 11, v[130:131]
	v_lshl_add_u64 v[130:131], v[132:133], 0, v[130:131]
	s_lshl_b64 s[0:1], s[50:51], 1
	v_lshl_add_u64 v[130:131], v[130:131], 0, s[0:1]
	v_lshlrev_b32_e32 v184, 1, v182
	v_lshl_add_u64 v[130:131], v[130:131], 0, v[184:185]
	v_or_b32_e32 v218, 16, v212
	global_load_dwordx4 v[246:249], v[130:131], off
	global_load_dwordx4 v[250:253], v[130:131], off offset:256
	v_add_u32_e32 v130, 0xffff8010, v212
	v_ashrrev_i32_e32 v219, 31, v218
	v_cmp_gt_i32_e64 s[8:9], s76, v218
	v_or_b32_e32 v216, 32, v212
	v_ashrrev_i32_e32 v217, 31, v216
	v_cndmask_b32_e64 v131, 0, v219, s[8:9]
	v_cndmask_b32_e64 v130, v130, v218, s[8:9]
	v_cndmask_b32_e64 v133, v134, v135, s[8:9]
	v_cndmask_b32_e64 v132, v136, v137, s[8:9]
	v_lshlrev_b64 v[130:131], 11, v[130:131]
	v_lshl_add_u64 v[130:131], v[132:133], 0, v[130:131]
	v_lshl_add_u64 v[130:131], v[130:131], 0, s[0:1]
	v_lshl_add_u64 v[130:131], v[130:131], 0, v[184:185]
	global_load_dwordx4 v[150:153], v[130:131], off
	global_load_dwordx4 v[146:149], v[130:131], off offset:256
	v_add_u32_e32 v130, 0xffff8020, v212
	v_cmp_gt_i32_e64 s[10:11], s76, v216
	v_or_b32_e32 v214, 48, v212
	v_ashrrev_i32_e32 v215, 31, v214
	v_cndmask_b32_e64 v131, 0, v217, s[10:11]
	v_cndmask_b32_e64 v130, v130, v216, s[10:11]
	v_cndmask_b32_e64 v133, v134, v135, s[10:11]
	v_cndmask_b32_e64 v132, v136, v137, s[10:11]
	v_lshlrev_b64 v[130:131], 11, v[130:131]
	v_lshl_add_u64 v[130:131], v[132:133], 0, v[130:131]
	v_lshl_add_u64 v[130:131], v[130:131], 0, s[0:1]
	v_lshl_add_u64 v[130:131], v[130:131], 0, v[184:185]
	global_load_dwordx4 v[142:145], v[130:131], off
	global_load_dwordx4 v[138:141], v[130:131], off offset:256
	v_add_u32_e32 v130, 0xffff8030, v212
	v_cmp_gt_i32_e32 vcc, s76, v214
	s_waitcnt vmcnt(0)
	v_pk_mul_f32 v[210:211], v[194:195], 0.5 op_sel_hi:[1,0]
	v_cndmask_b32_e32 v131, 0, v215, vcc
	v_cndmask_b32_e32 v130, v130, v214, vcc
	v_cndmask_b32_e32 v133, v134, v135, vcc
	v_cndmask_b32_e32 v132, v136, v137, vcc
	v_lshlrev_b64 v[130:131], 11, v[130:131]
	v_lshl_add_u64 v[130:131], v[132:133], 0, v[130:131]
	v_lshl_add_u64 v[130:131], v[130:131], 0, s[0:1]
	v_lshl_add_u64 v[130:131], v[130:131], 0, v[184:185]
	global_load_dwordx4 v[134:137], v[130:131], off
	s_nop 0
	global_load_dwordx4 v[130:133], v[130:131], off offset:256
	v_pk_mul_f32 v[202:203], v[220:221], 0.5 op_sel_hi:[1,0]
	v_pk_mul_f32 v[208:209], v[198:199], 0.5 op_sel_hi:[1,0]
	v_pk_mul_f32 v[206:207], v[196:197], 0.5 op_sel_hi:[1,0]
	v_pk_mul_f32 v[204:205], v[200:201], 0.5 op_sel_hi:[1,0]
	v_pk_mul_f32 v[198:199], v[222:223], 0.5 op_sel_hi:[1,0]
	v_pk_mul_f32 v[200:201], v[224:225], 0.5 op_sel_hi:[1,0]
	v_pk_mul_f32 v[196:197], v[226:227], 0.5 op_sel_hi:[1,0]
	v_mov_b32_e32 v195, s51
	v_or_b32_e32 v194, s50, v182
	v_lshlrev_b32_e32 v220, 16, v246
	v_and_b32_e32 v221, 0xffff0000, v246
	v_pk_fma_f32 v[220:221], v[126:127], v[210:211], v[220:221]
	v_lshlrev_b32_e32 v126, 16, v250
	v_and_b32_e32 v127, 0xffff0000, v250
	v_pk_fma_f32 v[118:119], v[118:119], v[208:209], v[126:127]
	v_lshlrev_b32_e32 v126, 16, v247
	v_and_b32_e32 v127, 0xffff0000, v247
	v_pk_fma_f32 v[222:223], v[128:129], v[206:207], v[126:127]
	v_lshlrev_b32_e32 v126, 16, v251
	v_and_b32_e32 v127, 0xffff0000, v251
	v_pk_fma_f32 v[120:121], v[120:121], v[204:205], v[126:127]
	v_lshlrev_b32_e32 v126, 16, v248
	v_and_b32_e32 v127, 0xffff0000, v248
	v_pk_fma_f32 v[224:225], v[122:123], v[202:203], v[126:127]
	v_lshlrev_b32_e32 v122, 16, v252
	v_and_b32_e32 v123, 0xffff0000, v252
	v_pk_fma_f32 v[114:115], v[114:115], v[200:201], v[122:123]
	v_lshlrev_b32_e32 v122, 16, v249
	v_and_b32_e32 v123, 0xffff0000, v249
	v_pk_fma_f32 v[226:227], v[124:125], v[198:199], v[122:123]
	v_lshlrev_b32_e32 v122, 16, v253
	v_and_b32_e32 v123, 0xffff0000, v253
	v_pk_fma_f32 v[116:117], v[116:117], v[196:197], v[122:123]
	v_lshlrev_b64 v[122:123], 10, v[212:213]
	v_lshl_add_u64 v[228:229], v[122:123], 0, v[194:195]
	s_and_saveexec_b64 s[0:1], s[6:7]
	s_cbranch_execz .LBB0_825
	v_lshl_add_u64 v[126:127], v[228:229], 1, s[28:29]
	v_cvt_pk_bf16_f32 v122, v220, v221
	v_cvt_pk_bf16_f32 v123, v222, v223
	v_cvt_pk_bf16_f32 v124, v224, v225
	v_cvt_pk_bf16_f32 v125, v226, v227
	global_store_dwordx4 v[126:127], v[122:125], off nt
	s_nop 1
	v_cvt_pk_bf16_f32 v122, v118, v119
	v_cvt_pk_bf16_f32 v123, v120, v121
	v_cvt_pk_bf16_f32 v124, v114, v115
	v_cvt_pk_bf16_f32 v125, v116, v117
	global_store_dwordx4 v[126:127], v[122:125], off offset:256 nt

.LBB0_868:
	s_add_u32 s12, s12, 0xb0080
	s_addc_u32 s13, s13, 0
	s_add_u32 s78, s14, 0x100
	s_addc_u32 s79, s15, 0
	s_mov_b32 s87, -2
	ds_read_b128 v[146:149], v142
	ds_read_b128 v[150:153], v142 offset:1024
	ds_read_b128 v[154:157], v142 offset:2048
	ds_read_b128 v[158:161], v142 offset:3072
	s_add_u32 s14, s12, 0xfff50080
	s_addc_u32 s15, s13, -1
	s_cmp_eq_u32 s87, 18
	s_cselect_b32 s17, s1, s15
	s_cselect_b32 s16, s0, s14
	s_cselect_b32 s15, s7, s79
	s_cselect_b32 s14, s6, s78
	s_mov_b32 m0, s68
	v_lshl_add_u64 v[208:209], s[12:13], 0, v[132:133]
	ds_read_b128 v[162:165], v143
	ds_read_b128 v[166:169], v143 offset:1024
	ds_read_b128 v[184:187], v143 offset:2048
	ds_read_b128 v[188:191], v143 offset:3072
	ds_read_b128 v[192:195], v143 offset:4096
	ds_read_b128 v[196:199], v143 offset:5120
	ds_read_b128 v[200:203], v143 offset:6144
	ds_read_b128 v[204:207], v143 offset:7168
	global_load_lds_dwordx4 v[208:209], off
	v_lshl_add_u64 v[208:209], s[12:13], 0, v[134:135]
	s_mov_b32 m0, s69
	s_nop 0
	global_load_lds_dwordx4 v[208:209], off
	s_waitcnt lgkmcnt(8)
	s_setprio 1
	s_barrier
	s_waitcnt lgkmcnt(0)
	v_mfma_f32_16x16x32_bf16 v[126:129], v[146:149], v[162:165], 0
	v_mfma_f32_16x16x32_bf16 v[122:125], v[154:157], v[162:165], 0
	v_mfma_f32_16x16x32_bf16 v[118:121], v[146:149], v[184:187], 0
	v_mfma_f32_16x16x32_bf16 v[114:117], v[154:157], v[184:187], 0
	v_mfma_f32_16x16x32_bf16 v[102:105], v[146:149], v[192:195], 0
	v_mfma_f32_16x16x32_bf16 v[98:101], v[154:157], v[192:195], 0
	v_mfma_f32_16x16x32_bf16 v[86:89], v[146:149], v[200:203], 0
	v_mfma_f32_16x16x32_bf16 v[82:85], v[154:157], v[200:203], 0
	v_mfma_f32_16x16x32_bf16 v[126:129], v[150:153], v[166:169], v[126:129]
	v_mfma_f32_16x16x32_bf16 v[122:125], v[158:161], v[166:169], v[122:125]
	v_mfma_f32_16x16x32_bf16 v[118:121], v[150:153], v[188:191], v[118:121]
	v_mfma_f32_16x16x32_bf16 v[114:117], v[158:161], v[188:191], v[114:117]
	v_mfma_f32_16x16x32_bf16 v[102:105], v[150:153], v[196:199], v[102:105]
	v_mfma_f32_16x16x32_bf16 v[98:101], v[158:161], v[196:199], v[98:101]
	v_mfma_f32_16x16x32_bf16 v[86:89], v[150:153], v[204:207], v[86:89]
	v_mfma_f32_16x16x32_bf16 v[82:85], v[158:161], v[204:207], v[82:85]
	s_barrier
	s_setprio 0
	s_mov_b32 m0, s70
	v_lshl_add_u64 v[224:225], s[14:15], 0, v[176:177]
	ds_read_b128 v[208:211], v144
	ds_read_b128 v[212:215], v144 offset:1024
	ds_read_b128 v[216:219], v144 offset:2048
	ds_read_b128 v[220:223], v144 offset:3072
	global_load_lds_dwordx4 v[224:225], off
	v_lshl_add_u64 v[226:227], s[14:15], 0, v[180:181]
	s_mov_b32 m0, s71
	s_nop 0
	global_load_lds_dwordx4 v[226:227], off
	s_setprio 1
	s_barrier
	s_waitcnt lgkmcnt(0)
	v_mfma_f32_16x16x32_bf16 v[110:113], v[208:211], v[162:165], 0
	v_mfma_f32_16x16x32_bf16 v[106:109], v[216:219], v[162:165], 0
	v_mfma_f32_16x16x32_bf16 v[94:97], v[208:211], v[184:187], 0
	v_mfma_f32_16x16x32_bf16 v[90:93], v[216:219], v[184:187], 0
	v_mfma_f32_16x16x32_bf16 v[78:81], v[208:211], v[192:195], 0
	v_mfma_f32_16x16x32_bf16 v[74:77], v[216:219], v[192:195], 0
	v_mfma_f32_16x16x32_bf16 v[70:73], v[208:211], v[200:203], 0
	v_mfma_f32_16x16x32_bf16 v[66:69], v[216:219], v[200:203], 0
	v_mfma_f32_16x16x32_bf16 v[110:113], v[212:215], v[166:169], v[110:113]
	v_mfma_f32_16x16x32_bf16 v[106:109], v[220:223], v[166:169], v[106:109]
	v_mfma_f32_16x16x32_bf16 v[94:97], v[212:215], v[188:191], v[94:97]
	v_mfma_f32_16x16x32_bf16 v[90:93], v[220:223], v[188:191], v[90:93]
	v_mfma_f32_16x16x32_bf16 v[78:81], v[212:215], v[196:199], v[78:81]
	v_mfma_f32_16x16x32_bf16 v[74:77], v[220:223], v[196:199], v[74:77]
	v_mfma_f32_16x16x32_bf16 v[70:73], v[212:215], v[204:207], v[70:73]
	v_mfma_f32_16x16x32_bf16 v[66:69], v[220:223], v[204:207], v[66:69]
	s_barrier
	s_setprio 0
	s_mov_b32 m0, s40
	v_lshl_add_u64 v[228:229], s[16:17], 0, v[172:173]
	ds_read_b128 v[162:165], v143 offset:16384
	ds_read_b128 v[166:169], v143 offset:17408
	ds_read_b128 v[184:187], v143 offset:18432
	ds_read_b128 v[188:191], v143 offset:19456
	ds_read_b128 v[192:195], v143 offset:20480
	ds_read_b128 v[196:199], v143 offset:21504
	ds_read_b128 v[200:203], v143 offset:22528
	ds_read_b128 v[204:207], v143 offset:23552
	global_load_lds_dwordx4 v[228:229], off
	v_lshl_add_u64 v[234:235], s[16:17], 0, v[178:179]
	s_mov_b32 m0, s41
	s_nop 0
	global_load_lds_dwordx4 v[234:235], off
	s_setprio 1
	s_barrier
	s_waitcnt lgkmcnt(0)
	v_mfma_f32_16x16x32_bf16 v[62:65], v[146:149], v[162:165], 0
	v_mfma_f32_16x16x32_bf16 v[58:61], v[154:157], v[162:165], 0
	v_mfma_f32_16x16x32_bf16 v[54:57], v[146:149], v[184:187], 0
	v_mfma_f32_16x16x32_bf16 v[50:53], v[154:157], v[184:187], 0
	v_mfma_f32_16x16x32_bf16 v[38:41], v[146:149], v[192:195], 0
	v_mfma_f32_16x16x32_bf16 v[34:37], v[154:157], v[192:195], 0
	v_mfma_f32_16x16x32_bf16 v[22:25], v[146:149], v[200:203], 0
	v_mfma_f32_16x16x32_bf16 v[18:21], v[154:157], v[200:203], 0
	v_mfma_f32_16x16x32_bf16 v[62:65], v[150:153], v[166:169], v[62:65]
	v_mfma_f32_16x16x32_bf16 v[58:61], v[158:161], v[166:169], v[58:61]
	v_mfma_f32_16x16x32_bf16 v[54:57], v[150:153], v[188:191], v[54:57]
	v_mfma_f32_16x16x32_bf16 v[50:53], v[158:161], v[188:191], v[50:53]
	v_mfma_f32_16x16x32_bf16 v[38:41], v[150:153], v[196:199], v[38:41]
	v_mfma_f32_16x16x32_bf16 v[34:37], v[158:161], v[196:199], v[34:37]
	v_mfma_f32_16x16x32_bf16 v[22:25], v[150:153], v[204:207], v[22:25]
	v_mfma_f32_16x16x32_bf16 v[18:21], v[158:161], v[204:207], v[18:21]
	s_barrier
	s_setprio 0
	s_add_u32 s20, s14, 0xb0000
	s_addc_u32 s21, s15, 0
	s_add_i32 s60, s56, s35
	v_lshl_add_u64 v[146:147], s[20:21], 0, v[176:177]
	s_mov_b32 m0, s60
	s_nop 0
	global_load_lds_dwordx4 v[146:147], off
	v_lshl_add_u64 v[146:147], s[20:21], 0, v[180:181]
	s_add_i32 m0, s60, 0x2000
	s_nop 0
	global_load_lds_dwordx4 v[146:147], off
	s_waitcnt vmcnt(6)
	s_setprio 1
	s_barrier
	v_mfma_f32_16x16x32_bf16 v[46:49], v[208:211], v[162:165], 0
	v_mfma_f32_16x16x32_bf16 v[42:45], v[216:219], v[162:165], 0
	v_mfma_f32_16x16x32_bf16 v[30:33], v[208:211], v[184:187], 0
	v_mfma_f32_16x16x32_bf16 v[26:29], v[216:219], v[184:187], 0
	v_mfma_f32_16x16x32_bf16 v[14:17], v[208:211], v[192:195], 0
	v_mfma_f32_16x16x32_bf16 v[10:13], v[216:219], v[192:195], 0
	v_mfma_f32_16x16x32_bf16 v[6:9], v[208:211], v[200:203], 0
	v_mfma_f32_16x16x32_bf16 v[2:5], v[216:219], v[200:203], 0
	v_mfma_f32_16x16x32_bf16 v[46:49], v[212:215], v[166:169], v[46:49]
	v_mfma_f32_16x16x32_bf16 v[42:45], v[220:223], v[166:169], v[42:45]
	v_mfma_f32_16x16x32_bf16 v[30:33], v[212:215], v[188:191], v[30:33]
	v_mfma_f32_16x16x32_bf16 v[26:29], v[220:223], v[188:191], v[26:29]
	v_mfma_f32_16x16x32_bf16 v[14:17], v[212:215], v[196:199], v[14:17]
	v_mfma_f32_16x16x32_bf16 v[10:13], v[220:223], v[196:199], v[10:13]
	v_mfma_f32_16x16x32_bf16 v[6:9], v[212:215], v[204:207], v[6:9]
	v_mfma_f32_16x16x32_bf16 v[2:5], v[220:223], v[204:207], v[2:5]
	s_barrier
	s_setprio 0
	s_add_i32 s20, 0, 0x18000
	v_add_u32_e32 v145, s20, v141
	ds_read_b128 v[146:149], v145
	ds_read_b128 v[150:153], v145 offset:1024
	ds_read_b128 v[154:157], v145 offset:2048
	ds_read_b128 v[158:161], v145 offset:3072
	s_add_u32 s16, s16, 0xb0000
	s_addc_u32 s17, s17, 0
	s_mov_b32 m0, s48
	v_lshl_add_u64 v[208:209], s[16:17], 0, v[172:173]
	ds_read_b128 v[162:165], v143 offset:32768
	ds_read_b128 v[166:169], v143 offset:33792
	ds_read_b128 v[184:187], v143 offset:34816
	ds_read_b128 v[188:191], v143 offset:35840
	ds_read_b128 v[192:195], v143 offset:36864
	ds_read_b128 v[196:199], v143 offset:37888
	ds_read_b128 v[200:203], v143 offset:38912
	ds_read_b128 v[204:207], v143 offset:39936
	global_load_lds_dwordx4 v[208:209], off
	v_lshl_add_u64 v[208:209], s[16:17], 0, v[178:179]
	s_mov_b32 m0, s49
	s_nop 0
	global_load_lds_dwordx4 v[208:209], off
	s_waitcnt lgkmcnt(8)
	s_setprio 1
	s_barrier
	s_waitcnt lgkmcnt(0)
	v_mfma_f32_16x16x32_bf16 v[126:129], v[146:149], v[162:165], v[126:129]
	v_mfma_f32_16x16x32_bf16 v[122:125], v[154:157], v[162:165], v[122:125]
	v_mfma_f32_16x16x32_bf16 v[118:121], v[146:149], v[184:187], v[118:121]
	v_mfma_f32_16x16x32_bf16 v[114:117], v[154:157], v[184:187], v[114:117]
	v_mfma_f32_16x16x32_bf16 v[102:105], v[146:149], v[192:195], v[102:105]
	v_mfma_f32_16x16x32_bf16 v[98:101], v[154:157], v[192:195], v[98:101]
	v_mfma_f32_16x16x32_bf16 v[86:89], v[146:149], v[200:203], v[86:89]
	v_mfma_f32_16x16x32_bf16 v[82:85], v[154:157], v[200:203], v[82:85]
	v_mfma_f32_16x16x32_bf16 v[126:129], v[150:153], v[166:169], v[126:129]
	v_mfma_f32_16x16x32_bf16 v[122:125], v[158:161], v[166:169], v[122:125]
	v_mfma_f32_16x16x32_bf16 v[118:121], v[150:153], v[188:191], v[118:121]
	v_mfma_f32_16x16x32_bf16 v[114:117], v[158:161], v[188:191], v[114:117]
	v_mfma_f32_16x16x32_bf16 v[102:105], v[150:153], v[196:199], v[102:105]
	v_mfma_f32_16x16x32_bf16 v[98:101], v[158:161], v[196:199], v[98:101]
	v_mfma_f32_16x16x32_bf16 v[86:89], v[150:153], v[204:207], v[86:89]
	v_mfma_f32_16x16x32_bf16 v[82:85], v[158:161], v[204:207], v[82:85]
	s_barrier
	s_setprio 0
	s_add_i32 s16, 0, 0x1c000
	s_add_i32 s17, s20, s35
	v_add_u32_e32 v145, s16, v141
	v_lshl_add_u64 v[224:225], v[224:225], 0, s[8:9]
	s_mov_b32 m0, s17
	ds_read_b128 v[208:211], v145
	ds_read_b128 v[212:215], v145 offset:1024
	ds_read_b128 v[216:219], v145 offset:2048
	ds_read_b128 v[220:223], v145 offset:3072
	global_load_lds_dwordx4 v[224:225], off
	v_lshl_add_u64 v[224:225], v[226:227], 0, s[8:9]
	s_add_i32 m0, s17, 0x2000
	s_nop 0
	global_load_lds_dwordx4 v[224:225], off
	s_setprio 1
	s_barrier
	s_waitcnt lgkmcnt(0)
	v_mfma_f32_16x16x32_bf16 v[110:113], v[208:211], v[162:165], v[110:113]
	v_mfma_f32_16x16x32_bf16 v[106:109], v[216:219], v[162:165], v[106:109]
	v_mfma_f32_16x16x32_bf16 v[94:97], v[208:211], v[184:187], v[94:97]
	v_mfma_f32_16x16x32_bf16 v[90:93], v[216:219], v[184:187], v[90:93]
	v_mfma_f32_16x16x32_bf16 v[78:81], v[208:211], v[192:195], v[78:81]
	v_mfma_f32_16x16x32_bf16 v[74:77], v[216:219], v[192:195], v[74:77]
	v_mfma_f32_16x16x32_bf16 v[70:73], v[208:211], v[200:203], v[70:73]
	v_mfma_f32_16x16x32_bf16 v[66:69], v[216:219], v[200:203], v[66:69]
	v_mfma_f32_16x16x32_bf16 v[110:113], v[212:215], v[166:169], v[110:113]
	v_mfma_f32_16x16x32_bf16 v[106:109], v[220:223], v[166:169], v[106:109]
	v_mfma_f32_16x16x32_bf16 v[94:97], v[212:215], v[188:191], v[94:97]
	v_mfma_f32_16x16x32_bf16 v[90:93], v[220:223], v[188:191], v[90:93]
	v_mfma_f32_16x16x32_bf16 v[78:81], v[212:215], v[196:199], v[78:81]
	v_mfma_f32_16x16x32_bf16 v[74:77], v[220:223], v[196:199], v[74:77]
	v_mfma_f32_16x16x32_bf16 v[70:73], v[212:215], v[204:207], v[70:73]
	v_mfma_f32_16x16x32_bf16 v[66:69], v[220:223], v[204:207], v[66:69]
	s_barrier
	s_setprio 0
	s_mov_b32 m0, s54
	v_lshl_add_u64 v[224:225], v[228:229], 0, s[8:9]
	ds_read_b128 v[162:165], v143 offset:49152
	ds_read_b128 v[166:169], v143 offset:50176
	ds_read_b128 v[184:187], v143 offset:51200
	ds_read_b128 v[188:191], v143 offset:52224
	ds_read_b128 v[192:195], v143 offset:53248
	ds_read_b128 v[196:199], v143 offset:54272
	ds_read_b128 v[200:203], v143 offset:55296
	ds_read_b128 v[204:207], v143 offset:56320
	global_load_lds_dwordx4 v[224:225], off
	v_lshl_add_u64 v[224:225], v[234:235], 0, s[8:9]
	s_mov_b32 m0, s55
	s_nop 0
	global_load_lds_dwordx4 v[224:225], off
	s_setprio 1
	s_barrier
	s_waitcnt lgkmcnt(0)
	v_mfma_f32_16x16x32_bf16 v[62:65], v[146:149], v[162:165], v[62:65]
	v_mfma_f32_16x16x32_bf16 v[58:61], v[154:157], v[162:165], v[58:61]
	v_mfma_f32_16x16x32_bf16 v[54:57], v[146:149], v[184:187], v[54:57]
	v_mfma_f32_16x16x32_bf16 v[50:53], v[154:157], v[184:187], v[50:53]
	v_mfma_f32_16x16x32_bf16 v[38:41], v[146:149], v[192:195], v[38:41]
	v_mfma_f32_16x16x32_bf16 v[34:37], v[154:157], v[192:195], v[34:37]
	v_mfma_f32_16x16x32_bf16 v[22:25], v[146:149], v[200:203], v[22:25]
	v_mfma_f32_16x16x32_bf16 v[18:21], v[154:157], v[200:203], v[18:21]
	v_mfma_f32_16x16x32_bf16 v[62:65], v[150:153], v[166:169], v[62:65]
	v_mfma_f32_16x16x32_bf16 v[58:61], v[158:161], v[166:169], v[58:61]
	v_mfma_f32_16x16x32_bf16 v[54:57], v[150:153], v[188:191], v[54:57]
	v_mfma_f32_16x16x32_bf16 v[50:53], v[158:161], v[188:191], v[50:53]
	v_mfma_f32_16x16x32_bf16 v[38:41], v[150:153], v[196:199], v[38:41]
	v_mfma_f32_16x16x32_bf16 v[34:37], v[158:161], v[196:199], v[34:37]
	v_mfma_f32_16x16x32_bf16 v[22:25], v[150:153], v[204:207], v[22:25]
	v_mfma_f32_16x16x32_bf16 v[18:21], v[158:161], v[204:207], v[18:21]
	s_barrier
	s_setprio 0
	s_add_u32 s14, s14, 0xb0080
	s_addc_u32 s15, s15, 0
	s_add_i32 s16, s16, s35
	v_lshl_add_u64 v[146:147], s[14:15], 0, v[176:177]
	s_mov_b32 m0, s16
	s_nop 0
	global_load_lds_dwordx4 v[146:147], off
	v_lshl_add_u64 v[146:147], s[14:15], 0, v[180:181]
	s_add_i32 m0, s16, 0x2000
	s_nop 0
	global_load_lds_dwordx4 v[146:147], off
	s_waitcnt vmcnt(6)
	s_setprio 1
	s_barrier
	v_mfma_f32_16x16x32_bf16 v[46:49], v[208:211], v[162:165], v[46:49]
	v_mfma_f32_16x16x32_bf16 v[42:45], v[216:219], v[162:165], v[42:45]
	v_mfma_f32_16x16x32_bf16 v[30:33], v[208:211], v[184:187], v[30:33]
	v_mfma_f32_16x16x32_bf16 v[26:29], v[216:219], v[184:187], v[26:29]
	v_mfma_f32_16x16x32_bf16 v[14:17], v[208:211], v[192:195], v[14:17]
	v_mfma_f32_16x16x32_bf16 v[10:13], v[216:219], v[192:195], v[10:13]
	v_mfma_f32_16x16x32_bf16 v[6:9], v[208:211], v[200:203], v[6:9]
	v_mfma_f32_16x16x32_bf16 v[2:5], v[216:219], v[200:203], v[2:5]
	v_mfma_f32_16x16x32_bf16 v[46:49], v[212:215], v[166:169], v[46:49]
	v_mfma_f32_16x16x32_bf16 v[42:45], v[220:223], v[166:169], v[42:45]
	v_mfma_f32_16x16x32_bf16 v[30:33], v[212:215], v[188:191], v[30:33]
	v_mfma_f32_16x16x32_bf16 v[26:29], v[220:223], v[188:191], v[26:29]
	v_mfma_f32_16x16x32_bf16 v[14:17], v[212:215], v[196:199], v[14:17]
	v_mfma_f32_16x16x32_bf16 v[10:13], v[220:223], v[196:199], v[10:13]
	v_mfma_f32_16x16x32_bf16 v[6:9], v[212:215], v[204:207], v[6:9]
	v_mfma_f32_16x16x32_bf16 v[2:5], v[220:223], v[204:207], v[2:5]
	s_barrier
	s_setprio 0
	s_add_i32 s87, s87, 2
	s_add_u32 s12, s12, 0x100
	s_addc_u32 s13, s13, 0
	s_add_u32 s78, s78, 0x100
	s_addc_u32 s79, s79, 0
	s_cmp_gt_u32 s87, 19
.LBB0_869:
	ds_read_b128 v[146:149], v142
	ds_read_b128 v[150:153], v142 offset:1024
	ds_read_b128 v[154:157], v142 offset:2048
	ds_read_b128 v[158:161], v142 offset:3072
	s_add_u32 s14, s12, 0xfff50080
	s_addc_u32 s15, s13, -1
	s_cmp_eq_u32 s87, 18
	s_cselect_b32 s17, s1, s15
	s_cselect_b32 s16, s0, s14
	s_cselect_b32 s15, s7, s79
	s_cselect_b32 s14, s6, s78
	s_mov_b32 m0, s68
	v_lshl_add_u64 v[208:209], s[12:13], 0, v[132:133]
	ds_read_b128 v[162:165], v143
	ds_read_b128 v[166:169], v143 offset:1024
	ds_read_b128 v[184:187], v143 offset:2048
	ds_read_b128 v[188:191], v143 offset:3072
	ds_read_b128 v[192:195], v143 offset:4096
	ds_read_b128 v[196:199], v143 offset:5120
	ds_read_b128 v[200:203], v143 offset:6144
	ds_read_b128 v[204:207], v143 offset:7168
	global_load_lds_dwordx4 v[208:209], off
	v_lshl_add_u64 v[208:209], s[12:13], 0, v[134:135]
	s_mov_b32 m0, s69
	s_nop 0
	global_load_lds_dwordx4 v[208:209], off
	s_waitcnt lgkmcnt(8)
	s_setprio 1
	s_barrier
	s_waitcnt lgkmcnt(0)
	v_mfma_f32_16x16x32_bf16 v[126:129], v[146:149], v[162:165], v[126:129]
	v_mfma_f32_16x16x32_bf16 v[122:125], v[154:157], v[162:165], v[122:125]
	v_mfma_f32_16x16x32_bf16 v[118:121], v[146:149], v[184:187], v[118:121]
	v_mfma_f32_16x16x32_bf16 v[114:117], v[154:157], v[184:187], v[114:117]
	v_mfma_f32_16x16x32_bf16 v[102:105], v[146:149], v[192:195], v[102:105]
	v_mfma_f32_16x16x32_bf16 v[98:101], v[154:157], v[192:195], v[98:101]
	v_mfma_f32_16x16x32_bf16 v[86:89], v[146:149], v[200:203], v[86:89]
	v_mfma_f32_16x16x32_bf16 v[82:85], v[154:157], v[200:203], v[82:85]
	v_mfma_f32_16x16x32_bf16 v[126:129], v[150:153], v[166:169], v[126:129]
	v_mfma_f32_16x16x32_bf16 v[122:125], v[158:161], v[166:169], v[122:125]
	v_mfma_f32_16x16x32_bf16 v[118:121], v[150:153], v[188:191], v[118:121]
	v_mfma_f32_16x16x32_bf16 v[114:117], v[158:161], v[188:191], v[114:117]
	v_mfma_f32_16x16x32_bf16 v[102:105], v[150:153], v[196:199], v[102:105]
	v_mfma_f32_16x16x32_bf16 v[98:101], v[158:161], v[196:199], v[98:101]
	v_mfma_f32_16x16x32_bf16 v[86:89], v[150:153], v[204:207], v[86:89]
	v_mfma_f32_16x16x32_bf16 v[82:85], v[158:161], v[204:207], v[82:85]
	s_barrier
	s_setprio 0
	s_mov_b32 m0, s70
	v_lshl_add_u64 v[224:225], s[14:15], 0, v[176:177]
	ds_read_b128 v[208:211], v144
	ds_read_b128 v[212:215], v144 offset:1024
	ds_read_b128 v[216:219], v144 offset:2048
	ds_read_b128 v[220:223], v144 offset:3072
	global_load_lds_dwordx4 v[224:225], off
	v_lshl_add_u64 v[226:227], s[14:15], 0, v[180:181]
	s_mov_b32 m0, s71
	s_nop 0
	global_load_lds_dwordx4 v[226:227], off
	s_setprio 1
	s_barrier
	s_waitcnt lgkmcnt(0)
	v_mfma_f32_16x16x32_bf16 v[110:113], v[208:211], v[162:165], v[110:113]
	v_mfma_f32_16x16x32_bf16 v[106:109], v[216:219], v[162:165], v[106:109]
	v_mfma_f32_16x16x32_bf16 v[94:97], v[208:211], v[184:187], v[94:97]
	v_mfma_f32_16x16x32_bf16 v[90:93], v[216:219], v[184:187], v[90:93]
	v_mfma_f32_16x16x32_bf16 v[78:81], v[208:211], v[192:195], v[78:81]
	v_mfma_f32_16x16x32_bf16 v[74:77], v[216:219], v[192:195], v[74:77]
	v_mfma_f32_16x16x32_bf16 v[70:73], v[208:211], v[200:203], v[70:73]
	v_mfma_f32_16x16x32_bf16 v[66:69], v[216:219], v[200:203], v[66:69]
	v_mfma_f32_16x16x32_bf16 v[110:113], v[212:215], v[166:169], v[110:113]
	v_mfma_f32_16x16x32_bf16 v[106:109], v[220:223], v[166:169], v[106:109]
	v_mfma_f32_16x16x32_bf16 v[94:97], v[212:215], v[188:191], v[94:97]
	v_mfma_f32_16x16x32_bf16 v[90:93], v[220:223], v[188:191], v[90:93]
	v_mfma_f32_16x16x32_bf16 v[78:81], v[212:215], v[196:199], v[78:81]
	v_mfma_f32_16x16x32_bf16 v[74:77], v[220:223], v[196:199], v[74:77]
	v_mfma_f32_16x16x32_bf16 v[70:73], v[212:215], v[204:207], v[70:73]
	v_mfma_f32_16x16x32_bf16 v[66:69], v[220:223], v[204:207], v[66:69]
	s_barrier
	s_setprio 0
	s_mov_b32 m0, s40
	v_lshl_add_u64 v[228:229], s[16:17], 0, v[172:173]
	ds_read_b128 v[162:165], v143 offset:16384
	ds_read_b128 v[166:169], v143 offset:17408
	ds_read_b128 v[184:187], v143 offset:18432
	ds_read_b128 v[188:191], v143 offset:19456
	ds_read_b128 v[192:195], v143 offset:20480
	ds_read_b128 v[196:199], v143 offset:21504
	ds_read_b128 v[200:203], v143 offset:22528
	ds_read_b128 v[204:207], v143 offset:23552
	global_load_lds_dwordx4 v[228:229], off
	v_lshl_add_u64 v[234:235], s[16:17], 0, v[178:179]
	s_mov_b32 m0, s41
	s_nop 0
	global_load_lds_dwordx4 v[234:235], off
	s_setprio 1
	s_barrier
	s_waitcnt lgkmcnt(0)
	v_mfma_f32_16x16x32_bf16 v[62:65], v[146:149], v[162:165], v[62:65]
	v_mfma_f32_16x16x32_bf16 v[58:61], v[154:157], v[162:165], v[58:61]
	v_mfma_f32_16x16x32_bf16 v[54:57], v[146:149], v[184:187], v[54:57]
	v_mfma_f32_16x16x32_bf16 v[50:53], v[154:157], v[184:187], v[50:53]
	v_mfma_f32_16x16x32_bf16 v[38:41], v[146:149], v[192:195], v[38:41]
	v_mfma_f32_16x16x32_bf16 v[34:37], v[154:157], v[192:195], v[34:37]
	v_mfma_f32_16x16x32_bf16 v[22:25], v[146:149], v[200:203], v[22:25]
	v_mfma_f32_16x16x32_bf16 v[18:21], v[154:157], v[200:203], v[18:21]
	v_mfma_f32_16x16x32_bf16 v[62:65], v[150:153], v[166:169], v[62:65]
	v_mfma_f32_16x16x32_bf16 v[58:61], v[158:161], v[166:169], v[58:61]
	v_mfma_f32_16x16x32_bf16 v[54:57], v[150:153], v[188:191], v[54:57]
	v_mfma_f32_16x16x32_bf16 v[50:53], v[158:161], v[188:191], v[50:53]
	v_mfma_f32_16x16x32_bf16 v[38:41], v[150:153], v[196:199], v[38:41]
	v_mfma_f32_16x16x32_bf16 v[34:37], v[158:161], v[196:199], v[34:37]
	v_mfma_f32_16x16x32_bf16 v[22:25], v[150:153], v[204:207], v[22:25]
	v_mfma_f32_16x16x32_bf16 v[18:21], v[158:161], v[204:207], v[18:21]
	s_barrier
	s_setprio 0
	s_add_u32 s20, s14, 0xb0000
	s_addc_u32 s21, s15, 0
	s_add_i32 s60, s56, s35
	v_lshl_add_u64 v[146:147], s[20:21], 0, v[176:177]
	s_mov_b32 m0, s60
	s_nop 0
	global_load_lds_dwordx4 v[146:147], off
	v_lshl_add_u64 v[146:147], s[20:21], 0, v[180:181]
	s_add_i32 m0, s60, 0x2000
	s_nop 0
	global_load_lds_dwordx4 v[146:147], off
	s_waitcnt vmcnt(6)
	s_setprio 1
	s_barrier
	v_mfma_f32_16x16x32_bf16 v[46:49], v[208:211], v[162:165], v[46:49]
	v_mfma_f32_16x16x32_bf16 v[42:45], v[216:219], v[162:165], v[42:45]
	v_mfma_f32_16x16x32_bf16 v[30:33], v[208:211], v[184:187], v[30:33]
	v_mfma_f32_16x16x32_bf16 v[26:29], v[216:219], v[184:187], v[26:29]
	v_mfma_f32_16x16x32_bf16 v[14:17], v[208:211], v[192:195], v[14:17]
	v_mfma_f32_16x16x32_bf16 v[10:13], v[216:219], v[192:195], v[10:13]
	v_mfma_f32_16x16x32_bf16 v[6:9], v[208:211], v[200:203], v[6:9]
	v_mfma_f32_16x16x32_bf16 v[2:5], v[216:219], v[200:203], v[2:5]
	v_mfma_f32_16x16x32_bf16 v[46:49], v[212:215], v[166:169], v[46:49]
	v_mfma_f32_16x16x32_bf16 v[42:45], v[220:223], v[166:169], v[42:45]
	v_mfma_f32_16x16x32_bf16 v[30:33], v[212:215], v[188:191], v[30:33]
	v_mfma_f32_16x16x32_bf16 v[26:29], v[220:223], v[188:191], v[26:29]
	v_mfma_f32_16x16x32_bf16 v[14:17], v[212:215], v[196:199], v[14:17]
	v_mfma_f32_16x16x32_bf16 v[10:13], v[220:223], v[196:199], v[10:13]
	v_mfma_f32_16x16x32_bf16 v[6:9], v[212:215], v[204:207], v[6:9]
	v_mfma_f32_16x16x32_bf16 v[2:5], v[220:223], v[204:207], v[2:5]
	s_barrier
	s_setprio 0
	s_add_i32 s20, 0, 0x18000
	v_add_u32_e32 v145, s20, v141
	ds_read_b128 v[146:149], v145
	ds_read_b128 v[150:153], v145 offset:1024
	ds_read_b128 v[154:157], v145 offset:2048
	ds_read_b128 v[158:161], v145 offset:3072
	s_add_u32 s16, s16, 0xb0000
	s_addc_u32 s17, s17, 0
	s_mov_b32 m0, s48
	v_lshl_add_u64 v[208:209], s[16:17], 0, v[172:173]
	ds_read_b128 v[162:165], v143 offset:32768
	ds_read_b128 v[166:169], v143 offset:33792
	ds_read_b128 v[184:187], v143 offset:34816
	ds_read_b128 v[188:191], v143 offset:35840
	ds_read_b128 v[192:195], v143 offset:36864
	ds_read_b128 v[196:199], v143 offset:37888
	ds_read_b128 v[200:203], v143 offset:38912
	ds_read_b128 v[204:207], v143 offset:39936
	global_load_lds_dwordx4 v[208:209], off
	v_lshl_add_u64 v[208:209], s[16:17], 0, v[178:179]
	s_mov_b32 m0, s49
	s_nop 0
	global_load_lds_dwordx4 v[208:209], off
	s_waitcnt lgkmcnt(8)
	s_setprio 1
	s_barrier
	s_waitcnt lgkmcnt(0)
	v_mfma_f32_16x16x32_bf16 v[126:129], v[146:149], v[162:165], v[126:129]
	v_mfma_f32_16x16x32_bf16 v[122:125], v[154:157], v[162:165], v[122:125]
	v_mfma_f32_16x16x32_bf16 v[118:121], v[146:149], v[184:187], v[118:121]
	v_mfma_f32_16x16x32_bf16 v[114:117], v[154:157], v[184:187], v[114:117]
	v_mfma_f32_16x16x32_bf16 v[102:105], v[146:149], v[192:195], v[102:105]
	v_mfma_f32_16x16x32_bf16 v[98:101], v[154:157], v[192:195], v[98:101]
	v_mfma_f32_16x16x32_bf16 v[86:89], v[146:149], v[200:203], v[86:89]
	v_mfma_f32_16x16x32_bf16 v[82:85], v[154:157], v[200:203], v[82:85]
	v_mfma_f32_16x16x32_bf16 v[126:129], v[150:153], v[166:169], v[126:129]
	v_mfma_f32_16x16x32_bf16 v[122:125], v[158:161], v[166:169], v[122:125]
	v_mfma_f32_16x16x32_bf16 v[118:121], v[150:153], v[188:191], v[118:121]
	v_mfma_f32_16x16x32_bf16 v[114:117], v[158:161], v[188:191], v[114:117]
	v_mfma_f32_16x16x32_bf16 v[102:105], v[150:153], v[196:199], v[102:105]
	v_mfma_f32_16x16x32_bf16 v[98:101], v[158:161], v[196:199], v[98:101]
	v_mfma_f32_16x16x32_bf16 v[86:89], v[150:153], v[204:207], v[86:89]
	v_mfma_f32_16x16x32_bf16 v[82:85], v[158:161], v[204:207], v[82:85]
	s_barrier
	s_setprio 0
	s_add_i32 s16, 0, 0x1c000
	s_add_i32 s17, s20, s35
	v_add_u32_e32 v145, s16, v141
	v_lshl_add_u64 v[224:225], v[224:225], 0, s[8:9]
	s_mov_b32 m0, s17
	ds_read_b128 v[208:211], v145
	ds_read_b128 v[212:215], v145 offset:1024
	ds_read_b128 v[216:219], v145 offset:2048
	ds_read_b128 v[220:223], v145 offset:3072
	global_load_lds_dwordx4 v[224:225], off
	v_lshl_add_u64 v[224:225], v[226:227], 0, s[8:9]
	s_add_i32 m0, s17, 0x2000
	s_nop 0
	global_load_lds_dwordx4 v[224:225], off
	s_setprio 1
	s_barrier
	s_waitcnt lgkmcnt(0)
	v_mfma_f32_16x16x32_bf16 v[110:113], v[208:211], v[162:165], v[110:113]
	v_mfma_f32_16x16x32_bf16 v[106:109], v[216:219], v[162:165], v[106:109]
	v_mfma_f32_16x16x32_bf16 v[94:97], v[208:211], v[184:187], v[94:97]
	v_mfma_f32_16x16x32_bf16 v[90:93], v[216:219], v[184:187], v[90:93]
	v_mfma_f32_16x16x32_bf16 v[78:81], v[208:211], v[192:195], v[78:81]
	v_mfma_f32_16x16x32_bf16 v[74:77], v[216:219], v[192:195], v[74:77]
	v_mfma_f32_16x16x32_bf16 v[70:73], v[208:211], v[200:203], v[70:73]
	v_mfma_f32_16x16x32_bf16 v[66:69], v[216:219], v[200:203], v[66:69]
	v_mfma_f32_16x16x32_bf16 v[110:113], v[212:215], v[166:169], v[110:113]
	v_mfma_f32_16x16x32_bf16 v[106:109], v[220:223], v[166:169], v[106:109]
	v_mfma_f32_16x16x32_bf16 v[94:97], v[212:215], v[188:191], v[94:97]
	v_mfma_f32_16x16x32_bf16 v[90:93], v[220:223], v[188:191], v[90:93]
	v_mfma_f32_16x16x32_bf16 v[78:81], v[212:215], v[196:199], v[78:81]
	v_mfma_f32_16x16x32_bf16 v[74:77], v[220:223], v[196:199], v[74:77]
	v_mfma_f32_16x16x32_bf16 v[70:73], v[212:215], v[204:207], v[70:73]
	v_mfma_f32_16x16x32_bf16 v[66:69], v[220:223], v[204:207], v[66:69]
	s_barrier
	s_setprio 0
	s_mov_b32 m0, s54
	v_lshl_add_u64 v[224:225], v[228:229], 0, s[8:9]
	ds_read_b128 v[162:165], v143 offset:49152
	ds_read_b128 v[166:169], v143 offset:50176
	ds_read_b128 v[184:187], v143 offset:51200
	ds_read_b128 v[188:191], v143 offset:52224
	ds_read_b128 v[192:195], v143 offset:53248
	ds_read_b128 v[196:199], v143 offset:54272
	ds_read_b128 v[200:203], v143 offset:55296
	ds_read_b128 v[204:207], v143 offset:56320
	global_load_lds_dwordx4 v[224:225], off
	v_lshl_add_u64 v[224:225], v[234:235], 0, s[8:9]
	s_mov_b32 m0, s55
	s_nop 0
	global_load_lds_dwordx4 v[224:225], off
	s_setprio 1
	s_barrier
	s_waitcnt lgkmcnt(0)
	v_mfma_f32_16x16x32_bf16 v[62:65], v[146:149], v[162:165], v[62:65]
	v_mfma_f32_16x16x32_bf16 v[58:61], v[154:157], v[162:165], v[58:61]
	v_mfma_f32_16x16x32_bf16 v[54:57], v[146:149], v[184:187], v[54:57]
	v_mfma_f32_16x16x32_bf16 v[50:53], v[154:157], v[184:187], v[50:53]
	v_mfma_f32_16x16x32_bf16 v[38:41], v[146:149], v[192:195], v[38:41]
	v_mfma_f32_16x16x32_bf16 v[34:37], v[154:157], v[192:195], v[34:37]
	v_mfma_f32_16x16x32_bf16 v[22:25], v[146:149], v[200:203], v[22:25]
	v_mfma_f32_16x16x32_bf16 v[18:21], v[154:157], v[200:203], v[18:21]
	v_mfma_f32_16x16x32_bf16 v[62:65], v[150:153], v[166:169], v[62:65]
	v_mfma_f32_16x16x32_bf16 v[58:61], v[158:161], v[166:169], v[58:61]
	v_mfma_f32_16x16x32_bf16 v[54:57], v[150:153], v[188:191], v[54:57]
	v_mfma_f32_16x16x32_bf16 v[50:53], v[158:161], v[188:191], v[50:53]
	v_mfma_f32_16x16x32_bf16 v[38:41], v[150:153], v[196:199], v[38:41]
	v_mfma_f32_16x16x32_bf16 v[34:37], v[158:161], v[196:199], v[34:37]
	v_mfma_f32_16x16x32_bf16 v[22:25], v[150:153], v[204:207], v[22:25]
	v_mfma_f32_16x16x32_bf16 v[18:21], v[158:161], v[204:207], v[18:21]
	s_barrier
	s_setprio 0
	s_add_u32 s14, s14, 0xb0080
	s_addc_u32 s15, s15, 0
	s_add_i32 s16, s16, s35
	v_lshl_add_u64 v[146:147], s[14:15], 0, v[176:177]
	s_mov_b32 m0, s16
	s_nop 0
	global_load_lds_dwordx4 v[146:147], off
	v_lshl_add_u64 v[146:147], s[14:15], 0, v[180:181]
	s_add_i32 m0, s16, 0x2000
	s_nop 0
	global_load_lds_dwordx4 v[146:147], off
	s_waitcnt vmcnt(6)
	s_setprio 1
	s_barrier
	v_mfma_f32_16x16x32_bf16 v[46:49], v[208:211], v[162:165], v[46:49]
	v_mfma_f32_16x16x32_bf16 v[42:45], v[216:219], v[162:165], v[42:45]
	v_mfma_f32_16x16x32_bf16 v[30:33], v[208:211], v[184:187], v[30:33]
	v_mfma_f32_16x16x32_bf16 v[26:29], v[216:219], v[184:187], v[26:29]
	v_mfma_f32_16x16x32_bf16 v[14:17], v[208:211], v[192:195], v[14:17]
	v_mfma_f32_16x16x32_bf16 v[10:13], v[216:219], v[192:195], v[10:13]
	v_mfma_f32_16x16x32_bf16 v[6:9], v[208:211], v[200:203], v[6:9]
	v_mfma_f32_16x16x32_bf16 v[2:5], v[216:219], v[200:203], v[2:5]
	v_mfma_f32_16x16x32_bf16 v[46:49], v[212:215], v[166:169], v[46:49]
	v_mfma_f32_16x16x32_bf16 v[42:45], v[220:223], v[166:169], v[42:45]
	v_mfma_f32_16x16x32_bf16 v[30:33], v[212:215], v[188:191], v[30:33]
	v_mfma_f32_16x16x32_bf16 v[26:29], v[220:223], v[188:191], v[26:29]
	v_mfma_f32_16x16x32_bf16 v[14:17], v[212:215], v[196:199], v[14:17]
	v_mfma_f32_16x16x32_bf16 v[10:13], v[220:223], v[196:199], v[10:13]
	v_mfma_f32_16x16x32_bf16 v[6:9], v[212:215], v[204:207], v[6:9]
	v_mfma_f32_16x16x32_bf16 v[2:5], v[220:223], v[204:207], v[2:5]
	s_barrier
	s_setprio 0
	s_add_i32 s87, s87, 2
	s_add_u32 s12, s12, 0x100
	s_addc_u32 s13, s13, 0
	s_add_u32 s78, s78, 0x100
	s_addc_u32 s79, s79, 0
	s_cmp_gt_u32 s87, 19
	s_cbranch_scc0 .LBB0_869
	s_cmp_eq_u32 s75, 0
	s_cselect_b32 s12, 0, 0x800000
	s_add_u32 s14, s51, s12
	s_addc_u32 s15, s53, 0
	s_lshl_b32 s12, s77, 8
	s_ashr_i32 s13, s12, 31
	s_lshl_b64 s[12:13], s[12:13], 1
	s_add_u32 s12, s14, s12
	v_lshl_add_u32 v148, s76, 8, v140
	s_addc_u32 s13, s15, s13
	v_ashrrev_i32_e32 v149, 31, v148
	v_lshl_add_u64 v[146:147], s[12:13], 0, v[130:131]
	v_lshlrev_b64 v[150:151], 11, v[148:149]
	v_cvt_pk_bf16_f32 v110, v110, v111
	v_cvt_pk_bf16_f32 v111, v112, v113
	v_cvt_pk_bf16_f32 v112, v106, v107
	v_or_b32_e32 v106, 16, v148
	v_cvt_pk_bf16_f32 v46, v46, v47
	v_cvt_pk_bf16_f32 v47, v48, v49
	v_cvt_pk_bf16_f32 v48, v42, v43
	v_add_u32_e32 v42, 0x90, v148
	v_lshl_add_u64 v[150:151], v[146:147], 0, v[150:151]
	v_ashrrev_i32_e32 v107, 31, v106
	v_cvt_pk_bf16_f32 v94, v94, v95
	v_cvt_pk_bf16_f32 v95, v96, v97
	v_cvt_pk_bf16_f32 v96, v90, v91
	v_or_b32_e32 v90, 32, v148
	v_ashrrev_i32_e32 v43, 31, v42
	v_cvt_pk_bf16_f32 v30, v30, v31
	v_cvt_pk_bf16_f32 v31, v32, v33
	v_cvt_pk_bf16_f32 v32, v26, v27
	v_add_u32_e32 v26, 0xa0, v148
	v_cvt_pk_bf16_f32 v113, v108, v109
	v_lshlrev_b64 v[106:107], 11, v[106:107]
	v_ashrrev_i32_e32 v91, 31, v90
	v_cvt_pk_bf16_f32 v78, v78, v79
	v_cvt_pk_bf16_f32 v79, v80, v81
	v_cvt_pk_bf16_f32 v80, v74, v75
	v_or_b32_e32 v74, 48, v148
	v_cvt_pk_bf16_f32 v70, v70, v71
	v_cvt_pk_bf16_f32 v71, v72, v73
	v_cvt_pk_bf16_f32 v72, v66, v67
	v_lshl_add_u64 v[66:67], v[150:151], 0, s[10:11]
	v_cvt_pk_bf16_f32 v49, v44, v45
	v_lshlrev_b64 v[42:43], 11, v[42:43]
	v_ashrrev_i32_e32 v27, 31, v26
	v_cvt_pk_bf16_f32 v14, v14, v15
	v_cvt_pk_bf16_f32 v15, v16, v17
	v_cvt_pk_bf16_f32 v16, v10, v11
	v_add_u32_e32 v10, 0xb0, v148
	global_store_dwordx4 v[150:151], v[110:113], off offset:256 nt
	v_cvt_pk_bf16_f32 v97, v92, v93
	v_lshlrev_b64 v[90:91], 11, v[90:91]
	v_lshl_add_u64 v[110:111], v[146:147], 0, v[106:107]
	v_ashrrev_i32_e32 v75, 31, v74
	v_cvt_pk_bf16_f32 v62, v62, v63
	v_cvt_pk_bf16_f32 v63, v64, v65
	v_cvt_pk_bf16_f32 v64, v58, v59
	v_add_co_u32_e32 v58, vcc, s57, v150
	global_store_dwordx4 v[66:67], v[46:49], off offset:256 nt
	v_cvt_pk_bf16_f32 v33, v28, v29
	v_lshlrev_b64 v[26:27], 11, v[26:27]
	v_lshl_add_u64 v[46:47], v[146:147], 0, v[42:43]
	v_ashrrev_i32_e32 v11, 31, v10
	global_store_dwordx4 v[110:111], v[94:97], off offset:256 nt
	v_cvt_pk_bf16_f32 v81, v76, v77
	v_lshlrev_b64 v[74:75], 11, v[74:75]
	v_lshl_add_u64 v[94:95], v[146:147], 0, v[90:91]
	v_addc_co_u32_e32 v59, vcc, 0, v151, vcc
	global_store_dwordx4 v[46:47], v[30:33], off offset:256 nt
	v_cvt_pk_bf16_f32 v17, v12, v13
	v_lshlrev_b64 v[10:11], 11, v[10:11]
	v_lshl_add_u64 v[30:31], v[146:147], 0, v[26:27]
	v_cvt_pk_bf16_f32 v126, v126, v127
	v_cvt_pk_bf16_f32 v127, v128, v129
	v_cvt_pk_bf16_f32 v128, v122, v123
	v_cvt_pk_bf16_f32 v129, v124, v125
	v_cvt_pk_bf16_f32 v106, v118, v119
	v_cvt_pk_bf16_f32 v107, v120, v121
	v_cvt_pk_bf16_f32 v108, v114, v115
	v_cvt_pk_bf16_f32 v109, v116, v117
	v_cvt_pk_bf16_f32 v90, v102, v103
	v_cvt_pk_bf16_f32 v91, v104, v105
	v_cvt_pk_bf16_f32 v92, v98, v99
	v_cvt_pk_bf16_f32 v93, v100, v101
	global_store_dwordx4 v[94:95], v[78:81], off offset:256 nt
	v_cvt_pk_bf16_f32 v76, v82, v83
	v_cvt_pk_bf16_f32 v77, v84, v85
	v_lshl_add_u64 v[78:79], v[146:147], 0, v[74:75]
	v_cvt_pk_bf16_f32 v74, v86, v87
	v_cvt_pk_bf16_f32 v75, v88, v89
	v_cvt_pk_bf16_f32 v73, v68, v69
	v_cvt_pk_bf16_f32 v65, v60, v61
	v_cvt_pk_bf16_f32 v42, v54, v55
	v_cvt_pk_bf16_f32 v43, v56, v57
	v_cvt_pk_bf16_f32 v44, v50, v51
	v_cvt_pk_bf16_f32 v45, v52, v53
	v_cvt_pk_bf16_f32 v26, v38, v39
	v_cvt_pk_bf16_f32 v27, v40, v41
	v_cvt_pk_bf16_f32 v28, v34, v35
	v_cvt_pk_bf16_f32 v29, v36, v37
	global_store_dwordx4 v[30:31], v[14:17], off offset:256 nt
	v_cvt_pk_bf16_f32 v12, v18, v19
	v_cvt_pk_bf16_f32 v13, v20, v21
	v_lshl_add_u64 v[14:15], v[146:147], 0, v[10:11]
	v_cvt_pk_bf16_f32 v10, v22, v23
	v_cvt_pk_bf16_f32 v11, v24, v25
	v_cvt_pk_bf16_f32 v6, v6, v7
	v_cvt_pk_bf16_f32 v7, v8, v9
	v_cvt_pk_bf16_f32 v8, v2, v3
	v_cvt_pk_bf16_f32 v9, v4, v5
	s_and_b64 vcc, exec, s[4:5]
	s_mov_b32 s75, s72
	s_mov_b32 s77, s73
	s_mov_b32 s76, s74
	s_mov_b64 s[14:15], s[6:7]
	s_mov_b64 s[12:13], s[0:1]
	global_store_dwordx4 v[150:151], v[126:129], off nt
	global_store_dwordx4 v[110:111], v[106:109], off nt
	global_store_dwordx4 v[94:95], v[90:93], off nt
	global_store_dwordx4 v[78:79], v[74:77], off nt
	global_store_dwordx4 v[78:79], v[70:73], off offset:256 nt
	global_store_dwordx4 v[58:59], v[62:65], off nt
	global_store_dwordx4 v[46:47], v[42:45], off nt
	global_store_dwordx4 v[30:31], v[26:29], off nt
	global_store_dwordx4 v[14:15], v[10:13], off nt
	global_store_dwordx4 v[14:15], v[6:9], off offset:256 nt
	s_cbranch_vccz .LBB0_862
	s_waitcnt vmcnt(0)
	s_cmpk_gt_u32 s34, 0xff
	s_cbranch_scc1 .LBB0_873
	s_barrier

.LBB0_1374:
	s_ashr_i32 s41, s40, 31
	s_xor_b64 s[50:51], s[18:19], -1
	s_lshl_b64 s[20:21], s[40:41], 19
	s_add_u32 s48, s65, s20
	s_addc_u32 s49, s66, s21
	s_and_b64 s[20:21], s[18:19], exec
	s_cselect_b32 s3, s49, s35
	s_cselect_b32 s5, s48, s34
	s_ashr_i32 s39, s38, 31
	s_lshl_b64 s[20:21], s[38:39], 19
	s_add_u32 s52, s67, s20
	s_addc_u32 s53, s68, s21
	s_and_b64 s[18:19], s[18:19], exec
	s_cselect_b32 s39, s53, s55
	s_cselect_b32 s41, s52, s54
	s_add_u32 s34, s34, 0x40080
	s_addc_u32 s35, s35, 0
	s_add_u32 s56, s54, 0x100
	s_addc_u32 s57, s55, 0
	s_mov_b32 vcc_lo, -2
	s_waitcnt vmcnt(0)
	ds_read_b128 v[10:13], v225
	ds_read_b128 v[14:17], v225 offset:1024
	ds_read_b128 v[26:29], v225 offset:2048
	ds_read_b128 v[30:33], v225 offset:3072
	s_add_u32 s18, s34, 0xfffc0080
	s_addc_u32 s19, s35, -1
	s_cmp_eq_u32 vcc_lo, 12
	s_cselect_b32 s19, s3, s19
	s_cselect_b32 s18, s5, s18
	s_cselect_b32 s55, s39, s57
	s_cselect_b32 s54, s41, s56
	v_lshl_add_u64 v[202:203], s[34:35], 0, v[178:179]
	s_add_i32 m0, s72, 0xc000
	ds_read_b128 v[34:37], v226
	ds_read_b128 v[38:41], v226 offset:1024
	ds_read_b128 v[50:53], v226 offset:2048
	ds_read_b128 v[54:57], v226 offset:3072
	ds_read_b128 v[186:189], v226 offset:4096
	ds_read_b128 v[190:193], v226 offset:5120
	ds_read_b128 v[194:197], v226 offset:6144
	ds_read_b128 v[198:201], v226 offset:7168
	global_load_lds_dwordx4 v[202:203], off
	v_lshl_add_u64 v[202:203], s[34:35], 0, v[180:181]
	s_add_i32 m0, s72, 0xe000
	s_nop 0
	global_load_lds_dwordx4 v[202:203], off
	s_waitcnt lgkmcnt(8)
	s_setprio 1
	s_barrier
	s_waitcnt lgkmcnt(0)
	v_mfma_f32_16x16x32_bf16 v[158:161], v[10:13], v[34:37], 0
	v_mfma_f32_16x16x32_bf16 v[154:157], v[26:29], v[34:37], 0
	v_mfma_f32_16x16x32_bf16 v[142:145], v[10:13], v[50:53], 0
	v_mfma_f32_16x16x32_bf16 v[138:141], v[26:29], v[50:53], 0
	v_mfma_f32_16x16x32_bf16 v[126:129], v[10:13], v[186:189], 0
	v_mfma_f32_16x16x32_bf16 v[122:125], v[26:29], v[186:189], 0
	v_mfma_f32_16x16x32_bf16 v[110:113], v[10:13], v[194:197], 0
	v_mfma_f32_16x16x32_bf16 v[106:109], v[26:29], v[194:197], 0
	v_mfma_f32_16x16x32_bf16 v[158:161], v[14:17], v[38:41], v[158:161]
	v_mfma_f32_16x16x32_bf16 v[154:157], v[30:33], v[38:41], v[154:157]
	v_mfma_f32_16x16x32_bf16 v[142:145], v[14:17], v[54:57], v[142:145]
	v_mfma_f32_16x16x32_bf16 v[138:141], v[30:33], v[54:57], v[138:141]
	v_mfma_f32_16x16x32_bf16 v[126:129], v[14:17], v[190:193], v[126:129]
	v_mfma_f32_16x16x32_bf16 v[122:125], v[30:33], v[190:193], v[122:125]
	v_mfma_f32_16x16x32_bf16 v[110:113], v[14:17], v[198:201], v[110:113]
	v_mfma_f32_16x16x32_bf16 v[106:109], v[30:33], v[198:201], v[106:109]
	s_barrier
	s_setprio 0
	s_add_i32 s20, s33, s71
	v_lshl_add_u64 v[222:223], s[54:55], 0, v[164:165]
	s_mov_b32 m0, s20
	ds_read_b128 v[202:205], v227
	ds_read_b128 v[206:209], v227 offset:1024
	ds_read_b128 v[210:213], v227 offset:2048
	ds_read_b128 v[214:217], v227 offset:3072
	global_load_lds_dwordx4 v[222:223], off
	v_lshl_add_u64 v[238:239], s[54:55], 0, v[168:169]
	s_add_i32 m0, s20, 0x2000
	s_nop 0
	global_load_lds_dwordx4 v[238:239], off
	s_setprio 1
	s_barrier
	s_waitcnt lgkmcnt(0)
	v_mfma_f32_16x16x32_bf16 v[150:153], v[202:205], v[34:37], 0
	v_mfma_f32_16x16x32_bf16 v[34:37], v[210:213], v[34:37], 0
	v_mfma_f32_16x16x32_bf16 v[150:153], v[206:209], v[38:41], v[150:153]
	v_mfma_f32_16x16x32_bf16 v[34:37], v[214:217], v[38:41], v[34:37]
	v_mfma_f32_16x16x32_bf16 v[38:41], v[202:205], v[50:53], 0
	v_mfma_f32_16x16x32_bf16 v[50:53], v[210:213], v[50:53], 0
	v_mfma_f32_16x16x32_bf16 v[114:117], v[210:213], v[186:189], 0
	v_mfma_f32_16x16x32_bf16 v[102:105], v[202:205], v[194:197], 0
	v_mfma_f32_16x16x32_bf16 v[98:101], v[210:213], v[194:197], 0
	v_mfma_f32_16x16x32_bf16 v[38:41], v[206:209], v[54:57], v[38:41]
	v_mfma_f32_16x16x32_bf16 v[50:53], v[214:217], v[54:57], v[50:53]
	v_mfma_f32_16x16x32_bf16 v[54:57], v[202:205], v[186:189], 0
	v_mfma_f32_16x16x32_bf16 v[114:117], v[214:217], v[190:193], v[114:117]
	v_mfma_f32_16x16x32_bf16 v[102:105], v[206:209], v[198:201], v[102:105]
	v_mfma_f32_16x16x32_bf16 v[98:101], v[214:217], v[198:201], v[98:101]
	v_mfma_f32_16x16x32_bf16 v[54:57], v[206:209], v[190:193], v[54:57]
	s_barrier
	s_setprio 0
	s_mov_b32 m0, s72
	v_lshl_add_u64 v[240:241], s[18:19], 0, v[162:163]
	ds_read_b128 v[118:121], v226 offset:16384
	ds_read_b128 v[130:133], v226 offset:17408
	ds_read_b128 v[134:137], v226 offset:18432
	ds_read_b128 v[146:149], v226 offset:19456
	ds_read_b128 v[186:189], v226 offset:20480
	ds_read_b128 v[190:193], v226 offset:21504
	ds_read_b128 v[194:197], v226 offset:22528
	ds_read_b128 v[198:201], v226 offset:23552
	global_load_lds_dwordx4 v[240:241], off
	v_lshl_add_u64 v[242:243], s[18:19], 0, v[166:167]
	s_mov_b32 m0, s73
	s_nop 0
	global_load_lds_dwordx4 v[242:243], off
	s_setprio 1
	s_barrier
	s_waitcnt lgkmcnt(0)
	v_mfma_f32_16x16x32_bf16 v[94:97], v[10:13], v[118:121], 0
	v_mfma_f32_16x16x32_bf16 v[90:93], v[26:29], v[118:121], 0
	v_mfma_f32_16x16x32_bf16 v[78:81], v[10:13], v[134:137], 0
	v_mfma_f32_16x16x32_bf16 v[74:77], v[26:29], v[134:137], 0
	v_mfma_f32_16x16x32_bf16 v[62:65], v[10:13], v[186:189], 0
	v_mfma_f32_16x16x32_bf16 v[58:61], v[26:29], v[186:189], 0
	v_mfma_f32_16x16x32_bf16 v[10:13], v[10:13], v[194:197], 0
	v_mfma_f32_16x16x32_bf16 v[94:97], v[14:17], v[130:133], v[94:97]
	v_mfma_f32_16x16x32_bf16 v[90:93], v[30:33], v[130:133], v[90:93]
	v_mfma_f32_16x16x32_bf16 v[78:81], v[14:17], v[146:149], v[78:81]
	v_mfma_f32_16x16x32_bf16 v[74:77], v[30:33], v[146:149], v[74:77]
	v_mfma_f32_16x16x32_bf16 v[62:65], v[14:17], v[190:193], v[62:65]
	v_mfma_f32_16x16x32_bf16 v[58:61], v[30:33], v[190:193], v[58:61]
	v_mfma_f32_16x16x32_bf16 v[10:13], v[14:17], v[198:201], v[10:13]
	v_mfma_f32_16x16x32_bf16 v[14:17], v[26:29], v[194:197], 0
	v_mfma_f32_16x16x32_bf16 v[14:17], v[30:33], v[198:201], v[14:17]
	s_barrier
	s_setprio 0
	s_add_u32 s20, s54, 0x40000
	s_addc_u32 s21, s55, 0
	s_add_i32 s60, s64, s71
	v_lshl_add_u64 v[18:19], s[20:21], 0, v[164:165]
	s_mov_b32 m0, s60
	s_nop 0
	global_load_lds_dwordx4 v[18:19], off
	v_lshl_add_u64 v[18:19], s[20:21], 0, v[168:169]
	s_add_i32 m0, s60, 0x2000
	s_nop 0
	global_load_lds_dwordx4 v[18:19], off
	s_waitcnt vmcnt(6)
	s_setprio 1
	s_barrier
	v_mfma_f32_16x16x32_bf16 v[18:21], v[202:205], v[118:121], 0
	v_mfma_f32_16x16x32_bf16 v[26:29], v[206:209], v[130:133], v[18:21]
	v_mfma_f32_16x16x32_bf16 v[18:21], v[210:213], v[118:121], 0
	v_mfma_f32_16x16x32_bf16 v[30:33], v[214:217], v[130:133], v[18:21]
	v_mfma_f32_16x16x32_bf16 v[18:21], v[202:205], v[134:137], 0
	v_mfma_f32_16x16x32_bf16 v[70:73], v[206:209], v[146:149], v[18:21]
	v_mfma_f32_16x16x32_bf16 v[18:21], v[210:213], v[134:137], 0
	v_mfma_f32_16x16x32_bf16 v[66:69], v[214:217], v[146:149], v[18:21]
	v_mfma_f32_16x16x32_bf16 v[18:21], v[202:205], v[186:189], 0
	v_mfma_f32_16x16x32_bf16 v[46:49], v[206:209], v[190:193], v[18:21]
	v_mfma_f32_16x16x32_bf16 v[18:21], v[210:213], v[186:189], 0
	v_mfma_f32_16x16x32_bf16 v[6:9], v[202:205], v[194:197], 0
	v_mfma_f32_16x16x32_bf16 v[2:5], v[210:213], v[194:197], 0
	v_mfma_f32_16x16x32_bf16 v[42:45], v[214:217], v[190:193], v[18:21]
	v_mfma_f32_16x16x32_bf16 v[6:9], v[206:209], v[198:201], v[6:9]
	v_mfma_f32_16x16x32_bf16 v[2:5], v[214:217], v[198:201], v[2:5]
	s_barrier
	s_setprio 0
	s_add_i32 s20, 0, 0x18000
	v_add_u32_e32 v86, s20, v175
	ds_read_b128 v[18:21], v86
	ds_read_b128 v[22:25], v86 offset:1024
	ds_read_b128 v[82:85], v86 offset:2048
	ds_read_b128 v[86:89], v86 offset:3072
	s_add_u32 s18, s18, 0x40000
	s_addc_u32 s19, s19, 0
	s_mov_b32 m0, s74
	v_lshl_add_u64 v[134:135], s[18:19], 0, v[162:163]
	ds_read_b128 v[118:121], v226 offset:32768
	ds_read_b128 v[130:133], v226 offset:33792
	ds_read_b128 v[186:189], v226 offset:34816
	ds_read_b128 v[190:193], v226 offset:35840
	ds_read_b128 v[194:197], v226 offset:36864
	ds_read_b128 v[198:201], v226 offset:37888
	ds_read_b128 v[202:205], v226 offset:38912
	ds_read_b128 v[206:209], v226 offset:39936
	global_load_lds_dwordx4 v[134:135], off
	v_lshl_add_u64 v[134:135], s[18:19], 0, v[166:167]
	s_mov_b32 m0, s75
	s_nop 0
	global_load_lds_dwordx4 v[134:135], off
	s_waitcnt lgkmcnt(8)
	s_setprio 1
	s_barrier
	s_waitcnt lgkmcnt(0)
	v_mfma_f32_16x16x32_bf16 v[134:137], v[18:21], v[118:121], v[158:161]
	v_mfma_f32_16x16x32_bf16 v[158:161], v[22:25], v[130:133], v[134:137]
	v_mfma_f32_16x16x32_bf16 v[134:137], v[82:85], v[118:121], v[154:157]
	v_mfma_f32_16x16x32_bf16 v[154:157], v[86:89], v[130:133], v[134:137]
	v_mfma_f32_16x16x32_bf16 v[134:137], v[18:21], v[186:189], v[142:145]
	v_mfma_f32_16x16x32_bf16 v[142:145], v[22:25], v[190:193], v[134:137]
	v_mfma_f32_16x16x32_bf16 v[134:137], v[82:85], v[186:189], v[138:141]
	v_mfma_f32_16x16x32_bf16 v[126:129], v[18:21], v[194:197], v[126:129]
	v_mfma_f32_16x16x32_bf16 v[122:125], v[82:85], v[194:197], v[122:125]
	v_mfma_f32_16x16x32_bf16 v[110:113], v[18:21], v[202:205], v[110:113]
	v_mfma_f32_16x16x32_bf16 v[106:109], v[82:85], v[202:205], v[106:109]
	v_mfma_f32_16x16x32_bf16 v[138:141], v[86:89], v[190:193], v[134:137]
	v_mfma_f32_16x16x32_bf16 v[126:129], v[22:25], v[198:201], v[126:129]
	v_mfma_f32_16x16x32_bf16 v[122:125], v[86:89], v[198:201], v[122:125]
	v_mfma_f32_16x16x32_bf16 v[110:113], v[22:25], v[206:209], v[110:113]
	v_mfma_f32_16x16x32_bf16 v[106:109], v[86:89], v[206:209], v[106:109]
	s_barrier
	s_setprio 0
	s_add_i32 s21, 0, 0x1c000
	v_add_u32_e32 v134, s21, v175
	s_add_i32 s18, s20, s71
	ds_read_b128 v[210:213], v134
	ds_read_b128 v[214:217], v134 offset:1024
	ds_read_b128 v[218:221], v134 offset:2048
	ds_read_b128 v[234:237], v134 offset:3072
	v_lshl_add_u64 v[134:135], v[222:223], 0, s[24:25]
	s_mov_b32 m0, s18
	s_nop 0
	global_load_lds_dwordx4 v[134:135], off
	v_lshl_add_u64 v[134:135], v[238:239], 0, s[24:25]
	s_add_i32 m0, s18, 0x2000
	s_nop 0
	global_load_lds_dwordx4 v[134:135], off
	s_setprio 1
	s_barrier
	s_waitcnt lgkmcnt(0)
	v_mfma_f32_16x16x32_bf16 v[34:37], v[218:221], v[118:121], v[34:37]
	v_mfma_f32_16x16x32_bf16 v[134:137], v[210:213], v[118:121], v[150:153]
	v_mfma_f32_16x16x32_bf16 v[146:149], v[234:237], v[130:133], v[34:37]
	v_mfma_f32_16x16x32_bf16 v[34:37], v[210:213], v[186:189], v[38:41]
	v_mfma_f32_16x16x32_bf16 v[150:153], v[214:217], v[130:133], v[134:137]
	v_mfma_f32_16x16x32_bf16 v[134:137], v[214:217], v[190:193], v[34:37]
	v_mfma_f32_16x16x32_bf16 v[34:37], v[218:221], v[186:189], v[50:53]
	v_mfma_f32_16x16x32_bf16 v[130:133], v[234:237], v[190:193], v[34:37]
	v_mfma_f32_16x16x32_bf16 v[34:37], v[210:213], v[194:197], v[54:57]
	v_mfma_f32_16x16x32_bf16 v[118:121], v[214:217], v[198:201], v[34:37]
	v_mfma_f32_16x16x32_bf16 v[34:37], v[218:221], v[194:197], v[114:117]
	v_mfma_f32_16x16x32_bf16 v[114:117], v[234:237], v[198:201], v[34:37]
	v_mfma_f32_16x16x32_bf16 v[34:37], v[210:213], v[202:205], v[102:105]
	v_mfma_f32_16x16x32_bf16 v[102:105], v[214:217], v[206:209], v[34:37]
	v_mfma_f32_16x16x32_bf16 v[34:37], v[218:221], v[202:205], v[98:101]
	v_mfma_f32_16x16x32_bf16 v[98:101], v[234:237], v[206:209], v[34:37]
	s_barrier
	s_setprio 0
	s_mov_b32 m0, s95
	v_lshl_add_u64 v[202:203], v[240:241], 0, s[24:25]
	s_nop 2
	ds_read_b128 v[34:37], v226 offset:49152
	ds_read_b128 v[38:41], v226 offset:50176
	ds_read_b128 v[50:53], v226 offset:51200
	ds_read_b128 v[54:57], v226 offset:52224
	ds_read_b128 v[186:189], v226 offset:53248
	ds_read_b128 v[190:193], v226 offset:54272
	ds_read_b128 v[194:197], v226 offset:55296
	ds_read_b128 v[198:201], v226 offset:56320
	global_load_lds_dwordx4 v[202:203], off
	v_lshl_add_u64 v[202:203], v[242:243], 0, s[24:25]
	s_mov_b32 m0, s96
	s_nop 0
	global_load_lds_dwordx4 v[202:203], off
	s_setprio 1
	s_barrier
	s_waitcnt lgkmcnt(0)
	v_mfma_f32_16x16x32_bf16 v[94:97], v[18:21], v[34:37], v[94:97]
	v_mfma_f32_16x16x32_bf16 v[78:81], v[18:21], v[50:53], v[78:81]
	v_mfma_f32_16x16x32_bf16 v[62:65], v[18:21], v[186:189], v[62:65]
	v_mfma_f32_16x16x32_bf16 v[10:13], v[18:21], v[194:197], v[10:13]
	v_mfma_f32_16x16x32_bf16 v[94:97], v[22:25], v[38:41], v[94:97]
	v_mfma_f32_16x16x32_bf16 v[90:93], v[82:85], v[34:37], v[90:93]
	v_mfma_f32_16x16x32_bf16 v[78:81], v[22:25], v[54:57], v[78:81]
	v_mfma_f32_16x16x32_bf16 v[74:77], v[82:85], v[50:53], v[74:77]
	v_mfma_f32_16x16x32_bf16 v[62:65], v[22:25], v[190:193], v[62:65]
	v_mfma_f32_16x16x32_bf16 v[58:61], v[82:85], v[186:189], v[58:61]
	v_mfma_f32_16x16x32_bf16 v[22:25], v[22:25], v[198:201], v[10:13]
	v_mfma_f32_16x16x32_bf16 v[10:13], v[82:85], v[194:197], v[14:17]
	v_mfma_f32_16x16x32_bf16 v[90:93], v[86:89], v[38:41], v[90:93]
	v_mfma_f32_16x16x32_bf16 v[74:77], v[86:89], v[54:57], v[74:77]
	v_mfma_f32_16x16x32_bf16 v[58:61], v[86:89], v[190:193], v[58:61]
	v_mfma_f32_16x16x32_bf16 v[18:21], v[86:89], v[198:201], v[10:13]
	s_barrier
	s_setprio 0
	s_add_u32 s18, s54, 0x40080
	s_addc_u32 s19, s55, 0
	s_add_i32 s20, s21, s71
	v_lshl_add_u64 v[10:11], s[18:19], 0, v[164:165]
	s_mov_b32 m0, s20
	s_nop 0
	global_load_lds_dwordx4 v[10:11], off
	v_lshl_add_u64 v[10:11], s[18:19], 0, v[168:169]
	s_add_i32 m0, s20, 0x2000
	s_nop 0
	global_load_lds_dwordx4 v[10:11], off
	s_waitcnt vmcnt(6)
	s_setprio 1
	s_barrier
	v_mfma_f32_16x16x32_bf16 v[10:13], v[210:213], v[34:37], v[26:29]
	v_mfma_f32_16x16x32_bf16 v[86:89], v[214:217], v[38:41], v[10:13]
	v_mfma_f32_16x16x32_bf16 v[10:13], v[218:221], v[34:37], v[30:33]
	v_mfma_f32_16x16x32_bf16 v[82:85], v[234:237], v[38:41], v[10:13]
	v_mfma_f32_16x16x32_bf16 v[10:13], v[210:213], v[50:53], v[70:73]
	v_mfma_f32_16x16x32_bf16 v[70:73], v[214:217], v[54:57], v[10:13]
	v_mfma_f32_16x16x32_bf16 v[10:13], v[218:221], v[50:53], v[66:69]
	v_mfma_f32_16x16x32_bf16 v[66:69], v[234:237], v[54:57], v[10:13]
	v_mfma_f32_16x16x32_bf16 v[10:13], v[210:213], v[186:189], v[46:49]
	v_mfma_f32_16x16x32_bf16 v[46:49], v[214:217], v[190:193], v[10:13]
	v_mfma_f32_16x16x32_bf16 v[10:13], v[218:221], v[186:189], v[42:45]
	v_mfma_f32_16x16x32_bf16 v[6:9], v[210:213], v[194:197], v[6:9]
	v_mfma_f32_16x16x32_bf16 v[2:5], v[218:221], v[194:197], v[2:5]
	v_mfma_f32_16x16x32_bf16 v[42:45], v[234:237], v[190:193], v[10:13]
	v_mfma_f32_16x16x32_bf16 v[6:9], v[214:217], v[198:201], v[6:9]
	v_mfma_f32_16x16x32_bf16 v[2:5], v[234:237], v[198:201], v[2:5]
	s_barrier
	s_setprio 0
	s_add_i32 vcc_lo, vcc_lo, 2
	s_add_u32 s34, s34, 0x100
	s_addc_u32 s35, s35, 0
	s_add_u32 s56, s56, 0x100
	s_addc_u32 s57, s57, 0
	s_cmp_gt_u32 vcc_lo, 13
.LBB0_1375:
	ds_read_b128 v[10:13], v225
	ds_read_b128 v[14:17], v225 offset:1024
	ds_read_b128 v[26:29], v225 offset:2048
	ds_read_b128 v[30:33], v225 offset:3072
	s_add_u32 s18, s34, 0xfffc0080
	s_addc_u32 s19, s35, -1
	s_cmp_eq_u32 vcc_lo, 12
	s_cselect_b32 s19, s3, s19
	s_cselect_b32 s18, s5, s18
	s_cselect_b32 s55, s39, s57
	s_cselect_b32 s54, s41, s56
	v_lshl_add_u64 v[202:203], s[34:35], 0, v[178:179]
	s_add_i32 m0, s72, 0xc000
	ds_read_b128 v[34:37], v226
	ds_read_b128 v[38:41], v226 offset:1024
	ds_read_b128 v[50:53], v226 offset:2048
	ds_read_b128 v[54:57], v226 offset:3072
	ds_read_b128 v[186:189], v226 offset:4096
	ds_read_b128 v[190:193], v226 offset:5120
	ds_read_b128 v[194:197], v226 offset:6144
	ds_read_b128 v[198:201], v226 offset:7168
	global_load_lds_dwordx4 v[202:203], off
	v_lshl_add_u64 v[202:203], s[34:35], 0, v[180:181]
	s_add_i32 m0, s72, 0xe000
	s_nop 0
	global_load_lds_dwordx4 v[202:203], off
	s_waitcnt lgkmcnt(8)
	s_setprio 1
	s_barrier
	s_waitcnt lgkmcnt(0)
	v_mfma_f32_16x16x32_bf16 v[158:161], v[10:13], v[34:37], v[158:161]
	v_mfma_f32_16x16x32_bf16 v[154:157], v[26:29], v[34:37], v[154:157]
	v_mfma_f32_16x16x32_bf16 v[142:145], v[10:13], v[50:53], v[142:145]
	v_mfma_f32_16x16x32_bf16 v[138:141], v[26:29], v[50:53], v[138:141]
	v_mfma_f32_16x16x32_bf16 v[126:129], v[10:13], v[186:189], v[126:129]
	v_mfma_f32_16x16x32_bf16 v[122:125], v[26:29], v[186:189], v[122:125]
	v_mfma_f32_16x16x32_bf16 v[110:113], v[10:13], v[194:197], v[110:113]
	v_mfma_f32_16x16x32_bf16 v[106:109], v[26:29], v[194:197], v[106:109]
	v_mfma_f32_16x16x32_bf16 v[158:161], v[14:17], v[38:41], v[158:161]
	v_mfma_f32_16x16x32_bf16 v[154:157], v[30:33], v[38:41], v[154:157]
	v_mfma_f32_16x16x32_bf16 v[142:145], v[14:17], v[54:57], v[142:145]
	v_mfma_f32_16x16x32_bf16 v[138:141], v[30:33], v[54:57], v[138:141]
	v_mfma_f32_16x16x32_bf16 v[126:129], v[14:17], v[190:193], v[126:129]
	v_mfma_f32_16x16x32_bf16 v[122:125], v[30:33], v[190:193], v[122:125]
	v_mfma_f32_16x16x32_bf16 v[110:113], v[14:17], v[198:201], v[110:113]
	v_mfma_f32_16x16x32_bf16 v[106:109], v[30:33], v[198:201], v[106:109]
	s_barrier
	s_setprio 0
	s_add_i32 s20, s33, s71
	v_lshl_add_u64 v[222:223], s[54:55], 0, v[164:165]
	s_mov_b32 m0, s20
	ds_read_b128 v[202:205], v227
	ds_read_b128 v[206:209], v227 offset:1024
	ds_read_b128 v[210:213], v227 offset:2048
	ds_read_b128 v[214:217], v227 offset:3072
	global_load_lds_dwordx4 v[222:223], off
	v_lshl_add_u64 v[238:239], s[54:55], 0, v[168:169]
	s_add_i32 m0, s20, 0x2000
	s_nop 0
	global_load_lds_dwordx4 v[238:239], off
	s_setprio 1
	s_barrier
	s_waitcnt lgkmcnt(0)
	v_mfma_f32_16x16x32_bf16 v[150:153], v[202:205], v[34:37], v[150:153]
	v_mfma_f32_16x16x32_bf16 v[34:37], v[210:213], v[34:37], v[146:149]
	v_mfma_f32_16x16x32_bf16 v[150:153], v[206:209], v[38:41], v[150:153]
	v_mfma_f32_16x16x32_bf16 v[34:37], v[214:217], v[38:41], v[34:37]
	v_mfma_f32_16x16x32_bf16 v[38:41], v[202:205], v[50:53], v[134:137]
	v_mfma_f32_16x16x32_bf16 v[50:53], v[210:213], v[50:53], v[130:133]
	v_mfma_f32_16x16x32_bf16 v[114:117], v[210:213], v[186:189], v[114:117]
	v_mfma_f32_16x16x32_bf16 v[102:105], v[202:205], v[194:197], v[102:105]
	v_mfma_f32_16x16x32_bf16 v[98:101], v[210:213], v[194:197], v[98:101]
	v_mfma_f32_16x16x32_bf16 v[38:41], v[206:209], v[54:57], v[38:41]
	v_mfma_f32_16x16x32_bf16 v[50:53], v[214:217], v[54:57], v[50:53]
	v_mfma_f32_16x16x32_bf16 v[54:57], v[202:205], v[186:189], v[118:121]
	v_mfma_f32_16x16x32_bf16 v[114:117], v[214:217], v[190:193], v[114:117]
	v_mfma_f32_16x16x32_bf16 v[102:105], v[206:209], v[198:201], v[102:105]
	v_mfma_f32_16x16x32_bf16 v[98:101], v[214:217], v[198:201], v[98:101]
	v_mfma_f32_16x16x32_bf16 v[54:57], v[206:209], v[190:193], v[54:57]
	s_barrier
	s_setprio 0
	s_mov_b32 m0, s72
	v_lshl_add_u64 v[240:241], s[18:19], 0, v[162:163]
	ds_read_b128 v[118:121], v226 offset:16384
	ds_read_b128 v[130:133], v226 offset:17408
	ds_read_b128 v[134:137], v226 offset:18432
	ds_read_b128 v[146:149], v226 offset:19456
	ds_read_b128 v[186:189], v226 offset:20480
	ds_read_b128 v[190:193], v226 offset:21504
	ds_read_b128 v[194:197], v226 offset:22528
	ds_read_b128 v[198:201], v226 offset:23552
	global_load_lds_dwordx4 v[240:241], off
	v_lshl_add_u64 v[242:243], s[18:19], 0, v[166:167]
	s_mov_b32 m0, s73
	s_nop 0
	global_load_lds_dwordx4 v[242:243], off
	s_setprio 1
	s_barrier
	s_waitcnt lgkmcnt(0)
	v_mfma_f32_16x16x32_bf16 v[94:97], v[10:13], v[118:121], v[94:97]
	v_mfma_f32_16x16x32_bf16 v[90:93], v[26:29], v[118:121], v[90:93]
	v_mfma_f32_16x16x32_bf16 v[78:81], v[10:13], v[134:137], v[78:81]
	v_mfma_f32_16x16x32_bf16 v[74:77], v[26:29], v[134:137], v[74:77]
	v_mfma_f32_16x16x32_bf16 v[62:65], v[10:13], v[186:189], v[62:65]
	v_mfma_f32_16x16x32_bf16 v[58:61], v[26:29], v[186:189], v[58:61]
	v_mfma_f32_16x16x32_bf16 v[10:13], v[10:13], v[194:197], v[22:25]
	v_mfma_f32_16x16x32_bf16 v[94:97], v[14:17], v[130:133], v[94:97]
	v_mfma_f32_16x16x32_bf16 v[90:93], v[30:33], v[130:133], v[90:93]
	v_mfma_f32_16x16x32_bf16 v[78:81], v[14:17], v[146:149], v[78:81]
	v_mfma_f32_16x16x32_bf16 v[74:77], v[30:33], v[146:149], v[74:77]
	v_mfma_f32_16x16x32_bf16 v[62:65], v[14:17], v[190:193], v[62:65]
	v_mfma_f32_16x16x32_bf16 v[58:61], v[30:33], v[190:193], v[58:61]
	v_mfma_f32_16x16x32_bf16 v[10:13], v[14:17], v[198:201], v[10:13]
	v_mfma_f32_16x16x32_bf16 v[14:17], v[26:29], v[194:197], v[18:21]
	v_mfma_f32_16x16x32_bf16 v[14:17], v[30:33], v[198:201], v[14:17]
	s_barrier
	s_setprio 0
	s_add_u32 s20, s54, 0x40000
	s_addc_u32 s21, s55, 0
	s_add_i32 s60, s64, s71
	v_lshl_add_u64 v[18:19], s[20:21], 0, v[164:165]
	s_mov_b32 m0, s60
	s_nop 0
	global_load_lds_dwordx4 v[18:19], off
	v_lshl_add_u64 v[18:19], s[20:21], 0, v[168:169]
	s_add_i32 m0, s60, 0x2000
	s_nop 0
	global_load_lds_dwordx4 v[18:19], off
	s_waitcnt vmcnt(6)
	s_setprio 1
	s_barrier
	v_mfma_f32_16x16x32_bf16 v[18:21], v[202:205], v[118:121], v[86:89]
	v_mfma_f32_16x16x32_bf16 v[26:29], v[206:209], v[130:133], v[18:21]
	v_mfma_f32_16x16x32_bf16 v[18:21], v[210:213], v[118:121], v[82:85]
	v_mfma_f32_16x16x32_bf16 v[30:33], v[214:217], v[130:133], v[18:21]
	v_mfma_f32_16x16x32_bf16 v[18:21], v[202:205], v[134:137], v[70:73]
	v_mfma_f32_16x16x32_bf16 v[70:73], v[206:209], v[146:149], v[18:21]
	v_mfma_f32_16x16x32_bf16 v[18:21], v[210:213], v[134:137], v[66:69]
	v_mfma_f32_16x16x32_bf16 v[66:69], v[214:217], v[146:149], v[18:21]
	v_mfma_f32_16x16x32_bf16 v[18:21], v[202:205], v[186:189], v[46:49]
	v_mfma_f32_16x16x32_bf16 v[46:49], v[206:209], v[190:193], v[18:21]
	v_mfma_f32_16x16x32_bf16 v[18:21], v[210:213], v[186:189], v[42:45]
	v_mfma_f32_16x16x32_bf16 v[6:9], v[202:205], v[194:197], v[6:9]
	v_mfma_f32_16x16x32_bf16 v[2:5], v[210:213], v[194:197], v[2:5]
	v_mfma_f32_16x16x32_bf16 v[42:45], v[214:217], v[190:193], v[18:21]
	v_mfma_f32_16x16x32_bf16 v[6:9], v[206:209], v[198:201], v[6:9]
	v_mfma_f32_16x16x32_bf16 v[2:5], v[214:217], v[198:201], v[2:5]
	s_barrier
	s_setprio 0
	s_add_i32 s20, 0, 0x18000
	v_add_u32_e32 v86, s20, v175
	ds_read_b128 v[18:21], v86
	ds_read_b128 v[22:25], v86 offset:1024
	ds_read_b128 v[82:85], v86 offset:2048
	ds_read_b128 v[86:89], v86 offset:3072
	s_add_u32 s18, s18, 0x40000
	s_addc_u32 s19, s19, 0
	s_mov_b32 m0, s74
	v_lshl_add_u64 v[134:135], s[18:19], 0, v[162:163]
	ds_read_b128 v[118:121], v226 offset:32768
	ds_read_b128 v[130:133], v226 offset:33792
	ds_read_b128 v[186:189], v226 offset:34816
	ds_read_b128 v[190:193], v226 offset:35840
	ds_read_b128 v[194:197], v226 offset:36864
	ds_read_b128 v[198:201], v226 offset:37888
	ds_read_b128 v[202:205], v226 offset:38912
	ds_read_b128 v[206:209], v226 offset:39936
	global_load_lds_dwordx4 v[134:135], off
	v_lshl_add_u64 v[134:135], s[18:19], 0, v[166:167]
	s_mov_b32 m0, s75
	s_nop 0
	global_load_lds_dwordx4 v[134:135], off
	s_waitcnt lgkmcnt(8)
	s_setprio 1
	s_barrier
	s_waitcnt lgkmcnt(0)
	v_mfma_f32_16x16x32_bf16 v[134:137], v[18:21], v[118:121], v[158:161]
	v_mfma_f32_16x16x32_bf16 v[158:161], v[22:25], v[130:133], v[134:137]
	v_mfma_f32_16x16x32_bf16 v[134:137], v[82:85], v[118:121], v[154:157]
	v_mfma_f32_16x16x32_bf16 v[154:157], v[86:89], v[130:133], v[134:137]
	v_mfma_f32_16x16x32_bf16 v[134:137], v[18:21], v[186:189], v[142:145]
	v_mfma_f32_16x16x32_bf16 v[142:145], v[22:25], v[190:193], v[134:137]
	v_mfma_f32_16x16x32_bf16 v[134:137], v[82:85], v[186:189], v[138:141]
	v_mfma_f32_16x16x32_bf16 v[126:129], v[18:21], v[194:197], v[126:129]
	v_mfma_f32_16x16x32_bf16 v[122:125], v[82:85], v[194:197], v[122:125]
	v_mfma_f32_16x16x32_bf16 v[110:113], v[18:21], v[202:205], v[110:113]
	v_mfma_f32_16x16x32_bf16 v[106:109], v[82:85], v[202:205], v[106:109]
	v_mfma_f32_16x16x32_bf16 v[138:141], v[86:89], v[190:193], v[134:137]
	v_mfma_f32_16x16x32_bf16 v[126:129], v[22:25], v[198:201], v[126:129]
	v_mfma_f32_16x16x32_bf16 v[122:125], v[86:89], v[198:201], v[122:125]
	v_mfma_f32_16x16x32_bf16 v[110:113], v[22:25], v[206:209], v[110:113]
	v_mfma_f32_16x16x32_bf16 v[106:109], v[86:89], v[206:209], v[106:109]
	s_barrier
	s_setprio 0
	s_add_i32 s21, 0, 0x1c000
	v_add_u32_e32 v134, s21, v175
	s_add_i32 s18, s20, s71
	ds_read_b128 v[210:213], v134
	ds_read_b128 v[214:217], v134 offset:1024
	ds_read_b128 v[218:221], v134 offset:2048
	ds_read_b128 v[234:237], v134 offset:3072
	v_lshl_add_u64 v[134:135], v[222:223], 0, s[24:25]
	s_mov_b32 m0, s18
	s_nop 0
	global_load_lds_dwordx4 v[134:135], off
	v_lshl_add_u64 v[134:135], v[238:239], 0, s[24:25]
	s_add_i32 m0, s18, 0x2000
	s_nop 0
	global_load_lds_dwordx4 v[134:135], off
	s_setprio 1
	s_barrier
	s_waitcnt lgkmcnt(0)
	v_mfma_f32_16x16x32_bf16 v[34:37], v[218:221], v[118:121], v[34:37]
	v_mfma_f32_16x16x32_bf16 v[134:137], v[210:213], v[118:121], v[150:153]
	v_mfma_f32_16x16x32_bf16 v[146:149], v[234:237], v[130:133], v[34:37]
	v_mfma_f32_16x16x32_bf16 v[34:37], v[210:213], v[186:189], v[38:41]
	v_mfma_f32_16x16x32_bf16 v[150:153], v[214:217], v[130:133], v[134:137]
	v_mfma_f32_16x16x32_bf16 v[134:137], v[214:217], v[190:193], v[34:37]
	v_mfma_f32_16x16x32_bf16 v[34:37], v[218:221], v[186:189], v[50:53]
	v_mfma_f32_16x16x32_bf16 v[130:133], v[234:237], v[190:193], v[34:37]
	v_mfma_f32_16x16x32_bf16 v[34:37], v[210:213], v[194:197], v[54:57]
	v_mfma_f32_16x16x32_bf16 v[118:121], v[214:217], v[198:201], v[34:37]
	v_mfma_f32_16x16x32_bf16 v[34:37], v[218:221], v[194:197], v[114:117]
	v_mfma_f32_16x16x32_bf16 v[114:117], v[234:237], v[198:201], v[34:37]
	v_mfma_f32_16x16x32_bf16 v[34:37], v[210:213], v[202:205], v[102:105]
	v_mfma_f32_16x16x32_bf16 v[102:105], v[214:217], v[206:209], v[34:37]
	v_mfma_f32_16x16x32_bf16 v[34:37], v[218:221], v[202:205], v[98:101]
	v_mfma_f32_16x16x32_bf16 v[98:101], v[234:237], v[206:209], v[34:37]
	s_barrier
	s_setprio 0
	s_mov_b32 m0, s95
	v_lshl_add_u64 v[202:203], v[240:241], 0, s[24:25]
	s_nop 2
	ds_read_b128 v[34:37], v226 offset:49152
	ds_read_b128 v[38:41], v226 offset:50176
	ds_read_b128 v[50:53], v226 offset:51200
	ds_read_b128 v[54:57], v226 offset:52224
	ds_read_b128 v[186:189], v226 offset:53248
	ds_read_b128 v[190:193], v226 offset:54272
	ds_read_b128 v[194:197], v226 offset:55296
	ds_read_b128 v[198:201], v226 offset:56320
	global_load_lds_dwordx4 v[202:203], off
	v_lshl_add_u64 v[202:203], v[242:243], 0, s[24:25]
	s_mov_b32 m0, s96
	s_nop 0
	global_load_lds_dwordx4 v[202:203], off
	s_setprio 1
	s_barrier
	s_waitcnt lgkmcnt(0)
	v_mfma_f32_16x16x32_bf16 v[94:97], v[18:21], v[34:37], v[94:97]
	v_mfma_f32_16x16x32_bf16 v[78:81], v[18:21], v[50:53], v[78:81]
	v_mfma_f32_16x16x32_bf16 v[62:65], v[18:21], v[186:189], v[62:65]
	v_mfma_f32_16x16x32_bf16 v[10:13], v[18:21], v[194:197], v[10:13]
	v_mfma_f32_16x16x32_bf16 v[94:97], v[22:25], v[38:41], v[94:97]
	v_mfma_f32_16x16x32_bf16 v[90:93], v[82:85], v[34:37], v[90:93]
	v_mfma_f32_16x16x32_bf16 v[78:81], v[22:25], v[54:57], v[78:81]
	v_mfma_f32_16x16x32_bf16 v[74:77], v[82:85], v[50:53], v[74:77]
	v_mfma_f32_16x16x32_bf16 v[62:65], v[22:25], v[190:193], v[62:65]
	v_mfma_f32_16x16x32_bf16 v[58:61], v[82:85], v[186:189], v[58:61]
	v_mfma_f32_16x16x32_bf16 v[22:25], v[22:25], v[198:201], v[10:13]
	v_mfma_f32_16x16x32_bf16 v[10:13], v[82:85], v[194:197], v[14:17]
	v_mfma_f32_16x16x32_bf16 v[90:93], v[86:89], v[38:41], v[90:93]
	v_mfma_f32_16x16x32_bf16 v[74:77], v[86:89], v[54:57], v[74:77]
	v_mfma_f32_16x16x32_bf16 v[58:61], v[86:89], v[190:193], v[58:61]
	v_mfma_f32_16x16x32_bf16 v[18:21], v[86:89], v[198:201], v[10:13]
	s_barrier
	s_setprio 0
	s_add_u32 s18, s54, 0x40080
	s_addc_u32 s19, s55, 0
	s_add_i32 s20, s21, s71
	v_lshl_add_u64 v[10:11], s[18:19], 0, v[164:165]
	s_mov_b32 m0, s20
	s_nop 0
	global_load_lds_dwordx4 v[10:11], off
	v_lshl_add_u64 v[10:11], s[18:19], 0, v[168:169]
	s_add_i32 m0, s20, 0x2000
	s_nop 0
	global_load_lds_dwordx4 v[10:11], off
	s_waitcnt vmcnt(6)
	s_setprio 1
	s_barrier
	v_mfma_f32_16x16x32_bf16 v[10:13], v[210:213], v[34:37], v[26:29]
	v_mfma_f32_16x16x32_bf16 v[86:89], v[214:217], v[38:41], v[10:13]
	v_mfma_f32_16x16x32_bf16 v[10:13], v[218:221], v[34:37], v[30:33]
	v_mfma_f32_16x16x32_bf16 v[82:85], v[234:237], v[38:41], v[10:13]
	v_mfma_f32_16x16x32_bf16 v[10:13], v[210:213], v[50:53], v[70:73]
	v_mfma_f32_16x16x32_bf16 v[70:73], v[214:217], v[54:57], v[10:13]
	v_mfma_f32_16x16x32_bf16 v[10:13], v[218:221], v[50:53], v[66:69]
	v_mfma_f32_16x16x32_bf16 v[66:69], v[234:237], v[54:57], v[10:13]
	v_mfma_f32_16x16x32_bf16 v[10:13], v[210:213], v[186:189], v[46:49]
	v_mfma_f32_16x16x32_bf16 v[46:49], v[214:217], v[190:193], v[10:13]
	v_mfma_f32_16x16x32_bf16 v[10:13], v[218:221], v[186:189], v[42:45]
	v_mfma_f32_16x16x32_bf16 v[6:9], v[210:213], v[194:197], v[6:9]
	v_mfma_f32_16x16x32_bf16 v[2:5], v[218:221], v[194:197], v[2:5]
	v_mfma_f32_16x16x32_bf16 v[42:45], v[234:237], v[190:193], v[10:13]
	v_mfma_f32_16x16x32_bf16 v[6:9], v[214:217], v[198:201], v[6:9]
	v_mfma_f32_16x16x32_bf16 v[2:5], v[234:237], v[198:201], v[2:5]
	s_barrier
	s_setprio 0
	s_add_i32 vcc_lo, vcc_lo, 2
	s_add_u32 s34, s34, 0x100
	s_addc_u32 s35, s35, 0
	s_add_u32 s56, s56, 0x100
	s_addc_u32 s57, s57, 0
	s_cmp_gt_u32 vcc_lo, 13
	s_cbranch_scc0 .LBB0_1375
	s_min_i32 s3, s4, 0x80
	s_ashr_i32 s5, s3, 3
	s_lshl_b32 s3, s2, 8
	s_mul_hi_i32 s19, s5, 0x6000
	s_mulk_i32 s5, 0x6000
	v_or_b32_e32 v186, s3, v224
	s_add_u32 s18, s77, s5
	s_addc_u32 s19, s78, s19
	v_ashrrev_i32_e32 v187, 31, v186
	v_lshl_add_u64 v[10:11], v[186:187], 2, s[18:19]
	global_load_dwordx4 v[50:53], v[10:11], off offset:16
	global_load_dwordx4 v[54:57], v[10:11], off
	global_load_dwordx4 v[26:29], v[10:11], off offset:528
	global_load_dwordx4 v[30:33], v[10:11], off offset:512
	s_add_i32 s5, s2, -2
	s_cmp_gt_u32 s5, 3
	s_cbranch_scc1 .LBB0_1378
	v_lshl_add_u64 v[14:15], v[186:187], 2, s[6:7]
	global_load_dwordx4 v[38:41], v[14:15], off offset:-2048
	global_load_dwordx4 v[34:37], v[14:15], off offset:-2032
	global_load_dwordx4 v[10:13], v[14:15], off offset:-1536
	s_nop 0
	global_load_dwordx4 v[14:17], v[14:15], off offset:-1520

.LBB0_2625:
	v_add_u32_e32 v142, s57, v161
	ds_read_b128 v[130:133], v142
	ds_read_b128 v[134:137], v142 offset:1024
	ds_read_b128 v[138:141], v142 offset:2048
	ds_read_b128 v[142:145], v142 offset:3072
	s_add_u32 s18, s38, 0xfffc0080
	s_addc_u32 s19, s39, -1
	s_cmp_eq_u32 s72, 4
	s_cselect_b32 s19, s25, s19
	s_cselect_b32 s18, s68, s18
	s_cselect_b32 s43, s17, s71
	s_cselect_b32 s42, s69, s70
	v_lshl_add_u64 v[204:205], s[38:39], 0, v[164:165]
	s_add_i32 m0, s50, 0xc000
	ds_read_b128 v[146:149], v171
	ds_read_b128 v[176:179], v171 offset:1024
	ds_read_b128 v[180:183], v171 offset:2048
	ds_read_b128 v[184:187], v171 offset:3072
	ds_read_b128 v[188:191], v171 offset:4096
	ds_read_b128 v[192:195], v171 offset:5120
	ds_read_b128 v[196:199], v171 offset:6144
	ds_read_b128 v[200:203], v171 offset:7168
	global_load_lds_dwordx4 v[204:205], off
	v_lshl_add_u64 v[204:205], s[38:39], 0, v[166:167]
	s_add_i32 m0, s50, 0xe000
	s_nop 0
	global_load_lds_dwordx4 v[204:205], off
	s_waitcnt lgkmcnt(8)
	s_setprio 1
	s_barrier
	s_waitcnt lgkmcnt(0)
	v_mfma_f32_16x16x32_bf16 v[126:129], v[130:133], v[146:149], v[126:129]
	v_mfma_f32_16x16x32_bf16 v[122:125], v[138:141], v[146:149], v[122:125]
	v_mfma_f32_16x16x32_bf16 v[118:121], v[130:133], v[180:183], v[118:121]
	v_mfma_f32_16x16x32_bf16 v[114:117], v[138:141], v[180:183], v[114:117]
	v_mfma_f32_16x16x32_bf16 v[110:113], v[130:133], v[188:191], v[110:113]
	v_mfma_f32_16x16x32_bf16 v[106:109], v[138:141], v[188:191], v[106:109]
	v_mfma_f32_16x16x32_bf16 v[102:105], v[130:133], v[196:199], v[102:105]
	v_mfma_f32_16x16x32_bf16 v[98:101], v[138:141], v[196:199], v[98:101]
	v_mfma_f32_16x16x32_bf16 v[126:129], v[134:137], v[176:179], v[126:129]
	v_mfma_f32_16x16x32_bf16 v[122:125], v[142:145], v[176:179], v[122:125]
	v_mfma_f32_16x16x32_bf16 v[118:121], v[134:137], v[184:187], v[118:121]
	v_mfma_f32_16x16x32_bf16 v[114:117], v[142:145], v[184:187], v[114:117]
	v_mfma_f32_16x16x32_bf16 v[110:113], v[134:137], v[192:195], v[110:113]
	v_mfma_f32_16x16x32_bf16 v[106:109], v[142:145], v[192:195], v[106:109]
	v_mfma_f32_16x16x32_bf16 v[102:105], v[134:137], v[200:203], v[102:105]
	v_mfma_f32_16x16x32_bf16 v[98:101], v[142:145], v[200:203], v[98:101]
	s_barrier
	s_setprio 0
	s_add_i32 s20, s57, s48
	v_add_u32_e32 v158, s60, v161
	v_lshl_add_u64 v[220:221], s[42:43], 0, v[152:153]
	s_mov_b32 m0, s20
	ds_read_b128 v[204:207], v158
	ds_read_b128 v[208:211], v158 offset:1024
	ds_read_b128 v[212:215], v158 offset:2048
	ds_read_b128 v[216:219], v158 offset:3072
	global_load_lds_dwordx4 v[220:221], off
	v_lshl_add_u64 v[222:223], s[42:43], 0, v[156:157]
	s_add_i32 m0, s20, 0x2000
	s_nop 0
	global_load_lds_dwordx4 v[222:223], off
	s_setprio 1
	s_barrier
	s_waitcnt lgkmcnt(0)
	v_mfma_f32_16x16x32_bf16 v[94:97], v[204:207], v[146:149], v[94:97]
	v_mfma_f32_16x16x32_bf16 v[90:93], v[212:215], v[146:149], v[90:93]
	v_mfma_f32_16x16x32_bf16 v[86:89], v[204:207], v[180:183], v[86:89]
	v_mfma_f32_16x16x32_bf16 v[82:85], v[212:215], v[180:183], v[82:85]
	v_mfma_f32_16x16x32_bf16 v[78:81], v[204:207], v[188:191], v[78:81]
	v_mfma_f32_16x16x32_bf16 v[74:77], v[212:215], v[188:191], v[74:77]
	v_mfma_f32_16x16x32_bf16 v[70:73], v[204:207], v[196:199], v[70:73]
	v_mfma_f32_16x16x32_bf16 v[66:69], v[212:215], v[196:199], v[66:69]
	v_mfma_f32_16x16x32_bf16 v[94:97], v[208:211], v[176:179], v[94:97]
	v_mfma_f32_16x16x32_bf16 v[90:93], v[216:219], v[176:179], v[90:93]
	v_mfma_f32_16x16x32_bf16 v[86:89], v[208:211], v[184:187], v[86:89]
	v_mfma_f32_16x16x32_bf16 v[82:85], v[216:219], v[184:187], v[82:85]
	v_mfma_f32_16x16x32_bf16 v[78:81], v[208:211], v[192:195], v[78:81]
	v_mfma_f32_16x16x32_bf16 v[74:77], v[216:219], v[192:195], v[74:77]
	v_mfma_f32_16x16x32_bf16 v[70:73], v[208:211], v[200:203], v[70:73]
	v_mfma_f32_16x16x32_bf16 v[66:69], v[216:219], v[200:203], v[66:69]
	s_barrier
	s_setprio 0
	s_mov_b32 m0, s50
	v_lshl_add_u64 v[224:225], s[18:19], 0, v[150:151]
	ds_read_b128 v[146:149], v171 offset:16384
	ds_read_b128 v[176:179], v171 offset:17408
	ds_read_b128 v[180:183], v171 offset:18432
	ds_read_b128 v[184:187], v171 offset:19456
	ds_read_b128 v[188:191], v171 offset:20480
	ds_read_b128 v[192:195], v171 offset:21504
	ds_read_b128 v[196:199], v171 offset:22528
	ds_read_b128 v[200:203], v171 offset:23552
	global_load_lds_dwordx4 v[224:225], off
	v_lshl_add_u64 v[226:227], s[18:19], 0, v[154:155]
	s_mov_b32 m0, s51
	s_nop 0
	global_load_lds_dwordx4 v[226:227], off
	s_setprio 1
	s_barrier
	s_waitcnt lgkmcnt(0)
	v_mfma_f32_16x16x32_bf16 v[62:65], v[130:133], v[146:149], v[62:65]
	v_mfma_f32_16x16x32_bf16 v[58:61], v[138:141], v[146:149], v[58:61]
	v_mfma_f32_16x16x32_bf16 v[54:57], v[130:133], v[180:183], v[54:57]
	v_mfma_f32_16x16x32_bf16 v[50:53], v[138:141], v[180:183], v[50:53]
	v_mfma_f32_16x16x32_bf16 v[46:49], v[130:133], v[188:191], v[46:49]
	v_mfma_f32_16x16x32_bf16 v[42:45], v[138:141], v[188:191], v[42:45]
	v_mfma_f32_16x16x32_bf16 v[38:41], v[130:133], v[196:199], v[38:41]
	v_mfma_f32_16x16x32_bf16 v[34:37], v[138:141], v[196:199], v[34:37]
	v_mfma_f32_16x16x32_bf16 v[62:65], v[134:137], v[176:179], v[62:65]
	v_mfma_f32_16x16x32_bf16 v[58:61], v[142:145], v[176:179], v[58:61]
	v_mfma_f32_16x16x32_bf16 v[54:57], v[134:137], v[184:187], v[54:57]
	v_mfma_f32_16x16x32_bf16 v[50:53], v[142:145], v[184:187], v[50:53]
	v_mfma_f32_16x16x32_bf16 v[46:49], v[134:137], v[192:195], v[46:49]
	v_mfma_f32_16x16x32_bf16 v[42:45], v[142:145], v[192:195], v[42:45]
	v_mfma_f32_16x16x32_bf16 v[38:41], v[134:137], v[200:203], v[38:41]
	v_mfma_f32_16x16x32_bf16 v[34:37], v[142:145], v[200:203], v[34:37]
	s_barrier
	s_setprio 0
	s_add_u32 s20, s42, 0x40000
	s_addc_u32 s21, s43, 0
	s_add_i32 s73, s60, s48
	v_lshl_add_u64 v[130:131], s[20:21], 0, v[152:153]
	s_mov_b32 m0, s73
	s_nop 0
	global_load_lds_dwordx4 v[130:131], off
	v_lshl_add_u64 v[130:131], s[20:21], 0, v[156:157]
	s_add_i32 m0, s73, 0x2000
	s_nop 0
	global_load_lds_dwordx4 v[130:131], off
	s_waitcnt vmcnt(6)
	s_setprio 1
	s_barrier
	v_mfma_f32_16x16x32_bf16 v[30:33], v[204:207], v[146:149], v[30:33]
	v_mfma_f32_16x16x32_bf16 v[26:29], v[212:215], v[146:149], v[26:29]
	v_mfma_f32_16x16x32_bf16 v[22:25], v[204:207], v[180:183], v[22:25]
	v_mfma_f32_16x16x32_bf16 v[18:21], v[212:215], v[180:183], v[18:21]
	v_mfma_f32_16x16x32_bf16 v[14:17], v[204:207], v[188:191], v[14:17]
	v_mfma_f32_16x16x32_bf16 v[10:13], v[212:215], v[188:191], v[10:13]
	v_mfma_f32_16x16x32_bf16 v[6:9], v[204:207], v[196:199], v[6:9]
	v_mfma_f32_16x16x32_bf16 v[2:5], v[212:215], v[196:199], v[2:5]
	v_mfma_f32_16x16x32_bf16 v[30:33], v[208:211], v[176:179], v[30:33]
	v_mfma_f32_16x16x32_bf16 v[26:29], v[216:219], v[176:179], v[26:29]
	v_mfma_f32_16x16x32_bf16 v[22:25], v[208:211], v[184:187], v[22:25]
	v_mfma_f32_16x16x32_bf16 v[18:21], v[216:219], v[184:187], v[18:21]
	v_mfma_f32_16x16x32_bf16 v[14:17], v[208:211], v[192:195], v[14:17]
	v_mfma_f32_16x16x32_bf16 v[10:13], v[216:219], v[192:195], v[10:13]
	v_mfma_f32_16x16x32_bf16 v[6:9], v[208:211], v[200:203], v[6:9]
	v_mfma_f32_16x16x32_bf16 v[2:5], v[216:219], v[200:203], v[2:5]
	s_barrier
	s_setprio 0
	s_add_i32 s20, 0, 0x18000
	v_add_u32_e32 v142, s20, v161
	ds_read_b128 v[130:133], v142
	ds_read_b128 v[134:137], v142 offset:1024
	ds_read_b128 v[138:141], v142 offset:2048
	ds_read_b128 v[142:145], v142 offset:3072
	s_add_u32 s18, s18, 0x40000
	s_addc_u32 s19, s19, 0
	s_mov_b32 m0, s52
	v_lshl_add_u64 v[204:205], s[18:19], 0, v[150:151]
	ds_read_b128 v[146:149], v171 offset:32768
	ds_read_b128 v[176:179], v171 offset:33792
	ds_read_b128 v[180:183], v171 offset:34816
	ds_read_b128 v[184:187], v171 offset:35840
	ds_read_b128 v[188:191], v171 offset:36864
	ds_read_b128 v[192:195], v171 offset:37888
	ds_read_b128 v[196:199], v171 offset:38912
	ds_read_b128 v[200:203], v171 offset:39936
	global_load_lds_dwordx4 v[204:205], off
	v_lshl_add_u64 v[204:205], s[18:19], 0, v[154:155]
	s_mov_b32 m0, s53
	s_nop 0
	global_load_lds_dwordx4 v[204:205], off
	s_waitcnt lgkmcnt(8)
	s_setprio 1
	s_barrier
	s_waitcnt lgkmcnt(0)
	v_mfma_f32_16x16x32_bf16 v[126:129], v[130:133], v[146:149], v[126:129]
	v_mfma_f32_16x16x32_bf16 v[122:125], v[138:141], v[146:149], v[122:125]
	v_mfma_f32_16x16x32_bf16 v[118:121], v[130:133], v[180:183], v[118:121]
	v_mfma_f32_16x16x32_bf16 v[114:117], v[138:141], v[180:183], v[114:117]
	v_mfma_f32_16x16x32_bf16 v[110:113], v[130:133], v[188:191], v[110:113]
	v_mfma_f32_16x16x32_bf16 v[106:109], v[138:141], v[188:191], v[106:109]
	v_mfma_f32_16x16x32_bf16 v[102:105], v[130:133], v[196:199], v[102:105]
	v_mfma_f32_16x16x32_bf16 v[98:101], v[138:141], v[196:199], v[98:101]
	v_mfma_f32_16x16x32_bf16 v[126:129], v[134:137], v[176:179], v[126:129]
	v_mfma_f32_16x16x32_bf16 v[122:125], v[142:145], v[176:179], v[122:125]
	v_mfma_f32_16x16x32_bf16 v[118:121], v[134:137], v[184:187], v[118:121]
	v_mfma_f32_16x16x32_bf16 v[114:117], v[142:145], v[184:187], v[114:117]
	v_mfma_f32_16x16x32_bf16 v[110:113], v[134:137], v[192:195], v[110:113]
	v_mfma_f32_16x16x32_bf16 v[106:109], v[142:145], v[192:195], v[106:109]
	v_mfma_f32_16x16x32_bf16 v[102:105], v[134:137], v[200:203], v[102:105]
	v_mfma_f32_16x16x32_bf16 v[98:101], v[142:145], v[200:203], v[98:101]
	s_barrier
	s_setprio 0
	s_add_i32 s21, 0, 0x1c000
	s_add_i32 s18, s20, s48
	v_add_u32_e32 v158, s21, v161
	v_lshl_add_u64 v[220:221], v[220:221], 0, s[6:7]
	s_mov_b32 m0, s18
	ds_read_b128 v[204:207], v158
	ds_read_b128 v[208:211], v158 offset:1024
	ds_read_b128 v[212:215], v158 offset:2048
	ds_read_b128 v[216:219], v158 offset:3072
	global_load_lds_dwordx4 v[220:221], off
	v_lshl_add_u64 v[220:221], v[222:223], 0, s[6:7]
	s_add_i32 m0, s18, 0x2000
	s_nop 0
	global_load_lds_dwordx4 v[220:221], off
	s_setprio 1
	s_barrier
	s_waitcnt lgkmcnt(0)
	v_mfma_f32_16x16x32_bf16 v[94:97], v[204:207], v[146:149], v[94:97]
	v_mfma_f32_16x16x32_bf16 v[90:93], v[212:215], v[146:149], v[90:93]
	v_mfma_f32_16x16x32_bf16 v[86:89], v[204:207], v[180:183], v[86:89]
	v_mfma_f32_16x16x32_bf16 v[82:85], v[212:215], v[180:183], v[82:85]
	v_mfma_f32_16x16x32_bf16 v[78:81], v[204:207], v[188:191], v[78:81]
	v_mfma_f32_16x16x32_bf16 v[74:77], v[212:215], v[188:191], v[74:77]
	v_mfma_f32_16x16x32_bf16 v[70:73], v[204:207], v[196:199], v[70:73]
	v_mfma_f32_16x16x32_bf16 v[66:69], v[212:215], v[196:199], v[66:69]
	v_mfma_f32_16x16x32_bf16 v[94:97], v[208:211], v[176:179], v[94:97]
	v_mfma_f32_16x16x32_bf16 v[90:93], v[216:219], v[176:179], v[90:93]
	v_mfma_f32_16x16x32_bf16 v[86:89], v[208:211], v[184:187], v[86:89]
	v_mfma_f32_16x16x32_bf16 v[82:85], v[216:219], v[184:187], v[82:85]
	v_mfma_f32_16x16x32_bf16 v[78:81], v[208:211], v[192:195], v[78:81]
	v_mfma_f32_16x16x32_bf16 v[74:77], v[216:219], v[192:195], v[74:77]
	v_mfma_f32_16x16x32_bf16 v[70:73], v[208:211], v[200:203], v[70:73]
	v_mfma_f32_16x16x32_bf16 v[66:69], v[216:219], v[200:203], v[66:69]
	s_barrier
	s_setprio 0
	s_mov_b32 m0, s55
	v_lshl_add_u64 v[220:221], v[224:225], 0, s[6:7]
	ds_read_b128 v[146:149], v171 offset:49152
	ds_read_b128 v[176:179], v171 offset:50176
	ds_read_b128 v[180:183], v171 offset:51200
	ds_read_b128 v[184:187], v171 offset:52224
	ds_read_b128 v[188:191], v171 offset:53248
	ds_read_b128 v[192:195], v171 offset:54272
	ds_read_b128 v[196:199], v171 offset:55296
	ds_read_b128 v[200:203], v171 offset:56320
	global_load_lds_dwordx4 v[220:221], off
	v_lshl_add_u64 v[220:221], v[226:227], 0, s[6:7]
	s_mov_b32 m0, s56
	s_nop 0
	global_load_lds_dwordx4 v[220:221], off
	s_setprio 1
	s_barrier
	s_waitcnt lgkmcnt(0)
	v_mfma_f32_16x16x32_bf16 v[62:65], v[130:133], v[146:149], v[62:65]
	v_mfma_f32_16x16x32_bf16 v[58:61], v[138:141], v[146:149], v[58:61]
	v_mfma_f32_16x16x32_bf16 v[54:57], v[130:133], v[180:183], v[54:57]
	v_mfma_f32_16x16x32_bf16 v[50:53], v[138:141], v[180:183], v[50:53]
	v_mfma_f32_16x16x32_bf16 v[46:49], v[130:133], v[188:191], v[46:49]
	v_mfma_f32_16x16x32_bf16 v[42:45], v[138:141], v[188:191], v[42:45]
	v_mfma_f32_16x16x32_bf16 v[38:41], v[130:133], v[196:199], v[38:41]
	v_mfma_f32_16x16x32_bf16 v[34:37], v[138:141], v[196:199], v[34:37]
	v_mfma_f32_16x16x32_bf16 v[62:65], v[134:137], v[176:179], v[62:65]
	v_mfma_f32_16x16x32_bf16 v[58:61], v[142:145], v[176:179], v[58:61]
	v_mfma_f32_16x16x32_bf16 v[54:57], v[134:137], v[184:187], v[54:57]
	v_mfma_f32_16x16x32_bf16 v[50:53], v[142:145], v[184:187], v[50:53]
	v_mfma_f32_16x16x32_bf16 v[46:49], v[134:137], v[192:195], v[46:49]
	v_mfma_f32_16x16x32_bf16 v[42:45], v[142:145], v[192:195], v[42:45]
	v_mfma_f32_16x16x32_bf16 v[38:41], v[134:137], v[200:203], v[38:41]
	v_mfma_f32_16x16x32_bf16 v[34:37], v[142:145], v[200:203], v[34:37]
	s_barrier
	s_setprio 0
	s_add_u32 s18, s42, 0x40080
	s_addc_u32 s19, s43, 0
	s_add_i32 s20, s21, s48
	v_lshl_add_u64 v[130:131], s[18:19], 0, v[152:153]
	s_mov_b32 m0, s20
	s_nop 0
	global_load_lds_dwordx4 v[130:131], off
	v_lshl_add_u64 v[130:131], s[18:19], 0, v[156:157]
	s_add_i32 m0, s20, 0x2000
	s_nop 0
	global_load_lds_dwordx4 v[130:131], off
	s_waitcnt vmcnt(6)
	s_setprio 1
	s_barrier
	v_mfma_f32_16x16x32_bf16 v[30:33], v[204:207], v[146:149], v[30:33]
	v_mfma_f32_16x16x32_bf16 v[26:29], v[212:215], v[146:149], v[26:29]
	v_mfma_f32_16x16x32_bf16 v[22:25], v[204:207], v[180:183], v[22:25]
	v_mfma_f32_16x16x32_bf16 v[18:21], v[212:215], v[180:183], v[18:21]
	v_mfma_f32_16x16x32_bf16 v[14:17], v[204:207], v[188:191], v[14:17]
	v_mfma_f32_16x16x32_bf16 v[10:13], v[212:215], v[188:191], v[10:13]
	v_mfma_f32_16x16x32_bf16 v[6:9], v[204:207], v[196:199], v[6:9]
	v_mfma_f32_16x16x32_bf16 v[2:5], v[212:215], v[196:199], v[2:5]
	v_mfma_f32_16x16x32_bf16 v[30:33], v[208:211], v[176:179], v[30:33]
	v_mfma_f32_16x16x32_bf16 v[26:29], v[216:219], v[176:179], v[26:29]
	v_mfma_f32_16x16x32_bf16 v[22:25], v[208:211], v[184:187], v[22:25]
	v_mfma_f32_16x16x32_bf16 v[18:21], v[216:219], v[184:187], v[18:21]
	v_mfma_f32_16x16x32_bf16 v[14:17], v[208:211], v[192:195], v[14:17]
	v_mfma_f32_16x16x32_bf16 v[10:13], v[216:219], v[192:195], v[10:13]
	v_mfma_f32_16x16x32_bf16 v[6:9], v[208:211], v[200:203], v[6:9]
	v_mfma_f32_16x16x32_bf16 v[2:5], v[216:219], v[200:203], v[2:5]
	s_barrier
	s_setprio 0
	s_add_i32 s72, s72, 2
	s_add_u32 s38, s38, 0x100
	s_addc_u32 s39, s39, 0
	s_add_u32 s70, s70, 0x100
	s_addc_u32 s71, s71, 0
	s_cmp_gt_u32 s72, 5
	s_cbranch_scc0 .LBB0_2625
	s_cmp_lg_u32 s41, 1
	v_lshl_add_u32 v182, s40, 8, v1
	s_cselect_b64 s[38:39], -1, 0
	s_lshl_b32 s40, s67, 8
	v_or_b32_e32 v180, 16, v182
	v_or_b32_e32 v178, 32, v182
	v_or_b32_e32 v176, 48, v182
	s_ashr_i32 s41, s40, 31
	s_mov_b64 s[18:19], -1
	s_and_b64 vcc, exec, s[38:39]
	v_ashrrev_i32_e32 v183, 31, v182
	v_lshlrev_b32_e32 v158, 1, v160
	v_ashrrev_i32_e32 v181, 31, v180
	v_ashrrev_i32_e32 v179, 31, v178
	v_ashrrev_i32_e32 v177, 31, v176
	s_cbranch_vccnz .LBB0_2629
	s_andn2_b64 vcc, exec, s[18:19]
	s_cbranch_vccz .LBB0_2630

.LBB0_2844:
	s_ashr_i32 s37, s36, 31
	v_cmp_lt_i64_e32 vcc, s[18:19], v[192:193]
	s_lshl_b64 s[18:19], s[36:37], 19
	s_add_u32 s38, s48, s18
	s_addc_u32 s39, s49, s19
	s_and_b64 s[18:19], vcc, exec
	s_cselect_b32 s37, s39, s45
	s_cselect_b32 s43, s38, s44
	s_ashr_i32 s35, s34, 31
	s_lshl_b64 s[18:19], s[34:35], 19
	s_add_u32 s40, s50, s18
	s_addc_u32 s41, s51, s19
	s_and_b64 s[18:19], vcc, exec
	s_cselect_b32 s35, s41, s47
	s_cselect_b32 s70, s40, s46
	s_add_u32 s44, s44, 0x40080
	s_addc_u32 s45, s45, 0
	s_add_u32 s71, s46, 0x100
	s_addc_u32 s72, s47, 0
	s_mov_b32 s73, -2
	s_waitcnt lgkmcnt(0)
	s_waitcnt vmcnt(0)
	ds_read_b128 v[98:101], v173
	ds_read_b128 v[102:105], v173 offset:1024
	ds_read_b128 v[106:109], v173 offset:2048
	ds_read_b128 v[110:113], v173 offset:3072
	s_add_u32 s18, s44, 0xfffc0080
	s_addc_u32 s19, s45, -1
	s_cmp_eq_u32 s73, 12
	s_cselect_b32 s19, s37, s19
	s_cselect_b32 s18, s43, s18
	s_cselect_b32 s47, s35, s72
	s_cselect_b32 s46, s70, s71
	v_lshl_add_u64 v[204:205], s[44:45], 0, v[188:189]
	s_add_i32 m0, s53, 0xc000
	ds_read_b128 v[146:149], v185
	ds_read_b128 v[150:153], v185 offset:1024
	ds_read_b128 v[154:157], v185 offset:2048
	ds_read_b128 v[158:161], v185 offset:3072
	ds_read_b128 v[162:165], v185 offset:4096
	ds_read_b128 v[166:169], v185 offset:5120
	ds_read_b128 v[196:199], v185 offset:6144
	ds_read_b128 v[200:203], v185 offset:7168
	global_load_lds_dwordx4 v[204:205], off
	v_lshl_add_u64 v[204:205], s[44:45], 0, v[190:191]
	s_add_i32 m0, s53, 0xe000
	s_nop 0
	global_load_lds_dwordx4 v[204:205], off
	s_waitcnt lgkmcnt(8)
	s_setprio 1
	s_barrier
	s_waitcnt lgkmcnt(0)
	v_mfma_f32_16x16x32_bf16 v[142:145], v[98:101], v[146:149], 0
	v_mfma_f32_16x16x32_bf16 v[138:141], v[106:109], v[146:149], 0
	v_mfma_f32_16x16x32_bf16 v[126:129], v[98:101], v[154:157], 0
	v_mfma_f32_16x16x32_bf16 v[122:125], v[106:109], v[154:157], 0
	v_mfma_f32_16x16x32_bf16 v[94:97], v[98:101], v[162:165], 0
	v_mfma_f32_16x16x32_bf16 v[90:93], v[106:109], v[162:165], 0
	v_mfma_f32_16x16x32_bf16 v[78:81], v[98:101], v[196:199], 0
	v_mfma_f32_16x16x32_bf16 v[74:77], v[106:109], v[196:199], 0
	v_mfma_f32_16x16x32_bf16 v[142:145], v[102:105], v[150:153], v[142:145]
	v_mfma_f32_16x16x32_bf16 v[138:141], v[110:113], v[150:153], v[138:141]
	v_mfma_f32_16x16x32_bf16 v[126:129], v[102:105], v[158:161], v[126:129]
	v_mfma_f32_16x16x32_bf16 v[122:125], v[110:113], v[158:161], v[122:125]
	v_mfma_f32_16x16x32_bf16 v[94:97], v[102:105], v[166:169], v[94:97]
	v_mfma_f32_16x16x32_bf16 v[90:93], v[110:113], v[166:169], v[90:93]
	v_mfma_f32_16x16x32_bf16 v[78:81], v[102:105], v[200:203], v[78:81]
	v_mfma_f32_16x16x32_bf16 v[74:77], v[110:113], v[200:203], v[74:77]
	s_barrier
	s_setprio 0
	s_add_i32 s20, s65, s52
	v_lshl_add_u64 v[220:221], s[46:47], 0, v[176:177]
	s_mov_b32 m0, s20
	ds_read_b128 v[204:207], v222
	ds_read_b128 v[208:211], v222 offset:1024
	ds_read_b128 v[212:215], v222 offset:2048
	ds_read_b128 v[216:219], v222 offset:3072
	global_load_lds_dwordx4 v[220:221], off
	v_lshl_add_u64 v[224:225], s[46:47], 0, v[180:181]
	s_add_i32 m0, s20, 0x2000
	s_nop 0
	global_load_lds_dwordx4 v[224:225], off
	s_setprio 1
	s_barrier
	s_waitcnt lgkmcnt(0)
	v_mfma_f32_16x16x32_bf16 v[134:137], v[204:207], v[146:149], 0
	v_mfma_f32_16x16x32_bf16 v[130:133], v[212:215], v[146:149], 0
	v_mfma_f32_16x16x32_bf16 v[118:121], v[204:207], v[154:157], 0
	v_mfma_f32_16x16x32_bf16 v[114:117], v[212:215], v[154:157], 0
	v_mfma_f32_16x16x32_bf16 v[86:89], v[204:207], v[162:165], 0
	v_mfma_f32_16x16x32_bf16 v[82:85], v[212:215], v[162:165], 0
	v_mfma_f32_16x16x32_bf16 v[70:73], v[204:207], v[196:199], 0
	v_mfma_f32_16x16x32_bf16 v[66:69], v[212:215], v[196:199], 0
	v_mfma_f32_16x16x32_bf16 v[134:137], v[208:211], v[150:153], v[134:137]
	v_mfma_f32_16x16x32_bf16 v[130:133], v[216:219], v[150:153], v[130:133]
	v_mfma_f32_16x16x32_bf16 v[118:121], v[208:211], v[158:161], v[118:121]
	v_mfma_f32_16x16x32_bf16 v[114:117], v[216:219], v[158:161], v[114:117]
	v_mfma_f32_16x16x32_bf16 v[86:89], v[208:211], v[166:169], v[86:89]
	v_mfma_f32_16x16x32_bf16 v[82:85], v[216:219], v[166:169], v[82:85]
	v_mfma_f32_16x16x32_bf16 v[70:73], v[208:211], v[200:203], v[70:73]
	v_mfma_f32_16x16x32_bf16 v[66:69], v[216:219], v[200:203], v[66:69]
	s_barrier
	s_setprio 0
	s_mov_b32 m0, s53
	v_lshl_add_u64 v[226:227], s[18:19], 0, v[174:175]
	ds_read_b128 v[146:149], v185 offset:16384
	ds_read_b128 v[150:153], v185 offset:17408
	ds_read_b128 v[154:157], v185 offset:18432
	ds_read_b128 v[158:161], v185 offset:19456
	ds_read_b128 v[162:165], v185 offset:20480
	ds_read_b128 v[166:169], v185 offset:21504
	ds_read_b128 v[196:199], v185 offset:22528
	ds_read_b128 v[200:203], v185 offset:23552
	global_load_lds_dwordx4 v[226:227], off
	v_lshl_add_u64 v[228:229], s[18:19], 0, v[178:179]
	s_mov_b32 m0, s54
	s_nop 0
	global_load_lds_dwordx4 v[228:229], off
	s_setprio 1
	s_barrier
	s_waitcnt lgkmcnt(0)
	v_mfma_f32_16x16x32_bf16 v[62:65], v[98:101], v[146:149], 0
	v_mfma_f32_16x16x32_bf16 v[58:61], v[106:109], v[146:149], 0
	v_mfma_f32_16x16x32_bf16 v[46:49], v[98:101], v[154:157], 0
	v_mfma_f32_16x16x32_bf16 v[42:45], v[106:109], v[154:157], 0
	v_mfma_f32_16x16x32_bf16 v[30:33], v[98:101], v[162:165], 0
	v_mfma_f32_16x16x32_bf16 v[26:29], v[106:109], v[162:165], 0
	v_mfma_f32_16x16x32_bf16 v[14:17], v[98:101], v[196:199], 0
	v_mfma_f32_16x16x32_bf16 v[10:13], v[106:109], v[196:199], 0
	v_mfma_f32_16x16x32_bf16 v[62:65], v[102:105], v[150:153], v[62:65]
	v_mfma_f32_16x16x32_bf16 v[58:61], v[110:113], v[150:153], v[58:61]
	v_mfma_f32_16x16x32_bf16 v[46:49], v[102:105], v[158:161], v[46:49]
	v_mfma_f32_16x16x32_bf16 v[42:45], v[110:113], v[158:161], v[42:45]
	v_mfma_f32_16x16x32_bf16 v[30:33], v[102:105], v[166:169], v[30:33]
	v_mfma_f32_16x16x32_bf16 v[26:29], v[110:113], v[166:169], v[26:29]
	v_mfma_f32_16x16x32_bf16 v[14:17], v[102:105], v[200:203], v[14:17]
	v_mfma_f32_16x16x32_bf16 v[10:13], v[110:113], v[200:203], v[10:13]
	s_barrier
	s_setprio 0
	s_add_u32 s20, s46, 0x40000
	s_addc_u32 s21, s47, 0
	s_add_i32 s74, s66, s52
	v_lshl_add_u64 v[98:99], s[20:21], 0, v[176:177]
	s_mov_b32 m0, s74
	s_nop 0
	global_load_lds_dwordx4 v[98:99], off
	v_lshl_add_u64 v[98:99], s[20:21], 0, v[180:181]
	s_add_i32 m0, s74, 0x2000
	s_nop 0
	global_load_lds_dwordx4 v[98:99], off
	s_waitcnt vmcnt(6)
	s_setprio 1
	s_barrier
	v_mfma_f32_16x16x32_bf16 v[54:57], v[204:207], v[146:149], 0
	v_mfma_f32_16x16x32_bf16 v[50:53], v[212:215], v[146:149], 0
	v_mfma_f32_16x16x32_bf16 v[38:41], v[204:207], v[154:157], 0
	v_mfma_f32_16x16x32_bf16 v[34:37], v[212:215], v[154:157], 0
	v_mfma_f32_16x16x32_bf16 v[22:25], v[204:207], v[162:165], 0
	v_mfma_f32_16x16x32_bf16 v[18:21], v[212:215], v[162:165], 0
	v_mfma_f32_16x16x32_bf16 v[6:9], v[204:207], v[196:199], 0
	v_mfma_f32_16x16x32_bf16 v[2:5], v[212:215], v[196:199], 0
	v_mfma_f32_16x16x32_bf16 v[54:57], v[208:211], v[150:153], v[54:57]
	v_mfma_f32_16x16x32_bf16 v[50:53], v[216:219], v[150:153], v[50:53]
	v_mfma_f32_16x16x32_bf16 v[38:41], v[208:211], v[158:161], v[38:41]
	v_mfma_f32_16x16x32_bf16 v[34:37], v[216:219], v[158:161], v[34:37]
	v_mfma_f32_16x16x32_bf16 v[22:25], v[208:211], v[166:169], v[22:25]
	v_mfma_f32_16x16x32_bf16 v[18:21], v[216:219], v[166:169], v[18:21]
	v_mfma_f32_16x16x32_bf16 v[6:9], v[208:211], v[200:203], v[6:9]
	v_mfma_f32_16x16x32_bf16 v[2:5], v[216:219], v[200:203], v[2:5]
	s_barrier
	s_setprio 0
	s_add_i32 s20, 0, 0x18000
	v_add_u32_e32 v110, s20, v171
	ds_read_b128 v[98:101], v110
	ds_read_b128 v[102:105], v110 offset:1024
	ds_read_b128 v[106:109], v110 offset:2048
	ds_read_b128 v[110:113], v110 offset:3072
	s_add_u32 s18, s18, 0x40000
	s_addc_u32 s19, s19, 0
	s_mov_b32 m0, s55
	v_lshl_add_u64 v[204:205], s[18:19], 0, v[174:175]
	ds_read_b128 v[146:149], v185 offset:32768
	ds_read_b128 v[150:153], v185 offset:33792
	ds_read_b128 v[154:157], v185 offset:34816
	ds_read_b128 v[158:161], v185 offset:35840
	ds_read_b128 v[162:165], v185 offset:36864
	ds_read_b128 v[166:169], v185 offset:37888
	ds_read_b128 v[196:199], v185 offset:38912
	ds_read_b128 v[200:203], v185 offset:39936
	global_load_lds_dwordx4 v[204:205], off
	v_lshl_add_u64 v[204:205], s[18:19], 0, v[178:179]
	s_mov_b32 m0, s56
	s_nop 0
	global_load_lds_dwordx4 v[204:205], off
	s_waitcnt lgkmcnt(8)
	s_setprio 1
	s_barrier
	s_waitcnt lgkmcnt(0)
	v_mfma_f32_16x16x32_bf16 v[142:145], v[98:101], v[146:149], v[142:145]
	v_mfma_f32_16x16x32_bf16 v[138:141], v[106:109], v[146:149], v[138:141]
	v_mfma_f32_16x16x32_bf16 v[126:129], v[98:101], v[154:157], v[126:129]
	v_mfma_f32_16x16x32_bf16 v[122:125], v[106:109], v[154:157], v[122:125]
	v_mfma_f32_16x16x32_bf16 v[94:97], v[98:101], v[162:165], v[94:97]
	v_mfma_f32_16x16x32_bf16 v[90:93], v[106:109], v[162:165], v[90:93]
	v_mfma_f32_16x16x32_bf16 v[78:81], v[98:101], v[196:199], v[78:81]
	v_mfma_f32_16x16x32_bf16 v[74:77], v[106:109], v[196:199], v[74:77]
	v_mfma_f32_16x16x32_bf16 v[142:145], v[102:105], v[150:153], v[142:145]
	v_mfma_f32_16x16x32_bf16 v[138:141], v[110:113], v[150:153], v[138:141]
	v_mfma_f32_16x16x32_bf16 v[126:129], v[102:105], v[158:161], v[126:129]
	v_mfma_f32_16x16x32_bf16 v[122:125], v[110:113], v[158:161], v[122:125]
	v_mfma_f32_16x16x32_bf16 v[94:97], v[102:105], v[166:169], v[94:97]
	v_mfma_f32_16x16x32_bf16 v[90:93], v[110:113], v[166:169], v[90:93]
	v_mfma_f32_16x16x32_bf16 v[78:81], v[102:105], v[200:203], v[78:81]
	v_mfma_f32_16x16x32_bf16 v[74:77], v[110:113], v[200:203], v[74:77]
	s_barrier
	s_setprio 0
	s_add_i32 s21, 0, 0x1c000
	s_add_i32 s18, s20, s52
	v_add_u32_e32 v182, s21, v171
	v_lshl_add_u64 v[220:221], v[220:221], 0, s[10:11]
	s_mov_b32 m0, s18
	ds_read_b128 v[204:207], v182
	ds_read_b128 v[208:211], v182 offset:1024
	ds_read_b128 v[212:215], v182 offset:2048
	ds_read_b128 v[216:219], v182 offset:3072
	global_load_lds_dwordx4 v[220:221], off
	v_lshl_add_u64 v[220:221], v[224:225], 0, s[10:11]
	s_add_i32 m0, s18, 0x2000
	s_nop 0
	global_load_lds_dwordx4 v[220:221], off
	s_setprio 1
	s_barrier
	s_waitcnt lgkmcnt(0)
	v_mfma_f32_16x16x32_bf16 v[134:137], v[204:207], v[146:149], v[134:137]
	v_mfma_f32_16x16x32_bf16 v[130:133], v[212:215], v[146:149], v[130:133]
	v_mfma_f32_16x16x32_bf16 v[118:121], v[204:207], v[154:157], v[118:121]
	v_mfma_f32_16x16x32_bf16 v[114:117], v[212:215], v[154:157], v[114:117]
	v_mfma_f32_16x16x32_bf16 v[86:89], v[204:207], v[162:165], v[86:89]
	v_mfma_f32_16x16x32_bf16 v[82:85], v[212:215], v[162:165], v[82:85]
	v_mfma_f32_16x16x32_bf16 v[70:73], v[204:207], v[196:199], v[70:73]
	v_mfma_f32_16x16x32_bf16 v[66:69], v[212:215], v[196:199], v[66:69]
	v_mfma_f32_16x16x32_bf16 v[134:137], v[208:211], v[150:153], v[134:137]
	v_mfma_f32_16x16x32_bf16 v[130:133], v[216:219], v[150:153], v[130:133]
	v_mfma_f32_16x16x32_bf16 v[118:121], v[208:211], v[158:161], v[118:121]
	v_mfma_f32_16x16x32_bf16 v[114:117], v[216:219], v[158:161], v[114:117]
	v_mfma_f32_16x16x32_bf16 v[86:89], v[208:211], v[166:169], v[86:89]
	v_mfma_f32_16x16x32_bf16 v[82:85], v[216:219], v[166:169], v[82:85]
	v_mfma_f32_16x16x32_bf16 v[70:73], v[208:211], v[200:203], v[70:73]
	v_mfma_f32_16x16x32_bf16 v[66:69], v[216:219], v[200:203], v[66:69]
	s_barrier
	s_setprio 0
	s_mov_b32 m0, s62
	v_lshl_add_u64 v[220:221], v[226:227], 0, s[10:11]
	ds_read_b128 v[146:149], v185 offset:49152
	ds_read_b128 v[150:153], v185 offset:50176
	ds_read_b128 v[154:157], v185 offset:51200
	ds_read_b128 v[158:161], v185 offset:52224
	ds_read_b128 v[162:165], v185 offset:53248
	ds_read_b128 v[166:169], v185 offset:54272
	ds_read_b128 v[196:199], v185 offset:55296
	ds_read_b128 v[200:203], v185 offset:56320
	global_load_lds_dwordx4 v[220:221], off
	v_lshl_add_u64 v[220:221], v[228:229], 0, s[10:11]
	s_mov_b32 m0, s63
	s_nop 0
	global_load_lds_dwordx4 v[220:221], off
	s_setprio 1
	s_barrier
	s_waitcnt lgkmcnt(0)
	v_mfma_f32_16x16x32_bf16 v[62:65], v[98:101], v[146:149], v[62:65]
	v_mfma_f32_16x16x32_bf16 v[58:61], v[106:109], v[146:149], v[58:61]
	v_mfma_f32_16x16x32_bf16 v[46:49], v[98:101], v[154:157], v[46:49]
	v_mfma_f32_16x16x32_bf16 v[42:45], v[106:109], v[154:157], v[42:45]
	v_mfma_f32_16x16x32_bf16 v[30:33], v[98:101], v[162:165], v[30:33]
	v_mfma_f32_16x16x32_bf16 v[26:29], v[106:109], v[162:165], v[26:29]
	v_mfma_f32_16x16x32_bf16 v[14:17], v[98:101], v[196:199], v[14:17]
	v_mfma_f32_16x16x32_bf16 v[10:13], v[106:109], v[196:199], v[10:13]
	v_mfma_f32_16x16x32_bf16 v[62:65], v[102:105], v[150:153], v[62:65]
	v_mfma_f32_16x16x32_bf16 v[58:61], v[110:113], v[150:153], v[58:61]
	v_mfma_f32_16x16x32_bf16 v[46:49], v[102:105], v[158:161], v[46:49]
	v_mfma_f32_16x16x32_bf16 v[42:45], v[110:113], v[158:161], v[42:45]
	v_mfma_f32_16x16x32_bf16 v[30:33], v[102:105], v[166:169], v[30:33]
	v_mfma_f32_16x16x32_bf16 v[26:29], v[110:113], v[166:169], v[26:29]
	v_mfma_f32_16x16x32_bf16 v[14:17], v[102:105], v[200:203], v[14:17]
	v_mfma_f32_16x16x32_bf16 v[10:13], v[110:113], v[200:203], v[10:13]
	s_barrier
	s_setprio 0
	s_add_u32 s18, s46, 0x40080
	s_addc_u32 s19, s47, 0
	s_add_i32 s20, s21, s52
	v_lshl_add_u64 v[98:99], s[18:19], 0, v[176:177]
	s_mov_b32 m0, s20
	s_nop 0
	global_load_lds_dwordx4 v[98:99], off
	v_lshl_add_u64 v[98:99], s[18:19], 0, v[180:181]
	s_add_i32 m0, s20, 0x2000
	s_nop 0
	global_load_lds_dwordx4 v[98:99], off
	s_waitcnt vmcnt(6)
	s_setprio 1
	s_barrier
	v_mfma_f32_16x16x32_bf16 v[54:57], v[204:207], v[146:149], v[54:57]
	v_mfma_f32_16x16x32_bf16 v[50:53], v[212:215], v[146:149], v[50:53]
	v_mfma_f32_16x16x32_bf16 v[38:41], v[204:207], v[154:157], v[38:41]
	v_mfma_f32_16x16x32_bf16 v[34:37], v[212:215], v[154:157], v[34:37]
	v_mfma_f32_16x16x32_bf16 v[22:25], v[204:207], v[162:165], v[22:25]
	v_mfma_f32_16x16x32_bf16 v[18:21], v[212:215], v[162:165], v[18:21]
	v_mfma_f32_16x16x32_bf16 v[6:9], v[204:207], v[196:199], v[6:9]
	v_mfma_f32_16x16x32_bf16 v[2:5], v[212:215], v[196:199], v[2:5]
	v_mfma_f32_16x16x32_bf16 v[54:57], v[208:211], v[150:153], v[54:57]
	v_mfma_f32_16x16x32_bf16 v[50:53], v[216:219], v[150:153], v[50:53]
	v_mfma_f32_16x16x32_bf16 v[38:41], v[208:211], v[158:161], v[38:41]
	v_mfma_f32_16x16x32_bf16 v[34:37], v[216:219], v[158:161], v[34:37]
	v_mfma_f32_16x16x32_bf16 v[22:25], v[208:211], v[166:169], v[22:25]
	v_mfma_f32_16x16x32_bf16 v[18:21], v[216:219], v[166:169], v[18:21]
	v_mfma_f32_16x16x32_bf16 v[6:9], v[208:211], v[200:203], v[6:9]
	v_mfma_f32_16x16x32_bf16 v[2:5], v[216:219], v[200:203], v[2:5]
	s_barrier
	s_setprio 0
	s_add_i32 s73, s73, 2
	s_add_u32 s44, s44, 0x100
	s_addc_u32 s45, s45, 0
	s_add_u32 s71, s71, 0x100
	s_addc_u32 s72, s72, 0
	s_cmp_gt_u32 s73, 13
.LBB0_2845:
	ds_read_b128 v[98:101], v173
	ds_read_b128 v[102:105], v173 offset:1024
	ds_read_b128 v[106:109], v173 offset:2048
	ds_read_b128 v[110:113], v173 offset:3072
	s_add_u32 s18, s44, 0xfffc0080
	s_addc_u32 s19, s45, -1
	s_cmp_eq_u32 s73, 12
	s_cselect_b32 s19, s37, s19
	s_cselect_b32 s18, s43, s18
	s_cselect_b32 s47, s35, s72
	s_cselect_b32 s46, s70, s71
	v_lshl_add_u64 v[204:205], s[44:45], 0, v[188:189]
	s_add_i32 m0, s53, 0xc000
	ds_read_b128 v[146:149], v185
	ds_read_b128 v[150:153], v185 offset:1024
	ds_read_b128 v[154:157], v185 offset:2048
	ds_read_b128 v[158:161], v185 offset:3072
	ds_read_b128 v[162:165], v185 offset:4096
	ds_read_b128 v[166:169], v185 offset:5120
	ds_read_b128 v[196:199], v185 offset:6144
	ds_read_b128 v[200:203], v185 offset:7168
	global_load_lds_dwordx4 v[204:205], off
	v_lshl_add_u64 v[204:205], s[44:45], 0, v[190:191]
	s_add_i32 m0, s53, 0xe000
	s_nop 0
	global_load_lds_dwordx4 v[204:205], off
	s_waitcnt lgkmcnt(8)
	s_setprio 1
	s_barrier
	s_waitcnt lgkmcnt(0)
	v_mfma_f32_16x16x32_bf16 v[142:145], v[98:101], v[146:149], v[142:145]
	v_mfma_f32_16x16x32_bf16 v[138:141], v[106:109], v[146:149], v[138:141]
	v_mfma_f32_16x16x32_bf16 v[126:129], v[98:101], v[154:157], v[126:129]
	v_mfma_f32_16x16x32_bf16 v[122:125], v[106:109], v[154:157], v[122:125]
	v_mfma_f32_16x16x32_bf16 v[94:97], v[98:101], v[162:165], v[94:97]
	v_mfma_f32_16x16x32_bf16 v[90:93], v[106:109], v[162:165], v[90:93]
	v_mfma_f32_16x16x32_bf16 v[78:81], v[98:101], v[196:199], v[78:81]
	v_mfma_f32_16x16x32_bf16 v[74:77], v[106:109], v[196:199], v[74:77]
	v_mfma_f32_16x16x32_bf16 v[142:145], v[102:105], v[150:153], v[142:145]
	v_mfma_f32_16x16x32_bf16 v[138:141], v[110:113], v[150:153], v[138:141]
	v_mfma_f32_16x16x32_bf16 v[126:129], v[102:105], v[158:161], v[126:129]
	v_mfma_f32_16x16x32_bf16 v[122:125], v[110:113], v[158:161], v[122:125]
	v_mfma_f32_16x16x32_bf16 v[94:97], v[102:105], v[166:169], v[94:97]
	v_mfma_f32_16x16x32_bf16 v[90:93], v[110:113], v[166:169], v[90:93]
	v_mfma_f32_16x16x32_bf16 v[78:81], v[102:105], v[200:203], v[78:81]
	v_mfma_f32_16x16x32_bf16 v[74:77], v[110:113], v[200:203], v[74:77]
	s_barrier
	s_setprio 0
	s_add_i32 s20, s65, s52
	v_lshl_add_u64 v[220:221], s[46:47], 0, v[176:177]
	s_mov_b32 m0, s20
	ds_read_b128 v[204:207], v222
	ds_read_b128 v[208:211], v222 offset:1024
	ds_read_b128 v[212:215], v222 offset:2048
	ds_read_b128 v[216:219], v222 offset:3072
	global_load_lds_dwordx4 v[220:221], off
	v_lshl_add_u64 v[224:225], s[46:47], 0, v[180:181]
	s_add_i32 m0, s20, 0x2000
	s_nop 0
	global_load_lds_dwordx4 v[224:225], off
	s_setprio 1
	s_barrier
	s_waitcnt lgkmcnt(0)
	v_mfma_f32_16x16x32_bf16 v[134:137], v[204:207], v[146:149], v[134:137]
	v_mfma_f32_16x16x32_bf16 v[130:133], v[212:215], v[146:149], v[130:133]
	v_mfma_f32_16x16x32_bf16 v[118:121], v[204:207], v[154:157], v[118:121]
	v_mfma_f32_16x16x32_bf16 v[114:117], v[212:215], v[154:157], v[114:117]
	v_mfma_f32_16x16x32_bf16 v[86:89], v[204:207], v[162:165], v[86:89]
	v_mfma_f32_16x16x32_bf16 v[82:85], v[212:215], v[162:165], v[82:85]
	v_mfma_f32_16x16x32_bf16 v[70:73], v[204:207], v[196:199], v[70:73]
	v_mfma_f32_16x16x32_bf16 v[66:69], v[212:215], v[196:199], v[66:69]
	v_mfma_f32_16x16x32_bf16 v[134:137], v[208:211], v[150:153], v[134:137]
	v_mfma_f32_16x16x32_bf16 v[130:133], v[216:219], v[150:153], v[130:133]
	v_mfma_f32_16x16x32_bf16 v[118:121], v[208:211], v[158:161], v[118:121]
	v_mfma_f32_16x16x32_bf16 v[114:117], v[216:219], v[158:161], v[114:117]
	v_mfma_f32_16x16x32_bf16 v[86:89], v[208:211], v[166:169], v[86:89]
	v_mfma_f32_16x16x32_bf16 v[82:85], v[216:219], v[166:169], v[82:85]
	v_mfma_f32_16x16x32_bf16 v[70:73], v[208:211], v[200:203], v[70:73]
	v_mfma_f32_16x16x32_bf16 v[66:69], v[216:219], v[200:203], v[66:69]
	s_barrier
	s_setprio 0
	s_mov_b32 m0, s53
	v_lshl_add_u64 v[226:227], s[18:19], 0, v[174:175]
	ds_read_b128 v[146:149], v185 offset:16384
	ds_read_b128 v[150:153], v185 offset:17408
	ds_read_b128 v[154:157], v185 offset:18432
	ds_read_b128 v[158:161], v185 offset:19456
	ds_read_b128 v[162:165], v185 offset:20480
	ds_read_b128 v[166:169], v185 offset:21504
	ds_read_b128 v[196:199], v185 offset:22528
	ds_read_b128 v[200:203], v185 offset:23552
	global_load_lds_dwordx4 v[226:227], off
	v_lshl_add_u64 v[228:229], s[18:19], 0, v[178:179]
	s_mov_b32 m0, s54
	s_nop 0
	global_load_lds_dwordx4 v[228:229], off
	s_setprio 1
	s_barrier
	s_waitcnt lgkmcnt(0)
	v_mfma_f32_16x16x32_bf16 v[62:65], v[98:101], v[146:149], v[62:65]
	v_mfma_f32_16x16x32_bf16 v[58:61], v[106:109], v[146:149], v[58:61]
	v_mfma_f32_16x16x32_bf16 v[46:49], v[98:101], v[154:157], v[46:49]
	v_mfma_f32_16x16x32_bf16 v[42:45], v[106:109], v[154:157], v[42:45]
	v_mfma_f32_16x16x32_bf16 v[30:33], v[98:101], v[162:165], v[30:33]
	v_mfma_f32_16x16x32_bf16 v[26:29], v[106:109], v[162:165], v[26:29]
	v_mfma_f32_16x16x32_bf16 v[14:17], v[98:101], v[196:199], v[14:17]
	v_mfma_f32_16x16x32_bf16 v[10:13], v[106:109], v[196:199], v[10:13]
	v_mfma_f32_16x16x32_bf16 v[62:65], v[102:105], v[150:153], v[62:65]
	v_mfma_f32_16x16x32_bf16 v[58:61], v[110:113], v[150:153], v[58:61]
	v_mfma_f32_16x16x32_bf16 v[46:49], v[102:105], v[158:161], v[46:49]
	v_mfma_f32_16x16x32_bf16 v[42:45], v[110:113], v[158:161], v[42:45]
	v_mfma_f32_16x16x32_bf16 v[30:33], v[102:105], v[166:169], v[30:33]
	v_mfma_f32_16x16x32_bf16 v[26:29], v[110:113], v[166:169], v[26:29]
	v_mfma_f32_16x16x32_bf16 v[14:17], v[102:105], v[200:203], v[14:17]
	v_mfma_f32_16x16x32_bf16 v[10:13], v[110:113], v[200:203], v[10:13]
	s_barrier
	s_setprio 0
	s_add_u32 s20, s46, 0x40000
	s_addc_u32 s21, s47, 0
	s_add_i32 s74, s66, s52
	v_lshl_add_u64 v[98:99], s[20:21], 0, v[176:177]
	s_mov_b32 m0, s74
	s_nop 0
	global_load_lds_dwordx4 v[98:99], off
	v_lshl_add_u64 v[98:99], s[20:21], 0, v[180:181]
	s_add_i32 m0, s74, 0x2000
	s_nop 0
	global_load_lds_dwordx4 v[98:99], off
	s_waitcnt vmcnt(6)
	s_setprio 1
	s_barrier
	v_mfma_f32_16x16x32_bf16 v[54:57], v[204:207], v[146:149], v[54:57]
	v_mfma_f32_16x16x32_bf16 v[50:53], v[212:215], v[146:149], v[50:53]
	v_mfma_f32_16x16x32_bf16 v[38:41], v[204:207], v[154:157], v[38:41]
	v_mfma_f32_16x16x32_bf16 v[34:37], v[212:215], v[154:157], v[34:37]
	v_mfma_f32_16x16x32_bf16 v[22:25], v[204:207], v[162:165], v[22:25]
	v_mfma_f32_16x16x32_bf16 v[18:21], v[212:215], v[162:165], v[18:21]
	v_mfma_f32_16x16x32_bf16 v[6:9], v[204:207], v[196:199], v[6:9]
	v_mfma_f32_16x16x32_bf16 v[2:5], v[212:215], v[196:199], v[2:5]
	v_mfma_f32_16x16x32_bf16 v[54:57], v[208:211], v[150:153], v[54:57]
	v_mfma_f32_16x16x32_bf16 v[50:53], v[216:219], v[150:153], v[50:53]
	v_mfma_f32_16x16x32_bf16 v[38:41], v[208:211], v[158:161], v[38:41]
	v_mfma_f32_16x16x32_bf16 v[34:37], v[216:219], v[158:161], v[34:37]
	v_mfma_f32_16x16x32_bf16 v[22:25], v[208:211], v[166:169], v[22:25]
	v_mfma_f32_16x16x32_bf16 v[18:21], v[216:219], v[166:169], v[18:21]
	v_mfma_f32_16x16x32_bf16 v[6:9], v[208:211], v[200:203], v[6:9]
	v_mfma_f32_16x16x32_bf16 v[2:5], v[216:219], v[200:203], v[2:5]
	s_barrier
	s_setprio 0
	s_add_i32 s20, 0, 0x18000
	v_add_u32_e32 v110, s20, v171
	ds_read_b128 v[98:101], v110
	ds_read_b128 v[102:105], v110 offset:1024
	ds_read_b128 v[106:109], v110 offset:2048
	ds_read_b128 v[110:113], v110 offset:3072
	s_add_u32 s18, s18, 0x40000
	s_addc_u32 s19, s19, 0
	s_mov_b32 m0, s55
	v_lshl_add_u64 v[204:205], s[18:19], 0, v[174:175]
	ds_read_b128 v[146:149], v185 offset:32768
	ds_read_b128 v[150:153], v185 offset:33792
	ds_read_b128 v[154:157], v185 offset:34816
	ds_read_b128 v[158:161], v185 offset:35840
	ds_read_b128 v[162:165], v185 offset:36864
	ds_read_b128 v[166:169], v185 offset:37888
	ds_read_b128 v[196:199], v185 offset:38912
	ds_read_b128 v[200:203], v185 offset:39936
	global_load_lds_dwordx4 v[204:205], off
	v_lshl_add_u64 v[204:205], s[18:19], 0, v[178:179]
	s_mov_b32 m0, s56
	s_nop 0
	global_load_lds_dwordx4 v[204:205], off
	s_waitcnt lgkmcnt(8)
	s_setprio 1
	s_barrier
	s_waitcnt lgkmcnt(0)
	v_mfma_f32_16x16x32_bf16 v[142:145], v[98:101], v[146:149], v[142:145]
	v_mfma_f32_16x16x32_bf16 v[138:141], v[106:109], v[146:149], v[138:141]
	v_mfma_f32_16x16x32_bf16 v[126:129], v[98:101], v[154:157], v[126:129]
	v_mfma_f32_16x16x32_bf16 v[122:125], v[106:109], v[154:157], v[122:125]
	v_mfma_f32_16x16x32_bf16 v[94:97], v[98:101], v[162:165], v[94:97]
	v_mfma_f32_16x16x32_bf16 v[90:93], v[106:109], v[162:165], v[90:93]
	v_mfma_f32_16x16x32_bf16 v[78:81], v[98:101], v[196:199], v[78:81]
	v_mfma_f32_16x16x32_bf16 v[74:77], v[106:109], v[196:199], v[74:77]
	v_mfma_f32_16x16x32_bf16 v[142:145], v[102:105], v[150:153], v[142:145]
	v_mfma_f32_16x16x32_bf16 v[138:141], v[110:113], v[150:153], v[138:141]
	v_mfma_f32_16x16x32_bf16 v[126:129], v[102:105], v[158:161], v[126:129]
	v_mfma_f32_16x16x32_bf16 v[122:125], v[110:113], v[158:161], v[122:125]
	v_mfma_f32_16x16x32_bf16 v[94:97], v[102:105], v[166:169], v[94:97]
	v_mfma_f32_16x16x32_bf16 v[90:93], v[110:113], v[166:169], v[90:93]
	v_mfma_f32_16x16x32_bf16 v[78:81], v[102:105], v[200:203], v[78:81]
	v_mfma_f32_16x16x32_bf16 v[74:77], v[110:113], v[200:203], v[74:77]
	s_barrier
	s_setprio 0
	s_add_i32 s21, 0, 0x1c000
	s_add_i32 s18, s20, s52
	v_add_u32_e32 v182, s21, v171
	v_lshl_add_u64 v[220:221], v[220:221], 0, s[10:11]
	s_mov_b32 m0, s18
	ds_read_b128 v[204:207], v182
	ds_read_b128 v[208:211], v182 offset:1024
	ds_read_b128 v[212:215], v182 offset:2048
	ds_read_b128 v[216:219], v182 offset:3072
	global_load_lds_dwordx4 v[220:221], off
	v_lshl_add_u64 v[220:221], v[224:225], 0, s[10:11]
	s_add_i32 m0, s18, 0x2000
	s_nop 0
	global_load_lds_dwordx4 v[220:221], off
	s_setprio 1
	s_barrier
	s_waitcnt lgkmcnt(0)
	v_mfma_f32_16x16x32_bf16 v[134:137], v[204:207], v[146:149], v[134:137]
	v_mfma_f32_16x16x32_bf16 v[130:133], v[212:215], v[146:149], v[130:133]
	v_mfma_f32_16x16x32_bf16 v[118:121], v[204:207], v[154:157], v[118:121]
	v_mfma_f32_16x16x32_bf16 v[114:117], v[212:215], v[154:157], v[114:117]
	v_mfma_f32_16x16x32_bf16 v[86:89], v[204:207], v[162:165], v[86:89]
	v_mfma_f32_16x16x32_bf16 v[82:85], v[212:215], v[162:165], v[82:85]
	v_mfma_f32_16x16x32_bf16 v[70:73], v[204:207], v[196:199], v[70:73]
	v_mfma_f32_16x16x32_bf16 v[66:69], v[212:215], v[196:199], v[66:69]
	v_mfma_f32_16x16x32_bf16 v[134:137], v[208:211], v[150:153], v[134:137]
	v_mfma_f32_16x16x32_bf16 v[130:133], v[216:219], v[150:153], v[130:133]
	v_mfma_f32_16x16x32_bf16 v[118:121], v[208:211], v[158:161], v[118:121]
	v_mfma_f32_16x16x32_bf16 v[114:117], v[216:219], v[158:161], v[114:117]
	v_mfma_f32_16x16x32_bf16 v[86:89], v[208:211], v[166:169], v[86:89]
	v_mfma_f32_16x16x32_bf16 v[82:85], v[216:219], v[166:169], v[82:85]
	v_mfma_f32_16x16x32_bf16 v[70:73], v[208:211], v[200:203], v[70:73]
	v_mfma_f32_16x16x32_bf16 v[66:69], v[216:219], v[200:203], v[66:69]
	s_barrier
	s_setprio 0
	s_mov_b32 m0, s62
	v_lshl_add_u64 v[220:221], v[226:227], 0, s[10:11]
	ds_read_b128 v[146:149], v185 offset:49152
	ds_read_b128 v[150:153], v185 offset:50176
	ds_read_b128 v[154:157], v185 offset:51200
	ds_read_b128 v[158:161], v185 offset:52224
	ds_read_b128 v[162:165], v185 offset:53248
	ds_read_b128 v[166:169], v185 offset:54272
	ds_read_b128 v[196:199], v185 offset:55296
	ds_read_b128 v[200:203], v185 offset:56320
	global_load_lds_dwordx4 v[220:221], off
	v_lshl_add_u64 v[220:221], v[228:229], 0, s[10:11]
	s_mov_b32 m0, s63
	s_nop 0
	global_load_lds_dwordx4 v[220:221], off
	s_setprio 1
	s_barrier
	s_waitcnt lgkmcnt(0)
	v_mfma_f32_16x16x32_bf16 v[62:65], v[98:101], v[146:149], v[62:65]
	v_mfma_f32_16x16x32_bf16 v[58:61], v[106:109], v[146:149], v[58:61]
	v_mfma_f32_16x16x32_bf16 v[46:49], v[98:101], v[154:157], v[46:49]
	v_mfma_f32_16x16x32_bf16 v[42:45], v[106:109], v[154:157], v[42:45]
	v_mfma_f32_16x16x32_bf16 v[30:33], v[98:101], v[162:165], v[30:33]
	v_mfma_f32_16x16x32_bf16 v[26:29], v[106:109], v[162:165], v[26:29]
	v_mfma_f32_16x16x32_bf16 v[14:17], v[98:101], v[196:199], v[14:17]
	v_mfma_f32_16x16x32_bf16 v[10:13], v[106:109], v[196:199], v[10:13]
	v_mfma_f32_16x16x32_bf16 v[62:65], v[102:105], v[150:153], v[62:65]
	v_mfma_f32_16x16x32_bf16 v[58:61], v[110:113], v[150:153], v[58:61]
	v_mfma_f32_16x16x32_bf16 v[46:49], v[102:105], v[158:161], v[46:49]
	v_mfma_f32_16x16x32_bf16 v[42:45], v[110:113], v[158:161], v[42:45]
	v_mfma_f32_16x16x32_bf16 v[30:33], v[102:105], v[166:169], v[30:33]
	v_mfma_f32_16x16x32_bf16 v[26:29], v[110:113], v[166:169], v[26:29]
	v_mfma_f32_16x16x32_bf16 v[14:17], v[102:105], v[200:203], v[14:17]
	v_mfma_f32_16x16x32_bf16 v[10:13], v[110:113], v[200:203], v[10:13]
	s_barrier
	s_setprio 0
	s_add_u32 s18, s46, 0x40080
	s_addc_u32 s19, s47, 0
	s_add_i32 s20, s21, s52
	v_lshl_add_u64 v[98:99], s[18:19], 0, v[176:177]
	s_mov_b32 m0, s20
	s_nop 0
	global_load_lds_dwordx4 v[98:99], off
	v_lshl_add_u64 v[98:99], s[18:19], 0, v[180:181]
	s_add_i32 m0, s20, 0x2000
	s_nop 0
	global_load_lds_dwordx4 v[98:99], off
	s_waitcnt vmcnt(6)
	s_setprio 1
	s_barrier
	v_mfma_f32_16x16x32_bf16 v[54:57], v[204:207], v[146:149], v[54:57]
	v_mfma_f32_16x16x32_bf16 v[50:53], v[212:215], v[146:149], v[50:53]
	v_mfma_f32_16x16x32_bf16 v[38:41], v[204:207], v[154:157], v[38:41]
	v_mfma_f32_16x16x32_bf16 v[34:37], v[212:215], v[154:157], v[34:37]
	v_mfma_f32_16x16x32_bf16 v[22:25], v[204:207], v[162:165], v[22:25]
	v_mfma_f32_16x16x32_bf16 v[18:21], v[212:215], v[162:165], v[18:21]
	v_mfma_f32_16x16x32_bf16 v[6:9], v[204:207], v[196:199], v[6:9]
	v_mfma_f32_16x16x32_bf16 v[2:5], v[212:215], v[196:199], v[2:5]
	v_mfma_f32_16x16x32_bf16 v[54:57], v[208:211], v[150:153], v[54:57]
	v_mfma_f32_16x16x32_bf16 v[50:53], v[216:219], v[150:153], v[50:53]
	v_mfma_f32_16x16x32_bf16 v[38:41], v[208:211], v[158:161], v[38:41]
	v_mfma_f32_16x16x32_bf16 v[34:37], v[216:219], v[158:161], v[34:37]
	v_mfma_f32_16x16x32_bf16 v[22:25], v[208:211], v[166:169], v[22:25]
	v_mfma_f32_16x16x32_bf16 v[18:21], v[216:219], v[166:169], v[18:21]
	v_mfma_f32_16x16x32_bf16 v[6:9], v[208:211], v[200:203], v[6:9]
	v_mfma_f32_16x16x32_bf16 v[2:5], v[216:219], v[200:203], v[2:5]
	s_barrier
	s_setprio 0
	s_add_i32 s73, s73, 2
	s_add_u32 s44, s44, 0x100
	s_addc_u32 s45, s45, 0
	s_add_u32 s71, s71, 0x100
	s_addc_u32 s72, s72, 0
	s_cmp_gt_u32 s73, 13
	s_cbranch_scc0 .LBB0_2845
	s_ashr_i32 s18, s42, 3
	s_mul_hi_i32 s19, s18, 0x9000
	s_mul_i32 s18, s18, 0x9000
	s_add_u32 s20, s58, s18
	s_addc_u32 s21, s59, s19
	s_lshl_b32 s44, s0, 8
	v_lshl_add_u32 v220, s42, 8, v1
	s_ashr_i32 s45, s44, 31
	s_lshl_b64 s[18:19], s[44:45], 2
	v_ashrrev_i32_e32 v221, 31, v220
	v_lshl_add_u64 v[146:147], s[44:45], 1, v[186:187]
	v_lshlrev_b64 v[98:99], 11, v[220:221]
	s_add_u32 s18, s20, s18
	v_lshl_add_u64 v[98:99], v[146:147], 0, v[98:99]
	s_addc_u32 s19, s21, s19
	v_lshlrev_b32_e32 v182, 2, v184
	global_load_dwordx4 v[224:227], v[98:99], off
	global_load_dwordx4 v[234:237], v[98:99], off offset:256
	v_lshl_add_u64 v[98:99], s[18:19], 0, v[182:183]
	v_add_co_u32_e32 v102, vcc, s68, v98
	v_lshl_add_u64 v[100:101], v[98:99], 0, s[16:17]
	s_nop 0
	v_addc_co_u32_e32 v103, vcc, 0, v99, vcc
	global_load_dwordx4 v[198:201], v[102:103], off
	global_load_dwordx4 v[238:241], v[100:101], off offset:16
	global_load_dwordx4 v[202:205], v[102:103], off offset:512
	v_lshl_add_u64 v[100:101], v[98:99], 0, s[24:25]
	global_load_dwordx4 v[242:245], v[100:101], off offset:16
	v_add_co_u32_e32 v100, vcc, s67, v98
	v_or_b32_e32 v218, 16, v220
	s_nop 0
	v_addc_co_u32_e32 v101, vcc, 0, v99, vcc
	global_load_dwordx4 v[110:113], v[100:101], off
	global_load_dwordx4 v[106:109], v[100:101], off offset:512
	v_lshl_add_u64 v[100:101], v[98:99], 0, s[12:13]
	v_lshl_add_u64 v[98:99], v[98:99], 0, s[14:15]
	global_load_dwordx4 v[102:105], v[100:101], off offset:16
	v_or_b32_e32 v216, 32, v220
	global_load_dwordx4 v[98:101], v[98:99], off offset:16
	v_or_b32_e32 v214, 48, v220
	v_ashrrev_i32_e32 v219, 31, v218
	v_ashrrev_i32_e32 v217, 31, v216
	v_ashrrev_i32_e32 v215, 31, v214
	v_lshlrev_b64 v[148:149], 11, v[218:219]
	v_lshlrev_b64 v[150:151], 11, v[216:217]
	v_lshlrev_b64 v[152:153], 11, v[214:215]
	v_lshl_add_u64 v[148:149], v[146:147], 0, v[148:149]
	v_lshl_add_u64 v[150:151], v[146:147], 0, v[150:151]
	v_lshl_add_u64 v[146:147], v[146:147], 0, v[152:153]
	global_load_dwordx4 v[166:169], v[148:149], off
	global_load_dwordx4 v[162:165], v[148:149], off offset:256
	global_load_dwordx4 v[158:161], v[150:151], off
	global_load_dwordx4 v[154:157], v[150:151], off offset:256
	s_nop 0
	global_load_dwordx4 v[150:153], v[146:147], off
	s_nop 0
	global_load_dwordx4 v[146:149], v[146:147], off offset:256
	v_or_b32_e32 v196, s44, v184
	v_mov_b32_e32 v197, s45
	s_lshl_b32 s42, s0, 2
	s_ashr_i32 s43, s42, 31
	s_waitcnt vmcnt(0)
	v_lshlrev_b32_e32 v228, 16, v224
	v_and_b32_e32 v229, 0xffff0000, v224
	v_lshlrev_b32_e32 v224, 16, v225
	v_and_b32_e32 v225, 0xffff0000, v225
	v_lshlrev_b32_e32 v250, 16, v236
	v_and_b32_e32 v251, 0xffff0000, v236
	v_lshlrev_b32_e32 v248, 16, v226
	v_and_b32_e32 v249, 0xffff0000, v226
	v_lshlrev_b32_e32 v246, 16, v234
	v_and_b32_e32 v247, 0xffff0000, v234
	v_lshlrev_b32_e32 v234, 16, v235
	v_and_b32_e32 v235, 0xffff0000, v235
	v_pk_add_f32 v[210:211], v[202:203], 1.0 op_sel_hi:[1,0]
	v_pk_add_f32 v[206:207], v[204:205], 1.0 op_sel_hi:[1,0]
	v_pk_add_f32 v[208:209], v[200:201], 1.0 op_sel_hi:[1,0]
	v_pk_fma_f32 v[144:145], v[144:145], v[112:113], v[224:225]
	v_pk_fma_f32 v[142:143], v[142:143], v[110:111], v[228:229]
	v_pk_fma_f32 v[134:135], v[134:135], v[106:107], v[246:247]
	v_pk_fma_f32 v[136:137], v[136:137], v[108:109], v[234:235]
	v_pk_fma_f32 v[138:139], v[138:139], v[102:103], v[248:249]
	v_pk_mul_f32 v[234:235], v[210:211], v[134:135]
	v_pk_fma_f32 v[224:225], v[130:131], v[98:99], v[250:251]
	v_lshlrev_b32_e32 v130, 16, v227
	v_and_b32_e32 v131, 0xffff0000, v227
	v_pk_fma_f32 v[140:141], v[140:141], v[104:105], v[130:131]
	v_lshlrev_b32_e32 v130, 16, v237
	v_and_b32_e32 v131, 0xffff0000, v237
	v_pk_fma_f32 v[236:237], v[132:133], v[100:101], v[130:131]
	v_lshlrev_b64 v[130:131], 10, v[220:221]
	v_lshl_add_u64 v[130:131], v[130:131], 0, v[196:197]
	v_lshlrev_b64 v[248:249], 1, v[130:131]
	v_lshl_add_u64 v[250:251], s[28:29], 0, v[248:249]
	v_cvt_pk_bf16_f32 v130, v142, v143
	v_cvt_pk_bf16_f32 v131, v144, v145
	v_cvt_pk_bf16_f32 v132, v138, v139
	v_cvt_pk_bf16_f32 v133, v140, v141
	global_store_dwordx4 v[250:251], v[130:133], off nt
	v_pk_add_f32 v[200:201], v[240:241], 1.0 op_sel_hi:[1,0]
	v_pk_mul_f32 v[240:241], v[206:207], v[136:137]
	v_cvt_pk_bf16_f32 v130, v134, v135
	v_cvt_pk_bf16_f32 v131, v136, v137
	v_cvt_pk_bf16_f32 v132, v224, v225
	v_cvt_pk_bf16_f32 v133, v236, v237
	global_store_dwordx4 v[250:251], v[130:133], off offset:256 nt
	v_pk_add_f32 v[204:205], v[238:239], 1.0 op_sel_hi:[1,0]
	v_pk_add_f32 v[202:203], v[242:243], 1.0 op_sel_hi:[1,0]
	v_pk_mul_f32 v[132:133], v[134:135], v[134:135]
	v_pk_mul_f32 v[134:135], v[136:137], v[136:137]
	v_pk_fma_f32 v[132:133], v[142:143], v[142:143], v[132:133]
	v_pk_fma_f32 v[134:135], v[144:145], v[144:145], v[134:135]
	v_add_f32_e32 v132, v132, v133
	v_pk_mul_f32 v[136:137], v[224:225], v[224:225]
	v_add_f32_e32 v132, v134, v132
	v_pk_fma_f32 v[136:137], v[138:139], v[138:139], v[136:137]
	v_add_f32_e32 v132, v135, v132
	v_pk_mul_f32 v[242:243], v[204:205], v[138:139]
	v_pk_mul_f32 v[138:139], v[236:237], v[236:237]
	v_add_f32_e32 v132, v136, v132
	v_pk_fma_f32 v[138:139], v[140:141], v[140:141], v[138:139]
	v_add_f32_e32 v132, v137, v132
	v_add_f32_e32 v132, v138, v132
	v_and_b32_e32 v133, 64, v223
	v_add_f32_e32 v134, v139, v132
	v_xor_b32_e32 v132, 16, v223
	v_add_u32_e32 v135, 64, v133
	v_cmp_lt_i32_e32 vcc, v132, v135
	v_pk_add_f32 v[212:213], v[198:199], 1.0 op_sel_hi:[1,0]
	v_pk_mul_f32 v[238:239], v[208:209], v[144:145]
	v_cndmask_b32_e32 v132, v223, v132, vcc
	v_pk_mul_f32 v[228:229], v[212:213], v[142:143]
	v_lshlrev_b32_e32 v142, 2, v132
	v_pk_mul_f32 v[226:227], v[200:201], v[140:141]
	ds_bpermute_b32 v136, v142, v134
	v_lshl_add_u64 v[248:249], s[6:7], 0, v[248:249]
	v_cvt_pk_bf16_f32 v130, v228, v229
	v_cvt_pk_bf16_f32 v131, v238, v239
	v_cvt_pk_bf16_f32 v132, v242, v243
	v_cvt_pk_bf16_f32 v133, v226, v227
	global_store_dwordx4 v[248:249], v[130:133], off nt
	v_pk_add_f32 v[198:199], v[244:245], 1.0 op_sel_hi:[1,0]
	v_pk_mul_f32 v[244:245], v[202:203], v[224:225]
	v_xor_b32_e32 v131, 32, v223
	v_cmp_lt_i32_e32 vcc, v131, v135
	s_waitcnt lgkmcnt(0)
	v_add_f32_e32 v130, v134, v136
	v_pk_mul_f32 v[246:247], v[198:199], v[236:237]
	v_cndmask_b32_e32 v131, v223, v131, vcc
	v_lshlrev_b32_e32 v143, 2, v131
	ds_bpermute_b32 v131, v143, v130
	v_cvt_pk_bf16_f32 v132, v234, v235
	v_cvt_pk_bf16_f32 v133, v240, v241
	v_cvt_pk_bf16_f32 v134, v244, v245
	v_cvt_pk_bf16_f32 v135, v246, v247
	global_store_dwordx4 v[248:249], v[132:135], off offset:256 nt
	s_and_saveexec_b64 s[18:19], s[2:3]
	s_cbranch_execz .LBB0_2848
	s_waitcnt lgkmcnt(0)
	v_add_f32_e32 v132, v130, v131
	v_lshlrev_b64 v[130:131], 6, v[220:221]
	v_lshl_add_u64 v[130:131], s[8:9], 0, v[130:131]
	v_lshl_add_u64 v[130:131], s[42:43], 2, v[130:131]
	s_lshl_b32 s0, s61, 2
	v_lshl_add_u64 v[130:131], v[130:131], 0, s[0:1]
	global_store_dword v[130:131], v132, off

.LBB0_3264:
	s_ashr_i32 s11, s10, 31
	v_cmp_lt_i64_e32 vcc, s[12:13], v[162:163]
	s_lshl_b64 s[12:13], s[10:11], 19
	s_add_u32 s12, s36, s12
	s_addc_u32 s13, s37, s13
	s_and_b64 s[14:15], vcc, exec
	s_cselect_b32 s11, s13, s25
	s_cselect_b32 s57, s12, s24
	s_ashr_i32 s9, s8, 31
	s_lshl_b64 s[14:15], s[8:9], 19
	s_add_u32 s14, s38, s14
	s_addc_u32 s15, s39, s15
	s_and_b64 s[18:19], vcc, exec
	s_cselect_b32 s9, s15, s35
	s_cselect_b32 s60, s14, s34
	s_add_u32 s24, s24, 0x40080
	s_addc_u32 s25, s25, 0
	s_add_u32 s61, s34, 0x100
	s_addc_u32 s62, s35, 0
	s_mov_b32 s63, -2
	ds_read_b128 v[130:133], v171
	ds_read_b128 v[134:137], v171 offset:1024
	ds_read_b128 v[138:141], v171 offset:2048
	ds_read_b128 v[142:145], v171 offset:3072
	s_add_u32 s18, s24, 0xfffc0080
	s_addc_u32 s19, s25, -1
	s_cmp_eq_u32 s63, 12
	s_cselect_b32 s19, s11, s19
	s_cselect_b32 s18, s57, s18
	s_cselect_b32 s35, s9, s62
	s_cselect_b32 s34, s60, s61
	v_lshl_add_u64 v[174:175], s[24:25], 0, v[158:159]
	s_add_i32 m0, s43, 0xc000
	ds_read_b128 v[166:169], v173
	ds_read_b128 v[178:181], v173 offset:1024
	ds_read_b128 v[182:185], v173 offset:2048
	ds_read_b128 v[186:189], v173 offset:3072
	ds_read_b128 v[190:193], v173 offset:4096
	ds_read_b128 v[194:197], v173 offset:5120
	ds_read_b128 v[198:201], v173 offset:6144
	ds_read_b128 v[202:205], v173 offset:7168
	global_load_lds_dwordx4 v[174:175], off
	v_lshl_add_u64 v[174:175], s[24:25], 0, v[160:161]
	s_add_i32 m0, s43, 0xe000
	s_nop 0
	global_load_lds_dwordx4 v[174:175], off
	s_waitcnt lgkmcnt(8)
	s_setprio 1
	s_barrier
	s_waitcnt lgkmcnt(0)
	v_mfma_f32_16x16x32_bf16 v[126:129], v[130:133], v[166:169], 0
	v_mfma_f32_16x16x32_bf16 v[122:125], v[138:141], v[166:169], 0
	v_mfma_f32_16x16x32_bf16 v[110:113], v[130:133], v[182:185], 0
	v_mfma_f32_16x16x32_bf16 v[106:109], v[138:141], v[182:185], 0
	v_mfma_f32_16x16x32_bf16 v[94:97], v[130:133], v[190:193], 0
	v_mfma_f32_16x16x32_bf16 v[90:93], v[138:141], v[190:193], 0
	v_mfma_f32_16x16x32_bf16 v[78:81], v[130:133], v[198:201], 0
	v_mfma_f32_16x16x32_bf16 v[74:77], v[138:141], v[198:201], 0
	v_mfma_f32_16x16x32_bf16 v[126:129], v[134:137], v[178:181], v[126:129]
	v_mfma_f32_16x16x32_bf16 v[122:125], v[142:145], v[178:181], v[122:125]
	v_mfma_f32_16x16x32_bf16 v[110:113], v[134:137], v[186:189], v[110:113]
	v_mfma_f32_16x16x32_bf16 v[106:109], v[142:145], v[186:189], v[106:109]
	v_mfma_f32_16x16x32_bf16 v[94:97], v[134:137], v[194:197], v[94:97]
	v_mfma_f32_16x16x32_bf16 v[90:93], v[142:145], v[194:197], v[90:93]
	v_mfma_f32_16x16x32_bf16 v[78:81], v[134:137], v[202:205], v[78:81]
	v_mfma_f32_16x16x32_bf16 v[74:77], v[142:145], v[202:205], v[74:77]
	s_barrier
	s_setprio 0
	s_add_i32 s20, s54, s42
	v_lshl_add_u64 v[174:175], s[34:35], 0, v[150:151]
	s_mov_b32 m0, s20
	ds_read_b128 v[206:209], v177
	ds_read_b128 v[210:213], v177 offset:1024
	ds_read_b128 v[214:217], v177 offset:2048
	ds_read_b128 v[218:221], v177 offset:3072
	global_load_lds_dwordx4 v[174:175], off
	v_lshl_add_u64 v[222:223], s[34:35], 0, v[146:147]
	s_add_i32 m0, s20, 0x2000
	s_nop 0
	global_load_lds_dwordx4 v[222:223], off
	s_setprio 1
	s_barrier
	s_waitcnt lgkmcnt(0)
	v_mfma_f32_16x16x32_bf16 v[118:121], v[206:209], v[166:169], 0
	v_mfma_f32_16x16x32_bf16 v[114:117], v[214:217], v[166:169], 0
	v_mfma_f32_16x16x32_bf16 v[102:105], v[206:209], v[182:185], 0
	v_mfma_f32_16x16x32_bf16 v[98:101], v[214:217], v[182:185], 0
	v_mfma_f32_16x16x32_bf16 v[86:89], v[206:209], v[190:193], 0
	v_mfma_f32_16x16x32_bf16 v[82:85], v[214:217], v[190:193], 0
	v_mfma_f32_16x16x32_bf16 v[70:73], v[206:209], v[198:201], 0
	v_mfma_f32_16x16x32_bf16 v[66:69], v[214:217], v[198:201], 0
	v_mfma_f32_16x16x32_bf16 v[118:121], v[210:213], v[178:181], v[118:121]
	v_mfma_f32_16x16x32_bf16 v[114:117], v[218:221], v[178:181], v[114:117]
	v_mfma_f32_16x16x32_bf16 v[102:105], v[210:213], v[186:189], v[102:105]
	v_mfma_f32_16x16x32_bf16 v[98:101], v[218:221], v[186:189], v[98:101]
	v_mfma_f32_16x16x32_bf16 v[86:89], v[210:213], v[194:197], v[86:89]
	v_mfma_f32_16x16x32_bf16 v[82:85], v[218:221], v[194:197], v[82:85]
	v_mfma_f32_16x16x32_bf16 v[70:73], v[210:213], v[202:205], v[70:73]
	v_mfma_f32_16x16x32_bf16 v[66:69], v[218:221], v[202:205], v[66:69]
	s_barrier
	s_setprio 0
	s_mov_b32 m0, s43
	v_lshl_add_u64 v[224:225], s[18:19], 0, v[152:153]
	ds_read_b128 v[166:169], v173 offset:16384
	ds_read_b128 v[178:181], v173 offset:17408
	ds_read_b128 v[182:185], v173 offset:18432
	ds_read_b128 v[186:189], v173 offset:19456
	ds_read_b128 v[190:193], v173 offset:20480
	ds_read_b128 v[194:197], v173 offset:21504
	ds_read_b128 v[198:201], v173 offset:22528
	ds_read_b128 v[202:205], v173 offset:23552
	global_load_lds_dwordx4 v[224:225], off
	v_lshl_add_u64 v[226:227], s[18:19], 0, v[148:149]
	s_mov_b32 m0, s44
	s_nop 0
	global_load_lds_dwordx4 v[226:227], off
	s_setprio 1
	s_barrier
	s_waitcnt lgkmcnt(0)
	v_mfma_f32_16x16x32_bf16 v[62:65], v[130:133], v[166:169], 0
	v_mfma_f32_16x16x32_bf16 v[58:61], v[138:141], v[166:169], 0
	v_mfma_f32_16x16x32_bf16 v[46:49], v[130:133], v[182:185], 0
	v_mfma_f32_16x16x32_bf16 v[42:45], v[138:141], v[182:185], 0
	v_mfma_f32_16x16x32_bf16 v[30:33], v[130:133], v[190:193], 0
	v_mfma_f32_16x16x32_bf16 v[26:29], v[138:141], v[190:193], 0
	v_mfma_f32_16x16x32_bf16 v[14:17], v[130:133], v[198:201], 0
	v_mfma_f32_16x16x32_bf16 v[10:13], v[138:141], v[198:201], 0
	v_mfma_f32_16x16x32_bf16 v[62:65], v[134:137], v[178:181], v[62:65]
	v_mfma_f32_16x16x32_bf16 v[58:61], v[142:145], v[178:181], v[58:61]
	v_mfma_f32_16x16x32_bf16 v[46:49], v[134:137], v[186:189], v[46:49]
	v_mfma_f32_16x16x32_bf16 v[42:45], v[142:145], v[186:189], v[42:45]
	v_mfma_f32_16x16x32_bf16 v[30:33], v[134:137], v[194:197], v[30:33]
	v_mfma_f32_16x16x32_bf16 v[26:29], v[142:145], v[194:197], v[26:29]
	v_mfma_f32_16x16x32_bf16 v[14:17], v[134:137], v[202:205], v[14:17]
	v_mfma_f32_16x16x32_bf16 v[10:13], v[142:145], v[202:205], v[10:13]
	s_barrier
	s_setprio 0
	s_add_u32 s20, s34, 0x40000
	s_addc_u32 s21, s35, 0
	s_add_i32 s64, s55, s42
	v_lshl_add_u64 v[130:131], s[20:21], 0, v[150:151]
	s_mov_b32 m0, s64
	s_nop 0
	global_load_lds_dwordx4 v[130:131], off
	v_lshl_add_u64 v[130:131], s[20:21], 0, v[146:147]
	s_add_i32 m0, s64, 0x2000
	s_nop 0
	global_load_lds_dwordx4 v[130:131], off
	s_waitcnt vmcnt(6)
	s_setprio 1
	s_barrier
	v_mfma_f32_16x16x32_bf16 v[54:57], v[206:209], v[166:169], 0
	v_mfma_f32_16x16x32_bf16 v[50:53], v[214:217], v[166:169], 0
	v_mfma_f32_16x16x32_bf16 v[38:41], v[206:209], v[182:185], 0
	v_mfma_f32_16x16x32_bf16 v[34:37], v[214:217], v[182:185], 0
	v_mfma_f32_16x16x32_bf16 v[22:25], v[206:209], v[190:193], 0
	v_mfma_f32_16x16x32_bf16 v[18:21], v[214:217], v[190:193], 0
	v_mfma_f32_16x16x32_bf16 v[6:9], v[206:209], v[198:201], 0
	v_mfma_f32_16x16x32_bf16 v[2:5], v[214:217], v[198:201], 0
	v_mfma_f32_16x16x32_bf16 v[54:57], v[210:213], v[178:181], v[54:57]
	v_mfma_f32_16x16x32_bf16 v[50:53], v[218:221], v[178:181], v[50:53]
	v_mfma_f32_16x16x32_bf16 v[38:41], v[210:213], v[186:189], v[38:41]
	v_mfma_f32_16x16x32_bf16 v[34:37], v[218:221], v[186:189], v[34:37]
	v_mfma_f32_16x16x32_bf16 v[22:25], v[210:213], v[194:197], v[22:25]
	v_mfma_f32_16x16x32_bf16 v[18:21], v[218:221], v[194:197], v[18:21]
	v_mfma_f32_16x16x32_bf16 v[6:9], v[210:213], v[202:205], v[6:9]
	v_mfma_f32_16x16x32_bf16 v[2:5], v[218:221], v[202:205], v[2:5]
	s_barrier
	s_setprio 0
	s_add_i32 s20, 0, 0x18000
	v_add_u32_e32 v142, s20, v157
	ds_read_b128 v[130:133], v142
	ds_read_b128 v[134:137], v142 offset:1024
	ds_read_b128 v[138:141], v142 offset:2048
	ds_read_b128 v[142:145], v142 offset:3072
	s_add_u32 s18, s18, 0x40000
	s_addc_u32 s19, s19, 0
	s_mov_b32 m0, s45
	v_lshl_add_u64 v[206:207], s[18:19], 0, v[152:153]
	ds_read_b128 v[166:169], v173 offset:32768
	ds_read_b128 v[178:181], v173 offset:33792
	ds_read_b128 v[182:185], v173 offset:34816
	ds_read_b128 v[186:189], v173 offset:35840
	ds_read_b128 v[190:193], v173 offset:36864
	ds_read_b128 v[194:197], v173 offset:37888
	ds_read_b128 v[198:201], v173 offset:38912
	ds_read_b128 v[202:205], v173 offset:39936
	global_load_lds_dwordx4 v[206:207], off
	v_lshl_add_u64 v[206:207], s[18:19], 0, v[148:149]
	s_mov_b32 m0, s46
	s_nop 0
	global_load_lds_dwordx4 v[206:207], off
	s_waitcnt lgkmcnt(8)
	s_setprio 1
	s_barrier
	s_waitcnt lgkmcnt(0)
	v_mfma_f32_16x16x32_bf16 v[126:129], v[130:133], v[166:169], v[126:129]
	v_mfma_f32_16x16x32_bf16 v[122:125], v[138:141], v[166:169], v[122:125]
	v_mfma_f32_16x16x32_bf16 v[110:113], v[130:133], v[182:185], v[110:113]
	v_mfma_f32_16x16x32_bf16 v[106:109], v[138:141], v[182:185], v[106:109]
	v_mfma_f32_16x16x32_bf16 v[94:97], v[130:133], v[190:193], v[94:97]
	v_mfma_f32_16x16x32_bf16 v[90:93], v[138:141], v[190:193], v[90:93]
	v_mfma_f32_16x16x32_bf16 v[78:81], v[130:133], v[198:201], v[78:81]
	v_mfma_f32_16x16x32_bf16 v[74:77], v[138:141], v[198:201], v[74:77]
	v_mfma_f32_16x16x32_bf16 v[126:129], v[134:137], v[178:181], v[126:129]
	v_mfma_f32_16x16x32_bf16 v[122:125], v[142:145], v[178:181], v[122:125]
	v_mfma_f32_16x16x32_bf16 v[110:113], v[134:137], v[186:189], v[110:113]
	v_mfma_f32_16x16x32_bf16 v[106:109], v[142:145], v[186:189], v[106:109]
	v_mfma_f32_16x16x32_bf16 v[94:97], v[134:137], v[194:197], v[94:97]
	v_mfma_f32_16x16x32_bf16 v[90:93], v[142:145], v[194:197], v[90:93]
	v_mfma_f32_16x16x32_bf16 v[78:81], v[134:137], v[202:205], v[78:81]
	v_mfma_f32_16x16x32_bf16 v[74:77], v[142:145], v[202:205], v[74:77]
	s_barrier
	s_setprio 0
	s_add_i32 s21, 0, 0x1c000
	s_add_i32 s18, s20, s42
	v_add_u32_e32 v154, s21, v157
	v_lshl_add_u64 v[174:175], v[174:175], 0, s[6:7]
	s_mov_b32 m0, s18
	ds_read_b128 v[206:209], v154
	ds_read_b128 v[210:213], v154 offset:1024
	ds_read_b128 v[214:217], v154 offset:2048
	ds_read_b128 v[218:221], v154 offset:3072
	global_load_lds_dwordx4 v[174:175], off
	v_lshl_add_u64 v[174:175], v[222:223], 0, s[6:7]
	s_add_i32 m0, s18, 0x2000
	s_nop 0
	global_load_lds_dwordx4 v[174:175], off
	s_setprio 1
	s_barrier
	s_waitcnt lgkmcnt(0)
	v_mfma_f32_16x16x32_bf16 v[118:121], v[206:209], v[166:169], v[118:121]
	v_mfma_f32_16x16x32_bf16 v[114:117], v[214:217], v[166:169], v[114:117]
	v_mfma_f32_16x16x32_bf16 v[102:105], v[206:209], v[182:185], v[102:105]
	v_mfma_f32_16x16x32_bf16 v[98:101], v[214:217], v[182:185], v[98:101]
	v_mfma_f32_16x16x32_bf16 v[86:89], v[206:209], v[190:193], v[86:89]
	v_mfma_f32_16x16x32_bf16 v[82:85], v[214:217], v[190:193], v[82:85]
	v_mfma_f32_16x16x32_bf16 v[70:73], v[206:209], v[198:201], v[70:73]
	v_mfma_f32_16x16x32_bf16 v[66:69], v[214:217], v[198:201], v[66:69]
	v_mfma_f32_16x16x32_bf16 v[118:121], v[210:213], v[178:181], v[118:121]
	v_mfma_f32_16x16x32_bf16 v[114:117], v[218:221], v[178:181], v[114:117]
	v_mfma_f32_16x16x32_bf16 v[102:105], v[210:213], v[186:189], v[102:105]
	v_mfma_f32_16x16x32_bf16 v[98:101], v[218:221], v[186:189], v[98:101]
	v_mfma_f32_16x16x32_bf16 v[86:89], v[210:213], v[194:197], v[86:89]
	v_mfma_f32_16x16x32_bf16 v[82:85], v[218:221], v[194:197], v[82:85]
	v_mfma_f32_16x16x32_bf16 v[70:73], v[210:213], v[202:205], v[70:73]
	v_mfma_f32_16x16x32_bf16 v[66:69], v[218:221], v[202:205], v[66:69]
	s_barrier
	s_setprio 0
	s_mov_b32 m0, s50
	v_lshl_add_u64 v[174:175], v[224:225], 0, s[6:7]
	ds_read_b128 v[166:169], v173 offset:49152
	ds_read_b128 v[178:181], v173 offset:50176
	ds_read_b128 v[182:185], v173 offset:51200
	ds_read_b128 v[186:189], v173 offset:52224
	ds_read_b128 v[190:193], v173 offset:53248
	ds_read_b128 v[194:197], v173 offset:54272
	ds_read_b128 v[198:201], v173 offset:55296
	ds_read_b128 v[202:205], v173 offset:56320
	global_load_lds_dwordx4 v[174:175], off
	v_lshl_add_u64 v[174:175], v[226:227], 0, s[6:7]
	s_mov_b32 m0, s51
	s_nop 0
	global_load_lds_dwordx4 v[174:175], off
	s_setprio 1
	s_barrier
	s_waitcnt lgkmcnt(0)
	v_mfma_f32_16x16x32_bf16 v[62:65], v[130:133], v[166:169], v[62:65]
	v_mfma_f32_16x16x32_bf16 v[58:61], v[138:141], v[166:169], v[58:61]
	v_mfma_f32_16x16x32_bf16 v[46:49], v[130:133], v[182:185], v[46:49]
	v_mfma_f32_16x16x32_bf16 v[42:45], v[138:141], v[182:185], v[42:45]
	v_mfma_f32_16x16x32_bf16 v[30:33], v[130:133], v[190:193], v[30:33]
	v_mfma_f32_16x16x32_bf16 v[26:29], v[138:141], v[190:193], v[26:29]
	v_mfma_f32_16x16x32_bf16 v[14:17], v[130:133], v[198:201], v[14:17]
	v_mfma_f32_16x16x32_bf16 v[10:13], v[138:141], v[198:201], v[10:13]
	v_mfma_f32_16x16x32_bf16 v[62:65], v[134:137], v[178:181], v[62:65]
	v_mfma_f32_16x16x32_bf16 v[58:61], v[142:145], v[178:181], v[58:61]
	v_mfma_f32_16x16x32_bf16 v[46:49], v[134:137], v[186:189], v[46:49]
	v_mfma_f32_16x16x32_bf16 v[42:45], v[142:145], v[186:189], v[42:45]
	v_mfma_f32_16x16x32_bf16 v[30:33], v[134:137], v[194:197], v[30:33]
	v_mfma_f32_16x16x32_bf16 v[26:29], v[142:145], v[194:197], v[26:29]
	v_mfma_f32_16x16x32_bf16 v[14:17], v[134:137], v[202:205], v[14:17]
	v_mfma_f32_16x16x32_bf16 v[10:13], v[142:145], v[202:205], v[10:13]
	s_barrier
	s_setprio 0
	s_add_u32 s18, s34, 0x40080
	s_addc_u32 s19, s35, 0
	s_add_i32 s20, s21, s42
	v_lshl_add_u64 v[130:131], s[18:19], 0, v[150:151]
	s_mov_b32 m0, s20
	s_nop 0
	global_load_lds_dwordx4 v[130:131], off
	v_lshl_add_u64 v[130:131], s[18:19], 0, v[146:147]
	s_add_i32 m0, s20, 0x2000
	s_nop 0
	global_load_lds_dwordx4 v[130:131], off
	s_waitcnt vmcnt(6)
	s_setprio 1
	s_barrier
	v_mfma_f32_16x16x32_bf16 v[54:57], v[206:209], v[166:169], v[54:57]
	v_mfma_f32_16x16x32_bf16 v[50:53], v[214:217], v[166:169], v[50:53]
	v_mfma_f32_16x16x32_bf16 v[38:41], v[206:209], v[182:185], v[38:41]
	v_mfma_f32_16x16x32_bf16 v[34:37], v[214:217], v[182:185], v[34:37]
	v_mfma_f32_16x16x32_bf16 v[22:25], v[206:209], v[190:193], v[22:25]
	v_mfma_f32_16x16x32_bf16 v[18:21], v[214:217], v[190:193], v[18:21]
	v_mfma_f32_16x16x32_bf16 v[6:9], v[206:209], v[198:201], v[6:9]
	v_mfma_f32_16x16x32_bf16 v[2:5], v[214:217], v[198:201], v[2:5]
	v_mfma_f32_16x16x32_bf16 v[54:57], v[210:213], v[178:181], v[54:57]
	v_mfma_f32_16x16x32_bf16 v[50:53], v[218:221], v[178:181], v[50:53]
	v_mfma_f32_16x16x32_bf16 v[38:41], v[210:213], v[186:189], v[38:41]
	v_mfma_f32_16x16x32_bf16 v[34:37], v[218:221], v[186:189], v[34:37]
	v_mfma_f32_16x16x32_bf16 v[22:25], v[210:213], v[194:197], v[22:25]
	v_mfma_f32_16x16x32_bf16 v[18:21], v[218:221], v[194:197], v[18:21]
	v_mfma_f32_16x16x32_bf16 v[6:9], v[210:213], v[202:205], v[6:9]
	v_mfma_f32_16x16x32_bf16 v[2:5], v[218:221], v[202:205], v[2:5]
	s_barrier
	s_setprio 0
	s_add_i32 s63, s63, 2
	s_add_u32 s24, s24, 0x100
	s_addc_u32 s25, s25, 0
	s_add_u32 s61, s61, 0x100
	s_addc_u32 s62, s62, 0
	s_cmp_gt_u32 s63, 13

.Lp12_nopf:
	v_lshl_add_u64 v[174:175], s[24:25], 0, v[158:159]
	s_add_i32 m0, s43, 0xc000
	ds_read_b128 v[166:169], v173
	ds_read_b128 v[178:181], v173 offset:1024
	ds_read_b128 v[182:185], v173 offset:2048
	ds_read_b128 v[186:189], v173 offset:3072
	ds_read_b128 v[190:193], v173 offset:4096
	ds_read_b128 v[194:197], v173 offset:5120
	ds_read_b128 v[198:201], v173 offset:6144
	ds_read_b128 v[202:205], v173 offset:7168
	global_load_lds_dwordx4 v[174:175], off
	v_lshl_add_u64 v[174:175], s[24:25], 0, v[160:161]
	s_add_i32 m0, s43, 0xe000
	s_nop 0
	global_load_lds_dwordx4 v[174:175], off
	s_waitcnt lgkmcnt(8)
	s_setprio 1
	s_barrier
	s_waitcnt lgkmcnt(0)
	v_mfma_f32_16x16x32_bf16 v[126:129], v[130:133], v[166:169], v[126:129]
	v_mfma_f32_16x16x32_bf16 v[122:125], v[138:141], v[166:169], v[122:125]
	v_mfma_f32_16x16x32_bf16 v[110:113], v[130:133], v[182:185], v[110:113]
	v_mfma_f32_16x16x32_bf16 v[106:109], v[138:141], v[182:185], v[106:109]
	v_mfma_f32_16x16x32_bf16 v[94:97], v[130:133], v[190:193], v[94:97]
	v_mfma_f32_16x16x32_bf16 v[90:93], v[138:141], v[190:193], v[90:93]
	v_mfma_f32_16x16x32_bf16 v[78:81], v[130:133], v[198:201], v[78:81]
	v_mfma_f32_16x16x32_bf16 v[74:77], v[138:141], v[198:201], v[74:77]
	v_mfma_f32_16x16x32_bf16 v[126:129], v[134:137], v[178:181], v[126:129]
	v_mfma_f32_16x16x32_bf16 v[122:125], v[142:145], v[178:181], v[122:125]
	v_mfma_f32_16x16x32_bf16 v[110:113], v[134:137], v[186:189], v[110:113]
	v_mfma_f32_16x16x32_bf16 v[106:109], v[142:145], v[186:189], v[106:109]
	v_mfma_f32_16x16x32_bf16 v[94:97], v[134:137], v[194:197], v[94:97]
	v_mfma_f32_16x16x32_bf16 v[90:93], v[142:145], v[194:197], v[90:93]
	v_mfma_f32_16x16x32_bf16 v[78:81], v[134:137], v[202:205], v[78:81]
	v_mfma_f32_16x16x32_bf16 v[74:77], v[142:145], v[202:205], v[74:77]
	s_barrier
	s_setprio 0
	s_add_i32 s20, s54, s42
	v_lshl_add_u64 v[174:175], s[34:35], 0, v[150:151]
	s_mov_b32 m0, s20
	ds_read_b128 v[206:209], v177
	ds_read_b128 v[210:213], v177 offset:1024
	ds_read_b128 v[214:217], v177 offset:2048
	ds_read_b128 v[218:221], v177 offset:3072
	global_load_lds_dwordx4 v[174:175], off
	v_lshl_add_u64 v[222:223], s[34:35], 0, v[146:147]
	s_add_i32 m0, s20, 0x2000
	s_nop 0
	global_load_lds_dwordx4 v[222:223], off
	s_setprio 1
	s_barrier
	s_waitcnt lgkmcnt(0)
	v_mfma_f32_16x16x32_bf16 v[118:121], v[206:209], v[166:169], v[118:121]
	v_mfma_f32_16x16x32_bf16 v[114:117], v[214:217], v[166:169], v[114:117]
	v_mfma_f32_16x16x32_bf16 v[102:105], v[206:209], v[182:185], v[102:105]
	v_mfma_f32_16x16x32_bf16 v[98:101], v[214:217], v[182:185], v[98:101]
	v_mfma_f32_16x16x32_bf16 v[86:89], v[206:209], v[190:193], v[86:89]
	v_mfma_f32_16x16x32_bf16 v[82:85], v[214:217], v[190:193], v[82:85]
	v_mfma_f32_16x16x32_bf16 v[70:73], v[206:209], v[198:201], v[70:73]
	v_mfma_f32_16x16x32_bf16 v[66:69], v[214:217], v[198:201], v[66:69]
	v_mfma_f32_16x16x32_bf16 v[118:121], v[210:213], v[178:181], v[118:121]
	v_mfma_f32_16x16x32_bf16 v[114:117], v[218:221], v[178:181], v[114:117]
	v_mfma_f32_16x16x32_bf16 v[102:105], v[210:213], v[186:189], v[102:105]
	v_mfma_f32_16x16x32_bf16 v[98:101], v[218:221], v[186:189], v[98:101]
	v_mfma_f32_16x16x32_bf16 v[86:89], v[210:213], v[194:197], v[86:89]
	v_mfma_f32_16x16x32_bf16 v[82:85], v[218:221], v[194:197], v[82:85]
	v_mfma_f32_16x16x32_bf16 v[70:73], v[210:213], v[202:205], v[70:73]
	v_mfma_f32_16x16x32_bf16 v[66:69], v[218:221], v[202:205], v[66:69]
	s_barrier
	s_setprio 0
	s_mov_b32 m0, s43
	v_lshl_add_u64 v[224:225], s[18:19], 0, v[152:153]
	ds_read_b128 v[166:169], v173 offset:16384
	ds_read_b128 v[178:181], v173 offset:17408
	ds_read_b128 v[182:185], v173 offset:18432
	ds_read_b128 v[186:189], v173 offset:19456
	ds_read_b128 v[190:193], v173 offset:20480
	ds_read_b128 v[194:197], v173 offset:21504
	ds_read_b128 v[198:201], v173 offset:22528
	ds_read_b128 v[202:205], v173 offset:23552
	global_load_lds_dwordx4 v[224:225], off
	v_lshl_add_u64 v[226:227], s[18:19], 0, v[148:149]
	s_mov_b32 m0, s44
	s_nop 0
	global_load_lds_dwordx4 v[226:227], off
	s_setprio 1
	s_barrier
	s_waitcnt lgkmcnt(0)
	v_mfma_f32_16x16x32_bf16 v[62:65], v[130:133], v[166:169], v[62:65]
	v_mfma_f32_16x16x32_bf16 v[58:61], v[138:141], v[166:169], v[58:61]
	v_mfma_f32_16x16x32_bf16 v[46:49], v[130:133], v[182:185], v[46:49]
	v_mfma_f32_16x16x32_bf16 v[42:45], v[138:141], v[182:185], v[42:45]
	v_mfma_f32_16x16x32_bf16 v[30:33], v[130:133], v[190:193], v[30:33]
	v_mfma_f32_16x16x32_bf16 v[26:29], v[138:141], v[190:193], v[26:29]
	v_mfma_f32_16x16x32_bf16 v[14:17], v[130:133], v[198:201], v[14:17]
	v_mfma_f32_16x16x32_bf16 v[10:13], v[138:141], v[198:201], v[10:13]
	v_mfma_f32_16x16x32_bf16 v[62:65], v[134:137], v[178:181], v[62:65]
	v_mfma_f32_16x16x32_bf16 v[58:61], v[142:145], v[178:181], v[58:61]
	v_mfma_f32_16x16x32_bf16 v[46:49], v[134:137], v[186:189], v[46:49]
	v_mfma_f32_16x16x32_bf16 v[42:45], v[142:145], v[186:189], v[42:45]
	v_mfma_f32_16x16x32_bf16 v[30:33], v[134:137], v[194:197], v[30:33]
	v_mfma_f32_16x16x32_bf16 v[26:29], v[142:145], v[194:197], v[26:29]
	v_mfma_f32_16x16x32_bf16 v[14:17], v[134:137], v[202:205], v[14:17]
	v_mfma_f32_16x16x32_bf16 v[10:13], v[142:145], v[202:205], v[10:13]
	s_barrier
	s_setprio 0
	s_add_u32 s20, s34, 0x40000
	s_addc_u32 s21, s35, 0
	s_add_i32 s64, s55, s42
	v_lshl_add_u64 v[130:131], s[20:21], 0, v[150:151]
	s_mov_b32 m0, s64
	s_nop 0
	global_load_lds_dwordx4 v[130:131], off
	v_lshl_add_u64 v[130:131], s[20:21], 0, v[146:147]
	s_add_i32 m0, s64, 0x2000
	s_nop 0
	global_load_lds_dwordx4 v[130:131], off
	s_waitcnt vmcnt(6)
	s_setprio 1
	s_barrier
	v_mfma_f32_16x16x32_bf16 v[54:57], v[206:209], v[166:169], v[54:57]
	v_mfma_f32_16x16x32_bf16 v[50:53], v[214:217], v[166:169], v[50:53]
	v_mfma_f32_16x16x32_bf16 v[38:41], v[206:209], v[182:185], v[38:41]
	v_mfma_f32_16x16x32_bf16 v[34:37], v[214:217], v[182:185], v[34:37]
	v_mfma_f32_16x16x32_bf16 v[22:25], v[206:209], v[190:193], v[22:25]
	v_mfma_f32_16x16x32_bf16 v[18:21], v[214:217], v[190:193], v[18:21]
	v_mfma_f32_16x16x32_bf16 v[6:9], v[206:209], v[198:201], v[6:9]
	v_mfma_f32_16x16x32_bf16 v[2:5], v[214:217], v[198:201], v[2:5]
	v_mfma_f32_16x16x32_bf16 v[54:57], v[210:213], v[178:181], v[54:57]
	v_mfma_f32_16x16x32_bf16 v[50:53], v[218:221], v[178:181], v[50:53]
	v_mfma_f32_16x16x32_bf16 v[38:41], v[210:213], v[186:189], v[38:41]
	v_mfma_f32_16x16x32_bf16 v[34:37], v[218:221], v[186:189], v[34:37]
	v_mfma_f32_16x16x32_bf16 v[22:25], v[210:213], v[194:197], v[22:25]
	v_mfma_f32_16x16x32_bf16 v[18:21], v[218:221], v[194:197], v[18:21]
	v_mfma_f32_16x16x32_bf16 v[6:9], v[210:213], v[202:205], v[6:9]
	v_mfma_f32_16x16x32_bf16 v[2:5], v[218:221], v[202:205], v[2:5]
	s_barrier
	s_setprio 0
	s_add_i32 s20, 0, 0x18000
	v_add_u32_e32 v142, s20, v157
	ds_read_b128 v[130:133], v142
	ds_read_b128 v[134:137], v142 offset:1024
	ds_read_b128 v[138:141], v142 offset:2048
	ds_read_b128 v[142:145], v142 offset:3072
	s_add_u32 s18, s18, 0x40000
	s_addc_u32 s19, s19, 0
	s_mov_b32 m0, s45
	v_lshl_add_u64 v[206:207], s[18:19], 0, v[152:153]
	ds_read_b128 v[166:169], v173 offset:32768
	ds_read_b128 v[178:181], v173 offset:33792
	ds_read_b128 v[182:185], v173 offset:34816
	ds_read_b128 v[186:189], v173 offset:35840
	ds_read_b128 v[190:193], v173 offset:36864
	ds_read_b128 v[194:197], v173 offset:37888
	ds_read_b128 v[198:201], v173 offset:38912
	ds_read_b128 v[202:205], v173 offset:39936
	global_load_lds_dwordx4 v[206:207], off
	v_lshl_add_u64 v[206:207], s[18:19], 0, v[148:149]
	s_mov_b32 m0, s46
	s_nop 0
	global_load_lds_dwordx4 v[206:207], off
	s_waitcnt lgkmcnt(8)
	s_setprio 1
	s_barrier
	s_waitcnt lgkmcnt(0)
	v_mfma_f32_16x16x32_bf16 v[126:129], v[130:133], v[166:169], v[126:129]
	v_mfma_f32_16x16x32_bf16 v[122:125], v[138:141], v[166:169], v[122:125]
	v_mfma_f32_16x16x32_bf16 v[110:113], v[130:133], v[182:185], v[110:113]
	v_mfma_f32_16x16x32_bf16 v[106:109], v[138:141], v[182:185], v[106:109]
	v_mfma_f32_16x16x32_bf16 v[94:97], v[130:133], v[190:193], v[94:97]
	v_mfma_f32_16x16x32_bf16 v[90:93], v[138:141], v[190:193], v[90:93]
	v_mfma_f32_16x16x32_bf16 v[78:81], v[130:133], v[198:201], v[78:81]
	v_mfma_f32_16x16x32_bf16 v[74:77], v[138:141], v[198:201], v[74:77]
	v_mfma_f32_16x16x32_bf16 v[126:129], v[134:137], v[178:181], v[126:129]
	v_mfma_f32_16x16x32_bf16 v[122:125], v[142:145], v[178:181], v[122:125]
	v_mfma_f32_16x16x32_bf16 v[110:113], v[134:137], v[186:189], v[110:113]
	v_mfma_f32_16x16x32_bf16 v[106:109], v[142:145], v[186:189], v[106:109]
	v_mfma_f32_16x16x32_bf16 v[94:97], v[134:137], v[194:197], v[94:97]
	v_mfma_f32_16x16x32_bf16 v[90:93], v[142:145], v[194:197], v[90:93]
	v_mfma_f32_16x16x32_bf16 v[78:81], v[134:137], v[202:205], v[78:81]
	v_mfma_f32_16x16x32_bf16 v[74:77], v[142:145], v[202:205], v[74:77]
	s_barrier
	s_setprio 0
	s_add_i32 s21, 0, 0x1c000
	s_add_i32 s18, s20, s42
	v_add_u32_e32 v154, s21, v157
	v_lshl_add_u64 v[174:175], v[174:175], 0, s[6:7]
	s_mov_b32 m0, s18
	ds_read_b128 v[206:209], v154
	ds_read_b128 v[210:213], v154 offset:1024
	ds_read_b128 v[214:217], v154 offset:2048
	ds_read_b128 v[218:221], v154 offset:3072
	global_load_lds_dwordx4 v[174:175], off
	v_lshl_add_u64 v[174:175], v[222:223], 0, s[6:7]
	s_add_i32 m0, s18, 0x2000
	s_nop 0
	global_load_lds_dwordx4 v[174:175], off
	s_setprio 1
	s_barrier
	s_waitcnt lgkmcnt(0)
	v_mfma_f32_16x16x32_bf16 v[118:121], v[206:209], v[166:169], v[118:121]
	v_mfma_f32_16x16x32_bf16 v[114:117], v[214:217], v[166:169], v[114:117]
	v_mfma_f32_16x16x32_bf16 v[102:105], v[206:209], v[182:185], v[102:105]
	v_mfma_f32_16x16x32_bf16 v[98:101], v[214:217], v[182:185], v[98:101]
	v_mfma_f32_16x16x32_bf16 v[86:89], v[206:209], v[190:193], v[86:89]
	v_mfma_f32_16x16x32_bf16 v[82:85], v[214:217], v[190:193], v[82:85]
	v_mfma_f32_16x16x32_bf16 v[70:73], v[206:209], v[198:201], v[70:73]
	v_mfma_f32_16x16x32_bf16 v[66:69], v[214:217], v[198:201], v[66:69]
	v_mfma_f32_16x16x32_bf16 v[118:121], v[210:213], v[178:181], v[118:121]
	v_mfma_f32_16x16x32_bf16 v[114:117], v[218:221], v[178:181], v[114:117]
	v_mfma_f32_16x16x32_bf16 v[102:105], v[210:213], v[186:189], v[102:105]
	v_mfma_f32_16x16x32_bf16 v[98:101], v[218:221], v[186:189], v[98:101]
	v_mfma_f32_16x16x32_bf16 v[86:89], v[210:213], v[194:197], v[86:89]
	v_mfma_f32_16x16x32_bf16 v[82:85], v[218:221], v[194:197], v[82:85]
	v_mfma_f32_16x16x32_bf16 v[70:73], v[210:213], v[202:205], v[70:73]
	v_mfma_f32_16x16x32_bf16 v[66:69], v[218:221], v[202:205], v[66:69]
	s_barrier
	s_setprio 0
	s_mov_b32 m0, s50
	v_lshl_add_u64 v[174:175], v[224:225], 0, s[6:7]
	ds_read_b128 v[166:169], v173 offset:49152
	ds_read_b128 v[178:181], v173 offset:50176
	ds_read_b128 v[182:185], v173 offset:51200
	ds_read_b128 v[186:189], v173 offset:52224
	ds_read_b128 v[190:193], v173 offset:53248
	ds_read_b128 v[194:197], v173 offset:54272
	ds_read_b128 v[198:201], v173 offset:55296
	ds_read_b128 v[202:205], v173 offset:56320
	global_load_lds_dwordx4 v[174:175], off
	v_lshl_add_u64 v[174:175], v[226:227], 0, s[6:7]
	s_mov_b32 m0, s51
	s_nop 0
	global_load_lds_dwordx4 v[174:175], off
	s_setprio 1
	s_barrier
	s_waitcnt lgkmcnt(0)
	v_mfma_f32_16x16x32_bf16 v[62:65], v[130:133], v[166:169], v[62:65]
	v_mfma_f32_16x16x32_bf16 v[58:61], v[138:141], v[166:169], v[58:61]
	v_mfma_f32_16x16x32_bf16 v[46:49], v[130:133], v[182:185], v[46:49]
	v_mfma_f32_16x16x32_bf16 v[42:45], v[138:141], v[182:185], v[42:45]
	v_mfma_f32_16x16x32_bf16 v[30:33], v[130:133], v[190:193], v[30:33]
	v_mfma_f32_16x16x32_bf16 v[26:29], v[138:141], v[190:193], v[26:29]
	v_mfma_f32_16x16x32_bf16 v[14:17], v[130:133], v[198:201], v[14:17]
	v_mfma_f32_16x16x32_bf16 v[10:13], v[138:141], v[198:201], v[10:13]
	v_mfma_f32_16x16x32_bf16 v[62:65], v[134:137], v[178:181], v[62:65]
	v_mfma_f32_16x16x32_bf16 v[58:61], v[142:145], v[178:181], v[58:61]
	v_mfma_f32_16x16x32_bf16 v[46:49], v[134:137], v[186:189], v[46:49]
	v_mfma_f32_16x16x32_bf16 v[42:45], v[142:145], v[186:189], v[42:45]
	v_mfma_f32_16x16x32_bf16 v[30:33], v[134:137], v[194:197], v[30:33]
	v_mfma_f32_16x16x32_bf16 v[26:29], v[142:145], v[194:197], v[26:29]
	v_mfma_f32_16x16x32_bf16 v[14:17], v[134:137], v[202:205], v[14:17]
	v_mfma_f32_16x16x32_bf16 v[10:13], v[142:145], v[202:205], v[10:13]
	s_barrier
	s_setprio 0
	s_add_u32 s18, s34, 0x40080
	s_addc_u32 s19, s35, 0
	s_add_i32 s20, s21, s42
	v_lshl_add_u64 v[130:131], s[18:19], 0, v[150:151]
	s_mov_b32 m0, s20
	s_nop 0
	global_load_lds_dwordx4 v[130:131], off
	v_lshl_add_u64 v[130:131], s[18:19], 0, v[146:147]
	s_add_i32 m0, s20, 0x2000
	s_nop 0
	global_load_lds_dwordx4 v[130:131], off
	s_waitcnt vmcnt(6)
	s_setprio 1
	s_barrier
	v_mfma_f32_16x16x32_bf16 v[54:57], v[206:209], v[166:169], v[54:57]
	v_mfma_f32_16x16x32_bf16 v[50:53], v[214:217], v[166:169], v[50:53]
	v_mfma_f32_16x16x32_bf16 v[38:41], v[206:209], v[182:185], v[38:41]
	v_mfma_f32_16x16x32_bf16 v[34:37], v[214:217], v[182:185], v[34:37]
	v_mfma_f32_16x16x32_bf16 v[22:25], v[206:209], v[190:193], v[22:25]
	v_mfma_f32_16x16x32_bf16 v[18:21], v[214:217], v[190:193], v[18:21]
	v_mfma_f32_16x16x32_bf16 v[6:9], v[206:209], v[198:201], v[6:9]
	v_mfma_f32_16x16x32_bf16 v[2:5], v[214:217], v[198:201], v[2:5]
	v_mfma_f32_16x16x32_bf16 v[54:57], v[210:213], v[178:181], v[54:57]
	v_mfma_f32_16x16x32_bf16 v[50:53], v[218:221], v[178:181], v[50:53]
	v_mfma_f32_16x16x32_bf16 v[38:41], v[210:213], v[186:189], v[38:41]
	v_mfma_f32_16x16x32_bf16 v[34:37], v[218:221], v[186:189], v[34:37]
	v_mfma_f32_16x16x32_bf16 v[22:25], v[210:213], v[194:197], v[22:25]
	v_mfma_f32_16x16x32_bf16 v[18:21], v[218:221], v[194:197], v[18:21]
	v_mfma_f32_16x16x32_bf16 v[6:9], v[210:213], v[202:205], v[6:9]
	v_mfma_f32_16x16x32_bf16 v[2:5], v[218:221], v[202:205], v[2:5]
	s_barrier
	s_setprio 0
	s_add_i32 s63, s63, 2
	s_add_u32 s24, s24, 0x100
	s_addc_u32 s25, s25, 0
	s_add_u32 s61, s61, 0x100
	s_addc_u32 s62, s62, 0
	s_cmp_gt_u32 s63, 13
	s_cbranch_scc0 .LBB0_3265
	s_ashr_i32 s9, s16, 3
	s_mul_hi_i32 s11, s9, 0x5800
	s_mulk_i32 s9, 0x5800
	s_add_u32 s9, s48, s9
	s_addc_u32 s11, s49, s11
	s_lshl_b32 s18, s17, 8
	s_ashr_i32 s19, s18, 31
	s_lshl_b64 s[18:19], s[18:19], 2
	v_lshl_add_u32 v180, s16, 8, v1
	s_add_u32 s18, s9, s18
	s_addc_u32 s19, s11, s19
	v_lshlrev_b32_e32 v130, 2, v156
	v_ashrrev_i32_e32 v181, 31, v180
	v_mov_b32_e32 v142, v236
	v_mov_b32_e32 v143, v237
	v_mov_b32_e32 v144, v238
	v_mov_b32_e32 v145, v239
	v_lshl_add_u64 v[182:183], v[180:181], 2, s[4:5]
	v_mov_b32_e32 v190, v228
	v_mov_b32_e32 v138, v240
	v_mov_b32_e32 v139, v241
	v_mov_b32_e32 v140, v242
	v_mov_b32_e32 v141, v243
	v_mov_b32_e32 v134, v244
	v_mov_b32_e32 v135, v245
	v_mov_b32_e32 v136, v246
	v_mov_b32_e32 v137, v247
	s_nop 0
	v_mov_b32_e32 v130, v248
	v_mov_b32_e32 v131, v249
	v_mov_b32_e32 v132, v250
	v_mov_b32_e32 v133, v251
	v_or_b32_e32 v192, 16, v180
	v_ashrrev_i32_e32 v193, 31, v192
	v_lshl_add_u64 v[168:169], v[192:193], 2, s[4:5]
	v_mov_b32_e32 v194, v229
	v_or_b32_e32 v188, 32, v180
	v_or_b32_e32 v184, 48, v180
	v_mov_b64_e32 v[166:167], s[0:1]
	v_add_u32_e32 v178, 0x90, v180
	v_add_u32_e32 v174, 0xa0, v180
	v_add_u32_e32 v168, 0xb0, v180
	v_ashrrev_i32_e32 v189, 31, v188
	v_ashrrev_i32_e32 v185, 31, v184
	v_add_u32_e32 v193, 0x80, v180
	v_mad_i64_i32 v[196:197], s[18:19], v180, s56, v[166:167]
	v_ashrrev_i32_e32 v179, 31, v178
	v_ashrrev_i32_e32 v175, 31, v174
	v_ashrrev_i32_e32 v169, 31, v168
	v_lshl_add_u64 v[180:181], v[188:189], 2, s[4:5]
	v_lshl_add_u64 v[186:187], v[184:185], 2, s[4:5]
	v_lshl_add_u64 v[198:199], v[178:179], 2, s[4:5]
	v_lshl_add_u64 v[200:201], v[174:175], 2, s[4:5]
	v_lshl_add_u64 v[202:203], v[168:169], 2, s[4:5]
	v_mov_b32_e32 v204, v233
	s_nop 0
	v_mov_b32_e32 v186, v234
	s_nop 0
	v_mov_b32_e32 v180, v252
	s_nop 0
	v_mov_b32_e32 v182, v235
	s_lshl_b32 s16, s17, 7
	s_ashr_i32 s17, s16, 31
	s_lshl_b64 s[16:17], s[16:17], 1
	v_lshlrev_b32_e32 v154, 1, v156
	v_lshl_add_u64 v[196:197], v[196:197], 0, s[16:17]
	s_and_b64 vcc, exec, s[2:3]
	s_mov_b64 s[34:35], s[14:15]
	s_mov_b64 s[24:25], s[12:13]
	v_pk_fma_f32 v[118:119], v[118:119], v[190:191], v[138:139] op_sel_hi:[1,0,1]
	v_pk_fma_f32 v[126:127], v[126:127], v[190:191], v[142:143] op_sel_hi:[1,0,1]
	v_pk_fma_f32 v[128:129], v[128:129], v[190:191], v[144:145] op_sel_hi:[1,0,1]
	v_pk_fma_f32 v[122:123], v[122:123], v[190:191], v[134:135] op_sel_hi:[1,0,1]
	v_pk_fma_f32 v[124:125], v[124:125], v[190:191], v[136:137] op_sel_hi:[1,0,1]
	v_mul_f32_e32 v169, 0xbfb8aa3b, v126
	v_mul_f32_e32 v175, 0xbfb8aa3b, v127
	v_mul_f32_e32 v179, 0xbfb8aa3b, v128
	v_mul_f32_e32 v181, 0xbfb8aa3b, v129
	v_mul_f32_e32 v183, 0xbfb8aa3b, v122
	v_mul_f32_e32 v185, 0xbfb8aa3b, v123
	v_mul_f32_e32 v187, 0xbfb8aa3b, v124
	v_mul_f32_e32 v189, 0xbfb8aa3b, v125
	v_exp_f32_e32 v169, v169
	v_exp_f32_e32 v175, v175
	v_exp_f32_e32 v179, v179
	v_exp_f32_e32 v181, v181
	v_exp_f32_e32 v183, v183
	v_exp_f32_e32 v185, v185
	v_exp_f32_e32 v187, v187
	v_exp_f32_e32 v189, v189
	v_add_f32_e32 v169, 1.0, v169
	v_add_f32_e32 v175, 1.0, v175
	v_add_f32_e32 v179, 1.0, v179
	v_add_f32_e32 v181, 1.0, v181
	v_add_f32_e32 v183, 1.0, v183
	v_add_f32_e32 v185, 1.0, v185
	v_add_f32_e32 v187, 1.0, v187
	v_add_f32_e32 v189, 1.0, v189
	v_pk_fma_f32 v[120:121], v[120:121], v[190:191], v[140:141] op_sel_hi:[1,0,1]
	v_pk_fma_f32 v[114:115], v[114:115], v[190:191], v[130:131] op_sel_hi:[1,0,1]
	v_pk_fma_f32 v[116:117], v[116:117], v[190:191], v[132:133] op_sel_hi:[1,0,1]
	v_rcp_f32_e32 v190, v169
	v_rcp_f32_e32 v191, v175
	v_rcp_f32_e32 v198, v179
	v_rcp_f32_e32 v199, v181
	v_rcp_f32_e32 v200, v183
	v_rcp_f32_e32 v201, v185
	v_rcp_f32_e32 v202, v187
	v_rcp_f32_e32 v203, v189
	v_pk_mul_f32 v[126:127], v[126:127], v[190:191]
	v_pk_mul_f32 v[128:129], v[128:129], v[198:199]
	v_pk_mul_f32 v[122:123], v[122:123], v[200:201]
	v_pk_mul_f32 v[124:125], v[124:125], v[202:203]
	v_pk_mul_f32 v[118:119], v[118:119], v[126:127]
	v_pk_mul_f32 v[120:121], v[120:121], v[128:129]
	v_pk_mul_f32 v[122:123], v[114:115], v[122:123]
	v_pk_mul_f32 v[124:125], v[116:117], v[124:125]
	v_pk_fma_f32 v[110:111], v[110:111], v[194:195], v[142:143] op_sel_hi:[1,0,1]
	v_lshl_add_u64 v[126:127], v[196:197], 0, v[154:155]
	v_cvt_pk_bf16_f32 v114, v118, v119
	v_cvt_pk_bf16_f32 v115, v120, v121
	v_cvt_pk_bf16_f32 v116, v122, v123
	v_cvt_pk_bf16_f32 v117, v124, v125
	v_mul_f32_e32 v118, 0xbfb8aa3b, v110
	v_mul_f32_e32 v119, 0xbfb8aa3b, v111
	v_pk_fma_f32 v[112:113], v[112:113], v[194:195], v[144:145] op_sel_hi:[1,0,1]
	v_exp_f32_e32 v118, v118
	v_exp_f32_e32 v119, v119
	global_store_dwordx4 v[126:127], v[114:117], off nt
	v_pk_fma_f32 v[102:103], v[102:103], v[194:195], v[138:139] op_sel_hi:[1,0,1]
	v_pk_fma_f32 v[106:107], v[106:107], v[194:195], v[134:135] op_sel_hi:[1,0,1]
	v_mul_f32_e32 v116, 0xbfb8aa3b, v112
	v_mul_f32_e32 v117, 0xbfb8aa3b, v113
	v_exp_f32_e32 v116, v116
	v_exp_f32_e32 v117, v117
	v_add_f32_e32 v114, 1.0, v118
	v_add_f32_e32 v115, 1.0, v119
	v_rcp_f32_e32 v114, v114
	v_rcp_f32_e32 v115, v115
	v_add_f32_e32 v116, 1.0, v116
	v_add_f32_e32 v117, 1.0, v117
	v_rcp_f32_e32 v116, v116
	v_rcp_f32_e32 v117, v117
	v_pk_mul_f32 v[110:111], v[110:111], v[114:115]
	v_pk_fma_f32 v[104:105], v[104:105], v[194:195], v[140:141] op_sel_hi:[1,0,1]
	v_pk_mul_f32 v[102:103], v[102:103], v[110:111]
	v_pk_mul_f32 v[110:111], v[112:113], v[116:117]
	v_mul_f32_e32 v112, 0xbfb8aa3b, v106
	v_mul_f32_e32 v113, 0xbfb8aa3b, v107
	v_exp_f32_e32 v112, v112
	v_exp_f32_e32 v113, v113
	v_pk_fma_f32 v[108:109], v[108:109], v[194:195], v[136:137] op_sel_hi:[1,0,1]
	v_pk_mul_f32 v[104:105], v[104:105], v[110:111]
	v_add_f32_e32 v110, 1.0, v112
	v_add_f32_e32 v111, 1.0, v113
	v_mul_f32_e32 v112, 0xbfb8aa3b, v108
	v_mul_f32_e32 v113, 0xbfb8aa3b, v109
	v_exp_f32_e32 v112, v112
	v_exp_f32_e32 v113, v113
	v_rcp_f32_e32 v110, v110
	v_rcp_f32_e32 v111, v111
	v_add_f32_e32 v112, 1.0, v112
	v_add_f32_e32 v113, 1.0, v113
	v_rcp_f32_e32 v112, v112
	v_rcp_f32_e32 v113, v113
	v_pk_mul_f32 v[106:107], v[106:107], v[110:111]
	v_pk_fma_f32 v[98:99], v[98:99], v[194:195], v[130:131] op_sel_hi:[1,0,1]
	v_pk_fma_f32 v[100:101], v[100:101], v[194:195], v[132:133] op_sel_hi:[1,0,1]
	v_pk_mul_f32 v[106:107], v[98:99], v[106:107]
	v_pk_mul_f32 v[98:99], v[108:109], v[112:113]
	v_pk_fma_f32 v[94:95], v[94:95], v[204:205], v[142:143] op_sel_hi:[1,0,1]
	v_pk_mul_f32 v[108:109], v[100:101], v[98:99]
	v_mad_i64_i32 v[98:99], s[18:19], v192, s56, v[166:167]
	v_lshl_add_u64 v[98:99], v[98:99], 0, s[16:17]
	v_lshl_add_u64 v[110:111], v[98:99], 0, v[154:155]
	v_cvt_pk_bf16_f32 v98, v102, v103
	v_cvt_pk_bf16_f32 v99, v104, v105
	v_cvt_pk_bf16_f32 v100, v106, v107
	v_cvt_pk_bf16_f32 v101, v108, v109
	v_mul_f32_e32 v102, 0xbfb8aa3b, v94
	v_mul_f32_e32 v103, 0xbfb8aa3b, v95
	v_pk_fma_f32 v[96:97], v[96:97], v[204:205], v[144:145] op_sel_hi:[1,0,1]
	v_exp_f32_e32 v102, v102
	v_exp_f32_e32 v103, v103
	global_store_dwordx4 v[110:111], v[98:101], off nt
	v_pk_fma_f32 v[86:87], v[86:87], v[204:205], v[138:139] op_sel_hi:[1,0,1]
	v_pk_fma_f32 v[90:91], v[90:91], v[204:205], v[134:135] op_sel_hi:[1,0,1]
	v_mul_f32_e32 v100, 0xbfb8aa3b, v96
	v_mul_f32_e32 v101, 0xbfb8aa3b, v97
	v_exp_f32_e32 v100, v100
	v_exp_f32_e32 v101, v101
	v_add_f32_e32 v98, 1.0, v102
	v_add_f32_e32 v99, 1.0, v103
	v_rcp_f32_e32 v98, v98
	v_rcp_f32_e32 v99, v99
	v_add_f32_e32 v100, 1.0, v100
	v_add_f32_e32 v101, 1.0, v101
	v_rcp_f32_e32 v100, v100
	v_rcp_f32_e32 v101, v101
	v_pk_mul_f32 v[94:95], v[94:95], v[98:99]
	v_pk_fma_f32 v[88:89], v[88:89], v[204:205], v[140:141] op_sel_hi:[1,0,1]
	v_pk_mul_f32 v[86:87], v[86:87], v[94:95]
	v_pk_mul_f32 v[94:95], v[96:97], v[100:101]
	v_mul_f32_e32 v96, 0xbfb8aa3b, v90
	v_mul_f32_e32 v97, 0xbfb8aa3b, v91
	v_exp_f32_e32 v96, v96
	v_exp_f32_e32 v97, v97
	v_pk_fma_f32 v[92:93], v[92:93], v[204:205], v[136:137] op_sel_hi:[1,0,1]
	v_pk_mul_f32 v[88:89], v[88:89], v[94:95]
	v_add_f32_e32 v94, 1.0, v96
	v_add_f32_e32 v95, 1.0, v97
	v_mul_f32_e32 v96, 0xbfb8aa3b, v92
	v_mul_f32_e32 v97, 0xbfb8aa3b, v93
	v_exp_f32_e32 v96, v96
	v_exp_f32_e32 v97, v97
	v_rcp_f32_e32 v94, v94
	v_rcp_f32_e32 v95, v95
	v_add_f32_e32 v96, 1.0, v96
	v_add_f32_e32 v97, 1.0, v97
	v_rcp_f32_e32 v96, v96
	v_rcp_f32_e32 v97, v97
	v_pk_mul_f32 v[90:91], v[90:91], v[94:95]
	v_pk_fma_f32 v[82:83], v[82:83], v[204:205], v[130:131] op_sel_hi:[1,0,1]
	v_pk_fma_f32 v[84:85], v[84:85], v[204:205], v[132:133] op_sel_hi:[1,0,1]
	v_pk_mul_f32 v[90:91], v[82:83], v[90:91]
	v_pk_mul_f32 v[82:83], v[92:93], v[96:97]
	v_pk_fma_f32 v[78:79], v[78:79], v[186:187], v[142:143] op_sel_hi:[1,0,1]
	v_pk_mul_f32 v[92:93], v[84:85], v[82:83]
	v_mad_i64_i32 v[82:83], s[18:19], v188, s56, v[166:167]
	v_lshl_add_u64 v[82:83], v[82:83], 0, s[16:17]
	v_lshl_add_u64 v[94:95], v[82:83], 0, v[154:155]
	v_cvt_pk_bf16_f32 v82, v86, v87
	v_cvt_pk_bf16_f32 v83, v88, v89
	v_cvt_pk_bf16_f32 v84, v90, v91
	v_cvt_pk_bf16_f32 v85, v92, v93
	v_mul_f32_e32 v86, 0xbfb8aa3b, v78
	v_mul_f32_e32 v87, 0xbfb8aa3b, v79
	v_pk_fma_f32 v[80:81], v[80:81], v[186:187], v[144:145] op_sel_hi:[1,0,1]
	v_exp_f32_e32 v86, v86
	v_exp_f32_e32 v87, v87
	global_store_dwordx4 v[94:95], v[82:85], off nt
	v_pk_fma_f32 v[70:71], v[70:71], v[186:187], v[138:139] op_sel_hi:[1,0,1]
	v_pk_fma_f32 v[74:75], v[74:75], v[186:187], v[134:135] op_sel_hi:[1,0,1]
	v_mul_f32_e32 v84, 0xbfb8aa3b, v80
	v_mul_f32_e32 v85, 0xbfb8aa3b, v81
	v_exp_f32_e32 v84, v84
	v_exp_f32_e32 v85, v85
	v_add_f32_e32 v82, 1.0, v86
	v_add_f32_e32 v83, 1.0, v87
	v_rcp_f32_e32 v82, v82
	v_rcp_f32_e32 v83, v83
	v_add_f32_e32 v84, 1.0, v84
	v_add_f32_e32 v85, 1.0, v85
	v_rcp_f32_e32 v84, v84
	v_rcp_f32_e32 v85, v85
	v_pk_mul_f32 v[78:79], v[78:79], v[82:83]
	v_pk_fma_f32 v[72:73], v[72:73], v[186:187], v[140:141] op_sel_hi:[1,0,1]
	v_pk_mul_f32 v[70:71], v[70:71], v[78:79]
	v_pk_mul_f32 v[78:79], v[80:81], v[84:85]
	v_mul_f32_e32 v80, 0xbfb8aa3b, v74
	v_mul_f32_e32 v81, 0xbfb8aa3b, v75
	v_exp_f32_e32 v80, v80
	v_exp_f32_e32 v81, v81
	v_pk_fma_f32 v[76:77], v[76:77], v[186:187], v[136:137] op_sel_hi:[1,0,1]
	v_pk_mul_f32 v[72:73], v[72:73], v[78:79]
	v_add_f32_e32 v78, 1.0, v80
	v_add_f32_e32 v79, 1.0, v81
	v_mul_f32_e32 v80, 0xbfb8aa3b, v76
	v_mul_f32_e32 v81, 0xbfb8aa3b, v77
	v_exp_f32_e32 v80, v80
	v_exp_f32_e32 v81, v81
	v_rcp_f32_e32 v78, v78
	v_rcp_f32_e32 v79, v79
	v_add_f32_e32 v80, 1.0, v80
	v_add_f32_e32 v81, 1.0, v81
	v_rcp_f32_e32 v80, v80
	v_rcp_f32_e32 v81, v81
	v_pk_mul_f32 v[74:75], v[74:75], v[78:79]
	v_pk_fma_f32 v[66:67], v[66:67], v[186:187], v[130:131] op_sel_hi:[1,0,1]
	v_pk_fma_f32 v[68:69], v[68:69], v[186:187], v[132:133] op_sel_hi:[1,0,1]
	v_pk_mul_f32 v[74:75], v[66:67], v[74:75]
	v_pk_mul_f32 v[66:67], v[76:77], v[80:81]
	v_pk_fma_f32 v[62:63], v[62:63], v[182:183], v[142:143] op_sel_hi:[1,0,1]
	v_pk_mul_f32 v[76:77], v[68:69], v[66:67]
	v_mad_i64_i32 v[66:67], s[18:19], v184, s56, v[166:167]
	v_lshl_add_u64 v[66:67], v[66:67], 0, s[16:17]
	v_lshl_add_u64 v[78:79], v[66:67], 0, v[154:155]
	v_cvt_pk_bf16_f32 v66, v70, v71
	v_cvt_pk_bf16_f32 v67, v72, v73
	v_cvt_pk_bf16_f32 v68, v74, v75
	v_cvt_pk_bf16_f32 v69, v76, v77
	v_mul_f32_e32 v70, 0xbfb8aa3b, v62
	v_mul_f32_e32 v71, 0xbfb8aa3b, v63
	v_pk_fma_f32 v[64:65], v[64:65], v[182:183], v[144:145] op_sel_hi:[1,0,1]
	v_exp_f32_e32 v70, v70
	v_exp_f32_e32 v71, v71
	global_store_dwordx4 v[78:79], v[66:69], off nt
	v_pk_fma_f32 v[54:55], v[54:55], v[182:183], v[138:139] op_sel_hi:[1,0,1]
	v_pk_fma_f32 v[58:59], v[58:59], v[182:183], v[134:135] op_sel_hi:[1,0,1]
	v_mul_f32_e32 v68, 0xbfb8aa3b, v64
	v_mul_f32_e32 v69, 0xbfb8aa3b, v65
	v_exp_f32_e32 v68, v68
	v_exp_f32_e32 v69, v69
	v_add_f32_e32 v66, 1.0, v70
	v_add_f32_e32 v67, 1.0, v71
	v_rcp_f32_e32 v66, v66
	v_rcp_f32_e32 v67, v67
	v_add_f32_e32 v68, 1.0, v68
	v_add_f32_e32 v69, 1.0, v69
	v_rcp_f32_e32 v68, v68
	v_rcp_f32_e32 v69, v69
	v_pk_mul_f32 v[62:63], v[62:63], v[66:67]
	v_pk_fma_f32 v[56:57], v[56:57], v[182:183], v[140:141] op_sel_hi:[1,0,1]
	v_pk_mul_f32 v[54:55], v[54:55], v[62:63]
	v_pk_mul_f32 v[62:63], v[64:65], v[68:69]
	v_mul_f32_e32 v64, 0xbfb8aa3b, v58
	v_mul_f32_e32 v65, 0xbfb8aa3b, v59
	v_exp_f32_e32 v64, v64
	v_exp_f32_e32 v65, v65
	v_pk_fma_f32 v[60:61], v[60:61], v[182:183], v[136:137] op_sel_hi:[1,0,1]
	v_pk_mul_f32 v[56:57], v[56:57], v[62:63]
	v_add_f32_e32 v62, 1.0, v64
	v_add_f32_e32 v63, 1.0, v65
	v_mul_f32_e32 v64, 0xbfb8aa3b, v60
	v_mul_f32_e32 v65, 0xbfb8aa3b, v61
	v_exp_f32_e32 v64, v64
	v_exp_f32_e32 v65, v65
	v_rcp_f32_e32 v62, v62
	v_rcp_f32_e32 v63, v63
	v_add_f32_e32 v64, 1.0, v64
	v_add_f32_e32 v65, 1.0, v65
	v_rcp_f32_e32 v64, v64
	v_rcp_f32_e32 v65, v65
	v_pk_mul_f32 v[58:59], v[58:59], v[62:63]
	v_pk_fma_f32 v[50:51], v[50:51], v[182:183], v[130:131] op_sel_hi:[1,0,1]
	v_pk_fma_f32 v[52:53], v[52:53], v[182:183], v[132:133] op_sel_hi:[1,0,1]
	v_pk_mul_f32 v[58:59], v[50:51], v[58:59]
	v_pk_mul_f32 v[50:51], v[60:61], v[64:65]
	v_pk_fma_f32 v[46:47], v[46:47], v[180:181], v[142:143] op_sel_hi:[1,0,1]
	v_pk_mul_f32 v[60:61], v[52:53], v[50:51]
	v_mad_i64_i32 v[50:51], s[18:19], v193, s56, v[166:167]
	v_lshl_add_u64 v[50:51], v[50:51], 0, s[16:17]
	v_lshl_add_u64 v[62:63], v[50:51], 0, v[154:155]
	v_cvt_pk_bf16_f32 v50, v54, v55
	v_cvt_pk_bf16_f32 v51, v56, v57
	v_cvt_pk_bf16_f32 v52, v58, v59
	v_cvt_pk_bf16_f32 v53, v60, v61
	v_mul_f32_e32 v54, 0xbfb8aa3b, v46
	v_mul_f32_e32 v55, 0xbfb8aa3b, v47
	v_pk_fma_f32 v[48:49], v[48:49], v[180:181], v[144:145] op_sel_hi:[1,0,1]
	v_exp_f32_e32 v54, v54
	v_exp_f32_e32 v55, v55
	global_store_dwordx4 v[62:63], v[50:53], off nt
	v_pk_fma_f32 v[38:39], v[38:39], v[180:181], v[138:139] op_sel_hi:[1,0,1]
	v_pk_fma_f32 v[42:43], v[42:43], v[180:181], v[134:135] op_sel_hi:[1,0,1]
	v_mul_f32_e32 v52, 0xbfb8aa3b, v48
	v_mul_f32_e32 v53, 0xbfb8aa3b, v49
	v_exp_f32_e32 v52, v52
	v_exp_f32_e32 v53, v53
	v_add_f32_e32 v50, 1.0, v54
	v_add_f32_e32 v51, 1.0, v55
	v_rcp_f32_e32 v50, v50
	v_rcp_f32_e32 v51, v51
	v_add_f32_e32 v52, 1.0, v52
	v_add_f32_e32 v53, 1.0, v53
	v_rcp_f32_e32 v52, v52
	v_rcp_f32_e32 v53, v53
	v_pk_mul_f32 v[46:47], v[46:47], v[50:51]
	v_pk_fma_f32 v[40:41], v[40:41], v[180:181], v[140:141] op_sel_hi:[1,0,1]
	v_pk_mul_f32 v[38:39], v[38:39], v[46:47]
	v_pk_mul_f32 v[46:47], v[48:49], v[52:53]
	v_mul_f32_e32 v48, 0xbfb8aa3b, v42
	v_mul_f32_e32 v49, 0xbfb8aa3b, v43
	v_exp_f32_e32 v48, v48
	v_exp_f32_e32 v49, v49
	v_pk_fma_f32 v[44:45], v[44:45], v[180:181], v[136:137] op_sel_hi:[1,0,1]
	v_pk_mul_f32 v[40:41], v[40:41], v[46:47]
	v_add_f32_e32 v46, 1.0, v48
	v_add_f32_e32 v47, 1.0, v49
	v_mul_f32_e32 v48, 0xbfb8aa3b, v44
	v_mul_f32_e32 v49, 0xbfb8aa3b, v45
	v_exp_f32_e32 v48, v48
	v_exp_f32_e32 v49, v49
	v_rcp_f32_e32 v46, v46
	v_rcp_f32_e32 v47, v47
	v_add_f32_e32 v48, 1.0, v48
	v_add_f32_e32 v49, 1.0, v49
	v_rcp_f32_e32 v48, v48
	v_rcp_f32_e32 v49, v49
	v_pk_mul_f32 v[42:43], v[42:43], v[46:47]
	v_pk_fma_f32 v[34:35], v[34:35], v[180:181], v[130:131] op_sel_hi:[1,0,1]
	v_pk_fma_f32 v[36:37], v[36:37], v[180:181], v[132:133] op_sel_hi:[1,0,1]
	v_pk_mul_f32 v[42:43], v[34:35], v[42:43]
	v_pk_mul_f32 v[34:35], v[44:45], v[48:49]
	v_pk_fma_f32 v[30:31], v[30:31], v[176:177], v[142:143] op_sel_hi:[1,0,1]
	v_pk_mul_f32 v[44:45], v[36:37], v[34:35]
	v_mad_i64_i32 v[34:35], s[18:19], v178, s56, v[166:167]
	v_lshl_add_u64 v[34:35], v[34:35], 0, s[16:17]
	v_lshl_add_u64 v[46:47], v[34:35], 0, v[154:155]
	v_cvt_pk_bf16_f32 v34, v38, v39
	v_cvt_pk_bf16_f32 v35, v40, v41
	v_cvt_pk_bf16_f32 v36, v42, v43
	v_cvt_pk_bf16_f32 v37, v44, v45
	v_mul_f32_e32 v38, 0xbfb8aa3b, v30
	v_mul_f32_e32 v39, 0xbfb8aa3b, v31
	v_pk_fma_f32 v[32:33], v[32:33], v[176:177], v[144:145] op_sel_hi:[1,0,1]
	v_exp_f32_e32 v38, v38
	v_exp_f32_e32 v39, v39
	global_store_dwordx4 v[46:47], v[34:37], off nt
	v_pk_fma_f32 v[22:23], v[22:23], v[176:177], v[138:139] op_sel_hi:[1,0,1]
	v_pk_fma_f32 v[26:27], v[26:27], v[176:177], v[134:135] op_sel_hi:[1,0,1]
	v_mul_f32_e32 v36, 0xbfb8aa3b, v32
	v_mul_f32_e32 v37, 0xbfb8aa3b, v33
	v_exp_f32_e32 v36, v36
	v_exp_f32_e32 v37, v37
	v_add_f32_e32 v34, 1.0, v38
	v_add_f32_e32 v35, 1.0, v39
	v_rcp_f32_e32 v34, v34
	v_rcp_f32_e32 v35, v35
	v_add_f32_e32 v36, 1.0, v36
	v_add_f32_e32 v37, 1.0, v37
	v_rcp_f32_e32 v36, v36
	v_rcp_f32_e32 v37, v37
	v_pk_mul_f32 v[30:31], v[30:31], v[34:35]
	v_pk_fma_f32 v[24:25], v[24:25], v[176:177], v[140:141] op_sel_hi:[1,0,1]
	v_pk_mul_f32 v[22:23], v[22:23], v[30:31]
	v_pk_mul_f32 v[30:31], v[32:33], v[36:37]
	v_mul_f32_e32 v32, 0xbfb8aa3b, v26
	v_mul_f32_e32 v33, 0xbfb8aa3b, v27
	v_exp_f32_e32 v32, v32
	v_exp_f32_e32 v33, v33
	v_pk_fma_f32 v[28:29], v[28:29], v[176:177], v[136:137] op_sel_hi:[1,0,1]
	v_pk_mul_f32 v[24:25], v[24:25], v[30:31]
	v_add_f32_e32 v30, 1.0, v32
	v_add_f32_e32 v31, 1.0, v33
	v_mul_f32_e32 v32, 0xbfb8aa3b, v28
	v_mul_f32_e32 v33, 0xbfb8aa3b, v29
	v_exp_f32_e32 v32, v32
	v_exp_f32_e32 v33, v33
	v_rcp_f32_e32 v30, v30
	v_rcp_f32_e32 v31, v31
	v_add_f32_e32 v32, 1.0, v32
	v_add_f32_e32 v33, 1.0, v33
	v_rcp_f32_e32 v32, v32
	v_rcp_f32_e32 v33, v33
	v_pk_mul_f32 v[26:27], v[26:27], v[30:31]
	v_pk_fma_f32 v[18:19], v[18:19], v[176:177], v[130:131] op_sel_hi:[1,0,1]
	v_pk_fma_f32 v[20:21], v[20:21], v[176:177], v[132:133] op_sel_hi:[1,0,1]
	v_pk_mul_f32 v[26:27], v[18:19], v[26:27]
	v_pk_mul_f32 v[18:19], v[28:29], v[32:33]
	v_pk_fma_f32 v[14:15], v[14:15], v[172:173], v[142:143] op_sel_hi:[1,0,1]
	v_pk_mul_f32 v[28:29], v[20:21], v[18:19]
	v_mad_i64_i32 v[18:19], s[18:19], v174, s56, v[166:167]
	v_lshl_add_u64 v[18:19], v[18:19], 0, s[16:17]
	v_lshl_add_u64 v[30:31], v[18:19], 0, v[154:155]
	v_cvt_pk_bf16_f32 v18, v22, v23
	v_cvt_pk_bf16_f32 v19, v24, v25
	v_cvt_pk_bf16_f32 v20, v26, v27
	v_cvt_pk_bf16_f32 v21, v28, v29
	v_mul_f32_e32 v22, 0xbfb8aa3b, v14
	v_mul_f32_e32 v23, 0xbfb8aa3b, v15
	v_pk_fma_f32 v[16:17], v[16:17], v[172:173], v[144:145] op_sel_hi:[1,0,1]
	v_exp_f32_e32 v22, v22
	v_exp_f32_e32 v23, v23
	global_store_dwordx4 v[30:31], v[18:21], off nt
	v_pk_fma_f32 v[6:7], v[6:7], v[172:173], v[138:139] op_sel_hi:[1,0,1]
	v_pk_fma_f32 v[10:11], v[10:11], v[172:173], v[134:135] op_sel_hi:[1,0,1]
	v_mul_f32_e32 v20, 0xbfb8aa3b, v16
	v_mul_f32_e32 v21, 0xbfb8aa3b, v17
	v_exp_f32_e32 v20, v20
	v_exp_f32_e32 v21, v21
	v_add_f32_e32 v18, 1.0, v22
	v_add_f32_e32 v19, 1.0, v23
	v_rcp_f32_e32 v18, v18
	v_rcp_f32_e32 v19, v19
	v_add_f32_e32 v20, 1.0, v20
	v_add_f32_e32 v21, 1.0, v21
	v_rcp_f32_e32 v20, v20
	v_rcp_f32_e32 v21, v21
	v_pk_mul_f32 v[14:15], v[14:15], v[18:19]
	v_pk_fma_f32 v[8:9], v[8:9], v[172:173], v[140:141] op_sel_hi:[1,0,1]
	v_pk_mul_f32 v[6:7], v[6:7], v[14:15]
	v_pk_mul_f32 v[14:15], v[16:17], v[20:21]
	v_mul_f32_e32 v16, 0xbfb8aa3b, v10
	v_mul_f32_e32 v17, 0xbfb8aa3b, v11
	v_exp_f32_e32 v16, v16
	v_exp_f32_e32 v17, v17
	v_pk_fma_f32 v[12:13], v[12:13], v[172:173], v[136:137] op_sel_hi:[1,0,1]
	v_pk_mul_f32 v[8:9], v[8:9], v[14:15]
	v_add_f32_e32 v14, 1.0, v16
	v_add_f32_e32 v15, 1.0, v17
	v_mul_f32_e32 v16, 0xbfb8aa3b, v12
	v_mul_f32_e32 v17, 0xbfb8aa3b, v13
	v_exp_f32_e32 v16, v16
	v_exp_f32_e32 v17, v17
	v_rcp_f32_e32 v14, v14
	v_rcp_f32_e32 v15, v15
	v_add_f32_e32 v16, 1.0, v16
	v_add_f32_e32 v17, 1.0, v17
	v_rcp_f32_e32 v16, v16
	v_rcp_f32_e32 v17, v17
	v_pk_mul_f32 v[10:11], v[10:11], v[14:15]
	v_pk_fma_f32 v[2:3], v[2:3], v[172:173], v[130:131] op_sel_hi:[1,0,1]
	v_pk_fma_f32 v[4:5], v[4:5], v[172:173], v[132:133] op_sel_hi:[1,0,1]
	v_pk_mul_f32 v[10:11], v[2:3], v[10:11]
	v_pk_mul_f32 v[2:3], v[12:13], v[16:17]
	s_nop 0
	v_pk_mul_f32 v[12:13], v[4:5], v[2:3]
	v_mad_i64_i32 v[2:3], s[18:19], v168, s56, v[166:167]
	v_lshl_add_u64 v[2:3], v[2:3], 0, s[16:17]
	v_lshl_add_u64 v[14:15], v[2:3], 0, v[154:155]
	v_cvt_pk_bf16_f32 v2, v6, v7
	v_cvt_pk_bf16_f32 v3, v8, v9
	v_cvt_pk_bf16_f32 v4, v10, v11
	v_cvt_pk_bf16_f32 v5, v12, v13
	s_mov_b32 s17, s8
	s_mov_b32 s16, s10
	global_store_dwordx4 v[14:15], v[2:5], off nt
	s_cbranch_vccz .LBB0_3262
	s_waitcnt vmcnt(0)
	s_cmpk_gt_u32 s33, 0xff
	s_cbranch_scc1 .LBB0_3269
	s_barrier

.LBB0_3482:
	s_add_u32 s24, s24, 0xb0080
	s_addc_u32 s25, s25, 0
	s_add_u32 s60, s34, 0x100
	s_addc_u32 s61, s35, 0
	s_mov_b32 s62, -2
	s_waitcnt lgkmcnt(0)
	s_waitcnt vmcnt(0)
	ds_read_b128 v[130:133], v171
	ds_read_b128 v[134:137], v171 offset:1024
	ds_read_b128 v[138:141], v171 offset:2048
	ds_read_b128 v[142:145], v171 offset:3072
	s_add_u32 s18, s24, 0xfff50080
	s_addc_u32 s19, s25, -1
	s_cmp_eq_u32 s62, 40
	s_cselect_b32 s19, s7, s19
	s_cselect_b32 s18, s6, s18
	s_cselect_b32 s35, s1, s61
	s_cselect_b32 s34, s0, s60
	v_lshl_add_u64 v[202:203], s[24:25], 0, v[168:169]
	s_add_i32 m0, s41, 0xc000
	ds_read_b128 v[146:149], v210
	ds_read_b128 v[150:153], v210 offset:1024
	ds_read_b128 v[178:181], v210 offset:2048
	ds_read_b128 v[182:185], v210 offset:3072
	ds_read_b128 v[186:189], v210 offset:4096
	ds_read_b128 v[190:193], v210 offset:5120
	ds_read_b128 v[194:197], v210 offset:6144
	ds_read_b128 v[198:201], v210 offset:7168
	global_load_lds_dwordx4 v[202:203], off
	v_lshl_add_u64 v[202:203], s[24:25], 0, v[172:173]
	s_add_i32 m0, s41, 0xe000
	s_nop 0
	global_load_lds_dwordx4 v[202:203], off
	s_waitcnt lgkmcnt(8)
	s_setprio 1
	s_barrier
	s_waitcnt lgkmcnt(0)
	v_mfma_f32_16x16x32_bf16 v[126:129], v[130:133], v[146:149], 0
	v_mfma_f32_16x16x32_bf16 v[122:125], v[138:141], v[146:149], 0
	v_mfma_f32_16x16x32_bf16 v[110:113], v[130:133], v[178:181], 0
	v_mfma_f32_16x16x32_bf16 v[106:109], v[138:141], v[178:181], 0
	v_mfma_f32_16x16x32_bf16 v[94:97], v[130:133], v[186:189], 0
	v_mfma_f32_16x16x32_bf16 v[90:93], v[138:141], v[186:189], 0
	v_mfma_f32_16x16x32_bf16 v[78:81], v[130:133], v[194:197], 0
	v_mfma_f32_16x16x32_bf16 v[74:77], v[138:141], v[194:197], 0
	v_mfma_f32_16x16x32_bf16 v[126:129], v[134:137], v[150:153], v[126:129]
	v_mfma_f32_16x16x32_bf16 v[122:125], v[142:145], v[150:153], v[122:125]
	v_mfma_f32_16x16x32_bf16 v[110:113], v[134:137], v[182:185], v[110:113]
	v_mfma_f32_16x16x32_bf16 v[106:109], v[142:145], v[182:185], v[106:109]
	v_mfma_f32_16x16x32_bf16 v[94:97], v[134:137], v[190:193], v[94:97]
	v_mfma_f32_16x16x32_bf16 v[90:93], v[142:145], v[190:193], v[90:93]
	v_mfma_f32_16x16x32_bf16 v[78:81], v[134:137], v[198:201], v[78:81]
	v_mfma_f32_16x16x32_bf16 v[74:77], v[142:145], v[198:201], v[74:77]
	s_barrier
	s_setprio 0
	s_add_i32 s20, s52, s40
	v_lshl_add_u64 v[222:223], s[34:35], 0, v[156:157]
	s_mov_b32 m0, s20
	ds_read_b128 v[202:205], v211
	ds_read_b128 v[206:209], v211 offset:1024
	ds_read_b128 v[214:217], v211 offset:2048
	ds_read_b128 v[218:221], v211 offset:3072
	global_load_lds_dwordx4 v[222:223], off
	v_lshl_add_u64 v[224:225], s[34:35], 0, v[160:161]
	s_add_i32 m0, s20, 0x2000
	s_nop 0
	global_load_lds_dwordx4 v[224:225], off
	s_setprio 1
	s_barrier
	s_waitcnt lgkmcnt(0)
	v_mfma_f32_16x16x32_bf16 v[118:121], v[202:205], v[146:149], 0
	v_mfma_f32_16x16x32_bf16 v[114:117], v[214:217], v[146:149], 0
	v_mfma_f32_16x16x32_bf16 v[102:105], v[202:205], v[178:181], 0
	v_mfma_f32_16x16x32_bf16 v[98:101], v[214:217], v[178:181], 0
	v_mfma_f32_16x16x32_bf16 v[86:89], v[202:205], v[186:189], 0
	v_mfma_f32_16x16x32_bf16 v[82:85], v[214:217], v[186:189], 0
	v_mfma_f32_16x16x32_bf16 v[70:73], v[202:205], v[194:197], 0
	v_mfma_f32_16x16x32_bf16 v[66:69], v[214:217], v[194:197], 0
	v_mfma_f32_16x16x32_bf16 v[118:121], v[206:209], v[150:153], v[118:121]
	v_mfma_f32_16x16x32_bf16 v[114:117], v[218:221], v[150:153], v[114:117]
	v_mfma_f32_16x16x32_bf16 v[102:105], v[206:209], v[182:185], v[102:105]
	v_mfma_f32_16x16x32_bf16 v[98:101], v[218:221], v[182:185], v[98:101]
	v_mfma_f32_16x16x32_bf16 v[86:89], v[206:209], v[190:193], v[86:89]
	v_mfma_f32_16x16x32_bf16 v[82:85], v[218:221], v[190:193], v[82:85]
	v_mfma_f32_16x16x32_bf16 v[70:73], v[206:209], v[198:201], v[70:73]
	v_mfma_f32_16x16x32_bf16 v[66:69], v[218:221], v[198:201], v[66:69]
	s_barrier
	s_setprio 0
	s_mov_b32 m0, s41
	v_lshl_add_u64 v[226:227], s[18:19], 0, v[154:155]
	ds_read_b128 v[146:149], v210 offset:16384
	ds_read_b128 v[150:153], v210 offset:17408
	ds_read_b128 v[178:181], v210 offset:18432
	ds_read_b128 v[182:185], v210 offset:19456
	ds_read_b128 v[186:189], v210 offset:20480
	ds_read_b128 v[190:193], v210 offset:21504
	ds_read_b128 v[194:197], v210 offset:22528
	ds_read_b128 v[198:201], v210 offset:23552
	global_load_lds_dwordx4 v[226:227], off
	v_lshl_add_u64 v[228:229], s[18:19], 0, v[158:159]
	s_mov_b32 m0, s42
	s_nop 0
	global_load_lds_dwordx4 v[228:229], off
	s_setprio 1
	s_barrier
	s_waitcnt lgkmcnt(0)
	v_mfma_f32_16x16x32_bf16 v[62:65], v[130:133], v[146:149], 0
	v_mfma_f32_16x16x32_bf16 v[58:61], v[138:141], v[146:149], 0
	v_mfma_f32_16x16x32_bf16 v[46:49], v[130:133], v[178:181], 0
	v_mfma_f32_16x16x32_bf16 v[42:45], v[138:141], v[178:181], 0
	v_mfma_f32_16x16x32_bf16 v[30:33], v[130:133], v[186:189], 0
	v_mfma_f32_16x16x32_bf16 v[26:29], v[138:141], v[186:189], 0
	v_mfma_f32_16x16x32_bf16 v[14:17], v[130:133], v[194:197], 0
	v_mfma_f32_16x16x32_bf16 v[10:13], v[138:141], v[194:197], 0
	v_mfma_f32_16x16x32_bf16 v[62:65], v[134:137], v[150:153], v[62:65]
	v_mfma_f32_16x16x32_bf16 v[58:61], v[142:145], v[150:153], v[58:61]
	v_mfma_f32_16x16x32_bf16 v[46:49], v[134:137], v[182:185], v[46:49]
	v_mfma_f32_16x16x32_bf16 v[42:45], v[142:145], v[182:185], v[42:45]
	v_mfma_f32_16x16x32_bf16 v[30:33], v[134:137], v[190:193], v[30:33]
	v_mfma_f32_16x16x32_bf16 v[26:29], v[142:145], v[190:193], v[26:29]
	v_mfma_f32_16x16x32_bf16 v[14:17], v[134:137], v[198:201], v[14:17]
	v_mfma_f32_16x16x32_bf16 v[10:13], v[142:145], v[198:201], v[10:13]
	s_barrier
	s_setprio 0
	s_add_u32 s20, s34, 0xb0000
	s_addc_u32 s21, s35, 0
	s_add_i32 s63, s53, s40
	v_lshl_add_u64 v[130:131], s[20:21], 0, v[156:157]
	s_mov_b32 m0, s63
	s_nop 0
	global_load_lds_dwordx4 v[130:131], off
	v_lshl_add_u64 v[130:131], s[20:21], 0, v[160:161]
	s_add_i32 m0, s63, 0x2000
	s_nop 0
	global_load_lds_dwordx4 v[130:131], off
	s_waitcnt vmcnt(6)
	s_setprio 1
	s_barrier
	v_mfma_f32_16x16x32_bf16 v[54:57], v[202:205], v[146:149], 0
	v_mfma_f32_16x16x32_bf16 v[50:53], v[214:217], v[146:149], 0
	v_mfma_f32_16x16x32_bf16 v[38:41], v[202:205], v[178:181], 0
	v_mfma_f32_16x16x32_bf16 v[34:37], v[214:217], v[178:181], 0
	v_mfma_f32_16x16x32_bf16 v[22:25], v[202:205], v[186:189], 0
	v_mfma_f32_16x16x32_bf16 v[18:21], v[214:217], v[186:189], 0
	v_mfma_f32_16x16x32_bf16 v[6:9], v[202:205], v[194:197], 0
	v_mfma_f32_16x16x32_bf16 v[2:5], v[214:217], v[194:197], 0
	v_mfma_f32_16x16x32_bf16 v[54:57], v[206:209], v[150:153], v[54:57]
	v_mfma_f32_16x16x32_bf16 v[50:53], v[218:221], v[150:153], v[50:53]
	v_mfma_f32_16x16x32_bf16 v[38:41], v[206:209], v[182:185], v[38:41]
	v_mfma_f32_16x16x32_bf16 v[34:37], v[218:221], v[182:185], v[34:37]
	v_mfma_f32_16x16x32_bf16 v[22:25], v[206:209], v[190:193], v[22:25]
	v_mfma_f32_16x16x32_bf16 v[18:21], v[218:221], v[190:193], v[18:21]
	v_mfma_f32_16x16x32_bf16 v[6:9], v[206:209], v[198:201], v[6:9]
	v_mfma_f32_16x16x32_bf16 v[2:5], v[218:221], v[198:201], v[2:5]
	s_barrier
	s_setprio 0
	s_add_i32 s20, 0, 0x18000
	v_add_u32_e32 v142, s20, v165
	ds_read_b128 v[130:133], v142
	ds_read_b128 v[134:137], v142 offset:1024
	ds_read_b128 v[138:141], v142 offset:2048
	ds_read_b128 v[142:145], v142 offset:3072
	s_add_u32 s18, s18, 0xb0000
	s_addc_u32 s19, s19, 0
	s_mov_b32 m0, s43
	v_lshl_add_u64 v[202:203], s[18:19], 0, v[154:155]
	ds_read_b128 v[146:149], v210 offset:32768
	ds_read_b128 v[150:153], v210 offset:33792
	ds_read_b128 v[178:181], v210 offset:34816
	ds_read_b128 v[182:185], v210 offset:35840
	ds_read_b128 v[186:189], v210 offset:36864
	ds_read_b128 v[190:193], v210 offset:37888
	ds_read_b128 v[194:197], v210 offset:38912
	ds_read_b128 v[198:201], v210 offset:39936
	global_load_lds_dwordx4 v[202:203], off
	v_lshl_add_u64 v[202:203], s[18:19], 0, v[158:159]
	s_mov_b32 m0, s44
	s_nop 0
	global_load_lds_dwordx4 v[202:203], off
	s_waitcnt lgkmcnt(8)
	s_setprio 1
	s_barrier
	s_waitcnt lgkmcnt(0)
	v_mfma_f32_16x16x32_bf16 v[126:129], v[130:133], v[146:149], v[126:129]
	v_mfma_f32_16x16x32_bf16 v[122:125], v[138:141], v[146:149], v[122:125]
	v_mfma_f32_16x16x32_bf16 v[110:113], v[130:133], v[178:181], v[110:113]
	v_mfma_f32_16x16x32_bf16 v[106:109], v[138:141], v[178:181], v[106:109]
	v_mfma_f32_16x16x32_bf16 v[94:97], v[130:133], v[186:189], v[94:97]
	v_mfma_f32_16x16x32_bf16 v[90:93], v[138:141], v[186:189], v[90:93]
	v_mfma_f32_16x16x32_bf16 v[78:81], v[130:133], v[194:197], v[78:81]
	v_mfma_f32_16x16x32_bf16 v[74:77], v[138:141], v[194:197], v[74:77]
	v_mfma_f32_16x16x32_bf16 v[126:129], v[134:137], v[150:153], v[126:129]
	v_mfma_f32_16x16x32_bf16 v[122:125], v[142:145], v[150:153], v[122:125]
	v_mfma_f32_16x16x32_bf16 v[110:113], v[134:137], v[182:185], v[110:113]
	v_mfma_f32_16x16x32_bf16 v[106:109], v[142:145], v[182:185], v[106:109]
	v_mfma_f32_16x16x32_bf16 v[94:97], v[134:137], v[190:193], v[94:97]
	v_mfma_f32_16x16x32_bf16 v[90:93], v[142:145], v[190:193], v[90:93]
	v_mfma_f32_16x16x32_bf16 v[78:81], v[134:137], v[198:201], v[78:81]
	v_mfma_f32_16x16x32_bf16 v[74:77], v[142:145], v[198:201], v[74:77]
	s_barrier
	s_setprio 0
	s_add_i32 s21, 0, 0x1c000
	s_add_i32 s18, s20, s40
	v_add_u32_e32 v162, s21, v165
	v_lshl_add_u64 v[222:223], v[222:223], 0, s[14:15]
	s_mov_b32 m0, s18
	ds_read_b128 v[202:205], v162
	ds_read_b128 v[206:209], v162 offset:1024
	ds_read_b128 v[214:217], v162 offset:2048
	ds_read_b128 v[218:221], v162 offset:3072
	global_load_lds_dwordx4 v[222:223], off
	v_lshl_add_u64 v[222:223], v[224:225], 0, s[14:15]
	s_add_i32 m0, s18, 0x2000
	s_nop 0
	global_load_lds_dwordx4 v[222:223], off
	s_setprio 1
	s_barrier
	s_waitcnt lgkmcnt(0)
	v_mfma_f32_16x16x32_bf16 v[118:121], v[202:205], v[146:149], v[118:121]
	v_mfma_f32_16x16x32_bf16 v[114:117], v[214:217], v[146:149], v[114:117]
	v_mfma_f32_16x16x32_bf16 v[102:105], v[202:205], v[178:181], v[102:105]
	v_mfma_f32_16x16x32_bf16 v[98:101], v[214:217], v[178:181], v[98:101]
	v_mfma_f32_16x16x32_bf16 v[86:89], v[202:205], v[186:189], v[86:89]
	v_mfma_f32_16x16x32_bf16 v[82:85], v[214:217], v[186:189], v[82:85]
	v_mfma_f32_16x16x32_bf16 v[70:73], v[202:205], v[194:197], v[70:73]
	v_mfma_f32_16x16x32_bf16 v[66:69], v[214:217], v[194:197], v[66:69]
	v_mfma_f32_16x16x32_bf16 v[118:121], v[206:209], v[150:153], v[118:121]
	v_mfma_f32_16x16x32_bf16 v[114:117], v[218:221], v[150:153], v[114:117]
	v_mfma_f32_16x16x32_bf16 v[102:105], v[206:209], v[182:185], v[102:105]
	v_mfma_f32_16x16x32_bf16 v[98:101], v[218:221], v[182:185], v[98:101]
	v_mfma_f32_16x16x32_bf16 v[86:89], v[206:209], v[190:193], v[86:89]
	v_mfma_f32_16x16x32_bf16 v[82:85], v[218:221], v[190:193], v[82:85]
	v_mfma_f32_16x16x32_bf16 v[70:73], v[206:209], v[198:201], v[70:73]
	v_mfma_f32_16x16x32_bf16 v[66:69], v[218:221], v[198:201], v[66:69]
	s_barrier
	s_setprio 0
	s_mov_b32 m0, s48
	v_lshl_add_u64 v[222:223], v[226:227], 0, s[14:15]
	ds_read_b128 v[146:149], v210 offset:49152
	ds_read_b128 v[150:153], v210 offset:50176
	ds_read_b128 v[178:181], v210 offset:51200
	ds_read_b128 v[182:185], v210 offset:52224
	ds_read_b128 v[186:189], v210 offset:53248
	ds_read_b128 v[190:193], v210 offset:54272
	ds_read_b128 v[194:197], v210 offset:55296
	ds_read_b128 v[198:201], v210 offset:56320
	global_load_lds_dwordx4 v[222:223], off
	v_lshl_add_u64 v[222:223], v[228:229], 0, s[14:15]
	s_mov_b32 m0, s49
	s_nop 0
	global_load_lds_dwordx4 v[222:223], off
	s_setprio 1
	s_barrier
	s_waitcnt lgkmcnt(0)
	v_mfma_f32_16x16x32_bf16 v[62:65], v[130:133], v[146:149], v[62:65]
	v_mfma_f32_16x16x32_bf16 v[58:61], v[138:141], v[146:149], v[58:61]
	v_mfma_f32_16x16x32_bf16 v[46:49], v[130:133], v[178:181], v[46:49]
	v_mfma_f32_16x16x32_bf16 v[42:45], v[138:141], v[178:181], v[42:45]
	v_mfma_f32_16x16x32_bf16 v[30:33], v[130:133], v[186:189], v[30:33]
	v_mfma_f32_16x16x32_bf16 v[26:29], v[138:141], v[186:189], v[26:29]
	v_mfma_f32_16x16x32_bf16 v[14:17], v[130:133], v[194:197], v[14:17]
	v_mfma_f32_16x16x32_bf16 v[10:13], v[138:141], v[194:197], v[10:13]
	v_mfma_f32_16x16x32_bf16 v[62:65], v[134:137], v[150:153], v[62:65]
	v_mfma_f32_16x16x32_bf16 v[58:61], v[142:145], v[150:153], v[58:61]
	v_mfma_f32_16x16x32_bf16 v[46:49], v[134:137], v[182:185], v[46:49]
	v_mfma_f32_16x16x32_bf16 v[42:45], v[142:145], v[182:185], v[42:45]
	v_mfma_f32_16x16x32_bf16 v[30:33], v[134:137], v[190:193], v[30:33]
	v_mfma_f32_16x16x32_bf16 v[26:29], v[142:145], v[190:193], v[26:29]
	v_mfma_f32_16x16x32_bf16 v[14:17], v[134:137], v[198:201], v[14:17]
	v_mfma_f32_16x16x32_bf16 v[10:13], v[142:145], v[198:201], v[10:13]
	s_barrier
	s_setprio 0
	s_add_u32 s18, s34, 0xb0080
	s_addc_u32 s19, s35, 0
	s_add_i32 s20, s21, s40
	v_lshl_add_u64 v[130:131], s[18:19], 0, v[156:157]
	s_mov_b32 m0, s20
	s_nop 0
	global_load_lds_dwordx4 v[130:131], off
	v_lshl_add_u64 v[130:131], s[18:19], 0, v[160:161]
	s_add_i32 m0, s20, 0x2000
	s_nop 0
	global_load_lds_dwordx4 v[130:131], off
	s_waitcnt vmcnt(6)
	s_setprio 1
	s_barrier
	v_mfma_f32_16x16x32_bf16 v[54:57], v[202:205], v[146:149], v[54:57]
	v_mfma_f32_16x16x32_bf16 v[50:53], v[214:217], v[146:149], v[50:53]
	v_mfma_f32_16x16x32_bf16 v[38:41], v[202:205], v[178:181], v[38:41]
	v_mfma_f32_16x16x32_bf16 v[34:37], v[214:217], v[178:181], v[34:37]
	v_mfma_f32_16x16x32_bf16 v[22:25], v[202:205], v[186:189], v[22:25]
	v_mfma_f32_16x16x32_bf16 v[18:21], v[214:217], v[186:189], v[18:21]
	v_mfma_f32_16x16x32_bf16 v[6:9], v[202:205], v[194:197], v[6:9]
	v_mfma_f32_16x16x32_bf16 v[2:5], v[214:217], v[194:197], v[2:5]
	v_mfma_f32_16x16x32_bf16 v[54:57], v[206:209], v[150:153], v[54:57]
	v_mfma_f32_16x16x32_bf16 v[50:53], v[218:221], v[150:153], v[50:53]
	v_mfma_f32_16x16x32_bf16 v[38:41], v[206:209], v[182:185], v[38:41]
	v_mfma_f32_16x16x32_bf16 v[34:37], v[218:221], v[182:185], v[34:37]
	v_mfma_f32_16x16x32_bf16 v[22:25], v[206:209], v[190:193], v[22:25]
	v_mfma_f32_16x16x32_bf16 v[18:21], v[218:221], v[190:193], v[18:21]
	v_mfma_f32_16x16x32_bf16 v[6:9], v[206:209], v[198:201], v[6:9]
	v_mfma_f32_16x16x32_bf16 v[2:5], v[218:221], v[198:201], v[2:5]
	s_barrier
	s_setprio 0
	s_add_i32 s62, s62, 2
	s_add_u32 s24, s24, 0x100
	s_addc_u32 s25, s25, 0
	s_add_u32 s60, s60, 0x100
	s_addc_u32 s61, s61, 0
	s_cmp_gt_u32 s62, 41
.LBB0_3483:
	ds_read_b128 v[130:133], v171
	ds_read_b128 v[134:137], v171 offset:1024
	ds_read_b128 v[138:141], v171 offset:2048
	ds_read_b128 v[142:145], v171 offset:3072
	s_add_u32 s18, s24, 0xfff50080
	s_addc_u32 s19, s25, -1
	s_cmp_eq_u32 s62, 40
	s_cselect_b32 s19, s7, s19
	s_cselect_b32 s18, s6, s18
	s_cselect_b32 s35, s1, s61
	s_cselect_b32 s34, s0, s60
	v_lshl_add_u64 v[202:203], s[24:25], 0, v[168:169]
	s_add_i32 m0, s41, 0xc000
	ds_read_b128 v[146:149], v210
	ds_read_b128 v[150:153], v210 offset:1024
	ds_read_b128 v[178:181], v210 offset:2048
	ds_read_b128 v[182:185], v210 offset:3072
	ds_read_b128 v[186:189], v210 offset:4096
	ds_read_b128 v[190:193], v210 offset:5120
	ds_read_b128 v[194:197], v210 offset:6144
	ds_read_b128 v[198:201], v210 offset:7168
	global_load_lds_dwordx4 v[202:203], off
	v_lshl_add_u64 v[202:203], s[24:25], 0, v[172:173]
	s_add_i32 m0, s41, 0xe000
	s_nop 0
	global_load_lds_dwordx4 v[202:203], off
	s_waitcnt lgkmcnt(8)
	s_setprio 1
	s_barrier
	s_waitcnt lgkmcnt(0)
	v_mfma_f32_16x16x32_bf16 v[126:129], v[130:133], v[146:149], v[126:129]
	v_mfma_f32_16x16x32_bf16 v[122:125], v[138:141], v[146:149], v[122:125]
	v_mfma_f32_16x16x32_bf16 v[110:113], v[130:133], v[178:181], v[110:113]
	v_mfma_f32_16x16x32_bf16 v[106:109], v[138:141], v[178:181], v[106:109]
	v_mfma_f32_16x16x32_bf16 v[94:97], v[130:133], v[186:189], v[94:97]
	v_mfma_f32_16x16x32_bf16 v[90:93], v[138:141], v[186:189], v[90:93]
	v_mfma_f32_16x16x32_bf16 v[78:81], v[130:133], v[194:197], v[78:81]
	v_mfma_f32_16x16x32_bf16 v[74:77], v[138:141], v[194:197], v[74:77]
	v_mfma_f32_16x16x32_bf16 v[126:129], v[134:137], v[150:153], v[126:129]
	v_mfma_f32_16x16x32_bf16 v[122:125], v[142:145], v[150:153], v[122:125]
	v_mfma_f32_16x16x32_bf16 v[110:113], v[134:137], v[182:185], v[110:113]
	v_mfma_f32_16x16x32_bf16 v[106:109], v[142:145], v[182:185], v[106:109]
	v_mfma_f32_16x16x32_bf16 v[94:97], v[134:137], v[190:193], v[94:97]
	v_mfma_f32_16x16x32_bf16 v[90:93], v[142:145], v[190:193], v[90:93]
	v_mfma_f32_16x16x32_bf16 v[78:81], v[134:137], v[198:201], v[78:81]
	v_mfma_f32_16x16x32_bf16 v[74:77], v[142:145], v[198:201], v[74:77]
	s_barrier
	s_setprio 0
	s_add_i32 s20, s52, s40
	v_lshl_add_u64 v[222:223], s[34:35], 0, v[156:157]
	s_mov_b32 m0, s20
	ds_read_b128 v[202:205], v211
	ds_read_b128 v[206:209], v211 offset:1024
	ds_read_b128 v[214:217], v211 offset:2048
	ds_read_b128 v[218:221], v211 offset:3072
	global_load_lds_dwordx4 v[222:223], off
	v_lshl_add_u64 v[224:225], s[34:35], 0, v[160:161]
	s_add_i32 m0, s20, 0x2000
	s_nop 0
	global_load_lds_dwordx4 v[224:225], off
	s_setprio 1
	s_barrier
	s_waitcnt lgkmcnt(0)
	v_mfma_f32_16x16x32_bf16 v[118:121], v[202:205], v[146:149], v[118:121]
	v_mfma_f32_16x16x32_bf16 v[114:117], v[214:217], v[146:149], v[114:117]
	v_mfma_f32_16x16x32_bf16 v[102:105], v[202:205], v[178:181], v[102:105]
	v_mfma_f32_16x16x32_bf16 v[98:101], v[214:217], v[178:181], v[98:101]
	v_mfma_f32_16x16x32_bf16 v[86:89], v[202:205], v[186:189], v[86:89]
	v_mfma_f32_16x16x32_bf16 v[82:85], v[214:217], v[186:189], v[82:85]
	v_mfma_f32_16x16x32_bf16 v[70:73], v[202:205], v[194:197], v[70:73]
	v_mfma_f32_16x16x32_bf16 v[66:69], v[214:217], v[194:197], v[66:69]
	v_mfma_f32_16x16x32_bf16 v[118:121], v[206:209], v[150:153], v[118:121]
	v_mfma_f32_16x16x32_bf16 v[114:117], v[218:221], v[150:153], v[114:117]
	v_mfma_f32_16x16x32_bf16 v[102:105], v[206:209], v[182:185], v[102:105]
	v_mfma_f32_16x16x32_bf16 v[98:101], v[218:221], v[182:185], v[98:101]
	v_mfma_f32_16x16x32_bf16 v[86:89], v[206:209], v[190:193], v[86:89]
	v_mfma_f32_16x16x32_bf16 v[82:85], v[218:221], v[190:193], v[82:85]
	v_mfma_f32_16x16x32_bf16 v[70:73], v[206:209], v[198:201], v[70:73]
	v_mfma_f32_16x16x32_bf16 v[66:69], v[218:221], v[198:201], v[66:69]
	s_barrier
	s_setprio 0
	s_mov_b32 m0, s41
	v_lshl_add_u64 v[226:227], s[18:19], 0, v[154:155]
	ds_read_b128 v[146:149], v210 offset:16384
	ds_read_b128 v[150:153], v210 offset:17408
	ds_read_b128 v[178:181], v210 offset:18432
	ds_read_b128 v[182:185], v210 offset:19456
	ds_read_b128 v[186:189], v210 offset:20480
	ds_read_b128 v[190:193], v210 offset:21504
	ds_read_b128 v[194:197], v210 offset:22528
	ds_read_b128 v[198:201], v210 offset:23552
	global_load_lds_dwordx4 v[226:227], off
	v_lshl_add_u64 v[228:229], s[18:19], 0, v[158:159]
	s_mov_b32 m0, s42
	s_nop 0
	global_load_lds_dwordx4 v[228:229], off
	s_setprio 1
	s_barrier
	s_waitcnt lgkmcnt(0)
	v_mfma_f32_16x16x32_bf16 v[62:65], v[130:133], v[146:149], v[62:65]
	v_mfma_f32_16x16x32_bf16 v[58:61], v[138:141], v[146:149], v[58:61]
	v_mfma_f32_16x16x32_bf16 v[46:49], v[130:133], v[178:181], v[46:49]
	v_mfma_f32_16x16x32_bf16 v[42:45], v[138:141], v[178:181], v[42:45]
	v_mfma_f32_16x16x32_bf16 v[30:33], v[130:133], v[186:189], v[30:33]
	v_mfma_f32_16x16x32_bf16 v[26:29], v[138:141], v[186:189], v[26:29]
	v_mfma_f32_16x16x32_bf16 v[14:17], v[130:133], v[194:197], v[14:17]
	v_mfma_f32_16x16x32_bf16 v[10:13], v[138:141], v[194:197], v[10:13]
	v_mfma_f32_16x16x32_bf16 v[62:65], v[134:137], v[150:153], v[62:65]
	v_mfma_f32_16x16x32_bf16 v[58:61], v[142:145], v[150:153], v[58:61]
	v_mfma_f32_16x16x32_bf16 v[46:49], v[134:137], v[182:185], v[46:49]
	v_mfma_f32_16x16x32_bf16 v[42:45], v[142:145], v[182:185], v[42:45]
	v_mfma_f32_16x16x32_bf16 v[30:33], v[134:137], v[190:193], v[30:33]
	v_mfma_f32_16x16x32_bf16 v[26:29], v[142:145], v[190:193], v[26:29]
	v_mfma_f32_16x16x32_bf16 v[14:17], v[134:137], v[198:201], v[14:17]
	v_mfma_f32_16x16x32_bf16 v[10:13], v[142:145], v[198:201], v[10:13]
	s_barrier
	s_setprio 0
	s_add_u32 s20, s34, 0xb0000
	s_addc_u32 s21, s35, 0
	s_add_i32 s63, s53, s40
	v_lshl_add_u64 v[130:131], s[20:21], 0, v[156:157]
	s_mov_b32 m0, s63
	s_nop 0
	global_load_lds_dwordx4 v[130:131], off
	v_lshl_add_u64 v[130:131], s[20:21], 0, v[160:161]
	s_add_i32 m0, s63, 0x2000
	s_nop 0
	global_load_lds_dwordx4 v[130:131], off
	s_waitcnt vmcnt(6)
	s_setprio 1
	s_barrier
	v_mfma_f32_16x16x32_bf16 v[54:57], v[202:205], v[146:149], v[54:57]
	v_mfma_f32_16x16x32_bf16 v[50:53], v[214:217], v[146:149], v[50:53]
	v_mfma_f32_16x16x32_bf16 v[38:41], v[202:205], v[178:181], v[38:41]
	v_mfma_f32_16x16x32_bf16 v[34:37], v[214:217], v[178:181], v[34:37]
	v_mfma_f32_16x16x32_bf16 v[22:25], v[202:205], v[186:189], v[22:25]
	v_mfma_f32_16x16x32_bf16 v[18:21], v[214:217], v[186:189], v[18:21]
	v_mfma_f32_16x16x32_bf16 v[6:9], v[202:205], v[194:197], v[6:9]
	v_mfma_f32_16x16x32_bf16 v[2:5], v[214:217], v[194:197], v[2:5]
	v_mfma_f32_16x16x32_bf16 v[54:57], v[206:209], v[150:153], v[54:57]
	v_mfma_f32_16x16x32_bf16 v[50:53], v[218:221], v[150:153], v[50:53]
	v_mfma_f32_16x16x32_bf16 v[38:41], v[206:209], v[182:185], v[38:41]
	v_mfma_f32_16x16x32_bf16 v[34:37], v[218:221], v[182:185], v[34:37]
	v_mfma_f32_16x16x32_bf16 v[22:25], v[206:209], v[190:193], v[22:25]
	v_mfma_f32_16x16x32_bf16 v[18:21], v[218:221], v[190:193], v[18:21]
	v_mfma_f32_16x16x32_bf16 v[6:9], v[206:209], v[198:201], v[6:9]
	v_mfma_f32_16x16x32_bf16 v[2:5], v[218:221], v[198:201], v[2:5]
	s_barrier
	s_setprio 0
	s_add_i32 s20, 0, 0x18000
	v_add_u32_e32 v142, s20, v165
	ds_read_b128 v[130:133], v142
	ds_read_b128 v[134:137], v142 offset:1024
	ds_read_b128 v[138:141], v142 offset:2048
	ds_read_b128 v[142:145], v142 offset:3072
	s_add_u32 s18, s18, 0xb0000
	s_addc_u32 s19, s19, 0
	s_mov_b32 m0, s43
	v_lshl_add_u64 v[202:203], s[18:19], 0, v[154:155]
	ds_read_b128 v[146:149], v210 offset:32768
	ds_read_b128 v[150:153], v210 offset:33792
	ds_read_b128 v[178:181], v210 offset:34816
	ds_read_b128 v[182:185], v210 offset:35840
	ds_read_b128 v[186:189], v210 offset:36864
	ds_read_b128 v[190:193], v210 offset:37888
	ds_read_b128 v[194:197], v210 offset:38912
	ds_read_b128 v[198:201], v210 offset:39936
	global_load_lds_dwordx4 v[202:203], off
	v_lshl_add_u64 v[202:203], s[18:19], 0, v[158:159]
	s_mov_b32 m0, s44
	s_nop 0
	global_load_lds_dwordx4 v[202:203], off
	s_waitcnt lgkmcnt(8)
	s_setprio 1
	s_barrier
	s_waitcnt lgkmcnt(0)
	v_mfma_f32_16x16x32_bf16 v[126:129], v[130:133], v[146:149], v[126:129]
	v_mfma_f32_16x16x32_bf16 v[122:125], v[138:141], v[146:149], v[122:125]
	v_mfma_f32_16x16x32_bf16 v[110:113], v[130:133], v[178:181], v[110:113]
	v_mfma_f32_16x16x32_bf16 v[106:109], v[138:141], v[178:181], v[106:109]
	v_mfma_f32_16x16x32_bf16 v[94:97], v[130:133], v[186:189], v[94:97]
	v_mfma_f32_16x16x32_bf16 v[90:93], v[138:141], v[186:189], v[90:93]
	v_mfma_f32_16x16x32_bf16 v[78:81], v[130:133], v[194:197], v[78:81]
	v_mfma_f32_16x16x32_bf16 v[74:77], v[138:141], v[194:197], v[74:77]
	v_mfma_f32_16x16x32_bf16 v[126:129], v[134:137], v[150:153], v[126:129]
	v_mfma_f32_16x16x32_bf16 v[122:125], v[142:145], v[150:153], v[122:125]
	v_mfma_f32_16x16x32_bf16 v[110:113], v[134:137], v[182:185], v[110:113]
	v_mfma_f32_16x16x32_bf16 v[106:109], v[142:145], v[182:185], v[106:109]
	v_mfma_f32_16x16x32_bf16 v[94:97], v[134:137], v[190:193], v[94:97]
	v_mfma_f32_16x16x32_bf16 v[90:93], v[142:145], v[190:193], v[90:93]
	v_mfma_f32_16x16x32_bf16 v[78:81], v[134:137], v[198:201], v[78:81]
	v_mfma_f32_16x16x32_bf16 v[74:77], v[142:145], v[198:201], v[74:77]
	s_barrier
	s_setprio 0
	s_add_i32 s21, 0, 0x1c000
	s_add_i32 s18, s20, s40
	v_add_u32_e32 v162, s21, v165
	v_lshl_add_u64 v[222:223], v[222:223], 0, s[14:15]
	s_mov_b32 m0, s18
	ds_read_b128 v[202:205], v162
	ds_read_b128 v[206:209], v162 offset:1024
	ds_read_b128 v[214:217], v162 offset:2048
	ds_read_b128 v[218:221], v162 offset:3072
	global_load_lds_dwordx4 v[222:223], off
	v_lshl_add_u64 v[222:223], v[224:225], 0, s[14:15]
	s_add_i32 m0, s18, 0x2000
	s_nop 0
	global_load_lds_dwordx4 v[222:223], off
	s_setprio 1
	s_barrier
	s_waitcnt lgkmcnt(0)
	v_mfma_f32_16x16x32_bf16 v[118:121], v[202:205], v[146:149], v[118:121]
	v_mfma_f32_16x16x32_bf16 v[114:117], v[214:217], v[146:149], v[114:117]
	v_mfma_f32_16x16x32_bf16 v[102:105], v[202:205], v[178:181], v[102:105]
	v_mfma_f32_16x16x32_bf16 v[98:101], v[214:217], v[178:181], v[98:101]
	v_mfma_f32_16x16x32_bf16 v[86:89], v[202:205], v[186:189], v[86:89]
	v_mfma_f32_16x16x32_bf16 v[82:85], v[214:217], v[186:189], v[82:85]
	v_mfma_f32_16x16x32_bf16 v[70:73], v[202:205], v[194:197], v[70:73]
	v_mfma_f32_16x16x32_bf16 v[66:69], v[214:217], v[194:197], v[66:69]
	v_mfma_f32_16x16x32_bf16 v[118:121], v[206:209], v[150:153], v[118:121]
	v_mfma_f32_16x16x32_bf16 v[114:117], v[218:221], v[150:153], v[114:117]
	v_mfma_f32_16x16x32_bf16 v[102:105], v[206:209], v[182:185], v[102:105]
	v_mfma_f32_16x16x32_bf16 v[98:101], v[218:221], v[182:185], v[98:101]
	v_mfma_f32_16x16x32_bf16 v[86:89], v[206:209], v[190:193], v[86:89]
	v_mfma_f32_16x16x32_bf16 v[82:85], v[218:221], v[190:193], v[82:85]
	v_mfma_f32_16x16x32_bf16 v[70:73], v[206:209], v[198:201], v[70:73]
	v_mfma_f32_16x16x32_bf16 v[66:69], v[218:221], v[198:201], v[66:69]
	s_barrier
	s_setprio 0
	s_mov_b32 m0, s48
	v_lshl_add_u64 v[222:223], v[226:227], 0, s[14:15]
	ds_read_b128 v[146:149], v210 offset:49152
	ds_read_b128 v[150:153], v210 offset:50176
	ds_read_b128 v[178:181], v210 offset:51200
	ds_read_b128 v[182:185], v210 offset:52224
	ds_read_b128 v[186:189], v210 offset:53248
	ds_read_b128 v[190:193], v210 offset:54272
	ds_read_b128 v[194:197], v210 offset:55296
	ds_read_b128 v[198:201], v210 offset:56320
	global_load_lds_dwordx4 v[222:223], off
	v_lshl_add_u64 v[222:223], v[228:229], 0, s[14:15]
	s_mov_b32 m0, s49
	s_nop 0
	global_load_lds_dwordx4 v[222:223], off
	s_setprio 1
	s_barrier
	s_waitcnt lgkmcnt(0)
	v_mfma_f32_16x16x32_bf16 v[62:65], v[130:133], v[146:149], v[62:65]
	v_mfma_f32_16x16x32_bf16 v[58:61], v[138:141], v[146:149], v[58:61]
	v_mfma_f32_16x16x32_bf16 v[46:49], v[130:133], v[178:181], v[46:49]
	v_mfma_f32_16x16x32_bf16 v[42:45], v[138:141], v[178:181], v[42:45]
	v_mfma_f32_16x16x32_bf16 v[30:33], v[130:133], v[186:189], v[30:33]
	v_mfma_f32_16x16x32_bf16 v[26:29], v[138:141], v[186:189], v[26:29]
	v_mfma_f32_16x16x32_bf16 v[14:17], v[130:133], v[194:197], v[14:17]
	v_mfma_f32_16x16x32_bf16 v[10:13], v[138:141], v[194:197], v[10:13]
	v_mfma_f32_16x16x32_bf16 v[62:65], v[134:137], v[150:153], v[62:65]
	v_mfma_f32_16x16x32_bf16 v[58:61], v[142:145], v[150:153], v[58:61]
	v_mfma_f32_16x16x32_bf16 v[46:49], v[134:137], v[182:185], v[46:49]
	v_mfma_f32_16x16x32_bf16 v[42:45], v[142:145], v[182:185], v[42:45]
	v_mfma_f32_16x16x32_bf16 v[30:33], v[134:137], v[190:193], v[30:33]
	v_mfma_f32_16x16x32_bf16 v[26:29], v[142:145], v[190:193], v[26:29]
	v_mfma_f32_16x16x32_bf16 v[14:17], v[134:137], v[198:201], v[14:17]
	v_mfma_f32_16x16x32_bf16 v[10:13], v[142:145], v[198:201], v[10:13]
	s_barrier
	s_setprio 0
	s_add_u32 s18, s34, 0xb0080
	s_addc_u32 s19, s35, 0
	s_add_i32 s20, s21, s40
	v_lshl_add_u64 v[130:131], s[18:19], 0, v[156:157]
	s_mov_b32 m0, s20
	s_nop 0
	global_load_lds_dwordx4 v[130:131], off
	v_lshl_add_u64 v[130:131], s[18:19], 0, v[160:161]
	s_add_i32 m0, s20, 0x2000
	s_nop 0
	global_load_lds_dwordx4 v[130:131], off
	s_waitcnt vmcnt(6)
	s_setprio 1
	s_barrier
	v_mfma_f32_16x16x32_bf16 v[54:57], v[202:205], v[146:149], v[54:57]
	v_mfma_f32_16x16x32_bf16 v[50:53], v[214:217], v[146:149], v[50:53]
	v_mfma_f32_16x16x32_bf16 v[38:41], v[202:205], v[178:181], v[38:41]
	v_mfma_f32_16x16x32_bf16 v[34:37], v[214:217], v[178:181], v[34:37]
	v_mfma_f32_16x16x32_bf16 v[22:25], v[202:205], v[186:189], v[22:25]
	v_mfma_f32_16x16x32_bf16 v[18:21], v[214:217], v[186:189], v[18:21]
	v_mfma_f32_16x16x32_bf16 v[6:9], v[202:205], v[194:197], v[6:9]
	v_mfma_f32_16x16x32_bf16 v[2:5], v[214:217], v[194:197], v[2:5]
	v_mfma_f32_16x16x32_bf16 v[54:57], v[206:209], v[150:153], v[54:57]
	v_mfma_f32_16x16x32_bf16 v[50:53], v[218:221], v[150:153], v[50:53]
	v_mfma_f32_16x16x32_bf16 v[38:41], v[206:209], v[182:185], v[38:41]
	v_mfma_f32_16x16x32_bf16 v[34:37], v[218:221], v[182:185], v[34:37]
	v_mfma_f32_16x16x32_bf16 v[22:25], v[206:209], v[190:193], v[22:25]
	v_mfma_f32_16x16x32_bf16 v[18:21], v[218:221], v[190:193], v[18:21]
	v_mfma_f32_16x16x32_bf16 v[6:9], v[206:209], v[198:201], v[6:9]
	v_mfma_f32_16x16x32_bf16 v[2:5], v[218:221], v[198:201], v[2:5]
	s_barrier
	s_setprio 0
	s_add_i32 s62, s62, 2
	s_add_u32 s24, s24, 0x100
	s_addc_u32 s25, s25, 0
	s_add_u32 s60, s60, 0x100
	s_addc_u32 s61, s61, 0
	s_cmp_gt_u32 s62, 41
	s_cbranch_scc0 .LBB0_3483
	s_ashr_i32 s18, s57, 3
	s_mul_hi_i32 s19, s18, 0x9000
	s_mul_i32 s18, s18, 0x9000
	s_add_u32 s20, s58, s18
	s_addc_u32 s21, s59, s19
	s_lshl_b32 s34, s8, 8
	v_lshl_add_u32 v206, s57, 8, v1
	s_ashr_i32 s35, s34, 31
	v_ashrrev_i32_e32 v207, 31, v206
	s_lshl_b64 s[18:19], s[34:35], 2
	v_lshl_add_u64 v[130:131], s[34:35], 1, v[166:167]
	v_lshlrev_b64 v[178:179], 11, v[206:207]
	s_add_u32 s18, s20, s18
	v_lshl_add_u64 v[132:133], v[130:131], 0, v[178:179]
	s_addc_u32 s19, s21, s19
	v_lshlrev_b32_e32 v162, 2, v164
	global_load_dwordx4 v[180:183], v[132:133], off
	global_load_dwordx4 v[184:187], v[132:133], off offset:256
	v_lshl_add_u64 v[132:133], s[18:19], 0, v[162:163]
	v_lshl_add_u64 v[134:135], v[132:133], 0, s[16:17]
	v_add_co_u32_e32 v132, vcc, s51, v132
	v_or_b32_e32 v204, 16, v206
	s_nop 0
	v_addc_co_u32_e32 v133, vcc, 0, v133, vcc
	global_load_dwordx4 v[188:191], v[132:133], off
	global_load_dwordx4 v[214:217], v[134:135], off offset:512
	global_load_dwordx4 v[218:221], v[134:135], off offset:16
	global_load_dwordx4 v[222:225], v[134:135], off offset:528
	v_or_b32_e32 v200, 32, v206
	v_or_b32_e32 v196, 48, v206
	v_ashrrev_i32_e32 v205, 31, v204
	v_ashrrev_i32_e32 v201, 31, v200
	v_ashrrev_i32_e32 v197, 31, v196
	v_lshlrev_b64 v[208:209], 11, v[204:205]
	v_lshlrev_b64 v[202:203], 11, v[200:201]
	v_lshlrev_b64 v[198:199], 11, v[196:197]
	v_lshl_add_u64 v[132:133], v[130:131], 0, v[208:209]
	v_lshl_add_u64 v[134:135], v[130:131], 0, v[202:203]
	v_lshl_add_u64 v[130:131], v[130:131], 0, v[198:199]
	global_load_dwordx4 v[150:153], v[132:133], off
	global_load_dwordx4 v[146:149], v[132:133], off offset:256
	global_load_dwordx4 v[142:145], v[134:135], off
	global_load_dwordx4 v[138:141], v[134:135], off offset:256
	s_nop 0
	global_load_dwordx4 v[134:137], v[130:131], off
	s_nop 0
	global_load_dwordx4 v[130:133], v[130:131], off offset:256
	v_lshl_add_u64 v[192:193], s[10:11], 0, v[178:179]
	v_or_b32_e32 v178, s34, v164
	v_mov_b32_e32 v179, s35
	v_lshl_add_u64 v[226:227], v[178:179], 1, v[192:193]
	s_lshl_b32 s24, s8, 2
	s_ashr_i32 s25, s24, 31
	s_waitcnt vmcnt(0)
	v_lshlrev_b32_e32 v228, 16, v180
	v_lshlrev_b32_e32 v232, 16, v184
	v_and_b32_e32 v233, 0xffff0000, v184
	v_and_b32_e32 v229, 0xffff0000, v180
	v_lshlrev_b32_e32 v234, 16, v181
	v_and_b32_e32 v235, 0xffff0000, v181
	v_lshlrev_b32_e32 v236, 16, v185
	v_pk_mul_f32 v[192:193], v[214:215], 0.5 op_sel_hi:[1,0]
	v_and_b32_e32 v237, 0xffff0000, v185
	v_lshlrev_b32_e32 v244, 16, v187
	v_and_b32_e32 v245, 0xffff0000, v187
	v_pk_mul_f32 v[194:195], v[188:189], 0.5 op_sel_hi:[1,0]
	v_pk_mul_f32 v[188:189], v[216:217], 0.5 op_sel_hi:[1,0]
	v_pk_mul_f32 v[180:181], v[224:225], 0.5 op_sel_hi:[1,0]
	v_pk_fma_f32 v[118:119], v[118:119], v[192:193], v[232:233]
	v_pk_mul_f32 v[190:191], v[190:191], 0.5 op_sel_hi:[1,0]
	v_pk_fma_f32 v[126:127], v[126:127], v[194:195], v[228:229]
	v_pk_fma_f32 v[120:121], v[120:121], v[188:189], v[236:237]
	v_pk_fma_f32 v[216:217], v[116:117], v[180:181], v[244:245]
	v_pk_mul_f32 v[116:117], v[118:119], v[118:119]
	v_lshlrev_b32_e32 v240, 16, v186
	v_and_b32_e32 v241, 0xffff0000, v186
	v_pk_mul_f32 v[186:187], v[218:219], 0.5 op_sel_hi:[1,0]
	v_pk_mul_f32 v[184:185], v[222:223], 0.5 op_sel_hi:[1,0]
	v_pk_fma_f32 v[128:129], v[128:129], v[190:191], v[234:235]
	v_pk_mul_f32 v[218:219], v[120:121], v[120:121]
	v_pk_fma_f32 v[116:117], v[126:127], v[126:127], v[116:117]
	v_lshlrev_b32_e32 v238, 16, v182
	v_and_b32_e32 v239, 0xffff0000, v182
	v_pk_fma_f32 v[214:215], v[114:115], v[184:185], v[240:241]
	v_cvt_pk_bf16_f32 v114, v126, v127
	v_pk_fma_f32 v[126:127], v[128:129], v[128:129], v[218:219]
	v_add_f32_e32 v116, v116, v117
	v_lshlrev_b32_e32 v242, 16, v183
	v_and_b32_e32 v243, 0xffff0000, v183
	v_pk_mul_f32 v[182:183], v[220:221], 0.5 op_sel_hi:[1,0]
	v_pk_fma_f32 v[122:123], v[122:123], v[186:187], v[238:239]
	v_pk_mul_f32 v[220:221], v[214:215], v[214:215]
	v_add_f32_e32 v116, v126, v116
	v_cvt_pk_bf16_f32 v115, v128, v129
	v_pk_fma_f32 v[128:129], v[122:123], v[122:123], v[220:221]
	v_add_f32_e32 v116, v127, v116
	v_pk_fma_f32 v[124:125], v[124:125], v[182:183], v[242:243]
	v_pk_mul_f32 v[222:223], v[216:217], v[216:217]
	v_add_f32_e32 v116, v128, v116
	v_pk_fma_f32 v[218:219], v[124:125], v[124:125], v[222:223]
	v_add_f32_e32 v116, v129, v116
	v_add_f32_e32 v116, v218, v116
	v_and_b32_e32 v117, 64, v212
	v_add_f32_e32 v127, v219, v116
	v_xor_b32_e32 v116, 16, v212
	v_add_u32_e32 v128, 64, v117
	v_cmp_lt_i32_e32 vcc, v116, v128
	v_cvt_pk_bf16_f32 v117, v124, v125
	s_nop 0
	v_cndmask_b32_e32 v116, v212, v116, vcc
	v_lshlrev_b32_e32 v126, 2, v116
	ds_bpermute_b32 v129, v126, v127
	v_cvt_pk_bf16_f32 v116, v122, v123
	global_store_dwordx4 v[226:227], v[114:117], off nt
	s_nop 1
	v_xor_b32_e32 v115, 32, v212
	v_cmp_lt_i32_e32 vcc, v115, v128
	s_waitcnt lgkmcnt(0)
	v_add_f32_e32 v114, v127, v129
	v_cvt_pk_bf16_f32 v116, v118, v119
	v_cndmask_b32_e32 v115, v212, v115, vcc
	v_lshlrev_b32_e32 v127, 2, v115
	ds_bpermute_b32 v115, v127, v114
	v_cvt_pk_bf16_f32 v117, v120, v121
	v_cvt_pk_bf16_f32 v118, v214, v215
	v_cvt_pk_bf16_f32 v119, v216, v217
	global_store_dwordx4 v[226:227], v[116:119], off offset:256 nt
	s_and_saveexec_b64 s[18:19], s[2:3]
	s_cbranch_execz .LBB0_3486
	s_waitcnt lgkmcnt(0)
	v_add_f32_e32 v116, v114, v115
	v_lshlrev_b64 v[114:115], 6, v[206:207]
	v_lshl_add_u64 v[114:115], s[12:13], 0, v[114:115]
	v_lshl_add_u64 v[114:115], s[24:25], 2, v[114:115]
	s_lshl_b32 s8, s47, 2
	v_lshl_add_u64 v[114:115], v[114:115], 0, s[8:9]
	global_store_dword v[114:115], v116, off
